# residual epilogue (MB=3 tiles) rewritten by hand: all gate/X loads of a tile issued together before packing, counted waits, gate row loaded once per pass; on top of the previous stack
# baseline (speedup 1.0000x reference)
; DI int tid() { int t; asm volatile("v_mov_b32 %0, %1" : "=v"(t) : "v"((int)threadIdx.x)); return t; }
; template <int MB, class Epi>
; DI void gemm_tile(const u16* __restrict__ A, int lda, int row0, int Mrows, const u16* __restrict__ Bt, int ldb, int K, char* smem, Epi& epi, int rot) {
;     ...
;   const int t = tid(), lane = t & 63, w = __builtin_amdgcn_readfirstlane(t >> 6), wm = w >> 2, wn = w & 3, r = lane & 31, h = lane >> 5;
;   constexpr int NAJ = MB;
;   const int lr = t >> 3;
;   const int lch = (t & 7) ^ ((lr >> 1) & 7);
;   unsigned aoff[NAJ];
; #pragma unroll
;   for (int j = 0; j < NAJ; ++j) {
;     int gr = row0 + lr + 64 * j;
;     gr = gr < 0 ? 0 : (gr > Mrows - 1 ? Mrows - 1 : gr);
;     aoff[j] = (unsigned)gr * (unsigned)lda + lch * 8;
;   }
;   const u16* bp = Bt + (size_t)lr * ldb + lch * 8;
;   f32x16 acc[2][MB];
; #pragma unroll
;   for (int nb = 0; nb < 2; ++nb)
; #pragma unroll
;     for (int mb = 0; mb < MB; ++mb)
; #pragma unroll
;       for (int i = 0; i < 16; ++i) acc[nb][mb][i] = 0.f;
;   const int KT = K >> 6;
;   int kcur = rot % KT;
;     ...
;   GEMM_STAGE(0)
;   asm volatile("s_waitcnt vmcnt(0)" ::: "memory");
;   __syncthreads();
;   const int sw = (r >> 1) & 7;
;   int foff[4];
; #pragma unroll
;   for (int ks = 0; ks < 4; ++ks) foff[ks] = r * 128 + (((2 * ks + h) ^ sw) << 4);
;   bf8 af[2][MB], bfr[2][2];
;   {
;     const char* as0 = As + wm * (32 * MB) * 128;
;     const char* bs0 = Bs + wn * 64 * 128;
; #pragma unroll
;     for (int mb = 0; mb < MB; ++mb) af[0][mb] = *(const bf8*)(as0 + mb * 32 * 128 + foff[0]);
; #pragma unroll
;     for (int nb = 0; nb < 2; ++nb) bfr[0][nb] = *(const bf8*)(bs0 + nb * 32 * 128 + foff[0]);
;   }
;   const int kbase = rot % KT;
;   if (KT > 1) {
;     const int k1_ = (kbase + 1 >= KT) ? kbase + 1 - KT : kbase + 1;
;     const int ko_ = k1_ * 64;
; #pragma unroll
;     for (int pc = 0; pc < 3; ++pc) GEMM_PIECE(1, pc)
; template <int MB>
; DI void phase_res_t(const Params& p, int l, int which, char* smem) {
;     ...
;   for (int tile = bid(); tile < MT * 4; tile += gridDim.x) {
;     int mt, nt;
;     if (!tile_map(tile, 4, MT, mt, nt)) continue;
;     EpiRes<MB> e;
;     e.X = (_Float16*)(p.ws + OFF_X); e.gate = gate; e.row0 = mt * TR; e.n0 = nt * 256; e.ostage = (u16*)smem;
;     gemm_tile<MB>(A, lda, mt * TR, rows, W + (size_t)nt * 256 * K, K, K, smem, e, tile);
.LBB0_647:
	s_ashr_i32 s2, s0, 3
	s_lshr_b32 s3, s2, 30
	s_add_i32 s3, s2, s3
	s_ashr_i32 s3, s3, 2
	s_and_b32 s10, s0, 7
	s_lshl_b32 s11, s3, 3
	s_or_b32 s10, s11, s10
	s_cmpk_gt_i32 s10, 0xbf
	s_cbranch_scc1 .LBB0_646
	s_mulk_i32 s10, 0xc0
	v_mov_b32 v124, v163
	s_lshl_b32 s3, s3, 2
	v_ashrrev_i32_e32 v2, 3, v124
	v_lshrrev_b32_e32 v0, 4, v124
	v_xor_b32_e32 v0, v0, v124
	v_add_u32_e32 v3, s10, v2
	s_movk_i32 s11, 0xffc0
	s_sub_i32 s2, s2, s3
	v_lshlrev_b32_e32 v0, 3, v0
	v_med3_i32 v6, v3, s11, v209
	s_movk_i32 s11, 0xff80
	s_ashr_i32 s3, s2, 31
	v_and_b32_e32 v0, 56, v0
	v_med3_i32 v4, v3, 0, v208
	v_med3_i32 v3, v3, s11, v210
	s_lshl_b64 s[12:13], s[2:3], 19
	v_lshl_or_b32 v3, v3, 10, v0
	s_add_u32 s12, s8, s12
	v_add_u32_e32 v122, 0x20000, v3
	v_ashrrev_i32_e32 v3, 31, v2
	s_addc_u32 s13, s9, s13
	v_lshlrev_b64 v[2:3], 11, v[2:3]
	v_lshl_add_u64 v[2:3], s[12:13], 0, v[2:3]
	s_ashr_i32 s12, s0, 31
	s_lshr_b32 s12, s12, 28
	s_add_i32 s12, s0, s12
	s_and_b32 s12, s12, -16
	v_readfirstlane_b32 s14, v124
	s_sub_i32 s16, s0, s12
	s_bfe_u32 s3, s14, 0x20006
	s_ashr_i32 s11, s14, 8
	s_lshl_b32 s12, s16, 6
	s_lshl_b32 s14, s14, 4
	v_lshl_or_b32 v4, v4, 10, v0
	v_lshl_or_b32 v6, v6, 10, v0
	v_lshlrev_b32_e32 v0, 1, v0
	s_ashr_i32 s13, s12, 31
	s_and_b32 s14, s14, 0xfffffc00
	v_lshl_add_u64 v[120:121], v[2:3], 0, v[0:1]
	s_lshl_b64 s[12:13], s[12:13], 1
	s_add_i32 s17, s14, 0x10000
	v_lshl_add_u64 v[2:3], v[120:121], 0, s[12:13]
	s_add_u32 s12, s20, s12
	s_addc_u32 s13, s21, s13
	v_lshlrev_b32_e32 v0, 1, v4
	v_add_u32_e32 v118, 0x10000, v6
	v_lshl_add_u64 v[6:7], s[12:13], 0, v[0:1]
	v_mov_b32_e32 v119, v1
	s_mov_b32 m0, s14
	s_nop 0
	global_load_lds_dwordx4 v[6:7], off
	v_lshlrev_b64 v[6:7], 1, v[118:119]
	v_lshl_add_u64 v[8:9], s[12:13], 0, v[6:7]
	v_mov_b32_e32 v123, v1
	s_add_i32 s18, s14, 0x2000
	s_mov_b32 m0, s18
	s_nop 0
	global_load_lds_dwordx4 v[8:9], off
	v_lshlrev_b64 v[8:9], 1, v[122:123]
	v_lshl_add_u64 v[10:11], s[12:13], 0, v[8:9]
	s_add_i32 s12, s14, 0x4000
	s_mov_b32 m0, s12
	s_nop 0
	global_load_lds_dwordx4 v[10:11], off
	s_mov_b32 m0, s17
	s_nop 0
	global_load_lds_dwordx4 v[2:3], off
	s_add_i32 s12, s14, 0x12000
	v_lshl_add_u64 v[10:11], v[2:3], 0, s[4:5]
	s_mov_b32 m0, s12
	s_nop 0
	global_load_lds_dwordx4 v[10:11], off
	s_add_i32 s12, s14, 0x14000
	v_lshl_add_u64 v[10:11], v[2:3], 0, s[6:7]
	s_mov_b32 m0, s12
	s_nop 0
	global_load_lds_dwordx4 v[10:11], off
	s_add_i32 s12, s14, 0x16000
	v_lshl_add_u64 v[2:3], v[2:3], 0, s[34:35]
	s_mov_b32 m0, s12
	s_nop 0
	global_load_lds_dwordx4 v[2:3], off
	s_lshl_b32 s12, s3, 13
	s_bitset1_b32 s12, 16
	s_cmp_lt_i32 s16, 15
	s_cselect_b32 s18, 0, -16
	s_add_i32 s18, s16, s18
	s_lshl_b32 s18, s18, 6
	v_lshrrev_b32_e32 v5, 5, v124
	v_and_b32_e32 v125, 31, v124
	v_bfe_u32 v2, v124, 1, 3
	s_add_i32 s18, s18, 64
	v_lshlrev_b32_e32 v3, 7, v125
	v_bitop3_b32 v5, v5, v2, 1 bitop3:0x6c
	s_ashr_i32 s19, s18, 31
	s_waitcnt vmcnt(0)
	v_bfe_u32 v126, v124, 5, 1
	v_lshl_or_b32 v5, v5, 4, v3
	s_mul_i32 s13, s11, 0x3000
	s_lshl_b64 s[18:19], s[18:19], 1
	v_bitop3_b32 v10, v126, v2, 2 bitop3:0x36
	v_or_b32_e32 v131, s13, v5
	s_add_u32 s18, s20, s18
	s_waitcnt vmcnt(0)
	s_barrier
	v_lshl_or_b32 v129, v10, 4, v3
	v_bitop3_b32 v10, v126, v2, 4 bitop3:0x36
	v_bitop3_b32 v2, v126, v2, 6 bitop3:0x36
	ds_read_b128 v[110:113], v131
	ds_read_b128 v[106:109], v131 offset:4096
	v_or_b32_e32 v130, s12, v5
	ds_read_b128 v[98:101], v131 offset:8192
	ds_read_b128 v[114:117], v130
	ds_read_b128 v[102:105], v130 offset:4096
	s_addc_u32 s19, s21, s19
	v_lshl_or_b32 v128, v10, 4, v3
	v_lshl_or_b32 v127, v2, 4, v3
	s_add_i32 s22, s14, 0x8000
	v_lshl_add_u64 v[2:3], s[18:19], 0, v[0:1]
	s_mov_b32 m0, s22
	s_nop 0
	global_load_lds_dwordx4 v[2:3], off
	v_lshl_add_u64 v[2:3], s[18:19], 0, v[6:7]
	s_add_i32 s22, s14, 0xa000
	s_mov_b32 m0, s22
	s_nop 0
	global_load_lds_dwordx4 v[2:3], off
	v_lshl_add_u64 v[2:3], s[18:19], 0, v[8:9]
	s_add_i32 s18, s14, 0xc000
	s_mov_b32 m0, s18
	s_nop 0
	global_load_lds_dwordx4 v[2:3], off
	v_mov_b32_e32 v34, 0
	s_mov_b32 s15, 0
	v_lshlrev_b32_e32 v0, 1, v4
	s_mov_b32 s22, 0
	v_mov_b32_e32 v35, v34
	v_mov_b32_e32 v36, v34
	v_mov_b32_e32 v37, v34
	v_mov_b32_e32 v38, v34
	v_mov_b32_e32 v39, v34
	v_mov_b32_e32 v40, v34
	v_mov_b32_e32 v41, v34
	v_mov_b32_e32 v42, v34
	v_mov_b32_e32 v43, v34
	v_mov_b32_e32 v44, v34
	v_mov_b32_e32 v45, v34
	v_mov_b32_e32 v46, v34
	v_mov_b32_e32 v47, v34
	v_mov_b32_e32 v48, v34
	v_mov_b32_e32 v49, v34
	v_mov_b32_e32 v66, v34
	v_mov_b32_e32 v67, v34
	v_mov_b32_e32 v68, v34
	v_mov_b32_e32 v69, v34
	v_mov_b32_e32 v70, v34
	v_mov_b32_e32 v71, v34
	v_mov_b32_e32 v72, v34
	v_mov_b32_e32 v73, v34
	v_mov_b32_e32 v74, v34
	v_mov_b32_e32 v75, v34
	v_mov_b32_e32 v76, v34
	v_mov_b32_e32 v77, v34
	v_mov_b32_e32 v78, v34
	v_mov_b32_e32 v79, v34
	v_mov_b32_e32 v80, v34
	v_mov_b32_e32 v81, v34
	v_mov_b32_e32 v2, v34
	v_mov_b32_e32 v3, v34
	v_mov_b32_e32 v4, v34
	v_mov_b32_e32 v5, v34
	v_mov_b32_e32 v6, v34
	v_mov_b32_e32 v7, v34
	v_mov_b32_e32 v8, v34
	v_mov_b32_e32 v9, v34
	v_mov_b32_e32 v10, v34
	v_mov_b32_e32 v11, v34
	v_mov_b32_e32 v12, v34
	v_mov_b32_e32 v13, v34
	v_mov_b32_e32 v14, v34
	v_mov_b32_e32 v15, v34
	v_mov_b32_e32 v16, v34
	v_mov_b32_e32 v17, v34
	v_mov_b32_e32 v82, v34
	v_mov_b32_e32 v83, v34
	v_mov_b32_e32 v84, v34
	v_mov_b32_e32 v85, v34
	v_mov_b32_e32 v86, v34
	v_mov_b32_e32 v87, v34
	v_mov_b32_e32 v88, v34
	v_mov_b32_e32 v89, v34
	v_mov_b32_e32 v90, v34
	v_mov_b32_e32 v91, v34
	v_mov_b32_e32 v92, v34
	v_mov_b32_e32 v93, v34
	v_mov_b32_e32 v94, v34
	v_mov_b32_e32 v95, v34
	v_mov_b32_e32 v96, v34
	v_mov_b32_e32 v97, v34
	v_mov_b32_e32 v50, v34
	v_mov_b32_e32 v51, v34
	v_mov_b32_e32 v52, v34
	v_mov_b32_e32 v53, v34
	v_mov_b32_e32 v54, v34
	v_mov_b32_e32 v55, v34
	v_mov_b32_e32 v56, v34
	v_mov_b32_e32 v57, v34
	v_mov_b32_e32 v58, v34
	v_mov_b32_e32 v59, v34
	v_mov_b32_e32 v60, v34
	v_mov_b32_e32 v61, v34
	v_mov_b32_e32 v62, v34
	v_mov_b32_e32 v63, v34
	v_mov_b32_e32 v64, v34
	v_mov_b32_e32 v65, v34
	v_mov_b32_e32 v18, v34
	v_mov_b32_e32 v19, v34
	v_mov_b32_e32 v20, v34
	v_mov_b32_e32 v21, v34
	v_mov_b32_e32 v22, v34
	v_mov_b32_e32 v23, v34
	v_mov_b32_e32 v24, v34
	v_mov_b32_e32 v25, v34
	v_mov_b32_e32 v26, v34
	v_mov_b32_e32 v27, v34
	v_mov_b32_e32 v28, v34
	v_mov_b32_e32 v29, v34
	v_mov_b32_e32 v30, v34
	v_mov_b32_e32 v31, v34
	v_mov_b32_e32 v32, v34
	v_mov_b32_e32 v33, v34
; template <int MB, class Epi>
; DI void gemm_tile(const u16* __restrict__ A, int lda, int row0, int Mrows, const u16* __restrict__ Bt, int ldb, int K, char* smem, Epi& epi, int rot) {
;     ...
;   for (int kt = 0; kt < KT; ++kt) {
;     const bool more = (kt + 1 < KT);
;     const bool more2 = (kt + 2 < KT);
;     const int nstg = (kt + 1) & 1;
;     const char* as = As + (kt & 1) * 32768 + wm * (32 * MB) * 128;
;     const char* bs = Bs + (kt & 1) * 32768 + wn * 64 * 128;
;     int k1_ = kbase + kt + 1; if (k1_ >= KT) k1_ -= KT;
;     int k2_ = kbase + kt + 2; if (k2_ >= KT) k2_ -= KT; if (k2_ >= KT) k2_ -= KT;
; #pragma unroll
;     for (int ks = 0; ks < 3; ++ks) {
; #pragma unroll
;       for (int idx = 0; idx < 2 * MB; ++idx) {
;         const int nb = idx / MB, mb = idx % MB;
;         acc[nb][mb] = mfma32(bfr[ks & 1][nb], af[ks & 1][mb], acc[nb][mb]);
;         if (idx < MB) af[(ks + 1) & 1][idx] = *(const bf8*)(as + idx * 32 * 128 + foff[ks + 1]);
;         else if (idx < MB + 2) bfr[(ks + 1) & 1][idx - MB] = *(const bf8*)(bs + (idx - MB) * 32 * 128 + foff[ks + 1]);
;         if (more && ks < 2 && idx < 3) {
;           const int ko_ = k1_ * 64;
;           GEMM_PIECE(nstg, 3 + ks * 3 + idx)
;         }
;         __builtin_amdgcn_sched_barrier(0);
;       }
;     }
;     if (more) {
;       asm volatile("s_waitcnt vmcnt(0)" ::: "memory");
;       __syncthreads();
;       if (more2) {
;         const int ko_ = k2_ * 64;
; #pragma unroll
;         for (int pc = 0; pc < 3; ++pc) GEMM_PIECE(kt & 1, pc)
;       }
;       __builtin_amdgcn_sched_barrier(0);
;       const char* asn = As + nstg * 32768 + wm * (32 * MB) * 128;
;       const char* bsn = Bs + nstg * 32768 + wn * 64 * 128;
; #pragma unroll
;       for (int mb = 0; mb < MB; ++mb) af[0][mb] = *(const bf8*)(asn + mb * 32 * 128 + foff[0]);
; #pragma unroll
;       for (int nb = 0; nb < 2; ++nb) bfr[0][nb] = *(const bf8*)(bsn + nb * 32 * 128 + foff[0]);
;     }
; #pragma unroll
;     for (int nb = 0; nb < 2; ++nb)
; #pragma unroll
;       for (int mb = 0; mb < MB; ++mb) acc[nb][mb] = mfma32(bfr[1][nb], af[1][mb], acc[nb][mb]);
; #pragma unroll
;     for (int gk = 0; gk < 2 * MB; ++gk) {
;       __builtin_amdgcn_sched_group_barrier(0x008, 1, 0);
;       __builtin_amdgcn_sched_group_barrier(0x100, 1, 0);
;     }
;     __builtin_amdgcn_sched_barrier(0);
;   }
.LBB0_649:
	s_and_b32 s23, s15, 0x8000
	s_add_i32 s19, s22, 1
	s_add_i32 s28, s13, s23
	s_add_i32 s25, s12, s23
	s_add_i32 s22, s16, s22
	s_cmp_lt_i32 s22, 15
	s_cselect_b32 s18, 0, -16
	s_waitcnt lgkmcnt(1)
	v_mfma_f32_32x32x16_bf16 v[66:81], v[114:117], v[110:113], v[66:81]
	s_add_i32 s18, s22, s18
	s_lshl_b32 s18, s18, 6
	s_add_i32 s26, s18, 64
	s_add_i32 s15, s15, 0x8000
	v_add_u32_e32 v144, s28, v129
	s_ashr_i32 s27, s26, 31
	s_and_b32 s18, s15, 0x8000
	ds_read_b128 v[132:135], v144
	v_lshl_add_u64 v[140:141], s[26:27], 1, v[120:121]
	s_add_i32 s26, s18, s17
	s_mov_b32 m0, s26
	s_nop 0
	global_load_lds_dwordx4 v[140:141], off
	v_mfma_f32_32x32x16_bf16 v[34:49], v[114:117], v[106:109], v[34:49]
	ds_read_b128 v[136:139], v144 offset:4096
	v_lshl_add_u64 v[142:143], v[140:141], 0, s[4:5]
	s_add_i32 s27, s26, 0x2000
	s_mov_b32 m0, s27
	s_nop 0
	global_load_lds_dwordx4 v[142:143], off
	v_mfma_f32_32x32x16_bf16 v[2:17], v[114:117], v[98:101], v[2:17]
	ds_read_b128 v[114:117], v144 offset:8192
	v_lshl_add_u64 v[142:143], v[140:141], 0, s[6:7]
	s_add_i32 s27, s26, 0x4000
	s_mov_b32 m0, s27
	s_nop 0
	global_load_lds_dwordx4 v[142:143], off
	s_waitcnt lgkmcnt(3)
	v_mfma_f32_32x32x16_bf16 v[82:97], v[102:105], v[110:113], v[82:97]
	v_add_u32_e32 v142, s25, v129
	ds_read_b128 v[110:113], v142
	v_mfma_f32_32x32x16_bf16 v[50:65], v[102:105], v[106:109], v[50:65]
	ds_read_b128 v[106:109], v142 offset:4096
	v_mfma_f32_32x32x16_bf16 v[18:33], v[102:105], v[98:101], v[18:33]
	s_waitcnt lgkmcnt(1)
	v_mfma_f32_32x32x16_bf16 v[66:81], v[110:113], v[132:135], v[66:81]
	v_add_u32_e32 v142, s28, v128
	ds_read_b128 v[98:101], v142
	v_lshl_add_u64 v[102:103], v[140:141], 0, s[34:35]
	s_addk_i32 s26, 0x6000
	s_mov_b32 m0, s26
	s_nop 0
	global_load_lds_dwordx4 v[102:103], off
	v_mfma_f32_32x32x16_bf16 v[34:49], v[110:113], v[136:139], v[34:49]
	ds_read_b128 v[102:105], v142 offset:4096
	v_mfma_f32_32x32x16_bf16 v[2:17], v[110:113], v[114:117], v[2:17]
	ds_read_b128 v[110:113], v142 offset:8192
	s_waitcnt lgkmcnt(3)
	v_mfma_f32_32x32x16_bf16 v[82:97], v[106:109], v[132:135], v[82:97]
	v_add_u32_e32 v140, s25, v128
	ds_read_b128 v[132:135], v140
	v_mfma_f32_32x32x16_bf16 v[50:65], v[106:109], v[136:139], v[50:65]
	ds_read_b128 v[136:139], v140 offset:4096
	v_mfma_f32_32x32x16_bf16 v[18:33], v[106:109], v[114:117], v[18:33]
	s_waitcnt lgkmcnt(1)
	v_mfma_f32_32x32x16_bf16 v[66:81], v[132:135], v[98:101], v[66:81]
	v_add_u32_e32 v106, s28, v127
	ds_read_b128 v[114:117], v106
	v_mfma_f32_32x32x16_bf16 v[34:49], v[132:135], v[102:105], v[34:49]
	ds_read_b128 v[140:143], v106 offset:4096
	v_mfma_f32_32x32x16_bf16 v[2:17], v[132:135], v[110:113], v[2:17]
	ds_read_b128 v[132:135], v106 offset:8192
	s_waitcnt lgkmcnt(3)
	v_mfma_f32_32x32x16_bf16 v[82:97], v[136:139], v[98:101], v[82:97]
	v_add_u32_e32 v106, s25, v127
	ds_read_b128 v[98:101], v106
	v_mfma_f32_32x32x16_bf16 v[50:65], v[136:139], v[102:105], v[50:65]
	ds_read_b128 v[144:147], v106 offset:4096
	v_mfma_f32_32x32x16_bf16 v[18:33], v[136:139], v[110:113], v[18:33]
	s_cmp_lt_i32 s22, 14
	s_cselect_b32 s25, 0, -16
	s_add_i32 s26, s22, s25
	s_add_i32 s26, s26, 2
	s_cmp_lt_i32 s26, 16
	s_cselect_b32 s26, 0, -16
	s_add_i32 s25, s25, s26
	s_add_i32 s22, s22, s25
	s_lshl_b32 s22, s22, 6
	s_add_i32 s26, s22, 0x80
	s_ashr_i32 s27, s26, 31
	s_lshl_b64 s[26:27], s[26:27], 1
	s_add_u32 s26, s20, s26
	s_addc_u32 s27, s21, s27
	s_waitcnt vmcnt(0)
	s_waitcnt lgkmcnt(0)
	s_barrier
	s_add_i32 s22, s23, s14
	v_lshl_add_u64 v[102:103], s[26:27], 0, v[0:1]
	s_mov_b32 m0, s22
	s_nop 0
	global_load_lds_dwordx4 v[102:103], off
	v_lshl_add_u64 v[102:103], v[118:119], 1, s[26:27]
	s_add_i32 s23, s22, 0x2000
	s_mov_b32 m0, s23
	s_nop 0
	global_load_lds_dwordx4 v[102:103], off
	v_lshl_add_u64 v[102:103], v[122:123], 1, s[26:27]
	s_addk_i32 s22, 0x4000
	s_mov_b32 m0, s22
	s_nop 0
	global_load_lds_dwordx4 v[102:103], off
	v_add_u32_e32 v102, s18, v131
	v_mfma_f32_32x32x16_bf16 v[66:81], v[98:101], v[114:117], v[66:81]
	ds_read_b128 v[110:113], v102
	v_mfma_f32_32x32x16_bf16 v[34:49], v[98:101], v[140:143], v[34:49]
	ds_read_b128 v[106:109], v102 offset:4096
	v_mfma_f32_32x32x16_bf16 v[2:17], v[98:101], v[132:135], v[2:17]
	ds_read_b128 v[98:101], v102 offset:8192
	v_add_u32_e32 v102, s18, v130
	v_mfma_f32_32x32x16_bf16 v[82:97], v[144:147], v[114:117], v[82:97]
	ds_read_b128 v[114:117], v102
	v_mfma_f32_32x32x16_bf16 v[50:65], v[144:147], v[140:143], v[50:65]
	ds_read_b128 v[102:105], v102 offset:4096
	v_mfma_f32_32x32x16_bf16 v[18:33], v[144:147], v[132:135], v[18:33]
	s_cmp_eq_u32 s19, 14
	s_mov_b32 s22, s19
	s_cbranch_scc0 .LBB0_649
; DI f32x16 mfma32(bf8 a, bf8 b, f32x16 c) { return __builtin_amdgcn_mfma_f32_32x32x16_bf16(a, b, c, 0, 0, 0); }
; template <int MB, class Epi>
; DI void gemm_tile(const u16* __restrict__ A, int lda, int row0, int Mrows, const u16* __restrict__ Bt, int ldb, int K, char* smem, Epi& epi, int rot) {
;     ...
;     if (more) {
;       asm volatile("s_waitcnt vmcnt(0)" ::: "memory");
;       __syncthreads();
;       if (more2) {
;         const int ko_ = k2_ * 64;
; #pragma unroll
;         for (int pc = 0; pc < 3; ++pc) GEMM_PIECE(kt & 1, pc)
;       }
;       __builtin_amdgcn_sched_barrier(0);
;       const char* asn = As + nstg * 32768 + wm * (32 * MB) * 128;
;       const char* bsn = Bs + nstg * 32768 + wn * 64 * 128;
; #pragma unroll
;       for (int mb = 0; mb < MB; ++mb) af[0][mb] = *(const bf8*)(asn + mb * 32 * 128 + foff[0]);
; #pragma unroll
;       for (int nb = 0; nb < 2; ++nb) bfr[0][nb] = *(const bf8*)(bsn + nb * 32 * 128 + foff[0]);
;     }
; #pragma unroll
;     for (int nb = 0; nb < 2; ++nb)
; #pragma unroll
;       for (int mb = 0; mb < MB; ++mb) acc[nb][mb] = mfma32(bfr[1][nb], af[1][mb], acc[nb][mb]);
; #pragma unroll
;     for (int gk = 0; gk < 2 * MB; ++gk) {
;       __builtin_amdgcn_sched_group_barrier(0x008, 1, 0);
;       __builtin_amdgcn_sched_group_barrier(0x100, 1, 0);
;     }
;     __builtin_amdgcn_sched_barrier(0);
;   }
;   __syncthreads();
;   epi(acc, wm, wn, r, h);
	s_add_i32 s15, s13, s18
	s_add_i32 s18, s12, s18
	s_add_i32 s16, s16, 14
	s_cmp_lt_i32 s16, 15
	s_cselect_b32 s17, 0, -16
	s_add_i32 s16, s16, s17
	s_lshl_b32 s16, s16, 6
	s_add_i32 s16, s16, 64
	s_ashr_i32 s17, s16, 31
	v_add_u32_e32 v0, s15, v129
	v_lshl_add_u64 v[122:123], s[16:17], 1, v[120:121]
	ds_read_b128 v[118:121], v0
	s_add_i32 s16, s14, 0x18000
	s_mov_b32 m0, s16
	s_nop 0
	global_load_lds_dwordx4 v[122:123], off
	s_waitcnt lgkmcnt(2)
	v_mfma_f32_32x32x16_bf16 v[66:81], v[114:117], v[110:113], v[66:81]
	ds_read_b128 v[132:135], v0 offset:4096
	v_lshl_add_u64 v[136:137], v[122:123], 0, s[4:5]
	s_add_i32 s16, s14, 0x1a000
	s_mov_b32 m0, s16
	s_nop 0
	global_load_lds_dwordx4 v[136:137], off
	v_mfma_f32_32x32x16_bf16 v[34:49], v[114:117], v[106:109], v[34:49]
	v_mfma_f32_32x32x16_bf16 v[2:17], v[114:117], v[98:101], v[2:17]
	ds_read_b128 v[114:117], v0 offset:8192
	v_lshl_add_u64 v[136:137], v[122:123], 0, s[6:7]
	s_add_i32 s16, s14, 0x1c000
	s_mov_b32 m0, s16
	s_nop 0
	global_load_lds_dwordx4 v[136:137], off
	v_add_u32_e32 v0, s18, v129
	s_waitcnt lgkmcnt(3)
	v_mfma_f32_32x32x16_bf16 v[82:97], v[102:105], v[110:113], v[82:97]
	ds_read_b128 v[110:113], v0
	v_mfma_f32_32x32x16_bf16 v[50:65], v[102:105], v[106:109], v[50:65]
	ds_read_b128 v[106:109], v0 offset:4096
	v_mfma_f32_32x32x16_bf16 v[18:33], v[102:105], v[98:101], v[18:33]
	v_add_u32_e32 v0, s15, v128
	ds_read_b128 v[98:101], v0
	v_lshl_add_u64 v[102:103], v[122:123], 0, s[34:35]
	s_add_i32 s14, s14, 0x1e000
	s_mov_b32 m0, s14
	s_nop 0
	global_load_lds_dwordx4 v[102:103], off
	s_waitcnt lgkmcnt(2)
	v_mfma_f32_32x32x16_bf16 v[66:81], v[110:113], v[118:121], v[66:81]
	ds_read_b128 v[102:105], v0 offset:4096
	v_mfma_f32_32x32x16_bf16 v[34:49], v[110:113], v[132:135], v[34:49]
	v_mfma_f32_32x32x16_bf16 v[2:17], v[110:113], v[114:117], v[2:17]
	ds_read_b128 v[110:113], v0 offset:8192
	v_add_u32_e32 v0, s18, v128
	s_waitcnt lgkmcnt(3)
	v_mfma_f32_32x32x16_bf16 v[82:97], v[106:109], v[118:121], v[82:97]
	ds_read_b128 v[118:121], v0
	v_mfma_f32_32x32x16_bf16 v[50:65], v[106:109], v[132:135], v[50:65]
	ds_read_b128 v[132:135], v0 offset:4096
	v_mfma_f32_32x32x16_bf16 v[18:33], v[106:109], v[114:117], v[18:33]
	v_add_u32_e32 v0, s15, v127
	ds_read_b128 v[106:109], v0
	s_waitcnt lgkmcnt(2)
	v_mfma_f32_32x32x16_bf16 v[66:81], v[118:121], v[98:101], v[66:81]
	ds_read_b128 v[114:117], v0 offset:4096
	v_mfma_f32_32x32x16_bf16 v[34:49], v[118:121], v[102:105], v[34:49]
	v_mfma_f32_32x32x16_bf16 v[2:17], v[118:121], v[110:113], v[2:17]
	ds_read_b128 v[118:121], v0 offset:8192
	v_add_u32_e32 v0, s18, v127
	s_waitcnt lgkmcnt(3)
	v_mfma_f32_32x32x16_bf16 v[82:97], v[132:135], v[98:101], v[82:97]
	ds_read_b128 v[98:101], v0
	v_mfma_f32_32x32x16_bf16 v[50:65], v[132:135], v[102:105], v[50:65]
	ds_read_b128 v[102:105], v0 offset:4096
	v_mfma_f32_32x32x16_bf16 v[18:33], v[132:135], v[110:113], v[18:33]
	s_waitcnt vmcnt(0)
	s_waitcnt lgkmcnt(0)
	s_barrier
	s_lshr_b32 s100, s0, 5
	s_lshl_b32 s100, s100, 3
	s_and_b32 s101, s0, 7
	s_or_b32 s100, s100, s101
	s_mul_i32 s100, s100, 0xc0
	s_lshr_b32 s101, s0, 3
	s_and_b32 s101, s101, 3
	s_lshl_b32 s101, s101, 9
	v_lshrrev_b32_e32 v237, 2, v163
	v_and_b32_e32 v238, 3, v163
	v_add_u32_e32 v237, s100, v237
	v_lshlrev_b32_e32 v237, 11, v237
	v_lshl_add_u32 v237, v238, 7, v237
	v_add_u32_e32 v237, s101, v237
	global_load_dword v255, v237, s[46:47]
	v_add_u32_e32 v237, 0x40000, v237
	global_load_dword v255, v237, s[46:47]
	v_mfma_f32_32x32x16_bf16 v[66:81], v[98:101], v[106:109], v[66:81]
	ds_read_b128 v[110:113], v131 offset:32768
	v_mfma_f32_32x32x16_bf16 v[34:49], v[98:101], v[114:117], v[34:49]
	ds_read_b128 v[132:135], v131 offset:36864
	v_mfma_f32_32x32x16_bf16 v[2:17], v[98:101], v[118:121], v[2:17]
	ds_read_b128 v[98:101], v131 offset:40960
	v_mfma_f32_32x32x16_bf16 v[82:97], v[102:105], v[106:109], v[82:97]
	ds_read_b128 v[106:109], v130 offset:32768
	v_mfma_f32_32x32x16_bf16 v[50:65], v[102:105], v[114:117], v[50:65]
	ds_read_b128 v[114:117], v130 offset:36864
	v_mfma_f32_32x32x16_bf16 v[18:33], v[102:105], v[118:121], v[18:33]
	v_add_u32_e32 v0, s13, v129
	ds_read_b128 v[102:105], v0 offset:32768
	s_lshl_b32 s14, s2, 8
	s_waitcnt lgkmcnt(2)
	v_mfma_f32_32x32x16_bf16 v[66:81], v[106:109], v[110:113], v[66:81]
	ds_read_b128 v[118:121], v0 offset:36864
	v_mfma_f32_32x32x16_bf16 v[34:49], v[106:109], v[132:135], v[34:49]
	v_mfma_f32_32x32x16_bf16 v[2:17], v[106:109], v[98:101], v[2:17]
	ds_read_b128 v[106:109], v0 offset:40960
	v_add_u32_e32 v0, s12, v129
	s_waitcnt lgkmcnt(3)
	v_mfma_f32_32x32x16_bf16 v[82:97], v[114:117], v[110:113], v[82:97]
	ds_read_b128 v[110:113], v0 offset:32768
	v_mfma_f32_32x32x16_bf16 v[50:65], v[114:117], v[132:135], v[50:65]
	ds_read_b128 v[130:133], v0 offset:36864
	v_mfma_f32_32x32x16_bf16 v[18:33], v[114:117], v[98:101], v[18:33]
	v_add_u32_e32 v0, s13, v128
	ds_read_b128 v[98:101], v0 offset:32768
	s_waitcnt lgkmcnt(2)
	v_mfma_f32_32x32x16_bf16 v[66:81], v[110:113], v[102:105], v[66:81]
	ds_read_b128 v[114:117], v0 offset:36864
	v_mfma_f32_32x32x16_bf16 v[34:49], v[110:113], v[118:121], v[34:49]
	v_mfma_f32_32x32x16_bf16 v[2:17], v[110:113], v[106:109], v[2:17]
	ds_read_b128 v[110:113], v0 offset:40960
	v_add_u32_e32 v0, s12, v128
	s_waitcnt lgkmcnt(3)
	v_mfma_f32_32x32x16_bf16 v[82:97], v[130:133], v[102:105], v[82:97]
	ds_read_b128 v[102:105], v0 offset:32768
	v_mfma_f32_32x32x16_bf16 v[50:65], v[130:133], v[118:121], v[50:65]
	ds_read_b128 v[118:121], v0 offset:36864
	v_mfma_f32_32x32x16_bf16 v[18:33], v[130:133], v[106:109], v[18:33]
	v_add_u32_e32 v0, s13, v127
	ds_read_b128 v[106:109], v0 offset:32768
	s_waitcnt lgkmcnt(2)
	v_mfma_f32_32x32x16_bf16 v[66:81], v[102:105], v[98:101], v[66:81]
	ds_read_b128 v[128:131], v0 offset:36864
	v_mfma_f32_32x32x16_bf16 v[34:49], v[102:105], v[114:117], v[34:49]
	v_mfma_f32_32x32x16_bf16 v[2:17], v[102:105], v[110:113], v[2:17]
	ds_read_b128 v[102:105], v0 offset:40960
	v_add_u32_e32 v0, s12, v127
	s_waitcnt lgkmcnt(3)
	v_mfma_f32_32x32x16_bf16 v[82:97], v[118:121], v[98:101], v[82:97]
	ds_read_b128 v[98:101], v0 offset:32768
	v_mfma_f32_32x32x16_bf16 v[50:65], v[118:121], v[114:117], v[50:65]
	ds_read_b128 v[114:117], v0 offset:36864
	v_mfma_f32_32x32x16_bf16 v[18:33], v[118:121], v[110:113], v[18:33]
	s_waitcnt lgkmcnt(1)
	v_mfma_f32_32x32x16_bf16 v[66:81], v[98:101], v[106:109], v[66:81]
	v_mfma_f32_32x32x16_bf16 v[34:49], v[98:101], v[128:131], v[34:49]
	v_mfma_f32_32x32x16_bf16 v[2:17], v[98:101], v[102:105], v[2:17]
	s_waitcnt lgkmcnt(0)
	v_mfma_f32_32x32x16_bf16 v[82:97], v[114:117], v[106:109], v[82:97]
	v_mfma_f32_32x32x16_bf16 v[50:65], v[114:117], v[128:131], v[50:65]
	v_mfma_f32_32x32x16_bf16 v[18:33], v[114:117], v[102:105], v[18:33]
	s_waitcnt lgkmcnt(0)
	s_barrier
; DI unsigned pack2(float a, float b) { f2 v = {a, b}; bf2 r = __builtin_convertvector(v, bf2); return __builtin_bit_cast(unsigned, r); }
;   DI void operator()(f32x16 (&acc)[2][MB], int wm, int wn, int r, int h) {
;     u16* slab = ostage + (wm * 4 + wn) * (64 * 72);
;     const int lane = h * 32 + r;
; #pragma unroll
;     for (int mb = 0; mb < MB; ++mb) {
;       const int tokl = (mb & 1) * 32 + r;
; #pragma unroll
;       for (int nb = 0; nb < 2; ++nb)
; #pragma unroll
;         for (int ig = 0; ig < 4; ++ig) {
;           u32x2 o;
;           o.x = pack2(acc[nb][mb][ig * 4 + 0], acc[nb][mb][ig * 4 + 1]);
;           o.y = pack2(acc[nb][mb][ig * 4 + 2], acc[nb][mb][ig * 4 + 3]);
;           *(u32x2*)(slab + tokl * 72 + nb * 32 + ig * 8 + h * 4) = o;
;         }
;       if ((mb & 1) || mb == MB - 1) {
;         asm volatile("s_waitcnt lgkmcnt(0)" ::: "memory");
;         const int ntok = (mb & 1) ? 64 : 32;
;         const int R0 = row0 + wm * (32 * MB) + (mb >> 1) * 64;
; #pragma unroll
;         for (int j = 0; j < 8; ++j) {
;           const int rowl = (lane >> 3) + 8 * j, ch = lane & 7;
;           if (rowl < ntok) {
;             const u32x4 yv = *(const u32x4*)(slab + rowl * 72 + ch * 8);
;             const int R = R0 + rowl;
;             const int mi = (R < NLAT) ? (R >> 11) : 16;
;             const int col = n0 + wn * 64 + ch * 8;
;             const float* g = gate + (size_t)mi * 6144 + col;
;             const f32x4n g0 = *(const f32x4n*)(g), g1 = *(const f32x4n*)(g + 4);
;             _Float16* xp = X + (size_t)R * 1024 + col;
;             const h8 xv = *(const h8*)xp;
;             const float y[8] = {__uint_as_float(yv.x << 16), __uint_as_float(yv.x & 0xffff0000u), __uint_as_float(yv.y << 16), __uint_as_float(yv.y & 0xffff0000u),
;                                 __uint_as_float(yv.z << 16), __uint_as_float(yv.z & 0xffff0000u), __uint_as_float(yv.w << 16), __uint_as_float(yv.w & 0xffff0000u)};
;             const float gg[8] = {g0.x, g0.y, g0.z, g0.w, g1.x, g1.y, g1.z, g1.w};
;             h8 o;
; #pragma unroll
;             for (int q = 0; q < 8; ++q) o[q] = (_Float16)(ALPHA * (float)xv[q] + gg[q] * y[q]);
;             *(h8*)xp = o;
;           }
;         }
;       }
;     }
	s_lshr_b32 s100, s0, 5
	s_lshl_b32 s100, s100, 3
	s_and_b32 s101, s0, 7
	s_or_b32 s100, s100, s101
	s_mul_i32 s100, s100, 0xc0
	v_readfirstlane_b32 s101, v163
	s_lshr_b32 s101, s101, 6
	s_mul_i32 s12, s101, 0x2400
	v_and_b32_e32 v0, 63, v163
	v_and_b32_e32 v250, 31, v0
	v_lshrrev_b32_e32 v251, 5, v0
	v_mul_u32_u24_e32 v237, 0x90, v250
	v_lshl_add_u32 v237, v251, 3, v237
	v_add_u32_e32 v237, s12, v237
	v_lshrrev_b32_e32 v252, 3, v0
	v_and_b32_e32 v0, 7, v0
	v_mul_u32_u24_e32 v238, 0x90, v252
	v_lshl_add_u32 v238, v0, 4, v238
	v_add_u32_e32 v238, s12, v238
	s_mul_i32 s12, s101, 0x1200
	s_add_i32 s12, s12, 0x12000
	v_mul_u32_u24_e32 v242, 0x90, v250
	v_lshl_add_u32 v242, v251, 3, v242
	v_add_u32_e32 v242, s12, v242
	v_mul_u32_u24_e32 v243, 0x90, v252
	v_lshl_add_u32 v243, v0, 4, v243
	v_add_u32_e32 v243, s12, v243
	s_lshr_b32 s12, s101, 2
	s_mul_i32 s12, s12, 0x60
	s_add_i32 s100, s100, s12
	s_and_b32 s12, s101, 3
	s_lshl_b32 s12, s12, 6
	s_lshr_b32 s101, s0, 3
	s_and_b32 s101, s101, 3
	s_lshl_b32 s101, s101, 8
	s_add_i32 s12, s12, s101
	v_lshl_add_u32 v240, v0, 3, s12
	v_add_u32_e32 v241, s100, v252
	v_lshlrev_b32_e32 v239, 11, v241
	v_lshl_add_u32 v239, v240, 1, v239
	v_lshlrev_b32_e32 v240, 2, v240
	v_min_i32_e32 v246, 0x8000, v241
	v_ashrrev_i32_e32 v246, 11, v246
	v_mul_u32_u24_e32 v245, 0x6000, v246
	v_add_u32_e32 v245, v245, v240
	global_load_dwordx4 v[98:101], v245, s[36:37]
	global_load_dwordx4 v[102:105], v245, s[36:37] offset:16
	v_add_u32_e32 v247, 56, v241
	v_min_i32_e32 v247, 0x8000, v247
	v_ashrrev_i32_e32 v247, 11, v247
	v_mul_u32_u24_e32 v245, 0x6000, v247
	v_add_u32_e32 v245, v245, v240
	global_load_dwordx4 v[106:109], v245, s[36:37]
	global_load_dwordx4 v[110:113], v245, s[36:37] offset:16
	global_load_dwordx4 v[114:117], v239, s[46:47]
	v_add_u32_e32 v245, 0x4000, v239
	global_load_dwordx4 v[118:121], v245, s[46:47]
	v_add_u32_e32 v245, 0x8000, v239
	global_load_dwordx4 v[122:125], v245, s[46:47]
	v_add_u32_e32 v245, 0xc000, v239
	global_load_dwordx4 v[126:129], v245, s[46:47]
	v_cvt_pk_bf16_f32 v66, v66, v67
	v_cvt_pk_bf16_f32 v67, v68, v69
	v_cvt_pk_bf16_f32 v68, v70, v71
	v_cvt_pk_bf16_f32 v69, v72, v73
	v_cvt_pk_bf16_f32 v70, v74, v75
	v_cvt_pk_bf16_f32 v71, v76, v77
	v_cvt_pk_bf16_f32 v72, v78, v79
	v_cvt_pk_bf16_f32 v73, v80, v81
	ds_write2_b64 v237, v[66:67], v[68:69] offset0:0 offset1:2
	ds_write2_b64 v237, v[70:71], v[72:73] offset0:4 offset1:6
	v_cvt_pk_bf16_f32 v82, v82, v83
	v_cvt_pk_bf16_f32 v83, v84, v85
	v_cvt_pk_bf16_f32 v84, v86, v87
	v_cvt_pk_bf16_f32 v85, v88, v89
	v_cvt_pk_bf16_f32 v86, v90, v91
	v_cvt_pk_bf16_f32 v87, v92, v93
	v_cvt_pk_bf16_f32 v88, v94, v95
	v_cvt_pk_bf16_f32 v89, v96, v97
	ds_write2_b64 v237, v[82:83], v[84:85] offset0:8 offset1:10
	ds_write2_b64 v237, v[86:87], v[88:89] offset0:12 offset1:14
	v_add_u32_e32 v245, 0x10000, v239
	global_load_dwordx4 v[66:69], v245, s[46:47]
	v_add_u32_e32 v245, 0x14000, v239
	global_load_dwordx4 v[70:73], v245, s[46:47]
	v_add_u32_e32 v245, 0x18000, v239
	global_load_dwordx4 v[74:77], v245, s[46:47]
	v_add_u32_e32 v245, 0x1c000, v239
	global_load_dwordx4 v[78:81], v245, s[46:47]
	v_add_u32_e32 v244, 0x1200, v237
	v_cvt_pk_bf16_f32 v34, v34, v35
	v_cvt_pk_bf16_f32 v35, v36, v37
	v_cvt_pk_bf16_f32 v36, v38, v39
	v_cvt_pk_bf16_f32 v37, v40, v41
	v_cvt_pk_bf16_f32 v38, v42, v43
	v_cvt_pk_bf16_f32 v39, v44, v45
	v_cvt_pk_bf16_f32 v40, v46, v47
	v_cvt_pk_bf16_f32 v41, v48, v49
	ds_write2_b64 v244, v[34:35], v[36:37] offset0:0 offset1:2
	ds_write2_b64 v244, v[38:39], v[40:41] offset0:4 offset1:6
	v_cvt_pk_bf16_f32 v50, v50, v51
	v_cvt_pk_bf16_f32 v51, v52, v53
	v_cvt_pk_bf16_f32 v52, v54, v55
	v_cvt_pk_bf16_f32 v53, v56, v57
	v_cvt_pk_bf16_f32 v54, v58, v59
	v_cvt_pk_bf16_f32 v55, v60, v61
	v_cvt_pk_bf16_f32 v56, v62, v63
	v_cvt_pk_bf16_f32 v57, v64, v65
	ds_write2_b64 v244, v[50:51], v[52:53] offset0:8 offset1:10
	ds_write2_b64 v244, v[54:55], v[56:57] offset0:12 offset1:14
	v_add_u32_e32 v248, 64, v241
	v_min_i32_e32 v248, 0x8000, v248
	v_ashrrev_i32_e32 v248, 11, v248
	v_mul_u32_u24_e32 v245, 0x6000, v248
	v_add_u32_e32 v245, v245, v240
	global_load_dwordx4 v[34:37], v245, s[36:37]
	global_load_dwordx4 v[38:41], v245, s[36:37] offset:16
	v_add_u32_e32 v249, 88, v241
	v_min_i32_e32 v249, 0x8000, v249
	v_ashrrev_i32_e32 v249, 11, v249
	v_mul_u32_u24_e32 v245, 0x6000, v249
	v_add_u32_e32 v245, v245, v240
	global_load_dwordx4 v[42:45], v245, s[36:37]
	global_load_dwordx4 v[46:49], v245, s[36:37] offset:16
	v_add_u32_e32 v245, 0x20000, v239
	global_load_dwordx4 v[50:53], v245, s[46:47]
	v_add_u32_e32 v245, 0x24000, v239
	global_load_dwordx4 v[54:57], v245, s[46:47]
	v_add_u32_e32 v245, 0x28000, v239
	global_load_dwordx4 v[58:61], v245, s[46:47]
	v_add_u32_e32 v245, 0x2c000, v239
	global_load_dwordx4 v[62:65], v245, s[46:47]
	v_cvt_pk_bf16_f32 v2, v2, v3
	v_cvt_pk_bf16_f32 v3, v4, v5
	v_cvt_pk_bf16_f32 v4, v6, v7
	v_cvt_pk_bf16_f32 v5, v8, v9
	v_cvt_pk_bf16_f32 v6, v10, v11
	v_cvt_pk_bf16_f32 v7, v12, v13
	v_cvt_pk_bf16_f32 v8, v14, v15
	v_cvt_pk_bf16_f32 v9, v16, v17
	ds_write2_b64 v242, v[2:3], v[4:5] offset0:0 offset1:2
	ds_write2_b64 v242, v[6:7], v[8:9] offset0:4 offset1:6
	v_cvt_pk_bf16_f32 v18, v18, v19
	v_cvt_pk_bf16_f32 v19, v20, v21
	v_cvt_pk_bf16_f32 v20, v22, v23
	v_cvt_pk_bf16_f32 v21, v24, v25
	v_cvt_pk_bf16_f32 v22, v26, v27
	v_cvt_pk_bf16_f32 v23, v28, v29
	v_cvt_pk_bf16_f32 v24, v30, v31
	v_cvt_pk_bf16_f32 v25, v32, v33
	ds_write2_b64 v242, v[18:19], v[20:21] offset0:8 offset1:10
	ds_write2_b64 v242, v[22:23], v[24:25] offset0:12 offset1:14
	v_cmp_ne_u32_e32 vcc, v246, v247
	s_cbranch_vccnz .Lres0_slowA
;   DI void operator()(f32x16 (&acc)[2][MB], int wm, int wn, int r, int h) {
;     ...
;         for (int j = 0; j < 8; ++j) {
;           const int rowl = (lane >> 3) + 8 * j, ch = lane & 7;
;           if (rowl < ntok) {
;             const u32x4 yv = *(const u32x4*)(slab + rowl * 72 + ch * 8);
;             const int R = R0 + rowl;
;             const int mi = (R < NLAT) ? (R >> 11) : 16;
;             const int col = n0 + wn * 64 + ch * 8;
;             const float* g = gate + (size_t)mi * 6144 + col;
;             const f32x4n g0 = *(const f32x4n*)(g), g1 = *(const f32x4n*)(g + 4);
;             _Float16* xp = X + (size_t)R * 1024 + col;
;             const h8 xv = *(const h8*)xp;
;             const float y[8] = {__uint_as_float(yv.x << 16), __uint_as_float(yv.x & 0xffff0000u), __uint_as_float(yv.y << 16), __uint_as_float(yv.y & 0xffff0000u),
;                                 __uint_as_float(yv.z << 16), __uint_as_float(yv.z & 0xffff0000u), __uint_as_float(yv.w << 16), __uint_as_float(yv.w & 0xffff0000u)};
;             const float gg[8] = {g0.x, g0.y, g0.z, g0.w, g1.x, g1.y, g1.z, g1.w};
;             h8 o;
; #pragma unroll
;             for (int q = 0; q < 8; ++q) o[q] = (_Float16)(ALPHA * (float)xv[q] + gg[q] * y[q]);
;             *(h8*)xp = o;
	ds_read_b128 v[2:5], v238
	ds_read_b128 v[6:9], v238 offset:1152
	s_waitcnt vmcnt(15) lgkmcnt(1)
	v_lshlrev_b32_e32 v10, 16, v2
	v_and_b32_e32 v11, 0xffff0000, v2
	v_lshlrev_b32_e32 v12, 16, v3
	v_and_b32_e32 v13, 0xffff0000, v3
	v_lshlrev_b32_e32 v14, 16, v4
	v_and_b32_e32 v15, 0xffff0000, v4
	v_lshlrev_b32_e32 v16, 16, v5
	v_and_b32_e32 v17, 0xffff0000, v5
	ds_read_b128 v[2:5], v238 offset:2304
	v_cvt_f32_f16_e32 v18, v114
	v_cvt_f32_f16_sdwa v19, v114 dst_sel:DWORD dst_unused:UNUSED_PAD src0_sel:WORD_1
	v_cvt_f32_f16_e32 v20, v115
	v_cvt_f32_f16_sdwa v21, v115 dst_sel:DWORD dst_unused:UNUSED_PAD src0_sel:WORD_1
	v_cvt_f32_f16_e32 v22, v116
	v_cvt_f32_f16_sdwa v23, v116 dst_sel:DWORD dst_unused:UNUSED_PAD src0_sel:WORD_1
	v_cvt_f32_f16_e32 v24, v117
	v_cvt_f32_f16_sdwa v25, v117 dst_sel:DWORD dst_unused:UNUSED_PAD src0_sel:WORD_1
	v_pk_mul_f32 v[18:19], v[18:19], s[30:31] op_sel_hi:[1,0]
	v_pk_mul_f32 v[20:21], v[20:21], s[30:31] op_sel_hi:[1,0]
	v_pk_mul_f32 v[22:23], v[22:23], s[30:31] op_sel_hi:[1,0]
	v_pk_mul_f32 v[24:25], v[24:25], s[30:31] op_sel_hi:[1,0]
	v_pk_fma_f32 v[18:19], v[98:99], v[10:11], v[18:19]
	v_pk_fma_f32 v[20:21], v[100:101], v[12:13], v[20:21]
	v_pk_fma_f32 v[22:23], v[102:103], v[14:15], v[22:23]
	v_pk_fma_f32 v[24:25], v[104:105], v[16:17], v[24:25]
	v_cvt_pk_f16_f32 v114, v18, v19
	v_cvt_pk_f16_f32 v115, v20, v21
	v_cvt_pk_f16_f32 v116, v22, v23
	v_cvt_pk_f16_f32 v117, v24, v25
	global_store_dwordx4 v239, v[114:117], s[46:47]
	s_waitcnt vmcnt(15) lgkmcnt(1)
	v_lshlrev_b32_e32 v10, 16, v6
	v_and_b32_e32 v11, 0xffff0000, v6
	v_lshlrev_b32_e32 v12, 16, v7
	v_and_b32_e32 v13, 0xffff0000, v7
	v_lshlrev_b32_e32 v14, 16, v8
	v_and_b32_e32 v15, 0xffff0000, v8
	v_lshlrev_b32_e32 v16, 16, v9
	v_and_b32_e32 v17, 0xffff0000, v9
	ds_read_b128 v[6:9], v238 offset:3456
	v_add_u32_e32 v0, 0x4000, v239
	v_cvt_f32_f16_e32 v18, v118
	v_cvt_f32_f16_sdwa v19, v118 dst_sel:DWORD dst_unused:UNUSED_PAD src0_sel:WORD_1
	v_cvt_f32_f16_e32 v20, v119
	v_cvt_f32_f16_sdwa v21, v119 dst_sel:DWORD dst_unused:UNUSED_PAD src0_sel:WORD_1
	v_cvt_f32_f16_e32 v22, v120
	v_cvt_f32_f16_sdwa v23, v120 dst_sel:DWORD dst_unused:UNUSED_PAD src0_sel:WORD_1
	v_cvt_f32_f16_e32 v24, v121
	v_cvt_f32_f16_sdwa v25, v121 dst_sel:DWORD dst_unused:UNUSED_PAD src0_sel:WORD_1
	v_pk_mul_f32 v[18:19], v[18:19], s[30:31] op_sel_hi:[1,0]
	v_pk_mul_f32 v[20:21], v[20:21], s[30:31] op_sel_hi:[1,0]
	v_pk_mul_f32 v[22:23], v[22:23], s[30:31] op_sel_hi:[1,0]
	v_pk_mul_f32 v[24:25], v[24:25], s[30:31] op_sel_hi:[1,0]
	v_pk_fma_f32 v[18:19], v[98:99], v[10:11], v[18:19]
	v_pk_fma_f32 v[20:21], v[100:101], v[12:13], v[20:21]
	v_pk_fma_f32 v[22:23], v[102:103], v[14:15], v[22:23]
	v_pk_fma_f32 v[24:25], v[104:105], v[16:17], v[24:25]
	v_cvt_pk_f16_f32 v118, v18, v19
	v_cvt_pk_f16_f32 v119, v20, v21
	v_cvt_pk_f16_f32 v120, v22, v23
	v_cvt_pk_f16_f32 v121, v24, v25
	global_store_dwordx4 v0, v[118:121], s[46:47]
	s_waitcnt vmcnt(15) lgkmcnt(1)
	v_lshlrev_b32_e32 v10, 16, v2
	v_and_b32_e32 v11, 0xffff0000, v2
	v_lshlrev_b32_e32 v12, 16, v3
	v_and_b32_e32 v13, 0xffff0000, v3
	v_lshlrev_b32_e32 v14, 16, v4
	v_and_b32_e32 v15, 0xffff0000, v4
	v_lshlrev_b32_e32 v16, 16, v5
	v_and_b32_e32 v17, 0xffff0000, v5
	ds_read_b128 v[2:5], v238 offset:4608
	v_add_u32_e32 v0, 0x8000, v239
	v_cvt_f32_f16_e32 v18, v122
	v_cvt_f32_f16_sdwa v19, v122 dst_sel:DWORD dst_unused:UNUSED_PAD src0_sel:WORD_1
	v_cvt_f32_f16_e32 v20, v123
	v_cvt_f32_f16_sdwa v21, v123 dst_sel:DWORD dst_unused:UNUSED_PAD src0_sel:WORD_1
	v_cvt_f32_f16_e32 v22, v124
	v_cvt_f32_f16_sdwa v23, v124 dst_sel:DWORD dst_unused:UNUSED_PAD src0_sel:WORD_1
	v_cvt_f32_f16_e32 v24, v125
	v_cvt_f32_f16_sdwa v25, v125 dst_sel:DWORD dst_unused:UNUSED_PAD src0_sel:WORD_1
	v_pk_mul_f32 v[18:19], v[18:19], s[30:31] op_sel_hi:[1,0]
	v_pk_mul_f32 v[20:21], v[20:21], s[30:31] op_sel_hi:[1,0]
	v_pk_mul_f32 v[22:23], v[22:23], s[30:31] op_sel_hi:[1,0]
	v_pk_mul_f32 v[24:25], v[24:25], s[30:31] op_sel_hi:[1,0]
	v_pk_fma_f32 v[18:19], v[98:99], v[10:11], v[18:19]
	v_pk_fma_f32 v[20:21], v[100:101], v[12:13], v[20:21]
	v_pk_fma_f32 v[22:23], v[102:103], v[14:15], v[22:23]
	v_pk_fma_f32 v[24:25], v[104:105], v[16:17], v[24:25]
	v_cvt_pk_f16_f32 v122, v18, v19
	v_cvt_pk_f16_f32 v123, v20, v21
	v_cvt_pk_f16_f32 v124, v22, v23
	v_cvt_pk_f16_f32 v125, v24, v25
	global_store_dwordx4 v0, v[122:125], s[46:47]
	s_waitcnt vmcnt(15) lgkmcnt(1)
	v_lshlrev_b32_e32 v10, 16, v6
	v_and_b32_e32 v11, 0xffff0000, v6
	v_lshlrev_b32_e32 v12, 16, v7
	v_and_b32_e32 v13, 0xffff0000, v7
	v_lshlrev_b32_e32 v14, 16, v8
	v_and_b32_e32 v15, 0xffff0000, v8
	v_lshlrev_b32_e32 v16, 16, v9
	v_and_b32_e32 v17, 0xffff0000, v9
	ds_read_b128 v[6:9], v238 offset:5760
	v_add_u32_e32 v0, 0xc000, v239
	v_cvt_f32_f16_e32 v18, v126
	v_cvt_f32_f16_sdwa v19, v126 dst_sel:DWORD dst_unused:UNUSED_PAD src0_sel:WORD_1
	v_cvt_f32_f16_e32 v20, v127
	v_cvt_f32_f16_sdwa v21, v127 dst_sel:DWORD dst_unused:UNUSED_PAD src0_sel:WORD_1
	v_cvt_f32_f16_e32 v22, v128
	v_cvt_f32_f16_sdwa v23, v128 dst_sel:DWORD dst_unused:UNUSED_PAD src0_sel:WORD_1
	v_cvt_f32_f16_e32 v24, v129
	v_cvt_f32_f16_sdwa v25, v129 dst_sel:DWORD dst_unused:UNUSED_PAD src0_sel:WORD_1
	v_pk_mul_f32 v[18:19], v[18:19], s[30:31] op_sel_hi:[1,0]
	v_pk_mul_f32 v[20:21], v[20:21], s[30:31] op_sel_hi:[1,0]
	v_pk_mul_f32 v[22:23], v[22:23], s[30:31] op_sel_hi:[1,0]
	v_pk_mul_f32 v[24:25], v[24:25], s[30:31] op_sel_hi:[1,0]
	v_pk_fma_f32 v[18:19], v[98:99], v[10:11], v[18:19]
	v_pk_fma_f32 v[20:21], v[100:101], v[12:13], v[20:21]
	v_pk_fma_f32 v[22:23], v[102:103], v[14:15], v[22:23]
	v_pk_fma_f32 v[24:25], v[104:105], v[16:17], v[24:25]
	v_cvt_pk_f16_f32 v126, v18, v19
	v_cvt_pk_f16_f32 v127, v20, v21
	v_cvt_pk_f16_f32 v128, v22, v23
	v_cvt_pk_f16_f32 v129, v24, v25
	global_store_dwordx4 v0, v[126:129], s[46:47]
	s_waitcnt vmcnt(15) lgkmcnt(1)
;   DI void operator()(f32x16 (&acc)[2][MB], int wm, int wn, int r, int h) {
;     ...
;         for (int j = 0; j < 8; ++j) {
;           const int rowl = (lane >> 3) + 8 * j, ch = lane & 7;
;           if (rowl < ntok) {
;             const u32x4 yv = *(const u32x4*)(slab + rowl * 72 + ch * 8);
;             const int R = R0 + rowl;
;             const int mi = (R < NLAT) ? (R >> 11) : 16;
;             const int col = n0 + wn * 64 + ch * 8;
;             const float* g = gate + (size_t)mi * 6144 + col;
;             const f32x4n g0 = *(const f32x4n*)(g), g1 = *(const f32x4n*)(g + 4);
;             _Float16* xp = X + (size_t)R * 1024 + col;
;             const h8 xv = *(const h8*)xp;
;             const float y[8] = {__uint_as_float(yv.x << 16), __uint_as_float(yv.x & 0xffff0000u), __uint_as_float(yv.y << 16), __uint_as_float(yv.y & 0xffff0000u),
;                                 __uint_as_float(yv.z << 16), __uint_as_float(yv.z & 0xffff0000u), __uint_as_float(yv.w << 16), __uint_as_float(yv.w & 0xffff0000u)};
;             const float gg[8] = {g0.x, g0.y, g0.z, g0.w, g1.x, g1.y, g1.z, g1.w};
;             h8 o;
; #pragma unroll
;             for (int q = 0; q < 8; ++q) o[q] = (_Float16)(ALPHA * (float)xv[q] + gg[q] * y[q]);
;             *(h8*)xp = o;
	v_lshlrev_b32_e32 v10, 16, v2
	v_and_b32_e32 v11, 0xffff0000, v2
	v_lshlrev_b32_e32 v12, 16, v3
	v_and_b32_e32 v13, 0xffff0000, v3
	v_lshlrev_b32_e32 v14, 16, v4
	v_and_b32_e32 v15, 0xffff0000, v4
	v_lshlrev_b32_e32 v16, 16, v5
	v_and_b32_e32 v17, 0xffff0000, v5
	ds_read_b128 v[2:5], v238 offset:6912
	v_add_u32_e32 v0, 0x10000, v239
	v_cvt_f32_f16_e32 v18, v66
	v_cvt_f32_f16_sdwa v19, v66 dst_sel:DWORD dst_unused:UNUSED_PAD src0_sel:WORD_1
	v_cvt_f32_f16_e32 v20, v67
	v_cvt_f32_f16_sdwa v21, v67 dst_sel:DWORD dst_unused:UNUSED_PAD src0_sel:WORD_1
	v_cvt_f32_f16_e32 v22, v68
	v_cvt_f32_f16_sdwa v23, v68 dst_sel:DWORD dst_unused:UNUSED_PAD src0_sel:WORD_1
	v_cvt_f32_f16_e32 v24, v69
	v_cvt_f32_f16_sdwa v25, v69 dst_sel:DWORD dst_unused:UNUSED_PAD src0_sel:WORD_1
	v_pk_mul_f32 v[18:19], v[18:19], s[30:31] op_sel_hi:[1,0]
	v_pk_mul_f32 v[20:21], v[20:21], s[30:31] op_sel_hi:[1,0]
	v_pk_mul_f32 v[22:23], v[22:23], s[30:31] op_sel_hi:[1,0]
	v_pk_mul_f32 v[24:25], v[24:25], s[30:31] op_sel_hi:[1,0]
	v_pk_fma_f32 v[18:19], v[98:99], v[10:11], v[18:19]
	v_pk_fma_f32 v[20:21], v[100:101], v[12:13], v[20:21]
	v_pk_fma_f32 v[22:23], v[102:103], v[14:15], v[22:23]
	v_pk_fma_f32 v[24:25], v[104:105], v[16:17], v[24:25]
	v_cvt_pk_f16_f32 v66, v18, v19
	v_cvt_pk_f16_f32 v67, v20, v21
	v_cvt_pk_f16_f32 v68, v22, v23
	v_cvt_pk_f16_f32 v69, v24, v25
	global_store_dwordx4 v0, v[66:69], s[46:47]
	s_waitcnt vmcnt(15) lgkmcnt(1)
	v_lshlrev_b32_e32 v10, 16, v6
	v_and_b32_e32 v11, 0xffff0000, v6
	v_lshlrev_b32_e32 v12, 16, v7
	v_and_b32_e32 v13, 0xffff0000, v7
	v_lshlrev_b32_e32 v14, 16, v8
	v_and_b32_e32 v15, 0xffff0000, v8
	v_lshlrev_b32_e32 v16, 16, v9
	v_and_b32_e32 v17, 0xffff0000, v9
	ds_read_b128 v[6:9], v238 offset:8064
	v_add_u32_e32 v0, 0x14000, v239
	v_cvt_f32_f16_e32 v18, v70
	v_cvt_f32_f16_sdwa v19, v70 dst_sel:DWORD dst_unused:UNUSED_PAD src0_sel:WORD_1
	v_cvt_f32_f16_e32 v20, v71
	v_cvt_f32_f16_sdwa v21, v71 dst_sel:DWORD dst_unused:UNUSED_PAD src0_sel:WORD_1
	v_cvt_f32_f16_e32 v22, v72
	v_cvt_f32_f16_sdwa v23, v72 dst_sel:DWORD dst_unused:UNUSED_PAD src0_sel:WORD_1
	v_cvt_f32_f16_e32 v24, v73
	v_cvt_f32_f16_sdwa v25, v73 dst_sel:DWORD dst_unused:UNUSED_PAD src0_sel:WORD_1
	v_pk_mul_f32 v[18:19], v[18:19], s[30:31] op_sel_hi:[1,0]
	v_pk_mul_f32 v[20:21], v[20:21], s[30:31] op_sel_hi:[1,0]
	v_pk_mul_f32 v[22:23], v[22:23], s[30:31] op_sel_hi:[1,0]
	v_pk_mul_f32 v[24:25], v[24:25], s[30:31] op_sel_hi:[1,0]
	v_pk_fma_f32 v[18:19], v[98:99], v[10:11], v[18:19]
	v_pk_fma_f32 v[20:21], v[100:101], v[12:13], v[20:21]
	v_pk_fma_f32 v[22:23], v[102:103], v[14:15], v[22:23]
	v_pk_fma_f32 v[24:25], v[104:105], v[16:17], v[24:25]
	v_cvt_pk_f16_f32 v70, v18, v19
	v_cvt_pk_f16_f32 v71, v20, v21
	v_cvt_pk_f16_f32 v72, v22, v23
	v_cvt_pk_f16_f32 v73, v24, v25
	global_store_dwordx4 v0, v[70:73], s[46:47]
	s_waitcnt vmcnt(15) lgkmcnt(1)
	v_lshlrev_b32_e32 v10, 16, v2
	v_and_b32_e32 v11, 0xffff0000, v2
	v_lshlrev_b32_e32 v12, 16, v3
	v_and_b32_e32 v13, 0xffff0000, v3
	v_lshlrev_b32_e32 v14, 16, v4
	v_and_b32_e32 v15, 0xffff0000, v4
	v_lshlrev_b32_e32 v16, 16, v5
	v_and_b32_e32 v17, 0xffff0000, v5
	v_add_u32_e32 v0, 0x18000, v239
	v_cvt_f32_f16_e32 v18, v74
	v_cvt_f32_f16_sdwa v19, v74 dst_sel:DWORD dst_unused:UNUSED_PAD src0_sel:WORD_1
	v_cvt_f32_f16_e32 v20, v75
	v_cvt_f32_f16_sdwa v21, v75 dst_sel:DWORD dst_unused:UNUSED_PAD src0_sel:WORD_1
	v_cvt_f32_f16_e32 v22, v76
	v_cvt_f32_f16_sdwa v23, v76 dst_sel:DWORD dst_unused:UNUSED_PAD src0_sel:WORD_1
	v_cvt_f32_f16_e32 v24, v77
	v_cvt_f32_f16_sdwa v25, v77 dst_sel:DWORD dst_unused:UNUSED_PAD src0_sel:WORD_1
	v_pk_mul_f32 v[18:19], v[18:19], s[30:31] op_sel_hi:[1,0]
	v_pk_mul_f32 v[20:21], v[20:21], s[30:31] op_sel_hi:[1,0]
	v_pk_mul_f32 v[22:23], v[22:23], s[30:31] op_sel_hi:[1,0]
	v_pk_mul_f32 v[24:25], v[24:25], s[30:31] op_sel_hi:[1,0]
	v_pk_fma_f32 v[18:19], v[98:99], v[10:11], v[18:19]
	v_pk_fma_f32 v[20:21], v[100:101], v[12:13], v[20:21]
	v_pk_fma_f32 v[22:23], v[102:103], v[14:15], v[22:23]
	v_pk_fma_f32 v[24:25], v[104:105], v[16:17], v[24:25]
	v_cvt_pk_f16_f32 v74, v18, v19
	v_cvt_pk_f16_f32 v75, v20, v21
	v_cvt_pk_f16_f32 v76, v22, v23
	v_cvt_pk_f16_f32 v77, v24, v25
	global_store_dwordx4 v0, v[74:77], s[46:47]
	s_waitcnt vmcnt(15) lgkmcnt(0)
	v_lshlrev_b32_e32 v10, 16, v6
	v_and_b32_e32 v11, 0xffff0000, v6
	v_lshlrev_b32_e32 v12, 16, v7
	v_and_b32_e32 v13, 0xffff0000, v7
	v_lshlrev_b32_e32 v14, 16, v8
	v_and_b32_e32 v15, 0xffff0000, v8
	v_lshlrev_b32_e32 v16, 16, v9
	v_and_b32_e32 v17, 0xffff0000, v9
	v_add_u32_e32 v0, 0x1c000, v239
	v_cvt_f32_f16_e32 v18, v78
	v_cvt_f32_f16_sdwa v19, v78 dst_sel:DWORD dst_unused:UNUSED_PAD src0_sel:WORD_1
	v_cvt_f32_f16_e32 v20, v79
	v_cvt_f32_f16_sdwa v21, v79 dst_sel:DWORD dst_unused:UNUSED_PAD src0_sel:WORD_1
	v_cvt_f32_f16_e32 v22, v80
	v_cvt_f32_f16_sdwa v23, v80 dst_sel:DWORD dst_unused:UNUSED_PAD src0_sel:WORD_1
	v_cvt_f32_f16_e32 v24, v81
	v_cvt_f32_f16_sdwa v25, v81 dst_sel:DWORD dst_unused:UNUSED_PAD src0_sel:WORD_1
	v_pk_mul_f32 v[18:19], v[18:19], s[30:31] op_sel_hi:[1,0]
	v_pk_mul_f32 v[20:21], v[20:21], s[30:31] op_sel_hi:[1,0]
	v_pk_mul_f32 v[22:23], v[22:23], s[30:31] op_sel_hi:[1,0]
	v_pk_mul_f32 v[24:25], v[24:25], s[30:31] op_sel_hi:[1,0]
	v_pk_fma_f32 v[18:19], v[98:99], v[10:11], v[18:19]
	v_pk_fma_f32 v[20:21], v[100:101], v[12:13], v[20:21]
	v_pk_fma_f32 v[22:23], v[102:103], v[14:15], v[22:23]
	v_pk_fma_f32 v[24:25], v[104:105], v[16:17], v[24:25]
	v_cvt_pk_f16_f32 v78, v18, v19
	v_cvt_pk_f16_f32 v79, v20, v21
	v_cvt_pk_f16_f32 v80, v22, v23
	v_cvt_pk_f16_f32 v81, v24, v25
	global_store_dwordx4 v0, v[78:81], s[46:47]
	s_branch .Lres0_B
;   DI void operator()(f32x16 (&acc)[2][MB], int wm, int wn, int r, int h) {
;     ...
;         for (int j = 0; j < 8; ++j) {
;           const int rowl = (lane >> 3) + 8 * j, ch = lane & 7;
;           if (rowl < ntok) {
;             const u32x4 yv = *(const u32x4*)(slab + rowl * 72 + ch * 8);
;             const int R = R0 + rowl;
;             const int mi = (R < NLAT) ? (R >> 11) : 16;
;             const int col = n0 + wn * 64 + ch * 8;
;             const float* g = gate + (size_t)mi * 6144 + col;
;             const f32x4n g0 = *(const f32x4n*)(g), g1 = *(const f32x4n*)(g + 4);
;             _Float16* xp = X + (size_t)R * 1024 + col;
;             const h8 xv = *(const h8*)xp;
;             const float y[8] = {__uint_as_float(yv.x << 16), __uint_as_float(yv.x & 0xffff0000u), __uint_as_float(yv.y << 16), __uint_as_float(yv.y & 0xffff0000u),
;                                 __uint_as_float(yv.z << 16), __uint_as_float(yv.z & 0xffff0000u), __uint_as_float(yv.w << 16), __uint_as_float(yv.w & 0xffff0000u)};
;             const float gg[8] = {g0.x, g0.y, g0.z, g0.w, g1.x, g1.y, g1.z, g1.w};
;             h8 o;
; #pragma unroll
;             for (int q = 0; q < 8; ++q) o[q] = (_Float16)(ALPHA * (float)xv[q] + gg[q] * y[q]);
;             *(h8*)xp = o;
.Lres0_slowA:
	ds_read_b128 v[2:5], v238
	ds_read_b128 v[6:9], v238 offset:1152
	s_waitcnt vmcnt(15) lgkmcnt(1)
	v_lshlrev_b32_e32 v10, 16, v2
	v_and_b32_e32 v11, 0xffff0000, v2
	v_lshlrev_b32_e32 v12, 16, v3
	v_and_b32_e32 v13, 0xffff0000, v3
	v_lshlrev_b32_e32 v14, 16, v4
	v_and_b32_e32 v15, 0xffff0000, v4
	v_lshlrev_b32_e32 v16, 16, v5
	v_and_b32_e32 v17, 0xffff0000, v5
	ds_read_b128 v[2:5], v238 offset:2304
	v_mov_b32_e32 v26, v241
	v_min_i32_e32 v26, 0x8000, v26
	v_ashrrev_i32_e32 v26, 11, v26
	v_cmp_eq_u32_e32 vcc, v26, v246
	s_and_saveexec_b64 s[100:101], vcc
	v_cvt_f32_f16_e32 v18, v114
	v_cvt_f32_f16_sdwa v19, v114 dst_sel:DWORD dst_unused:UNUSED_PAD src0_sel:WORD_1
	v_cvt_f32_f16_e32 v20, v115
	v_cvt_f32_f16_sdwa v21, v115 dst_sel:DWORD dst_unused:UNUSED_PAD src0_sel:WORD_1
	v_cvt_f32_f16_e32 v22, v116
	v_cvt_f32_f16_sdwa v23, v116 dst_sel:DWORD dst_unused:UNUSED_PAD src0_sel:WORD_1
	v_cvt_f32_f16_e32 v24, v117
	v_cvt_f32_f16_sdwa v25, v117 dst_sel:DWORD dst_unused:UNUSED_PAD src0_sel:WORD_1
	v_pk_mul_f32 v[18:19], v[18:19], s[30:31] op_sel_hi:[1,0]
	v_pk_mul_f32 v[20:21], v[20:21], s[30:31] op_sel_hi:[1,0]
	v_pk_mul_f32 v[22:23], v[22:23], s[30:31] op_sel_hi:[1,0]
	v_pk_mul_f32 v[24:25], v[24:25], s[30:31] op_sel_hi:[1,0]
	v_pk_fma_f32 v[18:19], v[98:99], v[10:11], v[18:19]
	v_pk_fma_f32 v[20:21], v[100:101], v[12:13], v[20:21]
	v_pk_fma_f32 v[22:23], v[102:103], v[14:15], v[22:23]
	v_pk_fma_f32 v[24:25], v[104:105], v[16:17], v[24:25]
	v_cvt_pk_f16_f32 v114, v18, v19
	v_cvt_pk_f16_f32 v115, v20, v21
	v_cvt_pk_f16_f32 v116, v22, v23
	v_cvt_pk_f16_f32 v117, v24, v25
	global_store_dwordx4 v239, v[114:117], s[46:47]
	s_xor_b64 exec, exec, s[100:101]
	v_cvt_f32_f16_e32 v18, v114
	v_cvt_f32_f16_sdwa v19, v114 dst_sel:DWORD dst_unused:UNUSED_PAD src0_sel:WORD_1
	v_cvt_f32_f16_e32 v20, v115
	v_cvt_f32_f16_sdwa v21, v115 dst_sel:DWORD dst_unused:UNUSED_PAD src0_sel:WORD_1
	v_cvt_f32_f16_e32 v22, v116
	v_cvt_f32_f16_sdwa v23, v116 dst_sel:DWORD dst_unused:UNUSED_PAD src0_sel:WORD_1
	v_cvt_f32_f16_e32 v24, v117
	v_cvt_f32_f16_sdwa v25, v117 dst_sel:DWORD dst_unused:UNUSED_PAD src0_sel:WORD_1
	v_pk_mul_f32 v[18:19], v[18:19], s[30:31] op_sel_hi:[1,0]
	v_pk_mul_f32 v[20:21], v[20:21], s[30:31] op_sel_hi:[1,0]
	v_pk_mul_f32 v[22:23], v[22:23], s[30:31] op_sel_hi:[1,0]
	v_pk_mul_f32 v[24:25], v[24:25], s[30:31] op_sel_hi:[1,0]
	v_pk_fma_f32 v[18:19], v[106:107], v[10:11], v[18:19]
	v_pk_fma_f32 v[20:21], v[108:109], v[12:13], v[20:21]
	v_pk_fma_f32 v[22:23], v[110:111], v[14:15], v[22:23]
	v_pk_fma_f32 v[24:25], v[112:113], v[16:17], v[24:25]
	v_cvt_pk_f16_f32 v114, v18, v19
	v_cvt_pk_f16_f32 v115, v20, v21
	v_cvt_pk_f16_f32 v116, v22, v23
	v_cvt_pk_f16_f32 v117, v24, v25
	global_store_dwordx4 v239, v[114:117], s[46:47]
	s_mov_b64 exec, s[100:101]
	s_waitcnt vmcnt(15) lgkmcnt(1)
	v_lshlrev_b32_e32 v10, 16, v6
	v_and_b32_e32 v11, 0xffff0000, v6
	v_lshlrev_b32_e32 v12, 16, v7
	v_and_b32_e32 v13, 0xffff0000, v7
	v_lshlrev_b32_e32 v14, 16, v8
	v_and_b32_e32 v15, 0xffff0000, v8
	v_lshlrev_b32_e32 v16, 16, v9
	v_and_b32_e32 v17, 0xffff0000, v9
	ds_read_b128 v[6:9], v238 offset:3456
	v_add_u32_e32 v0, 0x4000, v239
	v_add_u32_e32 v26, 8, v241
	v_min_i32_e32 v26, 0x8000, v26
	v_ashrrev_i32_e32 v26, 11, v26
	v_cmp_eq_u32_e32 vcc, v26, v246
	s_and_saveexec_b64 s[100:101], vcc
	v_cvt_f32_f16_e32 v18, v118
	v_cvt_f32_f16_sdwa v19, v118 dst_sel:DWORD dst_unused:UNUSED_PAD src0_sel:WORD_1
	v_cvt_f32_f16_e32 v20, v119
	v_cvt_f32_f16_sdwa v21, v119 dst_sel:DWORD dst_unused:UNUSED_PAD src0_sel:WORD_1
	v_cvt_f32_f16_e32 v22, v120
	v_cvt_f32_f16_sdwa v23, v120 dst_sel:DWORD dst_unused:UNUSED_PAD src0_sel:WORD_1
	v_cvt_f32_f16_e32 v24, v121
	v_cvt_f32_f16_sdwa v25, v121 dst_sel:DWORD dst_unused:UNUSED_PAD src0_sel:WORD_1
	v_pk_mul_f32 v[18:19], v[18:19], s[30:31] op_sel_hi:[1,0]
	v_pk_mul_f32 v[20:21], v[20:21], s[30:31] op_sel_hi:[1,0]
	v_pk_mul_f32 v[22:23], v[22:23], s[30:31] op_sel_hi:[1,0]
	v_pk_mul_f32 v[24:25], v[24:25], s[30:31] op_sel_hi:[1,0]
	v_pk_fma_f32 v[18:19], v[98:99], v[10:11], v[18:19]
	v_pk_fma_f32 v[20:21], v[100:101], v[12:13], v[20:21]
	v_pk_fma_f32 v[22:23], v[102:103], v[14:15], v[22:23]
	v_pk_fma_f32 v[24:25], v[104:105], v[16:17], v[24:25]
	v_cvt_pk_f16_f32 v118, v18, v19
	v_cvt_pk_f16_f32 v119, v20, v21
	v_cvt_pk_f16_f32 v120, v22, v23
	v_cvt_pk_f16_f32 v121, v24, v25
	global_store_dwordx4 v0, v[118:121], s[46:47]
	s_xor_b64 exec, exec, s[100:101]
	v_cvt_f32_f16_e32 v18, v118
	v_cvt_f32_f16_sdwa v19, v118 dst_sel:DWORD dst_unused:UNUSED_PAD src0_sel:WORD_1
	v_cvt_f32_f16_e32 v20, v119
	v_cvt_f32_f16_sdwa v21, v119 dst_sel:DWORD dst_unused:UNUSED_PAD src0_sel:WORD_1
	v_cvt_f32_f16_e32 v22, v120
	v_cvt_f32_f16_sdwa v23, v120 dst_sel:DWORD dst_unused:UNUSED_PAD src0_sel:WORD_1
	v_cvt_f32_f16_e32 v24, v121
	v_cvt_f32_f16_sdwa v25, v121 dst_sel:DWORD dst_unused:UNUSED_PAD src0_sel:WORD_1
	v_pk_mul_f32 v[18:19], v[18:19], s[30:31] op_sel_hi:[1,0]
	v_pk_mul_f32 v[20:21], v[20:21], s[30:31] op_sel_hi:[1,0]
	v_pk_mul_f32 v[22:23], v[22:23], s[30:31] op_sel_hi:[1,0]
	v_pk_mul_f32 v[24:25], v[24:25], s[30:31] op_sel_hi:[1,0]
	v_pk_fma_f32 v[18:19], v[106:107], v[10:11], v[18:19]
	v_pk_fma_f32 v[20:21], v[108:109], v[12:13], v[20:21]
	v_pk_fma_f32 v[22:23], v[110:111], v[14:15], v[22:23]
	v_pk_fma_f32 v[24:25], v[112:113], v[16:17], v[24:25]
	v_cvt_pk_f16_f32 v118, v18, v19
	v_cvt_pk_f16_f32 v119, v20, v21
	v_cvt_pk_f16_f32 v120, v22, v23
	v_cvt_pk_f16_f32 v121, v24, v25
	global_store_dwordx4 v0, v[118:121], s[46:47]
	s_mov_b64 exec, s[100:101]
	s_waitcnt vmcnt(15) lgkmcnt(1)
;   DI void operator()(f32x16 (&acc)[2][MB], int wm, int wn, int r, int h) {
;     ...
;         for (int j = 0; j < 8; ++j) {
;           const int rowl = (lane >> 3) + 8 * j, ch = lane & 7;
;           if (rowl < ntok) {
;             const u32x4 yv = *(const u32x4*)(slab + rowl * 72 + ch * 8);
;             const int R = R0 + rowl;
;             const int mi = (R < NLAT) ? (R >> 11) : 16;
;             const int col = n0 + wn * 64 + ch * 8;
;             const float* g = gate + (size_t)mi * 6144 + col;
;             const f32x4n g0 = *(const f32x4n*)(g), g1 = *(const f32x4n*)(g + 4);
;             _Float16* xp = X + (size_t)R * 1024 + col;
;             const h8 xv = *(const h8*)xp;
;             const float y[8] = {__uint_as_float(yv.x << 16), __uint_as_float(yv.x & 0xffff0000u), __uint_as_float(yv.y << 16), __uint_as_float(yv.y & 0xffff0000u),
;                                 __uint_as_float(yv.z << 16), __uint_as_float(yv.z & 0xffff0000u), __uint_as_float(yv.w << 16), __uint_as_float(yv.w & 0xffff0000u)};
;             const float gg[8] = {g0.x, g0.y, g0.z, g0.w, g1.x, g1.y, g1.z, g1.w};
;             h8 o;
; #pragma unroll
;             for (int q = 0; q < 8; ++q) o[q] = (_Float16)(ALPHA * (float)xv[q] + gg[q] * y[q]);
;             *(h8*)xp = o;
	v_lshlrev_b32_e32 v10, 16, v2
	v_and_b32_e32 v11, 0xffff0000, v2
	v_lshlrev_b32_e32 v12, 16, v3
	v_and_b32_e32 v13, 0xffff0000, v3
	v_lshlrev_b32_e32 v14, 16, v4
	v_and_b32_e32 v15, 0xffff0000, v4
	v_lshlrev_b32_e32 v16, 16, v5
	v_and_b32_e32 v17, 0xffff0000, v5
	ds_read_b128 v[2:5], v238 offset:4608
	v_add_u32_e32 v0, 0x8000, v239
	v_add_u32_e32 v26, 16, v241
	v_min_i32_e32 v26, 0x8000, v26
	v_ashrrev_i32_e32 v26, 11, v26
	v_cmp_eq_u32_e32 vcc, v26, v246
	s_and_saveexec_b64 s[100:101], vcc
	v_cvt_f32_f16_e32 v18, v122
	v_cvt_f32_f16_sdwa v19, v122 dst_sel:DWORD dst_unused:UNUSED_PAD src0_sel:WORD_1
	v_cvt_f32_f16_e32 v20, v123
	v_cvt_f32_f16_sdwa v21, v123 dst_sel:DWORD dst_unused:UNUSED_PAD src0_sel:WORD_1
	v_cvt_f32_f16_e32 v22, v124
	v_cvt_f32_f16_sdwa v23, v124 dst_sel:DWORD dst_unused:UNUSED_PAD src0_sel:WORD_1
	v_cvt_f32_f16_e32 v24, v125
	v_cvt_f32_f16_sdwa v25, v125 dst_sel:DWORD dst_unused:UNUSED_PAD src0_sel:WORD_1
	v_pk_mul_f32 v[18:19], v[18:19], s[30:31] op_sel_hi:[1,0]
	v_pk_mul_f32 v[20:21], v[20:21], s[30:31] op_sel_hi:[1,0]
	v_pk_mul_f32 v[22:23], v[22:23], s[30:31] op_sel_hi:[1,0]
	v_pk_mul_f32 v[24:25], v[24:25], s[30:31] op_sel_hi:[1,0]
	v_pk_fma_f32 v[18:19], v[98:99], v[10:11], v[18:19]
	v_pk_fma_f32 v[20:21], v[100:101], v[12:13], v[20:21]
	v_pk_fma_f32 v[22:23], v[102:103], v[14:15], v[22:23]
	v_pk_fma_f32 v[24:25], v[104:105], v[16:17], v[24:25]
	v_cvt_pk_f16_f32 v122, v18, v19
	v_cvt_pk_f16_f32 v123, v20, v21
	v_cvt_pk_f16_f32 v124, v22, v23
	v_cvt_pk_f16_f32 v125, v24, v25
	global_store_dwordx4 v0, v[122:125], s[46:47]
	s_xor_b64 exec, exec, s[100:101]
	v_cvt_f32_f16_e32 v18, v122
	v_cvt_f32_f16_sdwa v19, v122 dst_sel:DWORD dst_unused:UNUSED_PAD src0_sel:WORD_1
	v_cvt_f32_f16_e32 v20, v123
	v_cvt_f32_f16_sdwa v21, v123 dst_sel:DWORD dst_unused:UNUSED_PAD src0_sel:WORD_1
	v_cvt_f32_f16_e32 v22, v124
	v_cvt_f32_f16_sdwa v23, v124 dst_sel:DWORD dst_unused:UNUSED_PAD src0_sel:WORD_1
	v_cvt_f32_f16_e32 v24, v125
	v_cvt_f32_f16_sdwa v25, v125 dst_sel:DWORD dst_unused:UNUSED_PAD src0_sel:WORD_1
	v_pk_mul_f32 v[18:19], v[18:19], s[30:31] op_sel_hi:[1,0]
	v_pk_mul_f32 v[20:21], v[20:21], s[30:31] op_sel_hi:[1,0]
	v_pk_mul_f32 v[22:23], v[22:23], s[30:31] op_sel_hi:[1,0]
	v_pk_mul_f32 v[24:25], v[24:25], s[30:31] op_sel_hi:[1,0]
	v_pk_fma_f32 v[18:19], v[106:107], v[10:11], v[18:19]
	v_pk_fma_f32 v[20:21], v[108:109], v[12:13], v[20:21]
	v_pk_fma_f32 v[22:23], v[110:111], v[14:15], v[22:23]
	v_pk_fma_f32 v[24:25], v[112:113], v[16:17], v[24:25]
	v_cvt_pk_f16_f32 v122, v18, v19
	v_cvt_pk_f16_f32 v123, v20, v21
	v_cvt_pk_f16_f32 v124, v22, v23
	v_cvt_pk_f16_f32 v125, v24, v25
	global_store_dwordx4 v0, v[122:125], s[46:47]
	s_mov_b64 exec, s[100:101]
	s_waitcnt vmcnt(15) lgkmcnt(1)
	v_lshlrev_b32_e32 v10, 16, v6
	v_and_b32_e32 v11, 0xffff0000, v6
	v_lshlrev_b32_e32 v12, 16, v7
	v_and_b32_e32 v13, 0xffff0000, v7
	v_lshlrev_b32_e32 v14, 16, v8
	v_and_b32_e32 v15, 0xffff0000, v8
	v_lshlrev_b32_e32 v16, 16, v9
	v_and_b32_e32 v17, 0xffff0000, v9
	ds_read_b128 v[6:9], v238 offset:5760
	v_add_u32_e32 v0, 0xc000, v239
	v_add_u32_e32 v26, 24, v241
	v_min_i32_e32 v26, 0x8000, v26
	v_ashrrev_i32_e32 v26, 11, v26
	v_cmp_eq_u32_e32 vcc, v26, v246
	s_and_saveexec_b64 s[100:101], vcc
	v_cvt_f32_f16_e32 v18, v126
	v_cvt_f32_f16_sdwa v19, v126 dst_sel:DWORD dst_unused:UNUSED_PAD src0_sel:WORD_1
	v_cvt_f32_f16_e32 v20, v127
	v_cvt_f32_f16_sdwa v21, v127 dst_sel:DWORD dst_unused:UNUSED_PAD src0_sel:WORD_1
	v_cvt_f32_f16_e32 v22, v128
	v_cvt_f32_f16_sdwa v23, v128 dst_sel:DWORD dst_unused:UNUSED_PAD src0_sel:WORD_1
	v_cvt_f32_f16_e32 v24, v129
	v_cvt_f32_f16_sdwa v25, v129 dst_sel:DWORD dst_unused:UNUSED_PAD src0_sel:WORD_1
	v_pk_mul_f32 v[18:19], v[18:19], s[30:31] op_sel_hi:[1,0]
	v_pk_mul_f32 v[20:21], v[20:21], s[30:31] op_sel_hi:[1,0]
	v_pk_mul_f32 v[22:23], v[22:23], s[30:31] op_sel_hi:[1,0]
	v_pk_mul_f32 v[24:25], v[24:25], s[30:31] op_sel_hi:[1,0]
	v_pk_fma_f32 v[18:19], v[98:99], v[10:11], v[18:19]
	v_pk_fma_f32 v[20:21], v[100:101], v[12:13], v[20:21]
	v_pk_fma_f32 v[22:23], v[102:103], v[14:15], v[22:23]
	v_pk_fma_f32 v[24:25], v[104:105], v[16:17], v[24:25]
	v_cvt_pk_f16_f32 v126, v18, v19
	v_cvt_pk_f16_f32 v127, v20, v21
	v_cvt_pk_f16_f32 v128, v22, v23
	v_cvt_pk_f16_f32 v129, v24, v25
	global_store_dwordx4 v0, v[126:129], s[46:47]
	s_xor_b64 exec, exec, s[100:101]
	v_cvt_f32_f16_e32 v18, v126
	v_cvt_f32_f16_sdwa v19, v126 dst_sel:DWORD dst_unused:UNUSED_PAD src0_sel:WORD_1
	v_cvt_f32_f16_e32 v20, v127
	v_cvt_f32_f16_sdwa v21, v127 dst_sel:DWORD dst_unused:UNUSED_PAD src0_sel:WORD_1
	v_cvt_f32_f16_e32 v22, v128
	v_cvt_f32_f16_sdwa v23, v128 dst_sel:DWORD dst_unused:UNUSED_PAD src0_sel:WORD_1
	v_cvt_f32_f16_e32 v24, v129
	v_cvt_f32_f16_sdwa v25, v129 dst_sel:DWORD dst_unused:UNUSED_PAD src0_sel:WORD_1
	v_pk_mul_f32 v[18:19], v[18:19], s[30:31] op_sel_hi:[1,0]
	v_pk_mul_f32 v[20:21], v[20:21], s[30:31] op_sel_hi:[1,0]
	v_pk_mul_f32 v[22:23], v[22:23], s[30:31] op_sel_hi:[1,0]
	v_pk_mul_f32 v[24:25], v[24:25], s[30:31] op_sel_hi:[1,0]
	v_pk_fma_f32 v[18:19], v[106:107], v[10:11], v[18:19]
	v_pk_fma_f32 v[20:21], v[108:109], v[12:13], v[20:21]
	v_pk_fma_f32 v[22:23], v[110:111], v[14:15], v[22:23]
	v_pk_fma_f32 v[24:25], v[112:113], v[16:17], v[24:25]
	v_cvt_pk_f16_f32 v126, v18, v19
	v_cvt_pk_f16_f32 v127, v20, v21
	v_cvt_pk_f16_f32 v128, v22, v23
	v_cvt_pk_f16_f32 v129, v24, v25
	global_store_dwordx4 v0, v[126:129], s[46:47]
	s_mov_b64 exec, s[100:101]
	s_waitcnt vmcnt(15) lgkmcnt(1)
;   DI void operator()(f32x16 (&acc)[2][MB], int wm, int wn, int r, int h) {
;     ...
;         for (int j = 0; j < 8; ++j) {
;           const int rowl = (lane >> 3) + 8 * j, ch = lane & 7;
;           if (rowl < ntok) {
;             const u32x4 yv = *(const u32x4*)(slab + rowl * 72 + ch * 8);
;             const int R = R0 + rowl;
;             const int mi = (R < NLAT) ? (R >> 11) : 16;
;             const int col = n0 + wn * 64 + ch * 8;
;             const float* g = gate + (size_t)mi * 6144 + col;
;             const f32x4n g0 = *(const f32x4n*)(g), g1 = *(const f32x4n*)(g + 4);
;             _Float16* xp = X + (size_t)R * 1024 + col;
;             const h8 xv = *(const h8*)xp;
;             const float y[8] = {__uint_as_float(yv.x << 16), __uint_as_float(yv.x & 0xffff0000u), __uint_as_float(yv.y << 16), __uint_as_float(yv.y & 0xffff0000u),
;                                 __uint_as_float(yv.z << 16), __uint_as_float(yv.z & 0xffff0000u), __uint_as_float(yv.w << 16), __uint_as_float(yv.w & 0xffff0000u)};
;             const float gg[8] = {g0.x, g0.y, g0.z, g0.w, g1.x, g1.y, g1.z, g1.w};
;             h8 o;
; #pragma unroll
;             for (int q = 0; q < 8; ++q) o[q] = (_Float16)(ALPHA * (float)xv[q] + gg[q] * y[q]);
;             *(h8*)xp = o;
	v_lshlrev_b32_e32 v10, 16, v2
	v_and_b32_e32 v11, 0xffff0000, v2
	v_lshlrev_b32_e32 v12, 16, v3
	v_and_b32_e32 v13, 0xffff0000, v3
	v_lshlrev_b32_e32 v14, 16, v4
	v_and_b32_e32 v15, 0xffff0000, v4
	v_lshlrev_b32_e32 v16, 16, v5
	v_and_b32_e32 v17, 0xffff0000, v5
	ds_read_b128 v[2:5], v238 offset:6912
	v_add_u32_e32 v0, 0x10000, v239
	v_add_u32_e32 v26, 32, v241
	v_min_i32_e32 v26, 0x8000, v26
	v_ashrrev_i32_e32 v26, 11, v26
	v_cmp_eq_u32_e32 vcc, v26, v246
	s_and_saveexec_b64 s[100:101], vcc
	v_cvt_f32_f16_e32 v18, v66
	v_cvt_f32_f16_sdwa v19, v66 dst_sel:DWORD dst_unused:UNUSED_PAD src0_sel:WORD_1
	v_cvt_f32_f16_e32 v20, v67
	v_cvt_f32_f16_sdwa v21, v67 dst_sel:DWORD dst_unused:UNUSED_PAD src0_sel:WORD_1
	v_cvt_f32_f16_e32 v22, v68
	v_cvt_f32_f16_sdwa v23, v68 dst_sel:DWORD dst_unused:UNUSED_PAD src0_sel:WORD_1
	v_cvt_f32_f16_e32 v24, v69
	v_cvt_f32_f16_sdwa v25, v69 dst_sel:DWORD dst_unused:UNUSED_PAD src0_sel:WORD_1
	v_pk_mul_f32 v[18:19], v[18:19], s[30:31] op_sel_hi:[1,0]
	v_pk_mul_f32 v[20:21], v[20:21], s[30:31] op_sel_hi:[1,0]
	v_pk_mul_f32 v[22:23], v[22:23], s[30:31] op_sel_hi:[1,0]
	v_pk_mul_f32 v[24:25], v[24:25], s[30:31] op_sel_hi:[1,0]
	v_pk_fma_f32 v[18:19], v[98:99], v[10:11], v[18:19]
	v_pk_fma_f32 v[20:21], v[100:101], v[12:13], v[20:21]
	v_pk_fma_f32 v[22:23], v[102:103], v[14:15], v[22:23]
	v_pk_fma_f32 v[24:25], v[104:105], v[16:17], v[24:25]
	v_cvt_pk_f16_f32 v66, v18, v19
	v_cvt_pk_f16_f32 v67, v20, v21
	v_cvt_pk_f16_f32 v68, v22, v23
	v_cvt_pk_f16_f32 v69, v24, v25
	global_store_dwordx4 v0, v[66:69], s[46:47]
	s_xor_b64 exec, exec, s[100:101]
	v_cvt_f32_f16_e32 v18, v66
	v_cvt_f32_f16_sdwa v19, v66 dst_sel:DWORD dst_unused:UNUSED_PAD src0_sel:WORD_1
	v_cvt_f32_f16_e32 v20, v67
	v_cvt_f32_f16_sdwa v21, v67 dst_sel:DWORD dst_unused:UNUSED_PAD src0_sel:WORD_1
	v_cvt_f32_f16_e32 v22, v68
	v_cvt_f32_f16_sdwa v23, v68 dst_sel:DWORD dst_unused:UNUSED_PAD src0_sel:WORD_1
	v_cvt_f32_f16_e32 v24, v69
	v_cvt_f32_f16_sdwa v25, v69 dst_sel:DWORD dst_unused:UNUSED_PAD src0_sel:WORD_1
	v_pk_mul_f32 v[18:19], v[18:19], s[30:31] op_sel_hi:[1,0]
	v_pk_mul_f32 v[20:21], v[20:21], s[30:31] op_sel_hi:[1,0]
	v_pk_mul_f32 v[22:23], v[22:23], s[30:31] op_sel_hi:[1,0]
	v_pk_mul_f32 v[24:25], v[24:25], s[30:31] op_sel_hi:[1,0]
	v_pk_fma_f32 v[18:19], v[106:107], v[10:11], v[18:19]
	v_pk_fma_f32 v[20:21], v[108:109], v[12:13], v[20:21]
	v_pk_fma_f32 v[22:23], v[110:111], v[14:15], v[22:23]
	v_pk_fma_f32 v[24:25], v[112:113], v[16:17], v[24:25]
	v_cvt_pk_f16_f32 v66, v18, v19
	v_cvt_pk_f16_f32 v67, v20, v21
	v_cvt_pk_f16_f32 v68, v22, v23
	v_cvt_pk_f16_f32 v69, v24, v25
	global_store_dwordx4 v0, v[66:69], s[46:47]
	s_mov_b64 exec, s[100:101]
	s_waitcnt vmcnt(15) lgkmcnt(1)
	v_lshlrev_b32_e32 v10, 16, v6
	v_and_b32_e32 v11, 0xffff0000, v6
	v_lshlrev_b32_e32 v12, 16, v7
	v_and_b32_e32 v13, 0xffff0000, v7
	v_lshlrev_b32_e32 v14, 16, v8
	v_and_b32_e32 v15, 0xffff0000, v8
	v_lshlrev_b32_e32 v16, 16, v9
	v_and_b32_e32 v17, 0xffff0000, v9
	ds_read_b128 v[6:9], v238 offset:8064
	v_add_u32_e32 v0, 0x14000, v239
	v_add_u32_e32 v26, 40, v241
	v_min_i32_e32 v26, 0x8000, v26
	v_ashrrev_i32_e32 v26, 11, v26
	v_cmp_eq_u32_e32 vcc, v26, v246
	s_and_saveexec_b64 s[100:101], vcc
	v_cvt_f32_f16_e32 v18, v70
	v_cvt_f32_f16_sdwa v19, v70 dst_sel:DWORD dst_unused:UNUSED_PAD src0_sel:WORD_1
	v_cvt_f32_f16_e32 v20, v71
	v_cvt_f32_f16_sdwa v21, v71 dst_sel:DWORD dst_unused:UNUSED_PAD src0_sel:WORD_1
	v_cvt_f32_f16_e32 v22, v72
	v_cvt_f32_f16_sdwa v23, v72 dst_sel:DWORD dst_unused:UNUSED_PAD src0_sel:WORD_1
	v_cvt_f32_f16_e32 v24, v73
	v_cvt_f32_f16_sdwa v25, v73 dst_sel:DWORD dst_unused:UNUSED_PAD src0_sel:WORD_1
	v_pk_mul_f32 v[18:19], v[18:19], s[30:31] op_sel_hi:[1,0]
	v_pk_mul_f32 v[20:21], v[20:21], s[30:31] op_sel_hi:[1,0]
	v_pk_mul_f32 v[22:23], v[22:23], s[30:31] op_sel_hi:[1,0]
	v_pk_mul_f32 v[24:25], v[24:25], s[30:31] op_sel_hi:[1,0]
	v_pk_fma_f32 v[18:19], v[98:99], v[10:11], v[18:19]
	v_pk_fma_f32 v[20:21], v[100:101], v[12:13], v[20:21]
	v_pk_fma_f32 v[22:23], v[102:103], v[14:15], v[22:23]
	v_pk_fma_f32 v[24:25], v[104:105], v[16:17], v[24:25]
	v_cvt_pk_f16_f32 v70, v18, v19
	v_cvt_pk_f16_f32 v71, v20, v21
	v_cvt_pk_f16_f32 v72, v22, v23
	v_cvt_pk_f16_f32 v73, v24, v25
	global_store_dwordx4 v0, v[70:73], s[46:47]
	s_xor_b64 exec, exec, s[100:101]
	v_cvt_f32_f16_e32 v18, v70
	v_cvt_f32_f16_sdwa v19, v70 dst_sel:DWORD dst_unused:UNUSED_PAD src0_sel:WORD_1
	v_cvt_f32_f16_e32 v20, v71
	v_cvt_f32_f16_sdwa v21, v71 dst_sel:DWORD dst_unused:UNUSED_PAD src0_sel:WORD_1
	v_cvt_f32_f16_e32 v22, v72
	v_cvt_f32_f16_sdwa v23, v72 dst_sel:DWORD dst_unused:UNUSED_PAD src0_sel:WORD_1
	v_cvt_f32_f16_e32 v24, v73
	v_cvt_f32_f16_sdwa v25, v73 dst_sel:DWORD dst_unused:UNUSED_PAD src0_sel:WORD_1
	v_pk_mul_f32 v[18:19], v[18:19], s[30:31] op_sel_hi:[1,0]
	v_pk_mul_f32 v[20:21], v[20:21], s[30:31] op_sel_hi:[1,0]
	v_pk_mul_f32 v[22:23], v[22:23], s[30:31] op_sel_hi:[1,0]
	v_pk_mul_f32 v[24:25], v[24:25], s[30:31] op_sel_hi:[1,0]
	v_pk_fma_f32 v[18:19], v[106:107], v[10:11], v[18:19]
	v_pk_fma_f32 v[20:21], v[108:109], v[12:13], v[20:21]
	v_pk_fma_f32 v[22:23], v[110:111], v[14:15], v[22:23]
	v_pk_fma_f32 v[24:25], v[112:113], v[16:17], v[24:25]
	v_cvt_pk_f16_f32 v70, v18, v19
	v_cvt_pk_f16_f32 v71, v20, v21
	v_cvt_pk_f16_f32 v72, v22, v23
	v_cvt_pk_f16_f32 v73, v24, v25
	global_store_dwordx4 v0, v[70:73], s[46:47]
	s_mov_b64 exec, s[100:101]
	s_waitcnt vmcnt(15) lgkmcnt(1)
;   DI void operator()(f32x16 (&acc)[2][MB], int wm, int wn, int r, int h) {
;     ...
;         for (int j = 0; j < 8; ++j) {
;           const int rowl = (lane >> 3) + 8 * j, ch = lane & 7;
;           if (rowl < ntok) {
;             const u32x4 yv = *(const u32x4*)(slab + rowl * 72 + ch * 8);
;             const int R = R0 + rowl;
;             const int mi = (R < NLAT) ? (R >> 11) : 16;
;             const int col = n0 + wn * 64 + ch * 8;
;             const float* g = gate + (size_t)mi * 6144 + col;
;             const f32x4n g0 = *(const f32x4n*)(g), g1 = *(const f32x4n*)(g + 4);
;             _Float16* xp = X + (size_t)R * 1024 + col;
;             const h8 xv = *(const h8*)xp;
;             const float y[8] = {__uint_as_float(yv.x << 16), __uint_as_float(yv.x & 0xffff0000u), __uint_as_float(yv.y << 16), __uint_as_float(yv.y & 0xffff0000u),
;                                 __uint_as_float(yv.z << 16), __uint_as_float(yv.z & 0xffff0000u), __uint_as_float(yv.w << 16), __uint_as_float(yv.w & 0xffff0000u)};
;             const float gg[8] = {g0.x, g0.y, g0.z, g0.w, g1.x, g1.y, g1.z, g1.w};
;             h8 o;
; #pragma unroll
;             for (int q = 0; q < 8; ++q) o[q] = (_Float16)(ALPHA * (float)xv[q] + gg[q] * y[q]);
;             *(h8*)xp = o;
	v_lshlrev_b32_e32 v10, 16, v2
	v_and_b32_e32 v11, 0xffff0000, v2
	v_lshlrev_b32_e32 v12, 16, v3
	v_and_b32_e32 v13, 0xffff0000, v3
	v_lshlrev_b32_e32 v14, 16, v4
	v_and_b32_e32 v15, 0xffff0000, v4
	v_lshlrev_b32_e32 v16, 16, v5
	v_and_b32_e32 v17, 0xffff0000, v5
	v_add_u32_e32 v0, 0x18000, v239
	v_add_u32_e32 v26, 48, v241
	v_min_i32_e32 v26, 0x8000, v26
	v_ashrrev_i32_e32 v26, 11, v26
	v_cmp_eq_u32_e32 vcc, v26, v246
	s_and_saveexec_b64 s[100:101], vcc
	v_cvt_f32_f16_e32 v18, v74
	v_cvt_f32_f16_sdwa v19, v74 dst_sel:DWORD dst_unused:UNUSED_PAD src0_sel:WORD_1
	v_cvt_f32_f16_e32 v20, v75
	v_cvt_f32_f16_sdwa v21, v75 dst_sel:DWORD dst_unused:UNUSED_PAD src0_sel:WORD_1
	v_cvt_f32_f16_e32 v22, v76
	v_cvt_f32_f16_sdwa v23, v76 dst_sel:DWORD dst_unused:UNUSED_PAD src0_sel:WORD_1
	v_cvt_f32_f16_e32 v24, v77
	v_cvt_f32_f16_sdwa v25, v77 dst_sel:DWORD dst_unused:UNUSED_PAD src0_sel:WORD_1
	v_pk_mul_f32 v[18:19], v[18:19], s[30:31] op_sel_hi:[1,0]
	v_pk_mul_f32 v[20:21], v[20:21], s[30:31] op_sel_hi:[1,0]
	v_pk_mul_f32 v[22:23], v[22:23], s[30:31] op_sel_hi:[1,0]
	v_pk_mul_f32 v[24:25], v[24:25], s[30:31] op_sel_hi:[1,0]
	v_pk_fma_f32 v[18:19], v[98:99], v[10:11], v[18:19]
	v_pk_fma_f32 v[20:21], v[100:101], v[12:13], v[20:21]
	v_pk_fma_f32 v[22:23], v[102:103], v[14:15], v[22:23]
	v_pk_fma_f32 v[24:25], v[104:105], v[16:17], v[24:25]
	v_cvt_pk_f16_f32 v74, v18, v19
	v_cvt_pk_f16_f32 v75, v20, v21
	v_cvt_pk_f16_f32 v76, v22, v23
	v_cvt_pk_f16_f32 v77, v24, v25
	global_store_dwordx4 v0, v[74:77], s[46:47]
	s_xor_b64 exec, exec, s[100:101]
	v_cvt_f32_f16_e32 v18, v74
	v_cvt_f32_f16_sdwa v19, v74 dst_sel:DWORD dst_unused:UNUSED_PAD src0_sel:WORD_1
	v_cvt_f32_f16_e32 v20, v75
	v_cvt_f32_f16_sdwa v21, v75 dst_sel:DWORD dst_unused:UNUSED_PAD src0_sel:WORD_1
	v_cvt_f32_f16_e32 v22, v76
	v_cvt_f32_f16_sdwa v23, v76 dst_sel:DWORD dst_unused:UNUSED_PAD src0_sel:WORD_1
	v_cvt_f32_f16_e32 v24, v77
	v_cvt_f32_f16_sdwa v25, v77 dst_sel:DWORD dst_unused:UNUSED_PAD src0_sel:WORD_1
	v_pk_mul_f32 v[18:19], v[18:19], s[30:31] op_sel_hi:[1,0]
	v_pk_mul_f32 v[20:21], v[20:21], s[30:31] op_sel_hi:[1,0]
	v_pk_mul_f32 v[22:23], v[22:23], s[30:31] op_sel_hi:[1,0]
	v_pk_mul_f32 v[24:25], v[24:25], s[30:31] op_sel_hi:[1,0]
	v_pk_fma_f32 v[18:19], v[106:107], v[10:11], v[18:19]
	v_pk_fma_f32 v[20:21], v[108:109], v[12:13], v[20:21]
	v_pk_fma_f32 v[22:23], v[110:111], v[14:15], v[22:23]
	v_pk_fma_f32 v[24:25], v[112:113], v[16:17], v[24:25]
	v_cvt_pk_f16_f32 v74, v18, v19
	v_cvt_pk_f16_f32 v75, v20, v21
	v_cvt_pk_f16_f32 v76, v22, v23
	v_cvt_pk_f16_f32 v77, v24, v25
	global_store_dwordx4 v0, v[74:77], s[46:47]
	s_mov_b64 exec, s[100:101]
	s_waitcnt vmcnt(15) lgkmcnt(0)
	v_lshlrev_b32_e32 v10, 16, v6
	v_and_b32_e32 v11, 0xffff0000, v6
	v_lshlrev_b32_e32 v12, 16, v7
	v_and_b32_e32 v13, 0xffff0000, v7
	v_lshlrev_b32_e32 v14, 16, v8
	v_and_b32_e32 v15, 0xffff0000, v8
	v_lshlrev_b32_e32 v16, 16, v9
	v_and_b32_e32 v17, 0xffff0000, v9
	v_add_u32_e32 v0, 0x1c000, v239
	v_add_u32_e32 v26, 56, v241
	v_min_i32_e32 v26, 0x8000, v26
	v_ashrrev_i32_e32 v26, 11, v26
	v_cmp_eq_u32_e32 vcc, v26, v246
	s_and_saveexec_b64 s[100:101], vcc
	v_cvt_f32_f16_e32 v18, v78
	v_cvt_f32_f16_sdwa v19, v78 dst_sel:DWORD dst_unused:UNUSED_PAD src0_sel:WORD_1
	v_cvt_f32_f16_e32 v20, v79
	v_cvt_f32_f16_sdwa v21, v79 dst_sel:DWORD dst_unused:UNUSED_PAD src0_sel:WORD_1
	v_cvt_f32_f16_e32 v22, v80
	v_cvt_f32_f16_sdwa v23, v80 dst_sel:DWORD dst_unused:UNUSED_PAD src0_sel:WORD_1
	v_cvt_f32_f16_e32 v24, v81
	v_cvt_f32_f16_sdwa v25, v81 dst_sel:DWORD dst_unused:UNUSED_PAD src0_sel:WORD_1
	v_pk_mul_f32 v[18:19], v[18:19], s[30:31] op_sel_hi:[1,0]
	v_pk_mul_f32 v[20:21], v[20:21], s[30:31] op_sel_hi:[1,0]
	v_pk_mul_f32 v[22:23], v[22:23], s[30:31] op_sel_hi:[1,0]
	v_pk_mul_f32 v[24:25], v[24:25], s[30:31] op_sel_hi:[1,0]
	v_pk_fma_f32 v[18:19], v[98:99], v[10:11], v[18:19]
	v_pk_fma_f32 v[20:21], v[100:101], v[12:13], v[20:21]
	v_pk_fma_f32 v[22:23], v[102:103], v[14:15], v[22:23]
	v_pk_fma_f32 v[24:25], v[104:105], v[16:17], v[24:25]
	v_cvt_pk_f16_f32 v78, v18, v19
	v_cvt_pk_f16_f32 v79, v20, v21
	v_cvt_pk_f16_f32 v80, v22, v23
	v_cvt_pk_f16_f32 v81, v24, v25
	global_store_dwordx4 v0, v[78:81], s[46:47]
	s_xor_b64 exec, exec, s[100:101]
	v_cvt_f32_f16_e32 v18, v78
	v_cvt_f32_f16_sdwa v19, v78 dst_sel:DWORD dst_unused:UNUSED_PAD src0_sel:WORD_1
	v_cvt_f32_f16_e32 v20, v79
	v_cvt_f32_f16_sdwa v21, v79 dst_sel:DWORD dst_unused:UNUSED_PAD src0_sel:WORD_1
	v_cvt_f32_f16_e32 v22, v80
	v_cvt_f32_f16_sdwa v23, v80 dst_sel:DWORD dst_unused:UNUSED_PAD src0_sel:WORD_1
	v_cvt_f32_f16_e32 v24, v81
	v_cvt_f32_f16_sdwa v25, v81 dst_sel:DWORD dst_unused:UNUSED_PAD src0_sel:WORD_1
	v_pk_mul_f32 v[18:19], v[18:19], s[30:31] op_sel_hi:[1,0]
	v_pk_mul_f32 v[20:21], v[20:21], s[30:31] op_sel_hi:[1,0]
	v_pk_mul_f32 v[22:23], v[22:23], s[30:31] op_sel_hi:[1,0]
	v_pk_mul_f32 v[24:25], v[24:25], s[30:31] op_sel_hi:[1,0]
	v_pk_fma_f32 v[18:19], v[106:107], v[10:11], v[18:19]
	v_pk_fma_f32 v[20:21], v[108:109], v[12:13], v[20:21]
	v_pk_fma_f32 v[22:23], v[110:111], v[14:15], v[22:23]
	v_pk_fma_f32 v[24:25], v[112:113], v[16:17], v[24:25]
	v_cvt_pk_f16_f32 v78, v18, v19
	v_cvt_pk_f16_f32 v79, v20, v21
	v_cvt_pk_f16_f32 v80, v22, v23
	v_cvt_pk_f16_f32 v81, v24, v25
	global_store_dwordx4 v0, v[78:81], s[46:47]
	s_mov_b64 exec, s[100:101]
;   DI void operator()(f32x16 (&acc)[2][MB], int wm, int wn, int r, int h) {
;     ...
;       if ((mb & 1) || mb == MB - 1) {
;         asm volatile("s_waitcnt lgkmcnt(0)" ::: "memory");
;         const int ntok = (mb & 1) ? 64 : 32;
;         const int R0 = row0 + wm * (32 * MB) + (mb >> 1) * 64;
; #pragma unroll
;         for (int j = 0; j < 8; ++j) {
;           const int rowl = (lane >> 3) + 8 * j, ch = lane & 7;
;           if (rowl < ntok) {
;             const u32x4 yv = *(const u32x4*)(slab + rowl * 72 + ch * 8);
;             const int R = R0 + rowl;
;             const int mi = (R < NLAT) ? (R >> 11) : 16;
;             const int col = n0 + wn * 64 + ch * 8;
;             const float* g = gate + (size_t)mi * 6144 + col;
;             const f32x4n g0 = *(const f32x4n*)(g), g1 = *(const f32x4n*)(g + 4);
;             _Float16* xp = X + (size_t)R * 1024 + col;
;             const h8 xv = *(const h8*)xp;
;             const float y[8] = {__uint_as_float(yv.x << 16), __uint_as_float(yv.x & 0xffff0000u), __uint_as_float(yv.y << 16), __uint_as_float(yv.y & 0xffff0000u),
;                                 __uint_as_float(yv.z << 16), __uint_as_float(yv.z & 0xffff0000u), __uint_as_float(yv.w << 16), __uint_as_float(yv.w & 0xffff0000u)};
;             const float gg[8] = {g0.x, g0.y, g0.z, g0.w, g1.x, g1.y, g1.z, g1.w};
;             h8 o;
; #pragma unroll
;             for (int q = 0; q < 8; ++q) o[q] = (_Float16)(ALPHA * (float)xv[q] + gg[q] * y[q]);
;             *(h8*)xp = o;
.Lres0_B:
	v_cmp_ne_u32_e32 vcc, v248, v249
	s_cbranch_vccnz .Lres0_slowB
	ds_read_b128 v[2:5], v243
	ds_read_b128 v[6:9], v243 offset:1152
	s_waitcnt vmcnt(11) lgkmcnt(1)
	v_lshlrev_b32_e32 v10, 16, v2
	v_and_b32_e32 v11, 0xffff0000, v2
	v_lshlrev_b32_e32 v12, 16, v3
	v_and_b32_e32 v13, 0xffff0000, v3
	v_lshlrev_b32_e32 v14, 16, v4
	v_and_b32_e32 v15, 0xffff0000, v4
	v_lshlrev_b32_e32 v16, 16, v5
	v_and_b32_e32 v17, 0xffff0000, v5
	ds_read_b128 v[2:5], v243 offset:2304
	v_add_u32_e32 v0, 0x20000, v239
	v_cvt_f32_f16_e32 v18, v50
	v_cvt_f32_f16_sdwa v19, v50 dst_sel:DWORD dst_unused:UNUSED_PAD src0_sel:WORD_1
	v_cvt_f32_f16_e32 v20, v51
	v_cvt_f32_f16_sdwa v21, v51 dst_sel:DWORD dst_unused:UNUSED_PAD src0_sel:WORD_1
	v_cvt_f32_f16_e32 v22, v52
	v_cvt_f32_f16_sdwa v23, v52 dst_sel:DWORD dst_unused:UNUSED_PAD src0_sel:WORD_1
	v_cvt_f32_f16_e32 v24, v53
	v_cvt_f32_f16_sdwa v25, v53 dst_sel:DWORD dst_unused:UNUSED_PAD src0_sel:WORD_1
	v_pk_mul_f32 v[18:19], v[18:19], s[30:31] op_sel_hi:[1,0]
	v_pk_mul_f32 v[20:21], v[20:21], s[30:31] op_sel_hi:[1,0]
	v_pk_mul_f32 v[22:23], v[22:23], s[30:31] op_sel_hi:[1,0]
	v_pk_mul_f32 v[24:25], v[24:25], s[30:31] op_sel_hi:[1,0]
	v_pk_fma_f32 v[18:19], v[34:35], v[10:11], v[18:19]
	v_pk_fma_f32 v[20:21], v[36:37], v[12:13], v[20:21]
	v_pk_fma_f32 v[22:23], v[38:39], v[14:15], v[22:23]
	v_pk_fma_f32 v[24:25], v[40:41], v[16:17], v[24:25]
	v_cvt_pk_f16_f32 v50, v18, v19
	v_cvt_pk_f16_f32 v51, v20, v21
	v_cvt_pk_f16_f32 v52, v22, v23
	v_cvt_pk_f16_f32 v53, v24, v25
	global_store_dwordx4 v0, v[50:53], s[46:47]
	s_waitcnt vmcnt(11) lgkmcnt(1)
	v_lshlrev_b32_e32 v10, 16, v6
	v_and_b32_e32 v11, 0xffff0000, v6
	v_lshlrev_b32_e32 v12, 16, v7
	v_and_b32_e32 v13, 0xffff0000, v7
	v_lshlrev_b32_e32 v14, 16, v8
	v_and_b32_e32 v15, 0xffff0000, v8
	v_lshlrev_b32_e32 v16, 16, v9
	v_and_b32_e32 v17, 0xffff0000, v9
	ds_read_b128 v[6:9], v243 offset:3456
	v_add_u32_e32 v0, 0x24000, v239
	v_cvt_f32_f16_e32 v18, v54
	v_cvt_f32_f16_sdwa v19, v54 dst_sel:DWORD dst_unused:UNUSED_PAD src0_sel:WORD_1
	v_cvt_f32_f16_e32 v20, v55
	v_cvt_f32_f16_sdwa v21, v55 dst_sel:DWORD dst_unused:UNUSED_PAD src0_sel:WORD_1
	v_cvt_f32_f16_e32 v22, v56
	v_cvt_f32_f16_sdwa v23, v56 dst_sel:DWORD dst_unused:UNUSED_PAD src0_sel:WORD_1
	v_cvt_f32_f16_e32 v24, v57
	v_cvt_f32_f16_sdwa v25, v57 dst_sel:DWORD dst_unused:UNUSED_PAD src0_sel:WORD_1
	v_pk_mul_f32 v[18:19], v[18:19], s[30:31] op_sel_hi:[1,0]
	v_pk_mul_f32 v[20:21], v[20:21], s[30:31] op_sel_hi:[1,0]
	v_pk_mul_f32 v[22:23], v[22:23], s[30:31] op_sel_hi:[1,0]
	v_pk_mul_f32 v[24:25], v[24:25], s[30:31] op_sel_hi:[1,0]
	v_pk_fma_f32 v[18:19], v[34:35], v[10:11], v[18:19]
	v_pk_fma_f32 v[20:21], v[36:37], v[12:13], v[20:21]
	v_pk_fma_f32 v[22:23], v[38:39], v[14:15], v[22:23]
	v_pk_fma_f32 v[24:25], v[40:41], v[16:17], v[24:25]
	v_cvt_pk_f16_f32 v54, v18, v19
	v_cvt_pk_f16_f32 v55, v20, v21
	v_cvt_pk_f16_f32 v56, v22, v23
	v_cvt_pk_f16_f32 v57, v24, v25
	global_store_dwordx4 v0, v[54:57], s[46:47]
	s_waitcnt vmcnt(11) lgkmcnt(1)
	v_lshlrev_b32_e32 v10, 16, v2
	v_and_b32_e32 v11, 0xffff0000, v2
	v_lshlrev_b32_e32 v12, 16, v3
	v_and_b32_e32 v13, 0xffff0000, v3
	v_lshlrev_b32_e32 v14, 16, v4
	v_and_b32_e32 v15, 0xffff0000, v4
	v_lshlrev_b32_e32 v16, 16, v5
	v_and_b32_e32 v17, 0xffff0000, v5
	v_add_u32_e32 v0, 0x28000, v239
	v_cvt_f32_f16_e32 v18, v58
	v_cvt_f32_f16_sdwa v19, v58 dst_sel:DWORD dst_unused:UNUSED_PAD src0_sel:WORD_1
	v_cvt_f32_f16_e32 v20, v59
	v_cvt_f32_f16_sdwa v21, v59 dst_sel:DWORD dst_unused:UNUSED_PAD src0_sel:WORD_1
	v_cvt_f32_f16_e32 v22, v60
	v_cvt_f32_f16_sdwa v23, v60 dst_sel:DWORD dst_unused:UNUSED_PAD src0_sel:WORD_1
	v_cvt_f32_f16_e32 v24, v61
	v_cvt_f32_f16_sdwa v25, v61 dst_sel:DWORD dst_unused:UNUSED_PAD src0_sel:WORD_1
	v_pk_mul_f32 v[18:19], v[18:19], s[30:31] op_sel_hi:[1,0]
	v_pk_mul_f32 v[20:21], v[20:21], s[30:31] op_sel_hi:[1,0]
	v_pk_mul_f32 v[22:23], v[22:23], s[30:31] op_sel_hi:[1,0]
	v_pk_mul_f32 v[24:25], v[24:25], s[30:31] op_sel_hi:[1,0]
	v_pk_fma_f32 v[18:19], v[34:35], v[10:11], v[18:19]
	v_pk_fma_f32 v[20:21], v[36:37], v[12:13], v[20:21]
	v_pk_fma_f32 v[22:23], v[38:39], v[14:15], v[22:23]
	v_pk_fma_f32 v[24:25], v[40:41], v[16:17], v[24:25]
	v_cvt_pk_f16_f32 v58, v18, v19
	v_cvt_pk_f16_f32 v59, v20, v21
	v_cvt_pk_f16_f32 v60, v22, v23
	v_cvt_pk_f16_f32 v61, v24, v25
	global_store_dwordx4 v0, v[58:61], s[46:47]
	s_waitcnt vmcnt(11) lgkmcnt(0)
	v_lshlrev_b32_e32 v10, 16, v6
	v_and_b32_e32 v11, 0xffff0000, v6
	v_lshlrev_b32_e32 v12, 16, v7
	v_and_b32_e32 v13, 0xffff0000, v7
	v_lshlrev_b32_e32 v14, 16, v8
	v_and_b32_e32 v15, 0xffff0000, v8
	v_lshlrev_b32_e32 v16, 16, v9
	v_and_b32_e32 v17, 0xffff0000, v9
	v_add_u32_e32 v0, 0x2c000, v239
	v_cvt_f32_f16_e32 v18, v62
	v_cvt_f32_f16_sdwa v19, v62 dst_sel:DWORD dst_unused:UNUSED_PAD src0_sel:WORD_1
	v_cvt_f32_f16_e32 v20, v63
	v_cvt_f32_f16_sdwa v21, v63 dst_sel:DWORD dst_unused:UNUSED_PAD src0_sel:WORD_1
	v_cvt_f32_f16_e32 v22, v64
	v_cvt_f32_f16_sdwa v23, v64 dst_sel:DWORD dst_unused:UNUSED_PAD src0_sel:WORD_1
	v_cvt_f32_f16_e32 v24, v65
	v_cvt_f32_f16_sdwa v25, v65 dst_sel:DWORD dst_unused:UNUSED_PAD src0_sel:WORD_1
	v_pk_mul_f32 v[18:19], v[18:19], s[30:31] op_sel_hi:[1,0]
	v_pk_mul_f32 v[20:21], v[20:21], s[30:31] op_sel_hi:[1,0]
	v_pk_mul_f32 v[22:23], v[22:23], s[30:31] op_sel_hi:[1,0]
	v_pk_mul_f32 v[24:25], v[24:25], s[30:31] op_sel_hi:[1,0]
	v_pk_fma_f32 v[18:19], v[34:35], v[10:11], v[18:19]
	v_pk_fma_f32 v[20:21], v[36:37], v[12:13], v[20:21]
	v_pk_fma_f32 v[22:23], v[38:39], v[14:15], v[22:23]
	v_pk_fma_f32 v[24:25], v[40:41], v[16:17], v[24:25]
	v_cvt_pk_f16_f32 v62, v18, v19
	v_cvt_pk_f16_f32 v63, v20, v21
	v_cvt_pk_f16_f32 v64, v22, v23
	v_cvt_pk_f16_f32 v65, v24, v25
	global_store_dwordx4 v0, v[62:65], s[46:47]
	s_branch .Lres0_end
;   DI void operator()(f32x16 (&acc)[2][MB], int wm, int wn, int r, int h) {
;     ...
;         for (int j = 0; j < 8; ++j) {
;           const int rowl = (lane >> 3) + 8 * j, ch = lane & 7;
;           if (rowl < ntok) {
;             const u32x4 yv = *(const u32x4*)(slab + rowl * 72 + ch * 8);
;             const int R = R0 + rowl;
;             const int mi = (R < NLAT) ? (R >> 11) : 16;
;             const int col = n0 + wn * 64 + ch * 8;
;             const float* g = gate + (size_t)mi * 6144 + col;
;             const f32x4n g0 = *(const f32x4n*)(g), g1 = *(const f32x4n*)(g + 4);
;             _Float16* xp = X + (size_t)R * 1024 + col;
;             const h8 xv = *(const h8*)xp;
;             const float y[8] = {__uint_as_float(yv.x << 16), __uint_as_float(yv.x & 0xffff0000u), __uint_as_float(yv.y << 16), __uint_as_float(yv.y & 0xffff0000u),
;                                 __uint_as_float(yv.z << 16), __uint_as_float(yv.z & 0xffff0000u), __uint_as_float(yv.w << 16), __uint_as_float(yv.w & 0xffff0000u)};
;             const float gg[8] = {g0.x, g0.y, g0.z, g0.w, g1.x, g1.y, g1.z, g1.w};
;             h8 o;
; #pragma unroll
;             for (int q = 0; q < 8; ++q) o[q] = (_Float16)(ALPHA * (float)xv[q] + gg[q] * y[q]);
;             *(h8*)xp = o;
.Lres0_slowB:
	ds_read_b128 v[2:5], v243
	ds_read_b128 v[6:9], v243 offset:1152
	s_waitcnt vmcnt(11) lgkmcnt(1)
	v_lshlrev_b32_e32 v10, 16, v2
	v_and_b32_e32 v11, 0xffff0000, v2
	v_lshlrev_b32_e32 v12, 16, v3
	v_and_b32_e32 v13, 0xffff0000, v3
	v_lshlrev_b32_e32 v14, 16, v4
	v_and_b32_e32 v15, 0xffff0000, v4
	v_lshlrev_b32_e32 v16, 16, v5
	v_and_b32_e32 v17, 0xffff0000, v5
	ds_read_b128 v[2:5], v243 offset:2304
	v_add_u32_e32 v0, 0x20000, v239
	v_add_u32_e32 v26, 64, v241
	v_min_i32_e32 v26, 0x8000, v26
	v_ashrrev_i32_e32 v26, 11, v26
	v_cmp_eq_u32_e32 vcc, v26, v248
	s_and_saveexec_b64 s[100:101], vcc
	v_cvt_f32_f16_e32 v18, v50
	v_cvt_f32_f16_sdwa v19, v50 dst_sel:DWORD dst_unused:UNUSED_PAD src0_sel:WORD_1
	v_cvt_f32_f16_e32 v20, v51
	v_cvt_f32_f16_sdwa v21, v51 dst_sel:DWORD dst_unused:UNUSED_PAD src0_sel:WORD_1
	v_cvt_f32_f16_e32 v22, v52
	v_cvt_f32_f16_sdwa v23, v52 dst_sel:DWORD dst_unused:UNUSED_PAD src0_sel:WORD_1
	v_cvt_f32_f16_e32 v24, v53
	v_cvt_f32_f16_sdwa v25, v53 dst_sel:DWORD dst_unused:UNUSED_PAD src0_sel:WORD_1
	v_pk_mul_f32 v[18:19], v[18:19], s[30:31] op_sel_hi:[1,0]
	v_pk_mul_f32 v[20:21], v[20:21], s[30:31] op_sel_hi:[1,0]
	v_pk_mul_f32 v[22:23], v[22:23], s[30:31] op_sel_hi:[1,0]
	v_pk_mul_f32 v[24:25], v[24:25], s[30:31] op_sel_hi:[1,0]
	v_pk_fma_f32 v[18:19], v[34:35], v[10:11], v[18:19]
	v_pk_fma_f32 v[20:21], v[36:37], v[12:13], v[20:21]
	v_pk_fma_f32 v[22:23], v[38:39], v[14:15], v[22:23]
	v_pk_fma_f32 v[24:25], v[40:41], v[16:17], v[24:25]
	v_cvt_pk_f16_f32 v50, v18, v19
	v_cvt_pk_f16_f32 v51, v20, v21
	v_cvt_pk_f16_f32 v52, v22, v23
	v_cvt_pk_f16_f32 v53, v24, v25
	global_store_dwordx4 v0, v[50:53], s[46:47]
	s_xor_b64 exec, exec, s[100:101]
	v_cvt_f32_f16_e32 v18, v50
	v_cvt_f32_f16_sdwa v19, v50 dst_sel:DWORD dst_unused:UNUSED_PAD src0_sel:WORD_1
	v_cvt_f32_f16_e32 v20, v51
	v_cvt_f32_f16_sdwa v21, v51 dst_sel:DWORD dst_unused:UNUSED_PAD src0_sel:WORD_1
	v_cvt_f32_f16_e32 v22, v52
	v_cvt_f32_f16_sdwa v23, v52 dst_sel:DWORD dst_unused:UNUSED_PAD src0_sel:WORD_1
	v_cvt_f32_f16_e32 v24, v53
	v_cvt_f32_f16_sdwa v25, v53 dst_sel:DWORD dst_unused:UNUSED_PAD src0_sel:WORD_1
	v_pk_mul_f32 v[18:19], v[18:19], s[30:31] op_sel_hi:[1,0]
	v_pk_mul_f32 v[20:21], v[20:21], s[30:31] op_sel_hi:[1,0]
	v_pk_mul_f32 v[22:23], v[22:23], s[30:31] op_sel_hi:[1,0]
	v_pk_mul_f32 v[24:25], v[24:25], s[30:31] op_sel_hi:[1,0]
	v_pk_fma_f32 v[18:19], v[42:43], v[10:11], v[18:19]
	v_pk_fma_f32 v[20:21], v[44:45], v[12:13], v[20:21]
	v_pk_fma_f32 v[22:23], v[46:47], v[14:15], v[22:23]
	v_pk_fma_f32 v[24:25], v[48:49], v[16:17], v[24:25]
	v_cvt_pk_f16_f32 v50, v18, v19
	v_cvt_pk_f16_f32 v51, v20, v21
	v_cvt_pk_f16_f32 v52, v22, v23
	v_cvt_pk_f16_f32 v53, v24, v25
	global_store_dwordx4 v0, v[50:53], s[46:47]
	s_mov_b64 exec, s[100:101]
	s_waitcnt vmcnt(11) lgkmcnt(1)
	v_lshlrev_b32_e32 v10, 16, v6
	v_and_b32_e32 v11, 0xffff0000, v6
	v_lshlrev_b32_e32 v12, 16, v7
	v_and_b32_e32 v13, 0xffff0000, v7
	v_lshlrev_b32_e32 v14, 16, v8
	v_and_b32_e32 v15, 0xffff0000, v8
	v_lshlrev_b32_e32 v16, 16, v9
	v_and_b32_e32 v17, 0xffff0000, v9
	ds_read_b128 v[6:9], v243 offset:3456
	v_add_u32_e32 v0, 0x24000, v239
	v_add_u32_e32 v26, 72, v241
	v_min_i32_e32 v26, 0x8000, v26
	v_ashrrev_i32_e32 v26, 11, v26
	v_cmp_eq_u32_e32 vcc, v26, v248
	s_and_saveexec_b64 s[100:101], vcc
	v_cvt_f32_f16_e32 v18, v54
	v_cvt_f32_f16_sdwa v19, v54 dst_sel:DWORD dst_unused:UNUSED_PAD src0_sel:WORD_1
	v_cvt_f32_f16_e32 v20, v55
	v_cvt_f32_f16_sdwa v21, v55 dst_sel:DWORD dst_unused:UNUSED_PAD src0_sel:WORD_1
	v_cvt_f32_f16_e32 v22, v56
	v_cvt_f32_f16_sdwa v23, v56 dst_sel:DWORD dst_unused:UNUSED_PAD src0_sel:WORD_1
	v_cvt_f32_f16_e32 v24, v57
	v_cvt_f32_f16_sdwa v25, v57 dst_sel:DWORD dst_unused:UNUSED_PAD src0_sel:WORD_1
	v_pk_mul_f32 v[18:19], v[18:19], s[30:31] op_sel_hi:[1,0]
	v_pk_mul_f32 v[20:21], v[20:21], s[30:31] op_sel_hi:[1,0]
	v_pk_mul_f32 v[22:23], v[22:23], s[30:31] op_sel_hi:[1,0]
	v_pk_mul_f32 v[24:25], v[24:25], s[30:31] op_sel_hi:[1,0]
	v_pk_fma_f32 v[18:19], v[34:35], v[10:11], v[18:19]
	v_pk_fma_f32 v[20:21], v[36:37], v[12:13], v[20:21]
	v_pk_fma_f32 v[22:23], v[38:39], v[14:15], v[22:23]
	v_pk_fma_f32 v[24:25], v[40:41], v[16:17], v[24:25]
	v_cvt_pk_f16_f32 v54, v18, v19
	v_cvt_pk_f16_f32 v55, v20, v21
	v_cvt_pk_f16_f32 v56, v22, v23
	v_cvt_pk_f16_f32 v57, v24, v25
	global_store_dwordx4 v0, v[54:57], s[46:47]
	s_xor_b64 exec, exec, s[100:101]
	v_cvt_f32_f16_e32 v18, v54
	v_cvt_f32_f16_sdwa v19, v54 dst_sel:DWORD dst_unused:UNUSED_PAD src0_sel:WORD_1
	v_cvt_f32_f16_e32 v20, v55
	v_cvt_f32_f16_sdwa v21, v55 dst_sel:DWORD dst_unused:UNUSED_PAD src0_sel:WORD_1
	v_cvt_f32_f16_e32 v22, v56
	v_cvt_f32_f16_sdwa v23, v56 dst_sel:DWORD dst_unused:UNUSED_PAD src0_sel:WORD_1
	v_cvt_f32_f16_e32 v24, v57
	v_cvt_f32_f16_sdwa v25, v57 dst_sel:DWORD dst_unused:UNUSED_PAD src0_sel:WORD_1
	v_pk_mul_f32 v[18:19], v[18:19], s[30:31] op_sel_hi:[1,0]
	v_pk_mul_f32 v[20:21], v[20:21], s[30:31] op_sel_hi:[1,0]
	v_pk_mul_f32 v[22:23], v[22:23], s[30:31] op_sel_hi:[1,0]
	v_pk_mul_f32 v[24:25], v[24:25], s[30:31] op_sel_hi:[1,0]
	v_pk_fma_f32 v[18:19], v[42:43], v[10:11], v[18:19]
	v_pk_fma_f32 v[20:21], v[44:45], v[12:13], v[20:21]
	v_pk_fma_f32 v[22:23], v[46:47], v[14:15], v[22:23]
	v_pk_fma_f32 v[24:25], v[48:49], v[16:17], v[24:25]
	v_cvt_pk_f16_f32 v54, v18, v19
	v_cvt_pk_f16_f32 v55, v20, v21
	v_cvt_pk_f16_f32 v56, v22, v23
	v_cvt_pk_f16_f32 v57, v24, v25
	global_store_dwordx4 v0, v[54:57], s[46:47]
	s_mov_b64 exec, s[100:101]
	s_waitcnt vmcnt(11) lgkmcnt(1)
;   DI void operator()(f32x16 (&acc)[2][MB], int wm, int wn, int r, int h) {
;     ...
;         for (int j = 0; j < 8; ++j) {
;           const int rowl = (lane >> 3) + 8 * j, ch = lane & 7;
;           if (rowl < ntok) {
;             const u32x4 yv = *(const u32x4*)(slab + rowl * 72 + ch * 8);
;             const int R = R0 + rowl;
;             const int mi = (R < NLAT) ? (R >> 11) : 16;
;             const int col = n0 + wn * 64 + ch * 8;
;             const float* g = gate + (size_t)mi * 6144 + col;
;             const f32x4n g0 = *(const f32x4n*)(g), g1 = *(const f32x4n*)(g + 4);
;             _Float16* xp = X + (size_t)R * 1024 + col;
;             const h8 xv = *(const h8*)xp;
;             const float y[8] = {__uint_as_float(yv.x << 16), __uint_as_float(yv.x & 0xffff0000u), __uint_as_float(yv.y << 16), __uint_as_float(yv.y & 0xffff0000u),
;                                 __uint_as_float(yv.z << 16), __uint_as_float(yv.z & 0xffff0000u), __uint_as_float(yv.w << 16), __uint_as_float(yv.w & 0xffff0000u)};
;             const float gg[8] = {g0.x, g0.y, g0.z, g0.w, g1.x, g1.y, g1.z, g1.w};
;             h8 o;
; #pragma unroll
;             for (int q = 0; q < 8; ++q) o[q] = (_Float16)(ALPHA * (float)xv[q] + gg[q] * y[q]);
;             *(h8*)xp = o;
;           }
;         }
;       }
;     }
;     __syncthreads();
	v_lshlrev_b32_e32 v10, 16, v2
	v_and_b32_e32 v11, 0xffff0000, v2
	v_lshlrev_b32_e32 v12, 16, v3
	v_and_b32_e32 v13, 0xffff0000, v3
	v_lshlrev_b32_e32 v14, 16, v4
	v_and_b32_e32 v15, 0xffff0000, v4
	v_lshlrev_b32_e32 v16, 16, v5
	v_and_b32_e32 v17, 0xffff0000, v5
	v_add_u32_e32 v0, 0x28000, v239
	v_add_u32_e32 v26, 80, v241
	v_min_i32_e32 v26, 0x8000, v26
	v_ashrrev_i32_e32 v26, 11, v26
	v_cmp_eq_u32_e32 vcc, v26, v248
	s_and_saveexec_b64 s[100:101], vcc
	v_cvt_f32_f16_e32 v18, v58
	v_cvt_f32_f16_sdwa v19, v58 dst_sel:DWORD dst_unused:UNUSED_PAD src0_sel:WORD_1
	v_cvt_f32_f16_e32 v20, v59
	v_cvt_f32_f16_sdwa v21, v59 dst_sel:DWORD dst_unused:UNUSED_PAD src0_sel:WORD_1
	v_cvt_f32_f16_e32 v22, v60
	v_cvt_f32_f16_sdwa v23, v60 dst_sel:DWORD dst_unused:UNUSED_PAD src0_sel:WORD_1
	v_cvt_f32_f16_e32 v24, v61
	v_cvt_f32_f16_sdwa v25, v61 dst_sel:DWORD dst_unused:UNUSED_PAD src0_sel:WORD_1
	v_pk_mul_f32 v[18:19], v[18:19], s[30:31] op_sel_hi:[1,0]
	v_pk_mul_f32 v[20:21], v[20:21], s[30:31] op_sel_hi:[1,0]
	v_pk_mul_f32 v[22:23], v[22:23], s[30:31] op_sel_hi:[1,0]
	v_pk_mul_f32 v[24:25], v[24:25], s[30:31] op_sel_hi:[1,0]
	v_pk_fma_f32 v[18:19], v[34:35], v[10:11], v[18:19]
	v_pk_fma_f32 v[20:21], v[36:37], v[12:13], v[20:21]
	v_pk_fma_f32 v[22:23], v[38:39], v[14:15], v[22:23]
	v_pk_fma_f32 v[24:25], v[40:41], v[16:17], v[24:25]
	v_cvt_pk_f16_f32 v58, v18, v19
	v_cvt_pk_f16_f32 v59, v20, v21
	v_cvt_pk_f16_f32 v60, v22, v23
	v_cvt_pk_f16_f32 v61, v24, v25
	global_store_dwordx4 v0, v[58:61], s[46:47]
	s_xor_b64 exec, exec, s[100:101]
	v_cvt_f32_f16_e32 v18, v58
	v_cvt_f32_f16_sdwa v19, v58 dst_sel:DWORD dst_unused:UNUSED_PAD src0_sel:WORD_1
	v_cvt_f32_f16_e32 v20, v59
	v_cvt_f32_f16_sdwa v21, v59 dst_sel:DWORD dst_unused:UNUSED_PAD src0_sel:WORD_1
	v_cvt_f32_f16_e32 v22, v60
	v_cvt_f32_f16_sdwa v23, v60 dst_sel:DWORD dst_unused:UNUSED_PAD src0_sel:WORD_1
	v_cvt_f32_f16_e32 v24, v61
	v_cvt_f32_f16_sdwa v25, v61 dst_sel:DWORD dst_unused:UNUSED_PAD src0_sel:WORD_1
	v_pk_mul_f32 v[18:19], v[18:19], s[30:31] op_sel_hi:[1,0]
	v_pk_mul_f32 v[20:21], v[20:21], s[30:31] op_sel_hi:[1,0]
	v_pk_mul_f32 v[22:23], v[22:23], s[30:31] op_sel_hi:[1,0]
	v_pk_mul_f32 v[24:25], v[24:25], s[30:31] op_sel_hi:[1,0]
	v_pk_fma_f32 v[18:19], v[42:43], v[10:11], v[18:19]
	v_pk_fma_f32 v[20:21], v[44:45], v[12:13], v[20:21]
	v_pk_fma_f32 v[22:23], v[46:47], v[14:15], v[22:23]
	v_pk_fma_f32 v[24:25], v[48:49], v[16:17], v[24:25]
	v_cvt_pk_f16_f32 v58, v18, v19
	v_cvt_pk_f16_f32 v59, v20, v21
	v_cvt_pk_f16_f32 v60, v22, v23
	v_cvt_pk_f16_f32 v61, v24, v25
	global_store_dwordx4 v0, v[58:61], s[46:47]
	s_mov_b64 exec, s[100:101]
	s_waitcnt vmcnt(11) lgkmcnt(0)
	v_lshlrev_b32_e32 v10, 16, v6
	v_and_b32_e32 v11, 0xffff0000, v6
	v_lshlrev_b32_e32 v12, 16, v7
	v_and_b32_e32 v13, 0xffff0000, v7
	v_lshlrev_b32_e32 v14, 16, v8
	v_and_b32_e32 v15, 0xffff0000, v8
	v_lshlrev_b32_e32 v16, 16, v9
	v_and_b32_e32 v17, 0xffff0000, v9
	v_add_u32_e32 v0, 0x2c000, v239
	v_add_u32_e32 v26, 88, v241
	v_min_i32_e32 v26, 0x8000, v26
	v_ashrrev_i32_e32 v26, 11, v26
	v_cmp_eq_u32_e32 vcc, v26, v248
	s_and_saveexec_b64 s[100:101], vcc
	v_cvt_f32_f16_e32 v18, v62
	v_cvt_f32_f16_sdwa v19, v62 dst_sel:DWORD dst_unused:UNUSED_PAD src0_sel:WORD_1
	v_cvt_f32_f16_e32 v20, v63
	v_cvt_f32_f16_sdwa v21, v63 dst_sel:DWORD dst_unused:UNUSED_PAD src0_sel:WORD_1
	v_cvt_f32_f16_e32 v22, v64
	v_cvt_f32_f16_sdwa v23, v64 dst_sel:DWORD dst_unused:UNUSED_PAD src0_sel:WORD_1
	v_cvt_f32_f16_e32 v24, v65
	v_cvt_f32_f16_sdwa v25, v65 dst_sel:DWORD dst_unused:UNUSED_PAD src0_sel:WORD_1
	v_pk_mul_f32 v[18:19], v[18:19], s[30:31] op_sel_hi:[1,0]
	v_pk_mul_f32 v[20:21], v[20:21], s[30:31] op_sel_hi:[1,0]
	v_pk_mul_f32 v[22:23], v[22:23], s[30:31] op_sel_hi:[1,0]
	v_pk_mul_f32 v[24:25], v[24:25], s[30:31] op_sel_hi:[1,0]
	v_pk_fma_f32 v[18:19], v[34:35], v[10:11], v[18:19]
	v_pk_fma_f32 v[20:21], v[36:37], v[12:13], v[20:21]
	v_pk_fma_f32 v[22:23], v[38:39], v[14:15], v[22:23]
	v_pk_fma_f32 v[24:25], v[40:41], v[16:17], v[24:25]
	v_cvt_pk_f16_f32 v62, v18, v19
	v_cvt_pk_f16_f32 v63, v20, v21
	v_cvt_pk_f16_f32 v64, v22, v23
	v_cvt_pk_f16_f32 v65, v24, v25
	global_store_dwordx4 v0, v[62:65], s[46:47]
	s_xor_b64 exec, exec, s[100:101]
	v_cvt_f32_f16_e32 v18, v62
	v_cvt_f32_f16_sdwa v19, v62 dst_sel:DWORD dst_unused:UNUSED_PAD src0_sel:WORD_1
	v_cvt_f32_f16_e32 v20, v63
	v_cvt_f32_f16_sdwa v21, v63 dst_sel:DWORD dst_unused:UNUSED_PAD src0_sel:WORD_1
	v_cvt_f32_f16_e32 v22, v64
	v_cvt_f32_f16_sdwa v23, v64 dst_sel:DWORD dst_unused:UNUSED_PAD src0_sel:WORD_1
	v_cvt_f32_f16_e32 v24, v65
	v_cvt_f32_f16_sdwa v25, v65 dst_sel:DWORD dst_unused:UNUSED_PAD src0_sel:WORD_1
	v_pk_mul_f32 v[18:19], v[18:19], s[30:31] op_sel_hi:[1,0]
	v_pk_mul_f32 v[20:21], v[20:21], s[30:31] op_sel_hi:[1,0]
	v_pk_mul_f32 v[22:23], v[22:23], s[30:31] op_sel_hi:[1,0]
	v_pk_mul_f32 v[24:25], v[24:25], s[30:31] op_sel_hi:[1,0]
	v_pk_fma_f32 v[18:19], v[42:43], v[10:11], v[18:19]
	v_pk_fma_f32 v[20:21], v[44:45], v[12:13], v[20:21]
	v_pk_fma_f32 v[22:23], v[46:47], v[14:15], v[22:23]
	v_pk_fma_f32 v[24:25], v[48:49], v[16:17], v[24:25]
	v_cvt_pk_f16_f32 v62, v18, v19
	v_cvt_pk_f16_f32 v63, v20, v21
	v_cvt_pk_f16_f32 v64, v22, v23
	v_cvt_pk_f16_f32 v65, v24, v25
	global_store_dwordx4 v0, v[62:65], s[46:47]
	s_mov_b64 exec, s[100:101]
.Lres0_end:
	s_waitcnt lgkmcnt(0)
	s_barrier
	s_branch .LBB0_646

; template <int MB, class Epi>
; DI void gemm_tile(const u16* __restrict__ A, int lda, int row0, int Mrows, const u16* __restrict__ Bt, int ldb, int K, char* smem, Epi& epi, int rot) {
;     ...
;   for (int kt = 0; kt < KT; ++kt) {
;     const bool more = (kt + 1 < KT);
;     const bool more2 = (kt + 2 < KT);
;     const int nstg = (kt + 1) & 1;
;     const char* as = As + (kt & 1) * 32768 + wm * (32 * MB) * 128;
;     const char* bs = Bs + (kt & 1) * 32768 + wn * 64 * 128;
;     int k1_ = kbase + kt + 1; if (k1_ >= KT) k1_ -= KT;
;     int k2_ = kbase + kt + 2; if (k2_ >= KT) k2_ -= KT; if (k2_ >= KT) k2_ -= KT;
; #pragma unroll
;     for (int ks = 0; ks < 3; ++ks) {
; #pragma unroll
;       for (int idx = 0; idx < 2 * MB; ++idx) {
;         const int nb = idx / MB, mb = idx % MB;
;         acc[nb][mb] = mfma32(bfr[ks & 1][nb], af[ks & 1][mb], acc[nb][mb]);
;         if (idx < MB) af[(ks + 1) & 1][idx] = *(const bf8*)(as + idx * 32 * 128 + foff[ks + 1]);
;         else if (idx < MB + 2) bfr[(ks + 1) & 1][idx - MB] = *(const bf8*)(bs + (idx - MB) * 32 * 128 + foff[ks + 1]);
;         if (more && ks < 2 && idx < 3) {
;           const int ko_ = k1_ * 64;
;           GEMM_PIECE(nstg, 3 + ks * 3 + idx)
;         }
;         __builtin_amdgcn_sched_barrier(0);
;       }
;     }
;     if (more) {
;       asm volatile("s_waitcnt vmcnt(0)" ::: "memory");
;       __syncthreads();
;       if (more2) {
;         const int ko_ = k2_ * 64;
; #pragma unroll
;         for (int pc = 0; pc < 3; ++pc) GEMM_PIECE(kt & 1, pc)
;       }
;       __builtin_amdgcn_sched_barrier(0);
;       const char* asn = As + nstg * 32768 + wm * (32 * MB) * 128;
;       const char* bsn = Bs + nstg * 32768 + wn * 64 * 128;
; #pragma unroll
;       for (int mb = 0; mb < MB; ++mb) af[0][mb] = *(const bf8*)(asn + mb * 32 * 128 + foff[0]);
; #pragma unroll
;       for (int nb = 0; nb < 2; ++nb) bfr[0][nb] = *(const bf8*)(bsn + nb * 32 * 128 + foff[0]);
;     }
; #pragma unroll
;     for (int nb = 0; nb < 2; ++nb)
; #pragma unroll
;       for (int mb = 0; mb < MB; ++mb) acc[nb][mb] = mfma32(bfr[1][nb], af[1][mb], acc[nb][mb]);
; #pragma unroll
;     for (int gk = 0; gk < 2 * MB; ++gk) {
;       __builtin_amdgcn_sched_group_barrier(0x008, 1, 0);
;       __builtin_amdgcn_sched_group_barrier(0x100, 1, 0);
;     }
;     __builtin_amdgcn_sched_barrier(0);
;   }
.LBB0_658:
	s_and_b32 s16, s11, 0x8000
	s_add_i32 s18, s17, 1
	s_add_i32 s23, s10, s16
	s_add_i32 s22, s9, s16
	s_add_i32 s19, s13, s17
	s_cmp_lt_i32 s19, 15
	s_cselect_b32 s17, 0, -16
	s_add_i32 s17, s19, s17
	s_waitcnt lgkmcnt(1)
	v_mfma_f32_32x32x16_bf16 v[114:129], v[150:153], v[146:149], v[114:129]
	s_lshl_b32 s17, s17, 6
	s_add_i32 s26, s17, 64
	s_ashr_i32 s27, s26, 31
	s_add_i32 s11, s11, 0x8000
	v_add_u32_e32 v188, s23, v171
	s_lshl_b64 s[26:27], s[26:27], 1
	s_and_b32 s17, s11, 0x8000
	ds_read_b128 v[172:175], v188
	s_add_i32 s28, s17, s15
	v_lshl_add_u64 v[176:177], v[160:161], 0, s[26:27]
	s_mov_b32 m0, s28
	s_nop 0
	global_load_lds_dwordx4 v[176:177], off
	v_lshl_add_u64 v[184:185], v[158:159], 0, s[26:27]
	s_add_i32 s25, s17, s12
	v_mfma_f32_32x32x16_bf16 v[66:81], v[150:153], v[142:145], v[66:81]
	ds_read_b128 v[176:179], v188 offset:4096
	s_mov_b32 m0, s25
	s_nop 0
	global_load_lds_dwordx4 v[184:185], off
	v_mfma_f32_32x32x16_bf16 v[18:33], v[150:153], v[134:137], v[18:33]
	ds_read_b128 v[180:183], v188 offset:8192
	s_add_i32 s26, s25, 0x2000
	v_lshl_add_u64 v[186:187], v[184:185], 0, s[4:5]
	s_mov_b32 m0, s26
	s_nop 0
	global_load_lds_dwordx4 v[186:187], off
	v_mfma_f32_32x32x16_bf16 v[2:17], v[150:153], v[130:133], v[2:17]
	ds_read_b128 v[150:153], v188 offset:12288
	s_waitcnt lgkmcnt(4)
	v_mfma_f32_32x32x16_bf16 v[98:113], v[138:141], v[146:149], v[98:113]
	v_add_u32_e32 v186, s22, v171
	ds_read_b128 v[146:149], v186
	v_mfma_f32_32x32x16_bf16 v[82:97], v[138:141], v[142:145], v[82:97]
	ds_read_b128 v[142:145], v186 offset:4096
	v_mfma_f32_32x32x16_bf16 v[50:65], v[138:141], v[134:137], v[50:65]
	v_mfma_f32_32x32x16_bf16 v[34:49], v[138:141], v[130:133], v[34:49]
	s_waitcnt lgkmcnt(1)
	v_mfma_f32_32x32x16_bf16 v[114:129], v[146:149], v[172:175], v[114:129]
	v_add_u32_e32 v186, s23, v170
	ds_read_b128 v[130:133], v186
	s_add_i32 s26, s25, 0x4000
	v_lshl_add_u64 v[134:135], v[184:185], 0, s[6:7]
	s_mov_b32 m0, s26
	s_nop 0
	global_load_lds_dwordx4 v[134:135], off
	v_mfma_f32_32x32x16_bf16 v[66:81], v[146:149], v[176:179], v[66:81]
	ds_read_b128 v[134:137], v186 offset:4096
	s_addk_i32 s25, 0x6000
	v_lshl_add_u64 v[138:139], v[184:185], 0, s[34:35]
	s_mov_b32 m0, s25
	s_nop 0
	global_load_lds_dwordx4 v[138:139], off
	v_mfma_f32_32x32x16_bf16 v[18:33], v[146:149], v[180:183], v[18:33]
	ds_read_b128 v[138:141], v186 offset:8192
	v_mfma_f32_32x32x16_bf16 v[2:17], v[146:149], v[150:153], v[2:17]
	ds_read_b128 v[146:149], v186 offset:12288
	s_waitcnt lgkmcnt(4)
	v_mfma_f32_32x32x16_bf16 v[98:113], v[142:145], v[172:175], v[98:113]
	v_add_u32_e32 v184, s22, v170
	ds_read_b128 v[172:175], v184
	v_mfma_f32_32x32x16_bf16 v[82:97], v[142:145], v[176:179], v[82:97]
	ds_read_b128 v[176:179], v184 offset:4096
	v_mfma_f32_32x32x16_bf16 v[50:65], v[142:145], v[180:183], v[50:65]
	v_mfma_f32_32x32x16_bf16 v[34:49], v[142:145], v[150:153], v[34:49]
	s_waitcnt lgkmcnt(1)
	v_mfma_f32_32x32x16_bf16 v[114:129], v[172:175], v[130:133], v[114:129]
	v_add_u32_e32 v142, s23, v169
	ds_read_b128 v[150:153], v142
	v_mfma_f32_32x32x16_bf16 v[66:81], v[172:175], v[134:137], v[66:81]
	ds_read_b128 v[180:183], v142 offset:4096
	v_mfma_f32_32x32x16_bf16 v[18:33], v[172:175], v[138:141], v[18:33]
	ds_read_b128 v[184:187], v142 offset:8192
	v_mfma_f32_32x32x16_bf16 v[2:17], v[172:175], v[146:149], v[2:17]
	ds_read_b128 v[172:175], v142 offset:12288
	s_waitcnt lgkmcnt(4)
	v_mfma_f32_32x32x16_bf16 v[98:113], v[176:179], v[130:133], v[98:113]
	v_add_u32_e32 v142, s22, v169
	ds_read_b128 v[130:133], v142
	v_mfma_f32_32x32x16_bf16 v[82:97], v[176:179], v[134:137], v[82:97]
	ds_read_b128 v[188:191], v142 offset:4096
	v_mfma_f32_32x32x16_bf16 v[50:65], v[176:179], v[138:141], v[50:65]
	v_mfma_f32_32x32x16_bf16 v[34:49], v[176:179], v[146:149], v[34:49]
	s_cmp_lt_i32 s19, 14
	s_cselect_b32 s22, 0, -16
	s_add_i32 s23, s19, s22
	s_add_i32 s23, s23, 2
	s_cmp_lt_i32 s23, 16
	s_cselect_b32 s23, 0, -16
	s_add_i32 s22, s22, s23
	s_add_i32 s19, s19, s22
	s_lshl_b32 s19, s19, 6
	s_add_i32 s22, s19, 0x80
	s_ashr_i32 s23, s22, 31
	s_lshl_b64 s[22:23], s[22:23], 1
	s_add_u32 s22, s20, s22
	s_addc_u32 s23, s21, s23
	s_waitcnt vmcnt(0)
	s_waitcnt lgkmcnt(0)
	s_barrier
	s_add_i32 s19, s16, s14
	v_lshl_add_u64 v[134:135], s[22:23], 0, v[0:1]
	s_mov_b32 m0, s19
	s_nop 0
	global_load_lds_dwordx4 v[134:135], off
	v_lshl_add_u64 v[134:135], v[154:155], 1, s[22:23]
	s_add_i32 s25, s19, 0x2000
	s_mov_b32 m0, s25
	s_nop 0
	global_load_lds_dwordx4 v[134:135], off
	v_lshl_add_u64 v[134:135], v[156:157], 1, s[22:23]
	s_addk_i32 s19, 0x4000
	s_mov_b32 m0, s19
	s_nop 0
	global_load_lds_dwordx4 v[134:135], off
	v_add_u32_e32 v138, s17, v168
	v_mfma_f32_32x32x16_bf16 v[114:129], v[130:133], v[150:153], v[114:129]
	ds_read_b128 v[146:149], v138
	v_mfma_f32_32x32x16_bf16 v[66:81], v[130:133], v[180:183], v[66:81]
	ds_read_b128 v[142:145], v138 offset:4096
	v_mfma_f32_32x32x16_bf16 v[18:33], v[130:133], v[184:187], v[18:33]
	ds_read_b128 v[134:137], v138 offset:8192
	v_mfma_f32_32x32x16_bf16 v[2:17], v[130:133], v[172:175], v[2:17]
	ds_read_b128 v[130:133], v138 offset:12288
	v_add_u32_e32 v138, s17, v167
	v_mfma_f32_32x32x16_bf16 v[98:113], v[188:191], v[150:153], v[98:113]
	ds_read_b128 v[150:153], v138
	v_mfma_f32_32x32x16_bf16 v[82:97], v[188:191], v[180:183], v[82:97]
	ds_read_b128 v[138:141], v138 offset:4096
	v_mfma_f32_32x32x16_bf16 v[50:65], v[188:191], v[184:187], v[50:65]
	v_mfma_f32_32x32x16_bf16 v[34:49], v[188:191], v[172:175], v[34:49]
	s_cmp_lg_u32 s18, 14
	s_mov_b32 s17, s18
	s_cbranch_scc1 .LBB0_658
; template <int MB, class Epi>
; DI void gemm_tile(const u16* __restrict__ A, int lda, int row0, int Mrows, const u16* __restrict__ Bt, int ldb, int K, char* smem, Epi& epi, int rot) {
;     ...
;   for (int kt = 0; kt < KT; ++kt) {
;     const bool more = (kt + 1 < KT);
;     const bool more2 = (kt + 2 < KT);
;     const int nstg = (kt + 1) & 1;
;     const char* as = As + (kt & 1) * 32768 + wm * (32 * MB) * 128;
;     const char* bs = Bs + (kt & 1) * 32768 + wn * 64 * 128;
;     int k1_ = kbase + kt + 1; if (k1_ >= KT) k1_ -= KT;
;     int k2_ = kbase + kt + 2; if (k2_ >= KT) k2_ -= KT; if (k2_ >= KT) k2_ -= KT;
; #pragma unroll
;     for (int ks = 0; ks < 3; ++ks) {
; #pragma unroll
;       for (int idx = 0; idx < 2 * MB; ++idx) {
;         const int nb = idx / MB, mb = idx % MB;
;         acc[nb][mb] = mfma32(bfr[ks & 1][nb], af[ks & 1][mb], acc[nb][mb]);
;         if (idx < MB) af[(ks + 1) & 1][idx] = *(const bf8*)(as + idx * 32 * 128 + foff[ks + 1]);
;         else if (idx < MB + 2) bfr[(ks + 1) & 1][idx - MB] = *(const bf8*)(bs + (idx - MB) * 32 * 128 + foff[ks + 1]);
;         if (more && ks < 2 && idx < 3) {
;           const int ko_ = k1_ * 64;
;           GEMM_PIECE(nstg, 3 + ks * 3 + idx)
;         }
;         __builtin_amdgcn_sched_barrier(0);
;       }
;     }
;     if (more) {
;       asm volatile("s_waitcnt vmcnt(0)" ::: "memory");
;       __syncthreads();
;       if (more2) {
;         const int ko_ = k2_ * 64;
; #pragma unroll
;         for (int pc = 0; pc < 3; ++pc) GEMM_PIECE(kt & 1, pc)
;       }
;       __builtin_amdgcn_sched_barrier(0);
;       const char* asn = As + nstg * 32768 + wm * (32 * MB) * 128;
;       const char* bsn = Bs + nstg * 32768 + wn * 64 * 128;
; #pragma unroll
;       for (int mb = 0; mb < MB; ++mb) af[0][mb] = *(const bf8*)(asn + mb * 32 * 128 + foff[0]);
; #pragma unroll
;       for (int nb = 0; nb < 2; ++nb) bfr[0][nb] = *(const bf8*)(bsn + nb * 32 * 128 + foff[0]);
;     }
; #pragma unroll
;     for (int nb = 0; nb < 2; ++nb)
; #pragma unroll
;       for (int mb = 0; mb < MB; ++mb) acc[nb][mb] = mfma32(bfr[1][nb], af[1][mb], acc[nb][mb]);
; #pragma unroll
;     for (int gk = 0; gk < 2 * MB; ++gk) {
;       __builtin_amdgcn_sched_group_barrier(0x008, 1, 0);
;       __builtin_amdgcn_sched_group_barrier(0x100, 1, 0);
;     }
;     __builtin_amdgcn_sched_barrier(0);
;   }
	s_add_i32 s11, s13, 14
	s_cmp_lt_i32 s11, 15
	s_cselect_b32 s13, 0, -16
	s_add_i32 s11, s11, s13
	s_lshl_b32 s11, s11, 6
	s_add_i32 s18, s11, 64
	s_ashr_i32 s19, s18, 31
	v_add_u32_e32 v0, s10, v171
	s_lshl_b64 s[18:19], s[18:19], 1
	ds_read_b128 v[154:157], v0
	v_lshl_add_u64 v[176:177], v[158:159], 0, s[18:19]
	s_add_i32 s11, s16, s12
	s_add_i32 s12, s16, s15
	v_lshl_add_u64 v[158:159], v[160:161], 0, s[18:19]
	s_mov_b32 m0, s12
	s_nop 0
	global_load_lds_dwordx4 v[158:159], off
	s_waitcnt lgkmcnt(2)
	v_mfma_f32_32x32x16_bf16 v[114:129], v[150:153], v[146:149], v[114:129]
	ds_read_b128 v[158:161], v0 offset:4096
	s_mov_b32 m0, s11
	s_nop 0
	global_load_lds_dwordx4 v[176:177], off
	v_mfma_f32_32x32x16_bf16 v[66:81], v[150:153], v[142:145], v[66:81]
	ds_read_b128 v[172:175], v0 offset:8192
	s_add_i32 s12, s11, 0x2000
	v_lshl_add_u64 v[178:179], v[176:177], 0, s[4:5]
	s_mov_b32 m0, s12
	s_nop 0
	global_load_lds_dwordx4 v[178:179], off
	v_mfma_f32_32x32x16_bf16 v[18:33], v[150:153], v[134:137], v[18:33]
	v_mfma_f32_32x32x16_bf16 v[2:17], v[150:153], v[130:133], v[2:17]
	ds_read_b128 v[150:153], v0 offset:12288
	v_add_u32_e32 v178, s9, v171
	s_waitcnt lgkmcnt(4)
	v_mfma_f32_32x32x16_bf16 v[98:113], v[138:141], v[146:149], v[98:113]
	ds_read_b128 v[146:149], v178
	v_mfma_f32_32x32x16_bf16 v[82:97], v[138:141], v[142:145], v[82:97]
	ds_read_b128 v[142:145], v178 offset:4096
	v_mfma_f32_32x32x16_bf16 v[50:65], v[138:141], v[134:137], v[50:65]
	v_mfma_f32_32x32x16_bf16 v[34:49], v[138:141], v[130:133], v[34:49]
	v_add_u32_e32 v179, s10, v170
	ds_read_b128 v[130:133], v179
	s_add_i32 s12, s11, 0x4000
	v_lshl_add_u64 v[134:135], v[176:177], 0, s[6:7]
	s_mov_b32 m0, s12
	s_nop 0
	global_load_lds_dwordx4 v[134:135], off
	s_waitcnt lgkmcnt(2)
	v_mfma_f32_32x32x16_bf16 v[114:129], v[146:149], v[154:157], v[114:129]
	ds_read_b128 v[134:137], v179 offset:4096
	s_addk_i32 s11, 0x6000
	v_lshl_add_u64 v[138:139], v[176:177], 0, s[34:35]
	s_mov_b32 m0, s11
	s_nop 0
	global_load_lds_dwordx4 v[138:139], off
	v_mfma_f32_32x32x16_bf16 v[66:81], v[146:149], v[158:161], v[66:81]
	ds_read_b128 v[138:141], v179 offset:8192
	v_mfma_f32_32x32x16_bf16 v[18:33], v[146:149], v[172:175], v[18:33]
	v_mfma_f32_32x32x16_bf16 v[2:17], v[146:149], v[150:153], v[2:17]
	ds_read_b128 v[146:149], v179 offset:12288
	v_add_u32_e32 v176, s9, v170
	s_waitcnt lgkmcnt(4)
	v_mfma_f32_32x32x16_bf16 v[98:113], v[142:145], v[154:157], v[98:113]
	ds_read_b128 v[154:157], v176
	v_mfma_f32_32x32x16_bf16 v[82:97], v[142:145], v[158:161], v[82:97]
	ds_read_b128 v[158:161], v176 offset:4096
	v_mfma_f32_32x32x16_bf16 v[50:65], v[142:145], v[172:175], v[50:65]
	v_mfma_f32_32x32x16_bf16 v[34:49], v[142:145], v[150:153], v[34:49]
	v_add_u32_e32 v174, s10, v169
	ds_read_b128 v[142:145], v174
	s_waitcnt lgkmcnt(2)
	v_mfma_f32_32x32x16_bf16 v[114:129], v[154:157], v[130:133], v[114:129]
	ds_read_b128 v[150:153], v174 offset:4096
	v_mfma_f32_32x32x16_bf16 v[66:81], v[154:157], v[134:137], v[66:81]
	ds_read_b128 v[170:173], v174 offset:8192
	v_mfma_f32_32x32x16_bf16 v[18:33], v[154:157], v[138:141], v[18:33]
	v_mfma_f32_32x32x16_bf16 v[2:17], v[154:157], v[146:149], v[2:17]
	ds_read_b128 v[154:157], v174 offset:12288
	v_add_u32_e32 v175, s9, v169
	s_waitcnt lgkmcnt(4)
	v_mfma_f32_32x32x16_bf16 v[98:113], v[158:161], v[130:133], v[98:113]
	ds_read_b128 v[130:133], v175
	v_mfma_f32_32x32x16_bf16 v[82:97], v[158:161], v[134:137], v[82:97]
	ds_read_b128 v[134:137], v175 offset:4096
	v_mfma_f32_32x32x16_bf16 v[50:65], v[158:161], v[138:141], v[50:65]
	v_mfma_f32_32x32x16_bf16 v[34:49], v[158:161], v[146:149], v[34:49]
	s_waitcnt vmcnt(0)
	s_waitcnt lgkmcnt(0)
	s_barrier
	s_lshr_b32 s100, s0, 5
	s_lshl_b32 s100, s100, 3
	s_and_b32 s101, s0, 7
	s_or_b32 s100, s100, s101
	s_mul_i32 s100, s100, 0x100
	s_lshr_b32 s101, s0, 3
	s_and_b32 s101, s101, 3
	s_lshl_b32 s101, s101, 9
	v_lshrrev_b32_e32 v237, 2, v163
	v_and_b32_e32 v238, 3, v163
	v_add_u32_e32 v237, s100, v237
	v_lshlrev_b32_e32 v237, 11, v237
	v_lshl_add_u32 v237, v238, 7, v237
	v_add_u32_e32 v237, s101, v237
	global_load_dword v255, v237, s[46:47]
	v_add_u32_e32 v237, 0x40000, v237
	global_load_dword v255, v237, s[46:47]
	v_add_u32_e32 v168, s16, v168
	v_add_u32_e32 v167, s16, v167
	v_mfma_f32_32x32x16_bf16 v[114:129], v[130:133], v[142:145], v[114:129]
	ds_read_b128 v[138:141], v168
	v_mfma_f32_32x32x16_bf16 v[66:81], v[130:133], v[150:153], v[66:81]
	ds_read_b128 v[146:149], v168 offset:4096
	v_mfma_f32_32x32x16_bf16 v[18:33], v[130:133], v[170:173], v[18:33]
	ds_read_b128 v[158:161], v168 offset:8192
	v_mfma_f32_32x32x16_bf16 v[2:17], v[130:133], v[154:157], v[2:17]
	ds_read_b128 v[130:133], v168 offset:12288
	v_mfma_f32_32x32x16_bf16 v[98:113], v[134:137], v[142:145], v[98:113]
	ds_read_b128 v[142:145], v167
	v_mfma_f32_32x32x16_bf16 v[82:97], v[134:137], v[150:153], v[82:97]
	ds_read_b128 v[150:153], v167 offset:4096
	v_mfma_f32_32x32x16_bf16 v[50:65], v[134:137], v[170:173], v[50:65]
	v_mfma_f32_32x32x16_bf16 v[34:49], v[134:137], v[154:157], v[34:49]
	ds_read_b128 v[134:137], v0 offset:32768
	s_waitcnt lgkmcnt(2)
	v_mfma_f32_32x32x16_bf16 v[114:129], v[142:145], v[138:141], v[114:129]
	ds_read_b128 v[154:157], v0 offset:36864
	v_mfma_f32_32x32x16_bf16 v[66:81], v[142:145], v[146:149], v[66:81]
	ds_read_b128 v[168:171], v0 offset:40960
	v_mfma_f32_32x32x16_bf16 v[18:33], v[142:145], v[158:161], v[18:33]
	v_mfma_f32_32x32x16_bf16 v[2:17], v[142:145], v[130:133], v[2:17]
	ds_read_b128 v[142:145], v0 offset:45056
	s_waitcnt lgkmcnt(4)
; DI unsigned pack2(float a, float b) { f2 v = {a, b}; bf2 r = __builtin_convertvector(v, bf2); return __builtin_bit_cast(unsigned, r); }
; template <int MB, class Epi>
; DI void gemm_tile(const u16* __restrict__ A, int lda, int row0, int Mrows, const u16* __restrict__ Bt, int ldb, int K, char* smem, Epi& epi, int rot) {
;     ...
; #pragma unroll
;     for (int nb = 0; nb < 2; ++nb)
; #pragma unroll
;       for (int mb = 0; mb < MB; ++mb) acc[nb][mb] = mfma32(bfr[1][nb], af[1][mb], acc[nb][mb]);
;   DI void operator()(f32x16 (&acc)[2][MB], int wm, int wn, int r, int h) {
;     u16* slab = ostage + (wm * 4 + wn) * (64 * 72);
;     const int lane = h * 32 + r;
; #pragma unroll
;     for (int mb = 0; mb < MB; ++mb) {
;       const int tokl = (mb & 1) * 32 + r;
; #pragma unroll
;       for (int nb = 0; nb < 2; ++nb)
; #pragma unroll
;         for (int ig = 0; ig < 4; ++ig) {
;           u32x2 o;
;           o.x = pack2(acc[nb][mb][ig * 4 + 0], acc[nb][mb][ig * 4 + 1]);
;           o.y = pack2(acc[nb][mb][ig * 4 + 2], acc[nb][mb][ig * 4 + 3]);
;           *(u32x2*)(slab + tokl * 72 + nb * 32 + ig * 8 + h * 4) = o;
;         }
;       if ((mb & 1) || mb == MB - 1) {
;         asm volatile("s_waitcnt lgkmcnt(0)" ::: "memory");
;         const int ntok = (mb & 1) ? 64 : 32;
;         const int R0 = row0 + wm * (32 * MB) + (mb >> 1) * 64;
; #pragma unroll
;         for (int j = 0; j < 8; ++j) {
;           const int rowl = (lane >> 3) + 8 * j, ch = lane & 7;
;           if (rowl < ntok) {
;             const u32x4 yv = *(const u32x4*)(slab + rowl * 72 + ch * 8);
;             const int R = R0 + rowl;
;             const int mi = (R < NLAT) ? (R >> 11) : 16;
;             const int col = n0 + wn * 64 + ch * 8;
;             const float* g = gate + (size_t)mi * 6144 + col;
;             const f32x4n g0 = *(const f32x4n*)(g), g1 = *(const f32x4n*)(g + 4);
;             _Float16* xp = X + (size_t)R * 1024 + col;
;             const h8 xv = *(const h8*)xp;
;             const float y[8] = {__uint_as_float(yv.x << 16), __uint_as_float(yv.x & 0xffff0000u), __uint_as_float(yv.y << 16), __uint_as_float(yv.y & 0xffff0000u),
;                                 __uint_as_float(yv.z << 16), __uint_as_float(yv.z & 0xffff0000u), __uint_as_float(yv.w << 16), __uint_as_float(yv.w & 0xffff0000u)};
	v_mfma_f32_32x32x16_bf16 v[98:113], v[150:153], v[138:141], v[98:113]
	ds_read_b128 v[138:141], v178 offset:32768
	v_mfma_f32_32x32x16_bf16 v[82:97], v[150:153], v[146:149], v[82:97]
	ds_read_b128 v[146:149], v178 offset:36864
	v_mfma_f32_32x32x16_bf16 v[50:65], v[150:153], v[158:161], v[50:65]
	v_mfma_f32_32x32x16_bf16 v[34:49], v[150:153], v[130:133], v[34:49]
	ds_read_b128 v[130:133], v179 offset:32768
	s_waitcnt lgkmcnt(2)
	v_mfma_f32_32x32x16_bf16 v[114:129], v[138:141], v[134:137], v[114:129]
	ds_read_b128 v[150:153], v179 offset:36864
	v_mfma_f32_32x32x16_bf16 v[66:81], v[138:141], v[154:157], v[66:81]
	ds_read_b128 v[158:161], v179 offset:40960
	v_mfma_f32_32x32x16_bf16 v[18:33], v[138:141], v[168:171], v[18:33]
	v_mfma_f32_32x32x16_bf16 v[2:17], v[138:141], v[142:145], v[2:17]
	ds_read_b128 v[138:141], v179 offset:45056
	s_waitcnt lgkmcnt(4)
	v_mfma_f32_32x32x16_bf16 v[98:113], v[146:149], v[134:137], v[98:113]
	ds_read_b128 v[134:137], v176 offset:32768
	v_mfma_f32_32x32x16_bf16 v[82:97], v[146:149], v[154:157], v[82:97]
	ds_read_b128 v[154:157], v176 offset:36864
	v_mfma_f32_32x32x16_bf16 v[50:65], v[146:149], v[168:171], v[50:65]
	v_mfma_f32_32x32x16_bf16 v[34:49], v[146:149], v[142:145], v[34:49]
	ds_read_b128 v[142:145], v174 offset:32768
	s_waitcnt lgkmcnt(2)
	v_mfma_f32_32x32x16_bf16 v[114:129], v[134:137], v[130:133], v[114:129]
	ds_read_b128 v[146:149], v174 offset:36864
	v_mfma_f32_32x32x16_bf16 v[66:81], v[134:137], v[150:153], v[66:81]
	ds_read_b128 v[168:171], v174 offset:40960
	v_mfma_f32_32x32x16_bf16 v[18:33], v[134:137], v[158:161], v[18:33]
	v_mfma_f32_32x32x16_bf16 v[2:17], v[134:137], v[138:141], v[2:17]
	ds_read_b128 v[134:137], v174 offset:45056
	s_waitcnt lgkmcnt(4)
	v_mfma_f32_32x32x16_bf16 v[98:113], v[154:157], v[130:133], v[98:113]
	ds_read_b128 v[130:133], v175 offset:32768
	v_mfma_f32_32x32x16_bf16 v[82:97], v[154:157], v[150:153], v[82:97]
	ds_read_b128 v[150:153], v175 offset:36864
	v_mfma_f32_32x32x16_bf16 v[50:65], v[154:157], v[158:161], v[50:65]
	v_mfma_f32_32x32x16_bf16 v[34:49], v[154:157], v[138:141], v[34:49]
	s_waitcnt lgkmcnt(1)
	v_mfma_f32_32x32x16_bf16 v[114:129], v[130:133], v[142:145], v[114:129]
	v_mfma_f32_32x32x16_bf16 v[66:81], v[130:133], v[146:149], v[66:81]
	v_mfma_f32_32x32x16_bf16 v[18:33], v[130:133], v[168:171], v[18:33]
	v_mfma_f32_32x32x16_bf16 v[2:17], v[130:133], v[134:137], v[2:17]
	s_waitcnt lgkmcnt(0)
	v_mfma_f32_32x32x16_bf16 v[98:113], v[150:153], v[142:145], v[98:113]
	v_mfma_f32_32x32x16_bf16 v[82:97], v[150:153], v[146:149], v[82:97]
	v_mfma_f32_32x32x16_bf16 v[50:65], v[150:153], v[168:171], v[50:65]
	v_mfma_f32_32x32x16_bf16 v[34:49], v[150:153], v[134:137], v[34:49]
	s_lshl_b32 s10, s8, 2
	s_or_b32 s10, s10, s3
	s_mulk_i32 s10, 0x2400
	v_lshl_or_b32 v0, v166, 3, s10
	v_lshlrev_b32_e32 v130, 3, v165
	v_and_b32_e32 v132, 56, v130
	v_mad_u32_u24 v130, v165, s78, v0
	v_cvt_pk_bf16_f32 v66, v66, v67
	v_cvt_pk_bf16_f32 v67, v68, v69
	v_cvt_pk_bf16_f32 v68, v70, v71
	v_cvt_pk_bf16_f32 v69, v72, v73
	v_add_u32_e32 v70, 0x1000, v130
	s_barrier
	ds_write2_b64 v70, v[66:67], v[68:69] offset0:64 offset1:66
	v_cvt_pk_bf16_f32 v66, v74, v75
	v_cvt_pk_bf16_f32 v67, v76, v77
	v_cvt_pk_bf16_f32 v68, v78, v79
	v_cvt_pk_bf16_f32 v69, v80, v81
	s_lshl_b32 s8, s8, 7
	ds_write2_b64 v70, v[66:67], v[68:69] offset0:68 offset1:70
	v_cvt_pk_bf16_f32 v66, v82, v83
	v_cvt_pk_bf16_f32 v67, v84, v85
	v_cvt_pk_bf16_f32 v68, v86, v87
	v_cvt_pk_bf16_f32 v69, v88, v89
	s_lshl_b32 s9, s36, 8
	v_bfe_u32 v131, v164, 3, 3
	s_lshl_b32 s3, s3, 6
	ds_write2_b64 v70, v[66:67], v[68:69] offset0:72 offset1:74
	v_cvt_pk_bf16_f32 v66, v90, v91
	v_cvt_pk_bf16_f32 v67, v92, v93
	v_cvt_pk_bf16_f32 v68, v94, v95
	v_cvt_pk_bf16_f32 v69, v96, v97
	s_add_i32 s2, s8, s2
	ds_write2_b64 v70, v[66:67], v[68:69] offset0:76 offset1:78
	v_or_b32_e32 v66, s2, v131
	s_or_b32 s3, s3, s9
	v_cvt_pk_bf16_f32 v114, v114, v115
	v_cvt_pk_bf16_f32 v115, v116, v117
	v_cvt_pk_bf16_f32 v116, v118, v119
	v_cvt_pk_bf16_f32 v117, v120, v121
	v_cvt_pk_bf16_f32 v98, v98, v99
	v_cvt_pk_bf16_f32 v99, v100, v101
	v_cvt_pk_bf16_f32 v100, v102, v103
	v_cvt_pk_bf16_f32 v101, v104, v105
	v_or_b32_e32 v68, s3, v132
	v_ashrrev_i32_e32 v67, 31, v66
	ds_write2_b64 v130, v[114:115], v[116:117] offset1:2
	v_cvt_pk_bf16_f32 v114, v122, v123
	v_cvt_pk_bf16_f32 v115, v124, v125
	v_cvt_pk_bf16_f32 v116, v126, v127
	v_cvt_pk_bf16_f32 v117, v128, v129
	ds_write2_b64 v130, v[98:99], v[100:101] offset0:8 offset1:10
	v_cvt_pk_bf16_f32 v98, v106, v107
	v_cvt_pk_bf16_f32 v99, v108, v109
	v_cvt_pk_bf16_f32 v100, v110, v111
	v_cvt_pk_bf16_f32 v101, v112, v113
	v_min_i32_e32 v0, 0x8000, v66
	v_ashrrev_i32_e32 v69, 31, v68
	v_lshlrev_b64 v[66:67], 11, v[66:67]
	ds_write2_b64 v130, v[114:115], v[116:117] offset0:4 offset1:6
	ds_write2_b64 v130, v[98:99], v[100:101] offset0:12 offset1:14
	v_lshl_add_u64 v[72:73], s[46:47], 0, v[66:67]
	v_lshlrev_b64 v[66:67], 1, v[68:69]
	s_waitcnt lgkmcnt(0)
	v_lshl_add_u64 v[96:97], v[72:73], 0, v[66:67]
	global_load_dwordx4 v[72:75], v[96:97], off
	v_ashrrev_i32_e32 v0, 11, v0
	v_readlane_b32 s8, v234, 4
	v_mul_hi_i32_i24_e32 v77, 0x6000, v0
	v_mul_i32_i24_e32 v76, 0x6000, v0
	v_readlane_b32 s9, v234, 5
	v_lshlrev_b64 v[68:69], 2, v[68:69]
	v_or_b32_e32 v71, 8, v131
	v_lshl_add_u64 v[76:77], s[8:9], 0, v[76:77]
	v_lshl_add_u64 v[80:81], v[76:77], 0, v[68:69]
	global_load_dwordx4 v[76:79], v[80:81], off
	v_or_b32_e32 v98, s2, v71
	global_load_dwordx4 v[80:83], v[80:81], off offset:16
	v_ashrrev_i32_e32 v99, 31, v98
	v_lshl_or_b32 v0, v132, 1, s10
	v_lshlrev_b64 v[84:85], 11, v[98:99]
	v_mad_u32_u24 v0, v131, s78, v0
	v_lshl_add_u64 v[84:85], s[46:47], 0, v[84:85]
	v_lshl_add_u64 v[100:101], v[84:85], 0, v[66:67]
	ds_read_b128 v[84:87], v0
	global_load_dwordx4 v[92:95], v[100:101], off
	ds_read_b128 v[88:91], v0 offset:1152
	v_cvt_pk_bf16_f32 v2, v2, v3
	v_cvt_pk_bf16_f32 v3, v4, v5
	s_waitcnt lgkmcnt(1)
;   DI void operator()(f32x16 (&acc)[2][MB], int wm, int wn, int r, int h) {
;     ...
;         for (int j = 0; j < 8; ++j) {
;           const int rowl = (lane >> 3) + 8 * j, ch = lane & 7;
;           if (rowl < ntok) {
;             const u32x4 yv = *(const u32x4*)(slab + rowl * 72 + ch * 8);
;             const int R = R0 + rowl;
;             const int mi = (R < NLAT) ? (R >> 11) : 16;
;             const int col = n0 + wn * 64 + ch * 8;
;             const float* g = gate + (size_t)mi * 6144 + col;
;             const f32x4n g0 = *(const f32x4n*)(g), g1 = *(const f32x4n*)(g + 4);
;             _Float16* xp = X + (size_t)R * 1024 + col;
;             const h8 xv = *(const h8*)xp;
;             const float y[8] = {__uint_as_float(yv.x << 16), __uint_as_float(yv.x & 0xffff0000u), __uint_as_float(yv.y << 16), __uint_as_float(yv.y & 0xffff0000u),
;                                 __uint_as_float(yv.z << 16), __uint_as_float(yv.z & 0xffff0000u), __uint_as_float(yv.w << 16), __uint_as_float(yv.w & 0xffff0000u)};
;             const float gg[8] = {g0.x, g0.y, g0.z, g0.w, g1.x, g1.y, g1.z, g1.w};
;             h8 o;
; #pragma unroll
;             for (int q = 0; q < 8; ++q) o[q] = (_Float16)(ALPHA * (float)xv[q] + gg[q] * y[q]);
;             *(h8*)xp = o;
	v_lshlrev_b32_e32 v104, 16, v84
	v_and_b32_e32 v105, 0xffff0000, v84
	v_cvt_pk_bf16_f32 v4, v6, v7
	v_cvt_pk_bf16_f32 v5, v8, v9
	v_cvt_pk_bf16_f32 v6, v10, v11
	v_cvt_pk_bf16_f32 v7, v12, v13
	v_cvt_pk_bf16_f32 v8, v14, v15
	v_cvt_pk_bf16_f32 v9, v16, v17
	v_cvt_pk_bf16_f32 v10, v34, v35
	v_cvt_pk_bf16_f32 v11, v36, v37
	v_cvt_pk_bf16_f32 v12, v38, v39
	v_cvt_pk_bf16_f32 v13, v40, v41
	v_cvt_pk_bf16_f32 v14, v42, v43
	v_cvt_pk_bf16_f32 v15, v44, v45
	v_cvt_pk_bf16_f32 v16, v46, v47
	v_cvt_pk_bf16_f32 v17, v48, v49
	v_cvt_pk_bf16_f32 v18, v18, v19
	v_cvt_pk_bf16_f32 v19, v20, v21
	v_cvt_pk_bf16_f32 v20, v22, v23
	v_cvt_pk_bf16_f32 v21, v24, v25
	v_cvt_pk_bf16_f32 v22, v26, v27
	v_cvt_pk_bf16_f32 v23, v28, v29
	v_cvt_pk_bf16_f32 v24, v30, v31
	v_cvt_pk_bf16_f32 v25, v32, v33
	v_cvt_pk_bf16_f32 v26, v50, v51
	v_cvt_pk_bf16_f32 v27, v52, v53
	v_cvt_pk_bf16_f32 v28, v54, v55
	v_cvt_pk_bf16_f32 v29, v56, v57
	v_cvt_pk_bf16_f32 v30, v58, v59
	v_cvt_pk_bf16_f32 v31, v60, v61
	v_cvt_pk_bf16_f32 v32, v62, v63
	v_cvt_pk_bf16_f32 v33, v64, v65
	s_waitcnt vmcnt(3)
	v_cvt_f32_f16_e32 v102, v72
	v_cvt_f32_f16_sdwa v103, v72 dst_sel:DWORD dst_unused:UNUSED_PAD src0_sel:WORD_1
	v_cvt_f32_f16_e32 v106, v73
	v_cvt_f32_f16_sdwa v107, v73 dst_sel:DWORD dst_unused:UNUSED_PAD src0_sel:WORD_1
	v_pk_mul_f32 v[102:103], v[102:103], s[30:31] op_sel_hi:[1,0]
	s_waitcnt vmcnt(2)
	v_pk_fma_f32 v[76:77], v[76:77], v[104:105], v[102:103]
	s_nop 0
	v_cvt_pk_f16_f32 v72, v76, v77
	v_lshlrev_b32_e32 v76, 16, v85
	v_and_b32_e32 v77, 0xffff0000, v85
	v_pk_mul_f32 v[84:85], v[106:107], s[30:31] op_sel_hi:[1,0]
	s_waitcnt lgkmcnt(0)
	v_lshlrev_b32_e32 v102, 16, v90
	v_pk_fma_f32 v[76:77], v[78:79], v[76:77], v[84:85]
	v_cvt_f32_f16_e32 v78, v74
	v_cvt_f32_f16_sdwa v79, v74 dst_sel:DWORD dst_unused:UNUSED_PAD src0_sel:WORD_1
	v_cvt_pk_f16_f32 v73, v76, v77
	v_lshlrev_b32_e32 v76, 16, v86
	v_and_b32_e32 v77, 0xffff0000, v86
	v_pk_mul_f32 v[78:79], v[78:79], s[30:31] op_sel_hi:[1,0]
	s_waitcnt vmcnt(0)
	v_cvt_f32_f16_e32 v104, v92
	v_pk_fma_f32 v[76:77], v[80:81], v[76:77], v[78:79]
	v_cvt_f32_f16_e32 v78, v75
	v_cvt_f32_f16_sdwa v79, v75 dst_sel:DWORD dst_unused:UNUSED_PAD src0_sel:WORD_1
	v_cvt_pk_f16_f32 v74, v76, v77
	v_lshlrev_b32_e32 v76, 16, v87
	v_and_b32_e32 v77, 0xffff0000, v87
	v_pk_mul_f32 v[78:79], v[78:79], s[30:31] op_sel_hi:[1,0]
	v_cvt_f32_f16_sdwa v105, v92 dst_sel:DWORD dst_unused:UNUSED_PAD src0_sel:WORD_1
	v_pk_fma_f32 v[76:77], v[82:83], v[76:77], v[78:79]
	v_cvt_f32_f16_e32 v92, v93
	v_cvt_pk_f16_f32 v75, v76, v77
	global_store_dwordx4 v[96:97], v[72:75], off
	v_cvt_f32_f16_sdwa v93, v93 dst_sel:DWORD dst_unused:UNUSED_PAD src0_sel:WORD_1
	v_cvt_f32_f16_e32 v106, v94
	v_min_i32_e32 v72, 0x8000, v98
	v_ashrrev_i32_e32 v72, 11, v72
	v_mul_hi_i32_i24_e32 v73, 0x6000, v72
	v_mul_i32_i24_e32 v72, 0x6000, v72
	v_lshl_add_u64 v[72:73], s[8:9], 0, v[72:73]
	v_lshl_add_u64 v[72:73], v[72:73], 0, v[68:69]
	global_load_dwordx4 v[74:77], v[72:73], off
	global_load_dwordx4 v[78:81], v[72:73], off offset:16
	v_or_b32_e32 v72, 16, v131
	v_or_b32_e32 v82, s2, v72
	v_min_i32_e32 v73, 0x8000, v82
	v_ashrrev_i32_e32 v83, 31, v82
	v_ashrrev_i32_e32 v73, 11, v73
	v_lshlrev_b64 v[82:83], 11, v[82:83]
	v_cvt_f32_f16_sdwa v107, v94 dst_sel:DWORD dst_unused:UNUSED_PAD src0_sel:WORD_1
	v_cvt_f32_f16_e32 v94, v95
	v_cvt_f32_f16_sdwa v95, v95 dst_sel:DWORD dst_unused:UNUSED_PAD src0_sel:WORD_1
	v_mul_hi_i32_i24_e32 v85, 0x6000, v73
	v_mul_i32_i24_e32 v84, 0x6000, v73
	v_lshl_add_u64 v[82:83], s[46:47], 0, v[82:83]
	v_lshl_add_u64 v[84:85], s[8:9], 0, v[84:85]
	v_lshl_add_u64 v[98:99], v[82:83], 0, v[66:67]
	v_lshl_add_u64 v[86:87], v[84:85], 0, v[68:69]
	global_load_dwordx4 v[82:85], v[98:99], off
	v_lshlrev_b32_e32 v96, 16, v88
	v_and_b32_e32 v97, 0xffff0000, v88
	v_lshlrev_b32_e32 v88, 16, v89
	v_and_b32_e32 v89, 0xffff0000, v89
	v_and_b32_e32 v103, 0xffff0000, v90
	v_lshlrev_b32_e32 v90, 16, v91
	v_and_b32_e32 v91, 0xffff0000, v91
	v_pk_mul_f32 v[104:105], v[104:105], s[30:31] op_sel_hi:[1,0]
	v_pk_mul_f32 v[92:93], v[92:93], s[30:31] op_sel_hi:[1,0]
	v_pk_mul_f32 v[106:107], v[106:107], s[30:31] op_sel_hi:[1,0]
	v_pk_mul_f32 v[94:95], v[94:95], s[30:31] op_sel_hi:[1,0]
	v_or_b32_e32 v73, 24, v131
	s_waitcnt vmcnt(2)
	v_pk_fma_f32 v[74:75], v[74:75], v[96:97], v[104:105]
	v_pk_fma_f32 v[76:77], v[76:77], v[88:89], v[92:93]
	s_waitcnt vmcnt(1)
	v_pk_fma_f32 v[78:79], v[78:79], v[102:103], v[106:107]
	v_pk_fma_f32 v[80:81], v[80:81], v[90:91], v[94:95]
	v_cvt_pk_f16_f32 v74, v74, v75
	v_cvt_pk_f16_f32 v75, v76, v77
	v_cvt_pk_f16_f32 v76, v78, v79
	v_cvt_pk_f16_f32 v77, v80, v81
	global_store_dwordx4 v[100:101], v[74:77], off
	global_load_dwordx4 v[74:77], v[86:87], off
	s_waitcnt vmcnt(2)
	v_cvt_f32_f16_e32 v108, v82
	global_load_dwordx4 v[78:81], v[86:87], off offset:16
	v_or_b32_e32 v86, s2, v73
	v_min_i32_e32 v88, 0x8000, v86
	v_ashrrev_i32_e32 v87, 31, v86
	v_ashrrev_i32_e32 v88, 11, v88
	v_lshlrev_b64 v[86:87], 11, v[86:87]
	v_mul_hi_i32_i24_e32 v89, 0x6000, v88
	v_mul_i32_i24_e32 v88, 0x6000, v88
	v_lshl_add_u64 v[90:91], s[46:47], 0, v[86:87]
	v_lshl_add_u64 v[92:93], s[8:9], 0, v[88:89]
	ds_read_b128 v[86:89], v0 offset:2304
	v_cvt_f32_f16_sdwa v109, v82 dst_sel:DWORD dst_unused:UNUSED_PAD src0_sel:WORD_1
	v_cvt_f32_f16_e32 v82, v83
	v_cvt_f32_f16_sdwa v83, v83 dst_sel:DWORD dst_unused:UNUSED_PAD src0_sel:WORD_1
	v_cvt_f32_f16_e32 v110, v84
	v_cvt_f32_f16_sdwa v111, v84 dst_sel:DWORD dst_unused:UNUSED_PAD src0_sel:WORD_1
	v_cvt_f32_f16_e32 v84, v85
	v_cvt_f32_f16_sdwa v85, v85 dst_sel:DWORD dst_unused:UNUSED_PAD src0_sel:WORD_1
	v_lshl_add_u64 v[100:101], v[90:91], 0, v[66:67]
	global_load_dwordx4 v[94:97], v[100:101], off
	s_waitcnt lgkmcnt(0)
;   DI void operator()(f32x16 (&acc)[2][MB], int wm, int wn, int r, int h) {
;     ...
;         for (int j = 0; j < 8; ++j) {
;           const int rowl = (lane >> 3) + 8 * j, ch = lane & 7;
;           if (rowl < ntok) {
;             const u32x4 yv = *(const u32x4*)(slab + rowl * 72 + ch * 8);
;             const int R = R0 + rowl;
;             const int mi = (R < NLAT) ? (R >> 11) : 16;
;             const int col = n0 + wn * 64 + ch * 8;
;             const float* g = gate + (size_t)mi * 6144 + col;
;             const f32x4n g0 = *(const f32x4n*)(g), g1 = *(const f32x4n*)(g + 4);
;             _Float16* xp = X + (size_t)R * 1024 + col;
;             const h8 xv = *(const h8*)xp;
;             const float y[8] = {__uint_as_float(yv.x << 16), __uint_as_float(yv.x & 0xffff0000u), __uint_as_float(yv.y << 16), __uint_as_float(yv.y & 0xffff0000u),
;                                 __uint_as_float(yv.z << 16), __uint_as_float(yv.z & 0xffff0000u), __uint_as_float(yv.w << 16), __uint_as_float(yv.w & 0xffff0000u)};
;             const float gg[8] = {g0.x, g0.y, g0.z, g0.w, g1.x, g1.y, g1.z, g1.w};
;             h8 o;
; #pragma unroll
;             for (int q = 0; q < 8; ++q) o[q] = (_Float16)(ALPHA * (float)xv[q] + gg[q] * y[q]);
;             *(h8*)xp = o;
	v_lshlrev_b32_e32 v104, 16, v86
	v_and_b32_e32 v105, 0xffff0000, v86
	v_lshlrev_b32_e32 v86, 16, v87
	v_and_b32_e32 v87, 0xffff0000, v87
	v_lshlrev_b32_e32 v106, 16, v88
	v_and_b32_e32 v107, 0xffff0000, v88
	v_lshlrev_b32_e32 v88, 16, v89
	v_and_b32_e32 v89, 0xffff0000, v89
	v_pk_mul_f32 v[108:109], v[108:109], s[30:31] op_sel_hi:[1,0]
	v_pk_mul_f32 v[82:83], v[82:83], s[30:31] op_sel_hi:[1,0]
	v_pk_mul_f32 v[110:111], v[110:111], s[30:31] op_sel_hi:[1,0]
	v_pk_mul_f32 v[84:85], v[84:85], s[30:31] op_sel_hi:[1,0]
	v_lshl_add_u64 v[102:103], v[92:93], 0, v[68:69]
	ds_read_b128 v[90:93], v0 offset:3456
	s_waitcnt vmcnt(2)
	v_pk_fma_f32 v[74:75], v[74:75], v[104:105], v[108:109]
	v_pk_fma_f32 v[76:77], v[76:77], v[86:87], v[82:83]
	v_cvt_pk_f16_f32 v74, v74, v75
	v_cvt_pk_f16_f32 v75, v76, v77
	s_waitcnt lgkmcnt(0)
	v_lshlrev_b32_e32 v104, 16, v92
	v_and_b32_e32 v105, 0xffff0000, v92
	v_lshlrev_b32_e32 v92, 16, v93
	v_and_b32_e32 v93, 0xffff0000, v93
	s_waitcnt vmcnt(1)
	v_pk_fma_f32 v[78:79], v[78:79], v[106:107], v[110:111]
	v_pk_fma_f32 v[80:81], v[80:81], v[88:89], v[84:85]
	v_cvt_pk_f16_f32 v76, v78, v79
	v_cvt_pk_f16_f32 v77, v80, v81
	global_store_dwordx4 v[98:99], v[74:77], off
	global_load_dwordx4 v[76:79], v[102:103], off
	v_lshlrev_b32_e32 v98, 16, v90
	global_load_dwordx4 v[80:83], v[102:103], off offset:16
	v_or_b32_e32 v74, 32, v131
	v_or_b32_e32 v84, s2, v74
	v_min_i32_e32 v75, 0x8000, v84
	v_ashrrev_i32_e32 v85, 31, v84
	v_ashrrev_i32_e32 v75, 11, v75
	v_lshlrev_b64 v[84:85], 11, v[84:85]
	v_mul_hi_i32_i24_e32 v87, 0x6000, v75
	v_mul_i32_i24_e32 v86, 0x6000, v75
	v_lshl_add_u64 v[84:85], s[46:47], 0, v[84:85]
	v_lshl_add_u64 v[86:87], s[8:9], 0, v[86:87]
	v_lshl_add_u64 v[102:103], v[84:85], 0, v[66:67]
	s_waitcnt vmcnt(3)
	v_cvt_f32_f16_e32 v106, v94
	v_cvt_f32_f16_sdwa v107, v94 dst_sel:DWORD dst_unused:UNUSED_PAD src0_sel:WORD_1
	v_cvt_f32_f16_e32 v94, v95
	v_cvt_f32_f16_sdwa v95, v95 dst_sel:DWORD dst_unused:UNUSED_PAD src0_sel:WORD_1
	v_cvt_f32_f16_e32 v108, v96
	v_cvt_f32_f16_sdwa v109, v96 dst_sel:DWORD dst_unused:UNUSED_PAD src0_sel:WORD_1
	v_cvt_f32_f16_e32 v96, v97
	v_cvt_f32_f16_sdwa v97, v97 dst_sel:DWORD dst_unused:UNUSED_PAD src0_sel:WORD_1
	v_lshl_add_u64 v[88:89], v[86:87], 0, v[68:69]
	global_load_dwordx4 v[84:87], v[102:103], off
	v_and_b32_e32 v99, 0xffff0000, v90
	v_lshlrev_b32_e32 v90, 16, v91
	v_and_b32_e32 v91, 0xffff0000, v91
	v_pk_mul_f32 v[106:107], v[106:107], s[30:31] op_sel_hi:[1,0]
	v_pk_mul_f32 v[94:95], v[94:95], s[30:31] op_sel_hi:[1,0]
	v_pk_mul_f32 v[108:109], v[108:109], s[30:31] op_sel_hi:[1,0]
	v_pk_mul_f32 v[96:97], v[96:97], s[30:31] op_sel_hi:[1,0]
	v_or_b32_e32 v75, 40, v131
	s_waitcnt vmcnt(2)
	v_pk_fma_f32 v[76:77], v[76:77], v[98:99], v[106:107]
	v_pk_fma_f32 v[78:79], v[78:79], v[90:91], v[94:95]
	s_waitcnt vmcnt(1)
	v_pk_fma_f32 v[80:81], v[80:81], v[104:105], v[108:109]
	v_pk_fma_f32 v[82:83], v[82:83], v[92:93], v[96:97]
	v_cvt_pk_f16_f32 v76, v76, v77
	v_cvt_pk_f16_f32 v77, v78, v79
	v_cvt_pk_f16_f32 v78, v80, v81
	v_cvt_pk_f16_f32 v79, v82, v83
	global_store_dwordx4 v[100:101], v[76:79], off
	global_load_dwordx4 v[76:79], v[88:89], off
	s_waitcnt vmcnt(2)
	v_cvt_f32_f16_e32 v110, v84
	global_load_dwordx4 v[80:83], v[88:89], off offset:16
	v_or_b32_e32 v88, s2, v75
	v_min_i32_e32 v90, 0x8000, v88
	v_ashrrev_i32_e32 v89, 31, v88
	v_ashrrev_i32_e32 v90, 11, v90
	v_lshlrev_b64 v[88:89], 11, v[88:89]
	v_mul_hi_i32_i24_e32 v91, 0x6000, v90
	v_mul_i32_i24_e32 v90, 0x6000, v90
	v_lshl_add_u64 v[92:93], s[46:47], 0, v[88:89]
	v_lshl_add_u64 v[94:95], s[8:9], 0, v[90:91]
	ds_read_b128 v[88:91], v0 offset:4608
	v_cvt_f32_f16_sdwa v111, v84 dst_sel:DWORD dst_unused:UNUSED_PAD src0_sel:WORD_1
	v_cvt_f32_f16_e32 v84, v85
	v_cvt_f32_f16_sdwa v85, v85 dst_sel:DWORD dst_unused:UNUSED_PAD src0_sel:WORD_1
	v_cvt_f32_f16_e32 v112, v86
	v_cvt_f32_f16_sdwa v113, v86 dst_sel:DWORD dst_unused:UNUSED_PAD src0_sel:WORD_1
	v_cvt_f32_f16_e32 v86, v87
	v_cvt_f32_f16_sdwa v87, v87 dst_sel:DWORD dst_unused:UNUSED_PAD src0_sel:WORD_1
	v_lshl_add_u64 v[100:101], v[92:93], 0, v[66:67]
	global_load_dwordx4 v[96:99], v[100:101], off
	s_waitcnt lgkmcnt(0)
	v_lshlrev_b32_e32 v106, 16, v88
	v_and_b32_e32 v107, 0xffff0000, v88
	v_lshlrev_b32_e32 v88, 16, v89
	v_and_b32_e32 v89, 0xffff0000, v89
	v_lshlrev_b32_e32 v108, 16, v90
	v_and_b32_e32 v109, 0xffff0000, v90
	v_lshlrev_b32_e32 v90, 16, v91
	v_and_b32_e32 v91, 0xffff0000, v91
	v_pk_mul_f32 v[110:111], v[110:111], s[30:31] op_sel_hi:[1,0]
	v_pk_mul_f32 v[84:85], v[84:85], s[30:31] op_sel_hi:[1,0]
	v_pk_mul_f32 v[112:113], v[112:113], s[30:31] op_sel_hi:[1,0]
	v_pk_mul_f32 v[86:87], v[86:87], s[30:31] op_sel_hi:[1,0]
	v_lshl_add_u64 v[104:105], v[94:95], 0, v[68:69]
	ds_read_b128 v[92:95], v0 offset:5760
	s_waitcnt vmcnt(2)
	v_pk_fma_f32 v[76:77], v[76:77], v[106:107], v[110:111]
	v_pk_fma_f32 v[78:79], v[78:79], v[88:89], v[84:85]
	v_cvt_pk_f16_f32 v76, v76, v77
	v_cvt_pk_f16_f32 v77, v78, v79
	s_waitcnt lgkmcnt(0)
	v_lshlrev_b32_e32 v106, 16, v94
	v_and_b32_e32 v107, 0xffff0000, v94
	v_lshlrev_b32_e32 v94, 16, v95
	v_and_b32_e32 v95, 0xffff0000, v95
	s_waitcnt vmcnt(1)
	v_pk_fma_f32 v[80:81], v[80:81], v[108:109], v[112:113]
	v_pk_fma_f32 v[82:83], v[82:83], v[90:91], v[86:87]
	v_cvt_pk_f16_f32 v78, v80, v81
	v_cvt_pk_f16_f32 v79, v82, v83
	global_store_dwordx4 v[102:103], v[76:79], off
	global_load_dwordx4 v[78:81], v[104:105], off
	s_waitcnt vmcnt(2)
; DI unsigned pack2(float a, float b) { f2 v = {a, b}; bf2 r = __builtin_convertvector(v, bf2); return __builtin_bit_cast(unsigned, r); }
;   DI void operator()(f32x16 (&acc)[2][MB], int wm, int wn, int r, int h) {
;     ...
;     for (int mb = 0; mb < MB; ++mb) {
;       const int tokl = (mb & 1) * 32 + r;
; #pragma unroll
;       for (int nb = 0; nb < 2; ++nb)
; #pragma unroll
;         for (int ig = 0; ig < 4; ++ig) {
;           u32x2 o;
;           o.x = pack2(acc[nb][mb][ig * 4 + 0], acc[nb][mb][ig * 4 + 1]);
;           o.y = pack2(acc[nb][mb][ig * 4 + 2], acc[nb][mb][ig * 4 + 3]);
;           *(u32x2*)(slab + tokl * 72 + nb * 32 + ig * 8 + h * 4) = o;
;         }
;       if ((mb & 1) || mb == MB - 1) {
;         asm volatile("s_waitcnt lgkmcnt(0)" ::: "memory");
;         const int ntok = (mb & 1) ? 64 : 32;
;         const int R0 = row0 + wm * (32 * MB) + (mb >> 1) * 64;
; #pragma unroll
;         for (int j = 0; j < 8; ++j) {
;           const int rowl = (lane >> 3) + 8 * j, ch = lane & 7;
;           if (rowl < ntok) {
;             const u32x4 yv = *(const u32x4*)(slab + rowl * 72 + ch * 8);
;             const int R = R0 + rowl;
;             const int mi = (R < NLAT) ? (R >> 11) : 16;
;             const int col = n0 + wn * 64 + ch * 8;
;             const float* g = gate + (size_t)mi * 6144 + col;
;             const f32x4n g0 = *(const f32x4n*)(g), g1 = *(const f32x4n*)(g + 4);
;             _Float16* xp = X + (size_t)R * 1024 + col;
;             const h8 xv = *(const h8*)xp;
;             const float y[8] = {__uint_as_float(yv.x << 16), __uint_as_float(yv.x & 0xffff0000u), __uint_as_float(yv.y << 16), __uint_as_float(yv.y & 0xffff0000u),
;                                 __uint_as_float(yv.z << 16), __uint_as_float(yv.z & 0xffff0000u), __uint_as_float(yv.w << 16), __uint_as_float(yv.w & 0xffff0000u)};
;             const float gg[8] = {g0.x, g0.y, g0.z, g0.w, g1.x, g1.y, g1.z, g1.w};
;             h8 o;
; #pragma unroll
;             for (int q = 0; q < 8; ++q) o[q] = (_Float16)(ALPHA * (float)xv[q] + gg[q] * y[q]);
;             *(h8*)xp = o;
	v_cvt_f32_f16_e32 v108, v96
	global_load_dwordx4 v[82:85], v[104:105], off offset:16
	v_or_b32_e32 v76, 48, v131
	v_or_b32_e32 v86, s2, v76
	v_min_i32_e32 v77, 0x8000, v86
	v_ashrrev_i32_e32 v87, 31, v86
	v_ashrrev_i32_e32 v77, 11, v77
	v_lshlrev_b64 v[86:87], 11, v[86:87]
	v_cvt_f32_f16_sdwa v109, v96 dst_sel:DWORD dst_unused:UNUSED_PAD src0_sel:WORD_1
	v_cvt_f32_f16_e32 v96, v97
	v_cvt_f32_f16_sdwa v97, v97 dst_sel:DWORD dst_unused:UNUSED_PAD src0_sel:WORD_1
	v_cvt_f32_f16_e32 v110, v98
	v_cvt_f32_f16_sdwa v111, v98 dst_sel:DWORD dst_unused:UNUSED_PAD src0_sel:WORD_1
	v_cvt_f32_f16_e32 v98, v99
	v_cvt_f32_f16_sdwa v99, v99 dst_sel:DWORD dst_unused:UNUSED_PAD src0_sel:WORD_1
	v_mul_hi_i32_i24_e32 v89, 0x6000, v77
	v_mul_i32_i24_e32 v88, 0x6000, v77
	v_lshl_add_u64 v[86:87], s[46:47], 0, v[86:87]
	v_lshl_add_u64 v[88:89], s[8:9], 0, v[88:89]
	v_lshl_add_u64 v[102:103], v[86:87], 0, v[66:67]
	v_lshl_add_u64 v[90:91], v[88:89], 0, v[68:69]
	global_load_dwordx4 v[86:89], v[102:103], off
	v_lshlrev_b32_e32 v104, 16, v92
	v_and_b32_e32 v105, 0xffff0000, v92
	v_lshlrev_b32_e32 v92, 16, v93
	v_and_b32_e32 v93, 0xffff0000, v93
	v_pk_mul_f32 v[108:109], v[108:109], s[30:31] op_sel_hi:[1,0]
	v_pk_mul_f32 v[96:97], v[96:97], s[30:31] op_sel_hi:[1,0]
	v_pk_mul_f32 v[110:111], v[110:111], s[30:31] op_sel_hi:[1,0]
	v_pk_mul_f32 v[98:99], v[98:99], s[30:31] op_sel_hi:[1,0]
	v_or_b32_e32 v77, 56, v131
	s_waitcnt vmcnt(2)
	v_pk_fma_f32 v[78:79], v[78:79], v[104:105], v[108:109]
	v_pk_fma_f32 v[80:81], v[80:81], v[92:93], v[96:97]
	v_cvt_pk_f16_f32 v78, v78, v79
	v_cvt_pk_f16_f32 v79, v80, v81
	s_waitcnt vmcnt(1)
	v_pk_fma_f32 v[82:83], v[82:83], v[106:107], v[110:111]
	v_pk_fma_f32 v[84:85], v[84:85], v[94:95], v[98:99]
	v_cvt_pk_f16_f32 v80, v82, v83
	v_cvt_pk_f16_f32 v81, v84, v85
	global_store_dwordx4 v[100:101], v[78:81], off
	global_load_dwordx4 v[78:81], v[90:91], off
	s_waitcnt vmcnt(2)
	v_cvt_f32_f16_e32 v112, v86
	global_load_dwordx4 v[82:85], v[90:91], off offset:16
	v_or_b32_e32 v90, s2, v77
	v_min_i32_e32 v92, 0x8000, v90
	v_ashrrev_i32_e32 v91, 31, v90
	v_ashrrev_i32_e32 v92, 11, v92
	v_lshlrev_b64 v[90:91], 11, v[90:91]
	v_mul_hi_i32_i24_e32 v93, 0x6000, v92
	v_mul_i32_i24_e32 v92, 0x6000, v92
	v_lshl_add_u64 v[94:95], s[46:47], 0, v[90:91]
	v_lshl_add_u64 v[96:97], s[8:9], 0, v[92:93]
	ds_read_b128 v[90:93], v0 offset:6912
	v_cvt_f32_f16_sdwa v113, v86 dst_sel:DWORD dst_unused:UNUSED_PAD src0_sel:WORD_1
	v_cvt_f32_f16_e32 v86, v87
	v_cvt_f32_f16_sdwa v87, v87 dst_sel:DWORD dst_unused:UNUSED_PAD src0_sel:WORD_1
	v_cvt_f32_f16_e32 v114, v88
	v_cvt_f32_f16_sdwa v115, v88 dst_sel:DWORD dst_unused:UNUSED_PAD src0_sel:WORD_1
	v_cvt_f32_f16_e32 v88, v89
	v_cvt_f32_f16_sdwa v89, v89 dst_sel:DWORD dst_unused:UNUSED_PAD src0_sel:WORD_1
	v_lshl_add_u64 v[104:105], v[94:95], 0, v[66:67]
	global_load_dwordx4 v[98:101], v[104:105], off
	s_waitcnt lgkmcnt(0)
	v_lshlrev_b32_e32 v108, 16, v90
	v_and_b32_e32 v109, 0xffff0000, v90
	v_lshlrev_b32_e32 v90, 16, v91
	v_and_b32_e32 v91, 0xffff0000, v91
	v_lshlrev_b32_e32 v110, 16, v92
	v_and_b32_e32 v111, 0xffff0000, v92
	v_lshlrev_b32_e32 v92, 16, v93
	v_and_b32_e32 v93, 0xffff0000, v93
	v_pk_mul_f32 v[112:113], v[112:113], s[30:31] op_sel_hi:[1,0]
	v_pk_mul_f32 v[86:87], v[86:87], s[30:31] op_sel_hi:[1,0]
	v_pk_mul_f32 v[114:115], v[114:115], s[30:31] op_sel_hi:[1,0]
	v_pk_mul_f32 v[88:89], v[88:89], s[30:31] op_sel_hi:[1,0]
	v_lshl_add_u64 v[106:107], v[96:97], 0, v[68:69]
	ds_read_b128 v[94:97], v0 offset:8064
	ds_write2_b64 v70, v[10:11], v[12:13] offset0:72 offset1:74
	ds_write2_b64 v70, v[14:15], v[16:17] offset0:76 offset1:78
	s_add_i32 s2, s2, 64
	v_or_b32_e32 v34, s2, v131
	ds_write2_b64 v70, v[2:3], v[4:5] offset0:64 offset1:66
	ds_write2_b64 v70, v[6:7], v[8:9] offset0:68 offset1:70
	s_waitcnt lgkmcnt(4)
	v_lshlrev_b32_e32 v2, 16, v94
	v_and_b32_e32 v3, 0xffff0000, v94
	v_lshlrev_b32_e32 v4, 16, v95
	v_and_b32_e32 v5, 0xffff0000, v95
	v_lshlrev_b32_e32 v6, 16, v96
	v_and_b32_e32 v7, 0xffff0000, v96
	v_lshlrev_b32_e32 v8, 16, v97
	v_and_b32_e32 v9, 0xffff0000, v97
	v_ashrrev_i32_e32 v35, 31, v34
	v_lshlrev_b64 v[36:37], 11, v[34:35]
	v_lshl_add_u64 v[36:37], s[46:47], 0, v[36:37]
	ds_write2_b64 v130, v[18:19], v[20:21] offset1:2
	ds_write2_b64 v130, v[22:23], v[24:25] offset0:4 offset1:6
	ds_write2_b64 v130, v[26:27], v[28:29] offset0:8 offset1:10
	ds_write2_b64 v130, v[30:31], v[32:33] offset0:12 offset1:14
	v_lshl_add_u64 v[36:37], v[36:37], 0, v[66:67]
	s_waitcnt vmcnt(2)
	v_pk_fma_f32 v[78:79], v[78:79], v[108:109], v[112:113]
	v_pk_fma_f32 v[80:81], v[80:81], v[90:91], v[86:87]
	v_cvt_pk_f16_f32 v78, v78, v79
	v_cvt_pk_f16_f32 v79, v80, v81
	s_waitcnt vmcnt(1)
	v_pk_fma_f32 v[82:83], v[82:83], v[110:111], v[114:115]
	v_pk_fma_f32 v[84:85], v[84:85], v[92:93], v[88:89]
	v_cvt_pk_f16_f32 v80, v82, v83
	v_cvt_pk_f16_f32 v81, v84, v85
	global_store_dwordx4 v[102:103], v[78:81], off
	global_load_dwordx4 v[78:81], v[106:107], off
	s_waitcnt vmcnt(2)
	v_cvt_f32_f16_e32 v10, v98
	global_load_dwordx4 v[82:85], v[106:107], off offset:16
	v_cvt_f32_f16_sdwa v11, v98 dst_sel:DWORD dst_unused:UNUSED_PAD src0_sel:WORD_1
	v_cvt_f32_f16_e32 v12, v99
	v_cvt_f32_f16_sdwa v13, v99 dst_sel:DWORD dst_unused:UNUSED_PAD src0_sel:WORD_1
	v_cvt_f32_f16_e32 v14, v100
	v_cvt_f32_f16_sdwa v15, v100 dst_sel:DWORD dst_unused:UNUSED_PAD src0_sel:WORD_1
	v_cvt_f32_f16_e32 v16, v101
	v_cvt_f32_f16_sdwa v17, v101 dst_sel:DWORD dst_unused:UNUSED_PAD src0_sel:WORD_1
	v_pk_mul_f32 v[10:11], v[10:11], s[30:31] op_sel_hi:[1,0]
	v_pk_mul_f32 v[12:13], v[12:13], s[30:31] op_sel_hi:[1,0]
	v_pk_mul_f32 v[14:15], v[14:15], s[30:31] op_sel_hi:[1,0]
	v_pk_mul_f32 v[16:17], v[16:17], s[30:31] op_sel_hi:[1,0]
	s_waitcnt vmcnt(1)
;   DI void operator()(f32x16 (&acc)[2][MB], int wm, int wn, int r, int h) {
;     ...
;         for (int j = 0; j < 8; ++j) {
;           const int rowl = (lane >> 3) + 8 * j, ch = lane & 7;
;           if (rowl < ntok) {
;             const u32x4 yv = *(const u32x4*)(slab + rowl * 72 + ch * 8);
;             const int R = R0 + rowl;
;             const int mi = (R < NLAT) ? (R >> 11) : 16;
;             const int col = n0 + wn * 64 + ch * 8;
;             const float* g = gate + (size_t)mi * 6144 + col;
;             const f32x4n g0 = *(const f32x4n*)(g), g1 = *(const f32x4n*)(g + 4);
;             _Float16* xp = X + (size_t)R * 1024 + col;
;             const h8 xv = *(const h8*)xp;
;             const float y[8] = {__uint_as_float(yv.x << 16), __uint_as_float(yv.x & 0xffff0000u), __uint_as_float(yv.y << 16), __uint_as_float(yv.y & 0xffff0000u),
;                                 __uint_as_float(yv.z << 16), __uint_as_float(yv.z & 0xffff0000u), __uint_as_float(yv.w << 16), __uint_as_float(yv.w & 0xffff0000u)};
;             const float gg[8] = {g0.x, g0.y, g0.z, g0.w, g1.x, g1.y, g1.z, g1.w};
;             h8 o;
; #pragma unroll
;             for (int q = 0; q < 8; ++q) o[q] = (_Float16)(ALPHA * (float)xv[q] + gg[q] * y[q]);
;             *(h8*)xp = o;
	v_pk_fma_f32 v[2:3], v[78:79], v[2:3], v[10:11]
	v_pk_fma_f32 v[4:5], v[80:81], v[4:5], v[12:13]
	v_cvt_pk_f16_f32 v2, v2, v3
	v_cvt_pk_f16_f32 v3, v4, v5
	s_waitcnt vmcnt(0)
	v_pk_fma_f32 v[6:7], v[82:83], v[6:7], v[14:15]
	v_pk_fma_f32 v[8:9], v[84:85], v[8:9], v[16:17]
	v_cvt_pk_f16_f32 v4, v6, v7
	v_cvt_pk_f16_f32 v5, v8, v9
	global_store_dwordx4 v[104:105], v[2:5], off
	s_waitcnt lgkmcnt(0)
	global_load_dwordx4 v[2:5], v[36:37], off
	v_min_i32_e32 v6, 0x8000, v34
	v_ashrrev_i32_e32 v6, 11, v6
	v_mul_hi_i32_i24_e32 v7, 0x6000, v6
	v_mul_i32_i24_e32 v6, 0x6000, v6
	v_lshl_add_u64 v[6:7], s[8:9], 0, v[6:7]
	v_lshl_add_u64 v[10:11], v[6:7], 0, v[68:69]
	global_load_dwordx4 v[6:9], v[10:11], off
	v_or_b32_e32 v14, s2, v71
	global_load_dwordx4 v[10:13], v[10:11], off offset:16
	v_min_i32_e32 v16, 0x8000, v14
	v_ashrrev_i32_e32 v15, 31, v14
	v_ashrrev_i32_e32 v16, 11, v16
	v_lshlrev_b64 v[14:15], 11, v[14:15]
	v_mul_hi_i32_i24_e32 v17, 0x6000, v16
	v_mul_i32_i24_e32 v16, 0x6000, v16
	v_lshl_add_u64 v[18:19], s[46:47], 0, v[14:15]
	v_lshl_add_u64 v[20:21], s[8:9], 0, v[16:17]
	ds_read_b128 v[14:17], v0
	v_lshl_add_u64 v[26:27], v[18:19], 0, v[66:67]
	global_load_dwordx4 v[22:25], v[26:27], off
	v_lshl_add_u64 v[28:29], v[20:21], 0, v[68:69]
	ds_read_b128 v[18:21], v0 offset:1152
	s_waitcnt lgkmcnt(1)
	v_lshlrev_b32_e32 v30, 16, v14
	v_and_b32_e32 v31, 0xffff0000, v14
	v_lshlrev_b32_e32 v14, 16, v15
	v_and_b32_e32 v15, 0xffff0000, v15
	v_lshlrev_b32_e32 v32, 16, v16
	v_and_b32_e32 v33, 0xffff0000, v16
	v_lshlrev_b32_e32 v16, 16, v17
	v_and_b32_e32 v17, 0xffff0000, v17
	s_waitcnt vmcnt(3)
	v_cvt_f32_f16_e32 v34, v2
	v_cvt_f32_f16_sdwa v35, v2 dst_sel:DWORD dst_unused:UNUSED_PAD src0_sel:WORD_1
	v_cvt_f32_f16_e32 v2, v3
	v_cvt_f32_f16_sdwa v3, v3 dst_sel:DWORD dst_unused:UNUSED_PAD src0_sel:WORD_1
	v_cvt_f32_f16_e32 v38, v4
	v_cvt_f32_f16_sdwa v39, v4 dst_sel:DWORD dst_unused:UNUSED_PAD src0_sel:WORD_1
	v_cvt_f32_f16_e32 v4, v5
	v_cvt_f32_f16_sdwa v5, v5 dst_sel:DWORD dst_unused:UNUSED_PAD src0_sel:WORD_1
	v_pk_mul_f32 v[34:35], v[34:35], s[30:31] op_sel_hi:[1,0]
	v_pk_mul_f32 v[2:3], v[2:3], s[30:31] op_sel_hi:[1,0]
	v_pk_mul_f32 v[38:39], v[38:39], s[30:31] op_sel_hi:[1,0]
	v_pk_mul_f32 v[4:5], v[4:5], s[30:31] op_sel_hi:[1,0]
	s_waitcnt vmcnt(2)
	v_pk_fma_f32 v[6:7], v[6:7], v[30:31], v[34:35]
	v_pk_fma_f32 v[8:9], v[8:9], v[14:15], v[2:3]
	s_waitcnt vmcnt(1)
	v_pk_fma_f32 v[10:11], v[10:11], v[32:33], v[38:39]
	v_pk_fma_f32 v[12:13], v[12:13], v[16:17], v[4:5]
	v_cvt_pk_f16_f32 v2, v6, v7
	v_cvt_pk_f16_f32 v3, v8, v9
	v_cvt_pk_f16_f32 v4, v10, v11
	v_cvt_pk_f16_f32 v5, v12, v13
	global_store_dwordx4 v[36:37], v[2:5], off
	global_load_dwordx4 v[2:5], v[28:29], off
	v_or_b32_e32 v10, s2, v72
	global_load_dwordx4 v[6:9], v[28:29], off offset:16
	v_min_i32_e32 v12, 0x8000, v10
	v_ashrrev_i32_e32 v11, 31, v10
	v_ashrrev_i32_e32 v12, 11, v12
	v_lshlrev_b64 v[10:11], 11, v[10:11]
	s_waitcnt vmcnt(3)
	v_cvt_f32_f16_e32 v32, v22
	v_cvt_f32_f16_sdwa v33, v22 dst_sel:DWORD dst_unused:UNUSED_PAD src0_sel:WORD_1
	v_cvt_f32_f16_e32 v22, v23
	v_cvt_f32_f16_sdwa v23, v23 dst_sel:DWORD dst_unused:UNUSED_PAD src0_sel:WORD_1
	v_cvt_f32_f16_e32 v34, v24
	v_cvt_f32_f16_sdwa v35, v24 dst_sel:DWORD dst_unused:UNUSED_PAD src0_sel:WORD_1
	v_cvt_f32_f16_e32 v24, v25
	v_cvt_f32_f16_sdwa v25, v25 dst_sel:DWORD dst_unused:UNUSED_PAD src0_sel:WORD_1
	v_mul_hi_i32_i24_e32 v13, 0x6000, v12
	v_mul_i32_i24_e32 v12, 0x6000, v12
	v_lshl_add_u64 v[10:11], s[46:47], 0, v[10:11]
	v_lshl_add_u64 v[12:13], s[8:9], 0, v[12:13]
	v_lshl_add_u64 v[28:29], v[10:11], 0, v[66:67]
	v_lshl_add_u64 v[14:15], v[12:13], 0, v[68:69]
	global_load_dwordx4 v[10:13], v[28:29], off
	s_waitcnt lgkmcnt(0)
	v_lshlrev_b32_e32 v16, 16, v18
	v_and_b32_e32 v17, 0xffff0000, v18
	v_lshlrev_b32_e32 v18, 16, v19
	v_and_b32_e32 v19, 0xffff0000, v19
	v_lshlrev_b32_e32 v30, 16, v20
	v_and_b32_e32 v31, 0xffff0000, v20
	v_lshlrev_b32_e32 v20, 16, v21
	v_and_b32_e32 v21, 0xffff0000, v21
	v_pk_mul_f32 v[32:33], v[32:33], s[30:31] op_sel_hi:[1,0]
	v_pk_mul_f32 v[22:23], v[22:23], s[30:31] op_sel_hi:[1,0]
	v_pk_mul_f32 v[34:35], v[34:35], s[30:31] op_sel_hi:[1,0]
	v_pk_mul_f32 v[24:25], v[24:25], s[30:31] op_sel_hi:[1,0]
	s_waitcnt vmcnt(2)
	v_pk_fma_f32 v[2:3], v[2:3], v[16:17], v[32:33]
	v_pk_fma_f32 v[4:5], v[4:5], v[18:19], v[22:23]
	s_waitcnt vmcnt(1)
	v_pk_fma_f32 v[6:7], v[6:7], v[30:31], v[34:35]
	v_pk_fma_f32 v[8:9], v[8:9], v[20:21], v[24:25]
	v_cvt_pk_f16_f32 v2, v2, v3
	v_cvt_pk_f16_f32 v3, v4, v5
	v_cvt_pk_f16_f32 v4, v6, v7
	v_cvt_pk_f16_f32 v5, v8, v9
	global_store_dwordx4 v[26:27], v[2:5], off
	global_load_dwordx4 v[2:5], v[14:15], off
	s_waitcnt vmcnt(2)
	v_cvt_f32_f16_e32 v36, v10
	global_load_dwordx4 v[6:9], v[14:15], off offset:16
	v_or_b32_e32 v14, s2, v73
	v_min_i32_e32 v16, 0x8000, v14
	v_ashrrev_i32_e32 v15, 31, v14
	v_ashrrev_i32_e32 v16, 11, v16
	v_lshlrev_b64 v[14:15], 11, v[14:15]
	v_mul_hi_i32_i24_e32 v17, 0x6000, v16
	v_mul_i32_i24_e32 v16, 0x6000, v16
	v_lshl_add_u64 v[18:19], s[46:47], 0, v[14:15]
	v_lshl_add_u64 v[20:21], s[8:9], 0, v[16:17]
	ds_read_b128 v[14:17], v0 offset:2304
	v_cvt_f32_f16_sdwa v37, v10 dst_sel:DWORD dst_unused:UNUSED_PAD src0_sel:WORD_1
	v_cvt_f32_f16_e32 v10, v11
	v_cvt_f32_f16_sdwa v11, v11 dst_sel:DWORD dst_unused:UNUSED_PAD src0_sel:WORD_1
	v_cvt_f32_f16_e32 v38, v12
	v_cvt_f32_f16_sdwa v39, v12 dst_sel:DWORD dst_unused:UNUSED_PAD src0_sel:WORD_1
	v_cvt_f32_f16_e32 v12, v13
	v_cvt_f32_f16_sdwa v13, v13 dst_sel:DWORD dst_unused:UNUSED_PAD src0_sel:WORD_1
	v_lshl_add_u64 v[26:27], v[18:19], 0, v[66:67]
	global_load_dwordx4 v[22:25], v[26:27], off
	s_waitcnt lgkmcnt(0)
;   DI void operator()(f32x16 (&acc)[2][MB], int wm, int wn, int r, int h) {
;     ...
;         for (int j = 0; j < 8; ++j) {
;           const int rowl = (lane >> 3) + 8 * j, ch = lane & 7;
;           if (rowl < ntok) {
;             const u32x4 yv = *(const u32x4*)(slab + rowl * 72 + ch * 8);
;             const int R = R0 + rowl;
;             const int mi = (R < NLAT) ? (R >> 11) : 16;
;             const int col = n0 + wn * 64 + ch * 8;
;             const float* g = gate + (size_t)mi * 6144 + col;
;             const f32x4n g0 = *(const f32x4n*)(g), g1 = *(const f32x4n*)(g + 4);
;             _Float16* xp = X + (size_t)R * 1024 + col;
;             const h8 xv = *(const h8*)xp;
;             const float y[8] = {__uint_as_float(yv.x << 16), __uint_as_float(yv.x & 0xffff0000u), __uint_as_float(yv.y << 16), __uint_as_float(yv.y & 0xffff0000u),
;                                 __uint_as_float(yv.z << 16), __uint_as_float(yv.z & 0xffff0000u), __uint_as_float(yv.w << 16), __uint_as_float(yv.w & 0xffff0000u)};
;             const float gg[8] = {g0.x, g0.y, g0.z, g0.w, g1.x, g1.y, g1.z, g1.w};
;             h8 o;
; #pragma unroll
;             for (int q = 0; q < 8; ++q) o[q] = (_Float16)(ALPHA * (float)xv[q] + gg[q] * y[q]);
;             *(h8*)xp = o;
	v_lshlrev_b32_e32 v32, 16, v14
	v_and_b32_e32 v33, 0xffff0000, v14
	v_lshlrev_b32_e32 v14, 16, v15
	v_and_b32_e32 v15, 0xffff0000, v15
	v_lshlrev_b32_e32 v34, 16, v16
	v_and_b32_e32 v35, 0xffff0000, v16
	v_lshlrev_b32_e32 v16, 16, v17
	v_and_b32_e32 v17, 0xffff0000, v17
	v_pk_mul_f32 v[36:37], v[36:37], s[30:31] op_sel_hi:[1,0]
	v_pk_mul_f32 v[10:11], v[10:11], s[30:31] op_sel_hi:[1,0]
	v_pk_mul_f32 v[38:39], v[38:39], s[30:31] op_sel_hi:[1,0]
	v_pk_mul_f32 v[12:13], v[12:13], s[30:31] op_sel_hi:[1,0]
	v_lshl_add_u64 v[30:31], v[20:21], 0, v[68:69]
	ds_read_b128 v[18:21], v0 offset:3456
	s_waitcnt vmcnt(2)
	v_pk_fma_f32 v[2:3], v[2:3], v[32:33], v[36:37]
	v_pk_fma_f32 v[4:5], v[4:5], v[14:15], v[10:11]
	v_cvt_pk_f16_f32 v2, v2, v3
	v_cvt_pk_f16_f32 v3, v4, v5
	v_or_b32_e32 v10, s2, v74
	v_ashrrev_i32_e32 v11, 31, v10
	s_waitcnt vmcnt(1)
	v_pk_fma_f32 v[6:7], v[6:7], v[34:35], v[38:39]
	v_pk_fma_f32 v[8:9], v[8:9], v[16:17], v[12:13]
	v_cvt_pk_f16_f32 v4, v6, v7
	v_cvt_pk_f16_f32 v5, v8, v9
	global_store_dwordx4 v[28:29], v[2:5], off
	global_load_dwordx4 v[2:5], v[30:31], off
	v_min_i32_e32 v12, 0x8000, v10
	global_load_dwordx4 v[6:9], v[30:31], off offset:16
	v_ashrrev_i32_e32 v12, 11, v12
	v_lshlrev_b64 v[10:11], 11, v[10:11]
	v_mul_hi_i32_i24_e32 v13, 0x6000, v12
	v_mul_i32_i24_e32 v12, 0x6000, v12
	v_lshl_add_u64 v[10:11], s[46:47], 0, v[10:11]
	v_lshl_add_u64 v[12:13], s[8:9], 0, v[12:13]
	v_lshl_add_u64 v[28:29], v[10:11], 0, v[66:67]
	v_lshl_add_u64 v[14:15], v[12:13], 0, v[68:69]
	global_load_dwordx4 v[10:13], v[28:29], off
	s_waitcnt lgkmcnt(0)
	v_lshlrev_b32_e32 v16, 16, v18
	v_and_b32_e32 v17, 0xffff0000, v18
	s_waitcnt vmcnt(4)
	v_cvt_f32_f16_e32 v32, v22
	v_cvt_f32_f16_sdwa v33, v22 dst_sel:DWORD dst_unused:UNUSED_PAD src0_sel:WORD_1
	v_cvt_f32_f16_e32 v22, v23
	v_cvt_f32_f16_sdwa v23, v23 dst_sel:DWORD dst_unused:UNUSED_PAD src0_sel:WORD_1
	v_cvt_f32_f16_e32 v34, v24
	v_cvt_f32_f16_sdwa v35, v24 dst_sel:DWORD dst_unused:UNUSED_PAD src0_sel:WORD_1
	v_cvt_f32_f16_e32 v24, v25
	v_cvt_f32_f16_sdwa v25, v25 dst_sel:DWORD dst_unused:UNUSED_PAD src0_sel:WORD_1
	v_lshlrev_b32_e32 v18, 16, v19
	v_and_b32_e32 v19, 0xffff0000, v19
	v_lshlrev_b32_e32 v30, 16, v20
	v_and_b32_e32 v31, 0xffff0000, v20
	v_lshlrev_b32_e32 v20, 16, v21
	v_and_b32_e32 v21, 0xffff0000, v21
	v_pk_mul_f32 v[32:33], v[32:33], s[30:31] op_sel_hi:[1,0]
	v_pk_mul_f32 v[22:23], v[22:23], s[30:31] op_sel_hi:[1,0]
	v_pk_mul_f32 v[34:35], v[34:35], s[30:31] op_sel_hi:[1,0]
	v_pk_mul_f32 v[24:25], v[24:25], s[30:31] op_sel_hi:[1,0]
	s_waitcnt vmcnt(2)
	v_pk_fma_f32 v[2:3], v[2:3], v[16:17], v[32:33]
	v_pk_fma_f32 v[4:5], v[4:5], v[18:19], v[22:23]
	s_waitcnt vmcnt(1)
	v_pk_fma_f32 v[6:7], v[6:7], v[30:31], v[34:35]
	v_pk_fma_f32 v[8:9], v[8:9], v[20:21], v[24:25]
	v_cvt_pk_f16_f32 v2, v2, v3
	v_cvt_pk_f16_f32 v3, v4, v5
	v_cvt_pk_f16_f32 v4, v6, v7
	v_cvt_pk_f16_f32 v5, v8, v9
	global_store_dwordx4 v[26:27], v[2:5], off
	global_load_dwordx4 v[2:5], v[14:15], off
	s_waitcnt vmcnt(2)
	v_cvt_f32_f16_e32 v36, v10
	global_load_dwordx4 v[6:9], v[14:15], off offset:16
	v_or_b32_e32 v14, s2, v75
	v_min_i32_e32 v16, 0x8000, v14
	v_ashrrev_i32_e32 v15, 31, v14
	v_ashrrev_i32_e32 v16, 11, v16
	v_lshlrev_b64 v[14:15], 11, v[14:15]
	v_mul_hi_i32_i24_e32 v17, 0x6000, v16
	v_mul_i32_i24_e32 v16, 0x6000, v16
	v_lshl_add_u64 v[18:19], s[46:47], 0, v[14:15]
	v_lshl_add_u64 v[20:21], s[8:9], 0, v[16:17]
	ds_read_b128 v[14:17], v0 offset:4608
	v_cvt_f32_f16_sdwa v37, v10 dst_sel:DWORD dst_unused:UNUSED_PAD src0_sel:WORD_1
	v_cvt_f32_f16_e32 v10, v11
	v_cvt_f32_f16_sdwa v11, v11 dst_sel:DWORD dst_unused:UNUSED_PAD src0_sel:WORD_1
	v_cvt_f32_f16_e32 v38, v12
	v_cvt_f32_f16_sdwa v39, v12 dst_sel:DWORD dst_unused:UNUSED_PAD src0_sel:WORD_1
	v_cvt_f32_f16_e32 v12, v13
	v_cvt_f32_f16_sdwa v13, v13 dst_sel:DWORD dst_unused:UNUSED_PAD src0_sel:WORD_1
	v_lshl_add_u64 v[26:27], v[18:19], 0, v[66:67]
	global_load_dwordx4 v[22:25], v[26:27], off
	s_waitcnt lgkmcnt(0)
	v_lshlrev_b32_e32 v32, 16, v14
	v_and_b32_e32 v33, 0xffff0000, v14
	v_lshlrev_b32_e32 v14, 16, v15
	v_and_b32_e32 v15, 0xffff0000, v15
	v_lshlrev_b32_e32 v34, 16, v16
	v_and_b32_e32 v35, 0xffff0000, v16
	v_lshlrev_b32_e32 v16, 16, v17
	v_and_b32_e32 v17, 0xffff0000, v17
	v_pk_mul_f32 v[36:37], v[36:37], s[30:31] op_sel_hi:[1,0]
	v_pk_mul_f32 v[10:11], v[10:11], s[30:31] op_sel_hi:[1,0]
	v_pk_mul_f32 v[38:39], v[38:39], s[30:31] op_sel_hi:[1,0]
	v_pk_mul_f32 v[12:13], v[12:13], s[30:31] op_sel_hi:[1,0]
	v_lshl_add_u64 v[30:31], v[20:21], 0, v[68:69]
	ds_read_b128 v[18:21], v0 offset:5760
	s_waitcnt vmcnt(2)
	v_pk_fma_f32 v[2:3], v[2:3], v[32:33], v[36:37]
	v_pk_fma_f32 v[4:5], v[4:5], v[14:15], v[10:11]
	v_cvt_pk_f16_f32 v2, v2, v3
	s_waitcnt vmcnt(1)
	v_pk_fma_f32 v[6:7], v[6:7], v[34:35], v[38:39]
	v_pk_fma_f32 v[8:9], v[8:9], v[16:17], v[12:13]
	v_cvt_pk_f16_f32 v3, v4, v5
	v_cvt_pk_f16_f32 v4, v6, v7
	v_cvt_pk_f16_f32 v5, v8, v9
	global_store_dwordx4 v[28:29], v[2:5], off
	global_load_dwordx4 v[2:5], v[30:31], off
	v_or_b32_e32 v10, s2, v76
	global_load_dwordx4 v[6:9], v[30:31], off offset:16
	v_min_i32_e32 v12, 0x8000, v10
	v_ashrrev_i32_e32 v11, 31, v10
	v_ashrrev_i32_e32 v12, 11, v12
	v_lshlrev_b64 v[10:11], 11, v[10:11]
	v_mul_hi_i32_i24_e32 v13, 0x6000, v12
	v_mul_i32_i24_e32 v12, 0x6000, v12
	v_lshl_add_u64 v[10:11], s[46:47], 0, v[10:11]
	v_lshl_add_u64 v[12:13], s[8:9], 0, v[12:13]
	v_lshl_add_u64 v[28:29], v[10:11], 0, v[66:67]
	v_lshl_add_u64 v[14:15], v[12:13], 0, v[68:69]
	s_waitcnt vmcnt(3)
;   DI void operator()(f32x16 (&acc)[2][MB], int wm, int wn, int r, int h) {
;     ...
;         for (int j = 0; j < 8; ++j) {
;           const int rowl = (lane >> 3) + 8 * j, ch = lane & 7;
;           if (rowl < ntok) {
;             const u32x4 yv = *(const u32x4*)(slab + rowl * 72 + ch * 8);
;             const int R = R0 + rowl;
;             const int mi = (R < NLAT) ? (R >> 11) : 16;
;             const int col = n0 + wn * 64 + ch * 8;
;             const float* g = gate + (size_t)mi * 6144 + col;
;             const f32x4n g0 = *(const f32x4n*)(g), g1 = *(const f32x4n*)(g + 4);
;             _Float16* xp = X + (size_t)R * 1024 + col;
;             const h8 xv = *(const h8*)xp;
;             const float y[8] = {__uint_as_float(yv.x << 16), __uint_as_float(yv.x & 0xffff0000u), __uint_as_float(yv.y << 16), __uint_as_float(yv.y & 0xffff0000u),
;                                 __uint_as_float(yv.z << 16), __uint_as_float(yv.z & 0xffff0000u), __uint_as_float(yv.w << 16), __uint_as_float(yv.w & 0xffff0000u)};
;             const float gg[8] = {g0.x, g0.y, g0.z, g0.w, g1.x, g1.y, g1.z, g1.w};
;             h8 o;
; #pragma unroll
;             for (int q = 0; q < 8; ++q) o[q] = (_Float16)(ALPHA * (float)xv[q] + gg[q] * y[q]);
;             *(h8*)xp = o;
;           }
;         }
;       }
;     }
;     __syncthreads();
	v_cvt_f32_f16_e32 v32, v22
	v_cvt_f32_f16_sdwa v33, v22 dst_sel:DWORD dst_unused:UNUSED_PAD src0_sel:WORD_1
	v_cvt_f32_f16_e32 v22, v23
	v_cvt_f32_f16_sdwa v23, v23 dst_sel:DWORD dst_unused:UNUSED_PAD src0_sel:WORD_1
	v_cvt_f32_f16_e32 v34, v24
	v_cvt_f32_f16_sdwa v35, v24 dst_sel:DWORD dst_unused:UNUSED_PAD src0_sel:WORD_1
	v_cvt_f32_f16_e32 v24, v25
	v_cvt_f32_f16_sdwa v25, v25 dst_sel:DWORD dst_unused:UNUSED_PAD src0_sel:WORD_1
	global_load_dwordx4 v[10:13], v[28:29], off
	s_waitcnt lgkmcnt(0)
	v_lshlrev_b32_e32 v16, 16, v18
	v_and_b32_e32 v17, 0xffff0000, v18
	v_lshlrev_b32_e32 v18, 16, v19
	v_and_b32_e32 v19, 0xffff0000, v19
	v_lshlrev_b32_e32 v30, 16, v20
	v_and_b32_e32 v31, 0xffff0000, v20
	v_lshlrev_b32_e32 v20, 16, v21
	v_and_b32_e32 v21, 0xffff0000, v21
	v_pk_mul_f32 v[32:33], v[32:33], s[30:31] op_sel_hi:[1,0]
	v_pk_mul_f32 v[22:23], v[22:23], s[30:31] op_sel_hi:[1,0]
	v_pk_mul_f32 v[34:35], v[34:35], s[30:31] op_sel_hi:[1,0]
	v_pk_mul_f32 v[24:25], v[24:25], s[30:31] op_sel_hi:[1,0]
	s_waitcnt vmcnt(2)
	v_pk_fma_f32 v[2:3], v[2:3], v[16:17], v[32:33]
	v_pk_fma_f32 v[4:5], v[4:5], v[18:19], v[22:23]
	s_waitcnt vmcnt(1)
	v_pk_fma_f32 v[6:7], v[6:7], v[30:31], v[34:35]
	v_pk_fma_f32 v[8:9], v[8:9], v[20:21], v[24:25]
	v_cvt_pk_f16_f32 v2, v2, v3
	v_cvt_pk_f16_f32 v3, v4, v5
	v_cvt_pk_f16_f32 v4, v6, v7
	v_cvt_pk_f16_f32 v5, v8, v9
	global_store_dwordx4 v[26:27], v[2:5], off
	global_load_dwordx4 v[2:5], v[14:15], off
	s_waitcnt vmcnt(2)
	v_cvt_f32_f16_e32 v36, v10
	global_load_dwordx4 v[6:9], v[14:15], off offset:16
	v_or_b32_e32 v14, s2, v77
	v_min_i32_e32 v16, 0x8000, v14
	v_ashrrev_i32_e32 v15, 31, v14
	v_ashrrev_i32_e32 v16, 11, v16
	v_lshlrev_b64 v[14:15], 11, v[14:15]
	v_mul_hi_i32_i24_e32 v17, 0x6000, v16
	v_mul_i32_i24_e32 v16, 0x6000, v16
	v_lshl_add_u64 v[18:19], s[46:47], 0, v[14:15]
	v_lshl_add_u64 v[20:21], s[8:9], 0, v[16:17]
	ds_read_b128 v[14:17], v0 offset:6912
	v_cvt_f32_f16_sdwa v37, v10 dst_sel:DWORD dst_unused:UNUSED_PAD src0_sel:WORD_1
	v_cvt_f32_f16_e32 v10, v11
	v_cvt_f32_f16_sdwa v11, v11 dst_sel:DWORD dst_unused:UNUSED_PAD src0_sel:WORD_1
	v_cvt_f32_f16_e32 v38, v12
	v_cvt_f32_f16_sdwa v39, v12 dst_sel:DWORD dst_unused:UNUSED_PAD src0_sel:WORD_1
	v_cvt_f32_f16_e32 v12, v13
	v_cvt_f32_f16_sdwa v13, v13 dst_sel:DWORD dst_unused:UNUSED_PAD src0_sel:WORD_1
	v_lshl_add_u64 v[26:27], v[18:19], 0, v[66:67]
	global_load_dwordx4 v[22:25], v[26:27], off
	s_waitcnt lgkmcnt(0)
	v_lshlrev_b32_e32 v32, 16, v14
	v_and_b32_e32 v33, 0xffff0000, v14
	v_lshlrev_b32_e32 v14, 16, v15
	v_and_b32_e32 v15, 0xffff0000, v15
	v_lshlrev_b32_e32 v34, 16, v16
	v_and_b32_e32 v35, 0xffff0000, v16
	v_lshlrev_b32_e32 v16, 16, v17
	v_and_b32_e32 v17, 0xffff0000, v17
	v_pk_mul_f32 v[36:37], v[36:37], s[30:31] op_sel_hi:[1,0]
	v_pk_mul_f32 v[10:11], v[10:11], s[30:31] op_sel_hi:[1,0]
	v_pk_mul_f32 v[38:39], v[38:39], s[30:31] op_sel_hi:[1,0]
	v_pk_mul_f32 v[12:13], v[12:13], s[30:31] op_sel_hi:[1,0]
	v_lshl_add_u64 v[30:31], v[20:21], 0, v[68:69]
	ds_read_b128 v[18:21], v0 offset:8064
	s_waitcnt vmcnt(2)
	v_pk_fma_f32 v[2:3], v[2:3], v[32:33], v[36:37]
	v_pk_fma_f32 v[4:5], v[4:5], v[14:15], v[10:11]
	v_cvt_pk_f16_f32 v2, v2, v3
	v_cvt_pk_f16_f32 v3, v4, v5
	s_waitcnt lgkmcnt(0)
	v_lshlrev_b32_e32 v10, 16, v18
	v_and_b32_e32 v11, 0xffff0000, v18
	v_lshlrev_b32_e32 v14, 16, v20
	v_and_b32_e32 v15, 0xffff0000, v20
	s_waitcnt vmcnt(1)
	v_pk_fma_f32 v[6:7], v[6:7], v[34:35], v[38:39]
	v_pk_fma_f32 v[8:9], v[8:9], v[16:17], v[12:13]
	v_cvt_pk_f16_f32 v4, v6, v7
	v_cvt_pk_f16_f32 v5, v8, v9
	global_store_dwordx4 v[28:29], v[2:5], off
	global_load_dwordx4 v[2:5], v[30:31], off
	v_lshlrev_b32_e32 v12, 16, v19
	global_load_dwordx4 v[6:9], v[30:31], off offset:16
	v_and_b32_e32 v13, 0xffff0000, v19
	v_lshlrev_b32_e32 v16, 16, v21
	v_and_b32_e32 v17, 0xffff0000, v21
	s_waitcnt vmcnt(3)
	v_cvt_f32_f16_e32 v18, v22
	v_cvt_f32_f16_sdwa v19, v22 dst_sel:DWORD dst_unused:UNUSED_PAD src0_sel:WORD_1
	v_cvt_f32_f16_e32 v20, v23
	v_cvt_f32_f16_sdwa v21, v23 dst_sel:DWORD dst_unused:UNUSED_PAD src0_sel:WORD_1
	v_cvt_f32_f16_e32 v22, v24
	v_cvt_f32_f16_sdwa v23, v24 dst_sel:DWORD dst_unused:UNUSED_PAD src0_sel:WORD_1
	v_cvt_f32_f16_e32 v24, v25
	v_cvt_f32_f16_sdwa v25, v25 dst_sel:DWORD dst_unused:UNUSED_PAD src0_sel:WORD_1
	v_pk_mul_f32 v[18:19], v[18:19], s[30:31] op_sel_hi:[1,0]
	v_pk_mul_f32 v[20:21], v[20:21], s[30:31] op_sel_hi:[1,0]
	v_pk_mul_f32 v[22:23], v[22:23], s[30:31] op_sel_hi:[1,0]
	v_pk_mul_f32 v[24:25], v[24:25], s[30:31] op_sel_hi:[1,0]
	s_waitcnt vmcnt(1)
	v_pk_fma_f32 v[2:3], v[2:3], v[10:11], v[18:19]
	v_pk_fma_f32 v[4:5], v[4:5], v[12:13], v[20:21]
	s_waitcnt vmcnt(0)
	v_pk_fma_f32 v[6:7], v[6:7], v[14:15], v[22:23]
	v_pk_fma_f32 v[8:9], v[8:9], v[16:17], v[24:25]
	v_cvt_pk_f16_f32 v2, v2, v3
	v_cvt_pk_f16_f32 v3, v4, v5
	v_cvt_pk_f16_f32 v4, v6, v7
	v_cvt_pk_f16_f32 v5, v8, v9
	global_store_dwordx4 v[26:27], v[2:5], off
	s_barrier
	s_branch .LBB0_654

; DI int tid() { int t; asm volatile("v_mov_b32 %0, %1" : "=v"(t) : "v"((int)threadIdx.x)); return t; }
; template <int MB, class Epi>
; DI void gemm_tile(const u16* __restrict__ A, int lda, int row0, int Mrows, const u16* __restrict__ Bt, int ldb, int K, char* smem, Epi& epi, int rot) {
;   char* As = smem;
;   char* Bs = smem + 65536;
;   const unsigned lds_base = (unsigned)(size_t)(lds_char*)smem;
;   const int t = tid(), lane = t & 63, w = __builtin_amdgcn_readfirstlane(t >> 6), wm = w >> 2, wn = w & 3, r = lane & 31, h = lane >> 5;
;   constexpr int NAJ = MB;
;   const int lr = t >> 3;
;   const int lch = (t & 7) ^ ((lr >> 1) & 7);
;   unsigned aoff[NAJ];
; #pragma unroll
;   for (int j = 0; j < NAJ; ++j) {
;     int gr = row0 + lr + 64 * j;
;     gr = gr < 0 ? 0 : (gr > Mrows - 1 ? Mrows - 1 : gr);
;     aoff[j] = (unsigned)gr * (unsigned)lda + lch * 8;
;   }
;   const u16* bp = Bt + (size_t)lr * ldb + lch * 8;
;   f32x16 acc[2][MB];
; #pragma unroll
;   for (int nb = 0; nb < 2; ++nb)
; #pragma unroll
;     for (int mb = 0; mb < MB; ++mb)
; #pragma unroll
;       for (int i = 0; i < 16; ++i) acc[nb][mb][i] = 0.f;
;   const int KT = K >> 6;
;   int kcur = rot % KT;
;     ...
;   GEMM_STAGE(0)
;   asm volatile("s_waitcnt vmcnt(0)" ::: "memory");
;   __syncthreads();
;   const int sw = (r >> 1) & 7;
;   int foff[4];
; #pragma unroll
;   for (int ks = 0; ks < 4; ++ks) foff[ks] = r * 128 + (((2 * ks + h) ^ sw) << 4);
;   bf8 af[2][MB], bfr[2][2];
;   {
;     const char* as0 = As + wm * (32 * MB) * 128;
;     const char* bs0 = Bs + wn * 64 * 128;
; #pragma unroll
;     for (int mb = 0; mb < MB; ++mb) af[0][mb] = *(const bf8*)(as0 + mb * 32 * 128 + foff[0]);
; #pragma unroll
;     for (int nb = 0; nb < 2; ++nb) bfr[0][nb] = *(const bf8*)(bs0 + nb * 32 * 128 + foff[0]);
;   }
;   const int kbase = rot % KT;
;   if (KT > 1) {
;     const int k1_ = (kbase + 1 >= KT) ? kbase + 1 - KT : kbase + 1;
;     const int ko_ = k1_ * 64;
; #pragma unroll
;     for (int pc = 0; pc < 3; ++pc) GEMM_PIECE(1, pc)
.LBB0_854:
	s_ashr_i32 s8, s0, 3
	s_lshr_b32 s9, s8, 30
	s_add_i32 s9, s8, s9
	s_ashr_i32 s9, s9, 2
	s_and_b32 s10, s0, 7
	s_lshl_b32 s11, s9, 3
	s_or_b32 s10, s11, s10
	s_cmpk_gt_i32 s10, 0xbf
	s_cbranch_scc1 .LBB0_853
	s_lshl_b32 s9, s9, 2
	s_sub_i32 s12, s8, s9
	v_mov_b32 v124, v163
	s_mul_i32 s8, s10, 0xc0
	v_lshrrev_b32_e32 v2, 4, v124
	s_mul_i32 s10, s12, 0xb0000
	v_ashrrev_i32_e32 v0, 3, v124
	v_xor_b32_e32 v2, v2, v124
	s_ashr_i32 s11, s10, 31
	v_add_u32_e32 v3, s8, v0
	v_lshlrev_b32_e32 v2, 3, v2
	s_lshl_b64 s[10:11], s[10:11], 1
	v_and_b32_e32 v4, 56, v2
	v_med3_i32 v2, v3, 0, v208
	s_add_u32 s16, s2, s10
	v_mul_u32_u24_e32 v2, 0xb00, v2
	s_movk_i32 s10, 0xffc0
	v_or_b32_e32 v5, v2, v4
	v_med3_i32 v2, v3, s10, v209
	v_mul_i32_i24_e32 v2, 0xb00, v2
	v_or_b32_e32 v2, v2, v4
	s_movk_i32 s10, 0xff80
	v_add_u32_e32 v118, 0x2c000, v2
	v_med3_i32 v2, v3, s10, v210
	v_mul_i32_i24_e32 v2, 0xb00, v2
	s_addc_u32 s17, s3, s11
	v_or_b32_e32 v2, v2, v4
	v_add_u32_e32 v122, 0x58000, v2
	v_mov_b64_e32 v[2:3], s[16:17]
	s_movk_i32 s13, 0x1600
	v_mad_i64_i32 v[2:3], s[16:17], v0, s13, v[2:3]
	s_mul_hi_i32 s13, s0, 0x2e8ba2e9
	s_lshr_b32 s14, s13, 31
	s_ashr_i32 s13, s13, 3
	s_add_i32 s13, s13, s14
	s_mul_i32 s13, s13, 44
	v_readfirstlane_b32 s11, v124
	s_sub_i32 s16, s0, s13
	s_bfe_u32 s9, s11, 0x20006
	s_ashr_i32 s10, s11, 8
	s_lshl_b32 s18, s16, 6
	s_lshl_b32 s11, s11, 4
	v_lshlrev_b32_e32 v0, 1, v4
	s_ashr_i32 s19, s18, 31
	s_and_b32 s14, s11, 0xfffffc00
	v_lshl_add_u64 v[120:121], v[2:3], 0, v[0:1]
	s_lshl_b64 s[18:19], s[18:19], 1
	s_add_i32 s17, s14, 0x10000
	v_lshl_add_u64 v[2:3], v[120:121], 0, s[18:19]
	s_add_u32 s18, s20, s18
	v_mov_b32_e32 v0, v5
	s_addc_u32 s19, s21, s19
	v_lshlrev_b64 v[4:5], 1, v[0:1]
	v_lshl_add_u64 v[6:7], s[18:19], 0, v[4:5]
	v_mov_b32_e32 v119, v1
	s_mov_b32 m0, s14
	s_nop 0
	global_load_lds_dwordx4 v[6:7], off
	v_lshlrev_b64 v[6:7], 1, v[118:119]
	v_lshl_add_u64 v[8:9], s[18:19], 0, v[6:7]
	v_mov_b32_e32 v123, v1
	s_add_i32 s11, s14, 0x2000
	s_mov_b32 m0, s11
	s_nop 0
	global_load_lds_dwordx4 v[8:9], off
	v_lshlrev_b64 v[8:9], 1, v[122:123]
	v_lshl_add_u64 v[10:11], s[18:19], 0, v[8:9]
	s_add_i32 s11, s14, 0x4000
	s_mov_b32 m0, s11
	s_nop 0
	global_load_lds_dwordx4 v[10:11], off
	s_mov_b32 m0, s17
	s_nop 0
	global_load_lds_dwordx4 v[2:3], off
	s_mov_b64 s[40:41], 0x58000
	s_add_i32 s11, s14, 0x12000
	v_lshl_add_u64 v[10:11], v[2:3], 0, s[40:41]
	s_mov_b32 m0, s11
	s_nop 0
	global_load_lds_dwordx4 v[10:11], off
	s_mov_b64 s[48:49], 0xb0000
	s_add_i32 s11, s14, 0x14000
	v_lshl_add_u64 v[10:11], v[2:3], 0, s[48:49]
	s_mov_b32 m0, s11
	s_nop 0
	global_load_lds_dwordx4 v[10:11], off
	s_mov_b64 s[54:55], 0x108000
	s_add_i32 s11, s14, 0x16000
	v_lshl_add_u64 v[2:3], v[2:3], 0, s[54:55]
	s_mov_b32 m0, s11
	s_nop 0
	global_load_lds_dwordx4 v[2:3], off
	s_lshl_b32 s11, s9, 13
	s_bitset1_b32 s11, 16
	s_cmp_lt_i32 s16, 43
	s_cselect_b32 s18, 0, 0xffffffd4
	s_add_i32 s18, s16, s18
	s_lshl_b32 s18, s18, 6
	v_lshrrev_b32_e32 v12, 5, v124
	v_and_b32_e32 v125, 31, v124
	v_bfe_u32 v2, v124, 1, 3
	s_add_i32 s18, s18, 64
	v_lshlrev_b32_e32 v3, 7, v125
	v_bitop3_b32 v10, v12, v2, 1 bitop3:0x6c
	s_ashr_i32 s19, s18, 31
	s_waitcnt vmcnt(0)
	v_bfe_u32 v126, v124, 5, 1
	v_lshl_or_b32 v10, v10, 4, v3
	s_mul_i32 s13, s10, 0x3000
	s_lshl_b64 s[18:19], s[18:19], 1
	v_bitop3_b32 v11, v126, v2, 2 bitop3:0x36
	v_or_b32_e32 v131, s13, v10
	s_add_u32 s18, s20, s18
	s_waitcnt vmcnt(0)
	s_barrier
	v_lshl_or_b32 v129, v11, 4, v3
	v_bitop3_b32 v11, v126, v2, 4 bitop3:0x36
	v_bitop3_b32 v2, v126, v2, 6 bitop3:0x36
	ds_read_b128 v[110:113], v131
	ds_read_b128 v[106:109], v131 offset:4096
	v_or_b32_e32 v130, s11, v10
	ds_read_b128 v[98:101], v131 offset:8192
	ds_read_b128 v[114:117], v130
	ds_read_b128 v[102:105], v130 offset:4096
	s_addc_u32 s19, s21, s19
	v_lshl_or_b32 v128, v11, 4, v3
	v_lshl_or_b32 v127, v2, 4, v3
	s_add_i32 s22, s14, 0x8000
	v_lshl_add_u64 v[2:3], s[18:19], 0, v[4:5]
	s_mov_b32 m0, s22
	s_nop 0
	global_load_lds_dwordx4 v[2:3], off
	v_lshl_add_u64 v[2:3], s[18:19], 0, v[6:7]
	s_add_i32 s22, s14, 0xa000
	s_mov_b32 m0, s22
	s_nop 0
	global_load_lds_dwordx4 v[2:3], off
	v_lshl_add_u64 v[2:3], s[18:19], 0, v[8:9]
	s_add_i32 s18, s14, 0xc000
	s_mov_b32 m0, s18
	s_nop 0
	global_load_lds_dwordx4 v[2:3], off
	v_mov_b32_e32 v34, 0
	s_mov_b32 s15, 0
	s_mov_b32 s22, 0
	v_mov_b32_e32 v35, v34
	v_mov_b32_e32 v36, v34
	v_mov_b32_e32 v37, v34
	v_mov_b32_e32 v38, v34
	v_mov_b32_e32 v39, v34
	v_mov_b32_e32 v40, v34
	v_mov_b32_e32 v41, v34
	v_mov_b32_e32 v42, v34
	v_mov_b32_e32 v43, v34
	v_mov_b32_e32 v44, v34
	v_mov_b32_e32 v45, v34
	v_mov_b32_e32 v46, v34
	v_mov_b32_e32 v47, v34
	v_mov_b32_e32 v48, v34
	v_mov_b32_e32 v49, v34
	v_mov_b32_e32 v66, v34
	v_mov_b32_e32 v67, v34
	v_mov_b32_e32 v68, v34
	v_mov_b32_e32 v69, v34
	v_mov_b32_e32 v70, v34
	v_mov_b32_e32 v71, v34
	v_mov_b32_e32 v72, v34
	v_mov_b32_e32 v73, v34
	v_mov_b32_e32 v74, v34
	v_mov_b32_e32 v75, v34
	v_mov_b32_e32 v76, v34
	v_mov_b32_e32 v77, v34
	v_mov_b32_e32 v78, v34
	v_mov_b32_e32 v79, v34
	v_mov_b32_e32 v80, v34
	v_mov_b32_e32 v81, v34
	v_mov_b32_e32 v2, v34
	v_mov_b32_e32 v3, v34
	v_mov_b32_e32 v4, v34
	v_mov_b32_e32 v5, v34
	v_mov_b32_e32 v6, v34
	v_mov_b32_e32 v7, v34
	v_mov_b32_e32 v8, v34
	v_mov_b32_e32 v9, v34
	v_mov_b32_e32 v10, v34
	v_mov_b32_e32 v11, v34
	v_mov_b32_e32 v12, v34
	v_mov_b32_e32 v13, v34
	v_mov_b32_e32 v14, v34
	v_mov_b32_e32 v15, v34
	v_mov_b32_e32 v16, v34
	v_mov_b32_e32 v17, v34
	v_mov_b32_e32 v82, v34
	v_mov_b32_e32 v83, v34
	v_mov_b32_e32 v84, v34
	v_mov_b32_e32 v85, v34
	v_mov_b32_e32 v86, v34
	v_mov_b32_e32 v87, v34
	v_mov_b32_e32 v88, v34
	v_mov_b32_e32 v89, v34
	v_mov_b32_e32 v90, v34
	v_mov_b32_e32 v91, v34
	v_mov_b32_e32 v92, v34
	v_mov_b32_e32 v93, v34
	v_mov_b32_e32 v94, v34
	v_mov_b32_e32 v95, v34
	v_mov_b32_e32 v96, v34
	v_mov_b32_e32 v97, v34
	v_mov_b32_e32 v50, v34
	v_mov_b32_e32 v51, v34
	v_mov_b32_e32 v52, v34
	v_mov_b32_e32 v53, v34
	v_mov_b32_e32 v54, v34
	v_mov_b32_e32 v55, v34
	v_mov_b32_e32 v56, v34
	v_mov_b32_e32 v57, v34
	v_mov_b32_e32 v58, v34
	v_mov_b32_e32 v59, v34
	v_mov_b32_e32 v60, v34
	v_mov_b32_e32 v61, v34
	v_mov_b32_e32 v62, v34
	v_mov_b32_e32 v63, v34
	v_mov_b32_e32 v64, v34
	v_mov_b32_e32 v65, v34
	v_mov_b32_e32 v18, v34
	v_mov_b32_e32 v19, v34
	v_mov_b32_e32 v20, v34
	v_mov_b32_e32 v21, v34
	v_mov_b32_e32 v22, v34
	v_mov_b32_e32 v23, v34
	v_mov_b32_e32 v24, v34
	v_mov_b32_e32 v25, v34
	v_mov_b32_e32 v26, v34
	v_mov_b32_e32 v27, v34
	v_mov_b32_e32 v28, v34
	v_mov_b32_e32 v29, v34
	v_mov_b32_e32 v30, v34
	v_mov_b32_e32 v31, v34
	v_mov_b32_e32 v32, v34
	v_mov_b32_e32 v33, v34
; template <int MB, class Epi>
; DI void gemm_tile(const u16* __restrict__ A, int lda, int row0, int Mrows, const u16* __restrict__ Bt, int ldb, int K, char* smem, Epi& epi, int rot) {
;     ...
;   for (int kt = 0; kt < KT; ++kt) {
;     const bool more = (kt + 1 < KT);
;     const bool more2 = (kt + 2 < KT);
;     const int nstg = (kt + 1) & 1;
;     const char* as = As + (kt & 1) * 32768 + wm * (32 * MB) * 128;
;     const char* bs = Bs + (kt & 1) * 32768 + wn * 64 * 128;
;     int k1_ = kbase + kt + 1; if (k1_ >= KT) k1_ -= KT;
;     int k2_ = kbase + kt + 2; if (k2_ >= KT) k2_ -= KT; if (k2_ >= KT) k2_ -= KT;
; #pragma unroll
;     for (int ks = 0; ks < 3; ++ks) {
; #pragma unroll
;       for (int idx = 0; idx < 2 * MB; ++idx) {
;         const int nb = idx / MB, mb = idx % MB;
;         acc[nb][mb] = mfma32(bfr[ks & 1][nb], af[ks & 1][mb], acc[nb][mb]);
;         if (idx < MB) af[(ks + 1) & 1][idx] = *(const bf8*)(as + idx * 32 * 128 + foff[ks + 1]);
;         else if (idx < MB + 2) bfr[(ks + 1) & 1][idx - MB] = *(const bf8*)(bs + (idx - MB) * 32 * 128 + foff[ks + 1]);
;         if (more && ks < 2 && idx < 3) {
;           const int ko_ = k1_ * 64;
;           GEMM_PIECE(nstg, 3 + ks * 3 + idx)
;         }
;         __builtin_amdgcn_sched_barrier(0);
;       }
;     }
;     if (more) {
;       asm volatile("s_waitcnt vmcnt(0)" ::: "memory");
;       __syncthreads();
;       if (more2) {
;         const int ko_ = k2_ * 64;
; #pragma unroll
;         for (int pc = 0; pc < 3; ++pc) GEMM_PIECE(kt & 1, pc)
;       }
;       __builtin_amdgcn_sched_barrier(0);
;       const char* asn = As + nstg * 32768 + wm * (32 * MB) * 128;
;       const char* bsn = Bs + nstg * 32768 + wn * 64 * 128;
; #pragma unroll
;       for (int mb = 0; mb < MB; ++mb) af[0][mb] = *(const bf8*)(asn + mb * 32 * 128 + foff[0]);
; #pragma unroll
;       for (int nb = 0; nb < 2; ++nb) bfr[0][nb] = *(const bf8*)(bsn + nb * 32 * 128 + foff[0]);
;     }
; #pragma unroll
;     for (int nb = 0; nb < 2; ++nb)
; #pragma unroll
;       for (int mb = 0; mb < MB; ++mb) acc[nb][mb] = mfma32(bfr[1][nb], af[1][mb], acc[nb][mb]);
; #pragma unroll
;     for (int gk = 0; gk < 2 * MB; ++gk) {
;       __builtin_amdgcn_sched_group_barrier(0x008, 1, 0);
;       __builtin_amdgcn_sched_group_barrier(0x100, 1, 0);
;     }
;     __builtin_amdgcn_sched_barrier(0);
;   }
.LBB0_856:
	s_and_b32 s23, s15, 0x8000
	s_add_i32 s19, s22, 1
	s_add_i32 s28, s13, s23
	s_add_i32 s25, s11, s23
	s_add_i32 s22, s16, s22
	s_cmp_lt_i32 s22, 43
	s_cselect_b32 s18, 0, 0xffffffd4
	s_waitcnt lgkmcnt(1)
	v_mfma_f32_32x32x16_bf16 v[66:81], v[114:117], v[110:113], v[66:81]
	s_add_i32 s18, s22, s18
	s_lshl_b32 s18, s18, 6
	s_add_i32 s26, s18, 64
	s_add_i32 s15, s15, 0x8000
	v_add_u32_e32 v144, s28, v129
	s_ashr_i32 s27, s26, 31
	s_and_b32 s18, s15, 0x8000
	ds_read_b128 v[132:135], v144
	v_lshl_add_u64 v[140:141], s[26:27], 1, v[120:121]
	s_add_i32 s26, s18, s17
	s_mov_b32 m0, s26
	s_nop 0
	global_load_lds_dwordx4 v[140:141], off
	v_mfma_f32_32x32x16_bf16 v[34:49], v[114:117], v[106:109], v[34:49]
	ds_read_b128 v[136:139], v144 offset:4096
	v_lshl_add_u64 v[142:143], v[140:141], 0, s[40:41]
	s_add_i32 s27, s26, 0x2000
	s_mov_b32 m0, s27
	s_nop 0
	global_load_lds_dwordx4 v[142:143], off
	v_mfma_f32_32x32x16_bf16 v[2:17], v[114:117], v[98:101], v[2:17]
	ds_read_b128 v[114:117], v144 offset:8192
	v_lshl_add_u64 v[142:143], v[140:141], 0, s[48:49]
	s_add_i32 s27, s26, 0x4000
	s_mov_b32 m0, s27
	s_nop 0
	global_load_lds_dwordx4 v[142:143], off
	s_waitcnt lgkmcnt(3)
	v_mfma_f32_32x32x16_bf16 v[82:97], v[102:105], v[110:113], v[82:97]
	v_add_u32_e32 v142, s25, v129
	ds_read_b128 v[110:113], v142
	v_mfma_f32_32x32x16_bf16 v[50:65], v[102:105], v[106:109], v[50:65]
	ds_read_b128 v[106:109], v142 offset:4096
	v_mfma_f32_32x32x16_bf16 v[18:33], v[102:105], v[98:101], v[18:33]
	s_waitcnt lgkmcnt(1)
	v_mfma_f32_32x32x16_bf16 v[66:81], v[110:113], v[132:135], v[66:81]
	v_add_u32_e32 v142, s28, v128
	ds_read_b128 v[98:101], v142
	v_lshl_add_u64 v[102:103], v[140:141], 0, s[54:55]
	s_addk_i32 s26, 0x6000
	s_mov_b32 m0, s26
	s_nop 0
	global_load_lds_dwordx4 v[102:103], off
	v_mfma_f32_32x32x16_bf16 v[34:49], v[110:113], v[136:139], v[34:49]
	ds_read_b128 v[102:105], v142 offset:4096
	v_mfma_f32_32x32x16_bf16 v[2:17], v[110:113], v[114:117], v[2:17]
	ds_read_b128 v[110:113], v142 offset:8192
	s_waitcnt lgkmcnt(3)
	v_mfma_f32_32x32x16_bf16 v[82:97], v[106:109], v[132:135], v[82:97]
	v_add_u32_e32 v140, s25, v128
	ds_read_b128 v[132:135], v140
	v_mfma_f32_32x32x16_bf16 v[50:65], v[106:109], v[136:139], v[50:65]
	ds_read_b128 v[136:139], v140 offset:4096
	v_mfma_f32_32x32x16_bf16 v[18:33], v[106:109], v[114:117], v[18:33]
	s_waitcnt lgkmcnt(1)
	v_mfma_f32_32x32x16_bf16 v[66:81], v[132:135], v[98:101], v[66:81]
	v_add_u32_e32 v106, s28, v127
	ds_read_b128 v[114:117], v106
	v_mfma_f32_32x32x16_bf16 v[34:49], v[132:135], v[102:105], v[34:49]
	ds_read_b128 v[140:143], v106 offset:4096
	v_mfma_f32_32x32x16_bf16 v[2:17], v[132:135], v[110:113], v[2:17]
	ds_read_b128 v[132:135], v106 offset:8192
	s_waitcnt lgkmcnt(3)
	v_mfma_f32_32x32x16_bf16 v[82:97], v[136:139], v[98:101], v[82:97]
	v_add_u32_e32 v106, s25, v127
	ds_read_b128 v[98:101], v106
	v_mfma_f32_32x32x16_bf16 v[50:65], v[136:139], v[102:105], v[50:65]
	ds_read_b128 v[144:147], v106 offset:4096
	v_mfma_f32_32x32x16_bf16 v[18:33], v[136:139], v[110:113], v[18:33]
	s_cmp_lt_i32 s22, 42
	s_cselect_b32 s25, 0, 0xffffffd4
	s_add_i32 s26, s22, s25
	s_add_i32 s26, s26, 2
	s_cmp_lt_i32 s26, 44
	s_cselect_b32 s26, 0, 0xffffffd4
	s_add_i32 s25, s25, s26
	s_add_i32 s22, s22, s25
	s_lshl_b32 s22, s22, 6
	s_add_i32 s26, s22, 0x80
	s_ashr_i32 s27, s26, 31
	s_lshl_b64 s[26:27], s[26:27], 1
	s_add_u32 s26, s20, s26
	s_addc_u32 s27, s21, s27
	s_waitcnt vmcnt(0)
	s_waitcnt lgkmcnt(0)
	s_barrier
	s_add_i32 s22, s23, s14
	v_lshl_add_u64 v[102:103], v[0:1], 1, s[26:27]
	s_mov_b32 m0, s22
	s_nop 0
	global_load_lds_dwordx4 v[102:103], off
	v_lshl_add_u64 v[102:103], v[118:119], 1, s[26:27]
	s_add_i32 s23, s22, 0x2000
	s_mov_b32 m0, s23
	s_nop 0
	global_load_lds_dwordx4 v[102:103], off
	v_lshl_add_u64 v[102:103], v[122:123], 1, s[26:27]
	s_addk_i32 s22, 0x4000
	s_mov_b32 m0, s22
	s_nop 0
	global_load_lds_dwordx4 v[102:103], off
	v_add_u32_e32 v102, s18, v131
	v_mfma_f32_32x32x16_bf16 v[66:81], v[98:101], v[114:117], v[66:81]
	ds_read_b128 v[110:113], v102
	v_mfma_f32_32x32x16_bf16 v[34:49], v[98:101], v[140:143], v[34:49]
	ds_read_b128 v[106:109], v102 offset:4096
	v_mfma_f32_32x32x16_bf16 v[2:17], v[98:101], v[132:135], v[2:17]
	ds_read_b128 v[98:101], v102 offset:8192
	v_add_u32_e32 v102, s18, v130
	v_mfma_f32_32x32x16_bf16 v[82:97], v[144:147], v[114:117], v[82:97]
	ds_read_b128 v[114:117], v102
	v_mfma_f32_32x32x16_bf16 v[50:65], v[144:147], v[140:143], v[50:65]
	ds_read_b128 v[102:105], v102 offset:4096
	v_mfma_f32_32x32x16_bf16 v[18:33], v[144:147], v[132:135], v[18:33]
	s_cmp_eq_u32 s19, 42
	s_mov_b32 s22, s19
	s_cbranch_scc0 .LBB0_856
; template <int MB, class Epi>
; DI void gemm_tile(const u16* __restrict__ A, int lda, int row0, int Mrows, const u16* __restrict__ Bt, int ldb, int K, char* smem, Epi& epi, int rot) {
;     ...
;   for (int kt = 0; kt < KT; ++kt) {
;     const bool more = (kt + 1 < KT);
;     const bool more2 = (kt + 2 < KT);
;     const int nstg = (kt + 1) & 1;
;     const char* as = As + (kt & 1) * 32768 + wm * (32 * MB) * 128;
;     const char* bs = Bs + (kt & 1) * 32768 + wn * 64 * 128;
;     int k1_ = kbase + kt + 1; if (k1_ >= KT) k1_ -= KT;
;     int k2_ = kbase + kt + 2; if (k2_ >= KT) k2_ -= KT; if (k2_ >= KT) k2_ -= KT;
; #pragma unroll
;     for (int ks = 0; ks < 3; ++ks) {
; #pragma unroll
;       for (int idx = 0; idx < 2 * MB; ++idx) {
;         const int nb = idx / MB, mb = idx % MB;
;         acc[nb][mb] = mfma32(bfr[ks & 1][nb], af[ks & 1][mb], acc[nb][mb]);
;         if (idx < MB) af[(ks + 1) & 1][idx] = *(const bf8*)(as + idx * 32 * 128 + foff[ks + 1]);
;         else if (idx < MB + 2) bfr[(ks + 1) & 1][idx - MB] = *(const bf8*)(bs + (idx - MB) * 32 * 128 + foff[ks + 1]);
;         if (more && ks < 2 && idx < 3) {
;           const int ko_ = k1_ * 64;
;           GEMM_PIECE(nstg, 3 + ks * 3 + idx)
;         }
;         __builtin_amdgcn_sched_barrier(0);
;       }
;     }
;     if (more) {
;       asm volatile("s_waitcnt vmcnt(0)" ::: "memory");
;       __syncthreads();
;       if (more2) {
;         const int ko_ = k2_ * 64;
; #pragma unroll
;         for (int pc = 0; pc < 3; ++pc) GEMM_PIECE(kt & 1, pc)
;       }
;       __builtin_amdgcn_sched_barrier(0);
;       const char* asn = As + nstg * 32768 + wm * (32 * MB) * 128;
;       const char* bsn = Bs + nstg * 32768 + wn * 64 * 128;
; #pragma unroll
;       for (int mb = 0; mb < MB; ++mb) af[0][mb] = *(const bf8*)(asn + mb * 32 * 128 + foff[0]);
; #pragma unroll
;       for (int nb = 0; nb < 2; ++nb) bfr[0][nb] = *(const bf8*)(bsn + nb * 32 * 128 + foff[0]);
;     }
; #pragma unroll
;     for (int nb = 0; nb < 2; ++nb)
; #pragma unroll
;       for (int mb = 0; mb < MB; ++mb) acc[nb][mb] = mfma32(bfr[1][nb], af[1][mb], acc[nb][mb]);
; #pragma unroll
;     for (int gk = 0; gk < 2 * MB; ++gk) {
;       __builtin_amdgcn_sched_group_barrier(0x008, 1, 0);
;       __builtin_amdgcn_sched_group_barrier(0x100, 1, 0);
;     }
;     __builtin_amdgcn_sched_barrier(0);
;   }
;   __syncthreads();
;   epi(acc, wm, wn, r, h);
; }
	s_add_i32 s15, s13, s18
	s_add_i32 s18, s11, s18
	s_add_i32 s16, s16, 42
	s_cmp_lt_i32 s16, 43
	s_cselect_b32 s17, 0, 0xffffffd4
	s_add_i32 s16, s16, s17
	s_lshl_b32 s16, s16, 6
	s_add_i32 s16, s16, 64
	s_ashr_i32 s17, s16, 31
	v_add_u32_e32 v0, s15, v129
	v_lshl_add_u64 v[122:123], s[16:17], 1, v[120:121]
	ds_read_b128 v[118:121], v0
	s_add_i32 s16, s14, 0x18000
	s_mov_b32 m0, s16
	s_nop 0
	global_load_lds_dwordx4 v[122:123], off
	s_waitcnt lgkmcnt(2)
	v_mfma_f32_32x32x16_bf16 v[66:81], v[114:117], v[110:113], v[66:81]
	ds_read_b128 v[132:135], v0 offset:4096
	v_lshl_add_u64 v[136:137], v[122:123], 0, s[40:41]
	s_add_i32 s16, s14, 0x1a000
	s_mov_b32 m0, s16
	s_nop 0
	global_load_lds_dwordx4 v[136:137], off
	v_mfma_f32_32x32x16_bf16 v[34:49], v[114:117], v[106:109], v[34:49]
	v_mfma_f32_32x32x16_bf16 v[2:17], v[114:117], v[98:101], v[2:17]
	ds_read_b128 v[114:117], v0 offset:8192
	v_lshl_add_u64 v[136:137], v[122:123], 0, s[48:49]
	s_add_i32 s16, s14, 0x1c000
	s_mov_b32 m0, s16
	s_nop 0
	global_load_lds_dwordx4 v[136:137], off
	v_add_u32_e32 v0, s18, v129
	s_waitcnt lgkmcnt(3)
	v_mfma_f32_32x32x16_bf16 v[82:97], v[102:105], v[110:113], v[82:97]
	ds_read_b128 v[110:113], v0
	v_mfma_f32_32x32x16_bf16 v[50:65], v[102:105], v[106:109], v[50:65]
	ds_read_b128 v[106:109], v0 offset:4096
	v_mfma_f32_32x32x16_bf16 v[18:33], v[102:105], v[98:101], v[18:33]
	v_add_u32_e32 v0, s15, v128
	ds_read_b128 v[98:101], v0
	v_lshl_add_u64 v[102:103], v[122:123], 0, s[54:55]
	s_add_i32 s14, s14, 0x1e000
	s_mov_b32 m0, s14
	s_nop 0
	global_load_lds_dwordx4 v[102:103], off
	s_waitcnt lgkmcnt(2)
	v_mfma_f32_32x32x16_bf16 v[66:81], v[110:113], v[118:121], v[66:81]
	ds_read_b128 v[102:105], v0 offset:4096
	v_mfma_f32_32x32x16_bf16 v[34:49], v[110:113], v[132:135], v[34:49]
	v_mfma_f32_32x32x16_bf16 v[2:17], v[110:113], v[114:117], v[2:17]
	ds_read_b128 v[110:113], v0 offset:8192
	v_add_u32_e32 v0, s18, v128
	s_waitcnt lgkmcnt(3)
	v_mfma_f32_32x32x16_bf16 v[82:97], v[106:109], v[118:121], v[82:97]
	ds_read_b128 v[118:121], v0
	v_mfma_f32_32x32x16_bf16 v[50:65], v[106:109], v[132:135], v[50:65]
	ds_read_b128 v[132:135], v0 offset:4096
	v_mfma_f32_32x32x16_bf16 v[18:33], v[106:109], v[114:117], v[18:33]
	v_add_u32_e32 v0, s15, v127
	ds_read_b128 v[106:109], v0
	s_waitcnt lgkmcnt(2)
	v_mfma_f32_32x32x16_bf16 v[66:81], v[118:121], v[98:101], v[66:81]
	ds_read_b128 v[114:117], v0 offset:4096
	v_mfma_f32_32x32x16_bf16 v[34:49], v[118:121], v[102:105], v[34:49]
	v_mfma_f32_32x32x16_bf16 v[2:17], v[118:121], v[110:113], v[2:17]
	ds_read_b128 v[118:121], v0 offset:8192
	v_add_u32_e32 v0, s18, v127
	s_waitcnt lgkmcnt(3)
	v_mfma_f32_32x32x16_bf16 v[82:97], v[132:135], v[98:101], v[82:97]
	ds_read_b128 v[98:101], v0
	v_mfma_f32_32x32x16_bf16 v[50:65], v[132:135], v[102:105], v[50:65]
	ds_read_b128 v[102:105], v0 offset:4096
	v_mfma_f32_32x32x16_bf16 v[18:33], v[132:135], v[110:113], v[18:33]
	s_waitcnt vmcnt(0)
	s_waitcnt lgkmcnt(0)
	s_barrier
	s_lshr_b32 s100, s0, 5
	s_lshl_b32 s100, s100, 3
	s_and_b32 s101, s0, 7
	s_or_b32 s100, s100, s101
	s_mul_i32 s100, s100, 0xc0
	s_lshr_b32 s101, s0, 3
	s_and_b32 s101, s101, 3
	s_lshl_b32 s101, s101, 9
	v_lshrrev_b32_e32 v237, 2, v163
	v_and_b32_e32 v238, 3, v163
	v_add_u32_e32 v237, s100, v237
	v_lshlrev_b32_e32 v237, 11, v237
	v_lshl_add_u32 v237, v238, 7, v237
	v_add_u32_e32 v237, s101, v237
	global_load_dword v255, v237, s[46:47]
	v_add_u32_e32 v237, 0x40000, v237
	global_load_dword v255, v237, s[46:47]
	v_mfma_f32_32x32x16_bf16 v[66:81], v[98:101], v[106:109], v[66:81]
	ds_read_b128 v[110:113], v131 offset:32768
	v_mfma_f32_32x32x16_bf16 v[34:49], v[98:101], v[114:117], v[34:49]
	ds_read_b128 v[132:135], v131 offset:36864
	v_mfma_f32_32x32x16_bf16 v[2:17], v[98:101], v[118:121], v[2:17]
	ds_read_b128 v[98:101], v131 offset:40960
	v_mfma_f32_32x32x16_bf16 v[82:97], v[102:105], v[106:109], v[82:97]
	ds_read_b128 v[106:109], v130 offset:32768
	v_mfma_f32_32x32x16_bf16 v[50:65], v[102:105], v[114:117], v[50:65]
	ds_read_b128 v[114:117], v130 offset:36864
	v_mfma_f32_32x32x16_bf16 v[18:33], v[102:105], v[118:121], v[18:33]
	v_add_u32_e32 v0, s13, v129
	ds_read_b128 v[102:105], v0 offset:32768
	s_lshl_b32 s12, s12, 8
	s_waitcnt lgkmcnt(2)
	v_mfma_f32_32x32x16_bf16 v[66:81], v[106:109], v[110:113], v[66:81]
	ds_read_b128 v[118:121], v0 offset:36864
	v_mfma_f32_32x32x16_bf16 v[34:49], v[106:109], v[132:135], v[34:49]
	v_mfma_f32_32x32x16_bf16 v[2:17], v[106:109], v[98:101], v[2:17]
	ds_read_b128 v[106:109], v0 offset:40960
	v_add_u32_e32 v0, s11, v129
	s_waitcnt lgkmcnt(3)
	v_mfma_f32_32x32x16_bf16 v[82:97], v[114:117], v[110:113], v[82:97]
	ds_read_b128 v[110:113], v0 offset:32768
	v_mfma_f32_32x32x16_bf16 v[50:65], v[114:117], v[132:135], v[50:65]
	ds_read_b128 v[130:133], v0 offset:36864
	v_mfma_f32_32x32x16_bf16 v[18:33], v[114:117], v[98:101], v[18:33]
	v_add_u32_e32 v0, s13, v128
	ds_read_b128 v[98:101], v0 offset:32768
	s_waitcnt lgkmcnt(2)
	v_mfma_f32_32x32x16_bf16 v[66:81], v[110:113], v[102:105], v[66:81]
	ds_read_b128 v[114:117], v0 offset:36864
	v_mfma_f32_32x32x16_bf16 v[34:49], v[110:113], v[118:121], v[34:49]
	v_mfma_f32_32x32x16_bf16 v[2:17], v[110:113], v[106:109], v[2:17]
	ds_read_b128 v[110:113], v0 offset:40960
	v_add_u32_e32 v0, s11, v128
	s_waitcnt lgkmcnt(3)
	v_mfma_f32_32x32x16_bf16 v[82:97], v[130:133], v[102:105], v[82:97]
	ds_read_b128 v[102:105], v0 offset:32768
	v_mfma_f32_32x32x16_bf16 v[50:65], v[130:133], v[118:121], v[50:65]
	ds_read_b128 v[118:121], v0 offset:36864
	v_mfma_f32_32x32x16_bf16 v[18:33], v[130:133], v[106:109], v[18:33]
	v_add_u32_e32 v0, s13, v127
	ds_read_b128 v[106:109], v0 offset:32768
	s_waitcnt lgkmcnt(2)
	v_mfma_f32_32x32x16_bf16 v[66:81], v[102:105], v[98:101], v[66:81]
	ds_read_b128 v[128:131], v0 offset:36864
	v_mfma_f32_32x32x16_bf16 v[34:49], v[102:105], v[114:117], v[34:49]
	v_mfma_f32_32x32x16_bf16 v[2:17], v[102:105], v[110:113], v[2:17]
	ds_read_b128 v[102:105], v0 offset:40960
	v_add_u32_e32 v0, s11, v127
	s_waitcnt lgkmcnt(3)
	v_mfma_f32_32x32x16_bf16 v[82:97], v[118:121], v[98:101], v[82:97]
	ds_read_b128 v[98:101], v0 offset:32768
	v_mfma_f32_32x32x16_bf16 v[50:65], v[118:121], v[114:117], v[50:65]
	ds_read_b128 v[114:117], v0 offset:36864
	v_mfma_f32_32x32x16_bf16 v[18:33], v[118:121], v[110:113], v[18:33]
	s_waitcnt lgkmcnt(1)
	v_mfma_f32_32x32x16_bf16 v[66:81], v[98:101], v[106:109], v[66:81]
	v_mfma_f32_32x32x16_bf16 v[34:49], v[98:101], v[128:131], v[34:49]
	v_mfma_f32_32x32x16_bf16 v[2:17], v[98:101], v[102:105], v[2:17]
	s_waitcnt lgkmcnt(0)
	v_mfma_f32_32x32x16_bf16 v[82:97], v[114:117], v[106:109], v[82:97]
	v_mfma_f32_32x32x16_bf16 v[50:65], v[114:117], v[128:131], v[50:65]
	v_mfma_f32_32x32x16_bf16 v[18:33], v[114:117], v[102:105], v[18:33]
	s_waitcnt lgkmcnt(0)
	s_barrier
; DI unsigned pack2(float a, float b) { f2 v = {a, b}; bf2 r = __builtin_convertvector(v, bf2); return __builtin_bit_cast(unsigned, r); }
;   DI void operator()(f32x16 (&acc)[2][MB], int wm, int wn, int r, int h) {
;     u16* slab = ostage + (wm * 4 + wn) * (64 * 72);
;     const int lane = h * 32 + r;
; #pragma unroll
;     for (int mb = 0; mb < MB; ++mb) {
;       const int tokl = (mb & 1) * 32 + r;
; #pragma unroll
;       for (int nb = 0; nb < 2; ++nb)
; #pragma unroll
;         for (int ig = 0; ig < 4; ++ig) {
;           u32x2 o;
;           o.x = pack2(acc[nb][mb][ig * 4 + 0], acc[nb][mb][ig * 4 + 1]);
;           o.y = pack2(acc[nb][mb][ig * 4 + 2], acc[nb][mb][ig * 4 + 3]);
;           *(u32x2*)(slab + tokl * 72 + nb * 32 + ig * 8 + h * 4) = o;
;         }
;       if ((mb & 1) || mb == MB - 1) {
;         asm volatile("s_waitcnt lgkmcnt(0)" ::: "memory");
;         const int ntok = (mb & 1) ? 64 : 32;
;         const int R0 = row0 + wm * (32 * MB) + (mb >> 1) * 64;
; #pragma unroll
;         for (int j = 0; j < 8; ++j) {
;           const int rowl = (lane >> 3) + 8 * j, ch = lane & 7;
;           if (rowl < ntok) {
;             const u32x4 yv = *(const u32x4*)(slab + rowl * 72 + ch * 8);
;             const int R = R0 + rowl;
;             const int mi = (R < NLAT) ? (R >> 11) : 16;
;             const int col = n0 + wn * 64 + ch * 8;
;             const float* g = gate + (size_t)mi * 6144 + col;
;             const f32x4n g0 = *(const f32x4n*)(g), g1 = *(const f32x4n*)(g + 4);
;             _Float16* xp = X + (size_t)R * 1024 + col;
	s_lshr_b32 s100, s0, 5
	s_lshl_b32 s100, s100, 3
	s_and_b32 s101, s0, 7
	s_or_b32 s100, s100, s101
	s_mul_i32 s100, s100, 0xc0
	v_readfirstlane_b32 s101, v163
	s_lshr_b32 s101, s101, 6
	s_mul_i32 s11, s101, 0x2400
	v_and_b32_e32 v0, 63, v163
	v_and_b32_e32 v250, 31, v0
	v_lshrrev_b32_e32 v251, 5, v0
	v_mul_u32_u24_e32 v237, 0x90, v250
	v_lshl_add_u32 v237, v251, 3, v237
	v_add_u32_e32 v237, s11, v237
	v_lshrrev_b32_e32 v252, 3, v0
	v_and_b32_e32 v0, 7, v0
	v_mul_u32_u24_e32 v238, 0x90, v252
	v_lshl_add_u32 v238, v0, 4, v238
	v_add_u32_e32 v238, s11, v238
	s_mul_i32 s11, s101, 0x1200
	s_add_i32 s11, s11, 0x12000
	v_mul_u32_u24_e32 v242, 0x90, v250
	v_lshl_add_u32 v242, v251, 3, v242
	v_add_u32_e32 v242, s11, v242
	v_mul_u32_u24_e32 v243, 0x90, v252
	v_lshl_add_u32 v243, v0, 4, v243
	v_add_u32_e32 v243, s11, v243
	s_lshr_b32 s11, s101, 2
	s_mul_i32 s11, s11, 0x60
	s_add_i32 s100, s100, s11
	s_and_b32 s11, s101, 3
	s_lshl_b32 s11, s11, 6
	s_lshr_b32 s101, s0, 3
	s_and_b32 s101, s101, 3
	s_lshl_b32 s101, s101, 8
	s_add_i32 s11, s11, s101
	v_lshl_add_u32 v240, v0, 3, s11
	v_add_u32_e32 v241, s100, v252
	v_lshlrev_b32_e32 v239, 11, v241
	v_lshl_add_u32 v239, v240, 1, v239
	v_lshlrev_b32_e32 v240, 2, v240
	v_min_i32_e32 v246, 0x8000, v241
	v_ashrrev_i32_e32 v246, 11, v246
	v_mul_u32_u24_e32 v245, 0x6000, v246
	v_add_u32_e32 v245, v245, v240
	global_load_dwordx4 v[98:101], v245, s[36:37]
	global_load_dwordx4 v[102:105], v245, s[36:37] offset:16
	v_add_u32_e32 v247, 56, v241
	v_min_i32_e32 v247, 0x8000, v247
	v_ashrrev_i32_e32 v247, 11, v247
	v_mul_u32_u24_e32 v245, 0x6000, v247
	v_add_u32_e32 v245, v245, v240
	global_load_dwordx4 v[106:109], v245, s[36:37]
	global_load_dwordx4 v[110:113], v245, s[36:37] offset:16
	global_load_dwordx4 v[114:117], v239, s[46:47]
	v_add_u32_e32 v245, 0x4000, v239
	global_load_dwordx4 v[118:121], v245, s[46:47]
	v_add_u32_e32 v245, 0x8000, v239
	global_load_dwordx4 v[122:125], v245, s[46:47]
	v_add_u32_e32 v245, 0xc000, v239
	global_load_dwordx4 v[126:129], v245, s[46:47]
	v_cvt_pk_bf16_f32 v66, v66, v67
	v_cvt_pk_bf16_f32 v67, v68, v69
	v_cvt_pk_bf16_f32 v68, v70, v71
	v_cvt_pk_bf16_f32 v69, v72, v73
	v_cvt_pk_bf16_f32 v70, v74, v75
	v_cvt_pk_bf16_f32 v71, v76, v77
	v_cvt_pk_bf16_f32 v72, v78, v79
	v_cvt_pk_bf16_f32 v73, v80, v81
	ds_write2_b64 v237, v[66:67], v[68:69] offset0:0 offset1:2
	ds_write2_b64 v237, v[70:71], v[72:73] offset0:4 offset1:6
	v_cvt_pk_bf16_f32 v82, v82, v83
	v_cvt_pk_bf16_f32 v83, v84, v85
	v_cvt_pk_bf16_f32 v84, v86, v87
	v_cvt_pk_bf16_f32 v85, v88, v89
	v_cvt_pk_bf16_f32 v86, v90, v91
	v_cvt_pk_bf16_f32 v87, v92, v93
	v_cvt_pk_bf16_f32 v88, v94, v95
	v_cvt_pk_bf16_f32 v89, v96, v97
	ds_write2_b64 v237, v[82:83], v[84:85] offset0:8 offset1:10
	ds_write2_b64 v237, v[86:87], v[88:89] offset0:12 offset1:14
	v_add_u32_e32 v245, 0x10000, v239
	global_load_dwordx4 v[66:69], v245, s[46:47]
	v_add_u32_e32 v245, 0x14000, v239
	global_load_dwordx4 v[70:73], v245, s[46:47]
	v_add_u32_e32 v245, 0x18000, v239
	global_load_dwordx4 v[74:77], v245, s[46:47]
	v_add_u32_e32 v245, 0x1c000, v239
	global_load_dwordx4 v[78:81], v245, s[46:47]
	v_add_u32_e32 v244, 0x1200, v237
	v_cvt_pk_bf16_f32 v34, v34, v35
	v_cvt_pk_bf16_f32 v35, v36, v37
	v_cvt_pk_bf16_f32 v36, v38, v39
	v_cvt_pk_bf16_f32 v37, v40, v41
	v_cvt_pk_bf16_f32 v38, v42, v43
	v_cvt_pk_bf16_f32 v39, v44, v45
	v_cvt_pk_bf16_f32 v40, v46, v47
	v_cvt_pk_bf16_f32 v41, v48, v49
	ds_write2_b64 v244, v[34:35], v[36:37] offset0:0 offset1:2
	ds_write2_b64 v244, v[38:39], v[40:41] offset0:4 offset1:6
	v_cvt_pk_bf16_f32 v50, v50, v51
	v_cvt_pk_bf16_f32 v51, v52, v53
	v_cvt_pk_bf16_f32 v52, v54, v55
	v_cvt_pk_bf16_f32 v53, v56, v57
	v_cvt_pk_bf16_f32 v54, v58, v59
	v_cvt_pk_bf16_f32 v55, v60, v61
	v_cvt_pk_bf16_f32 v56, v62, v63
	v_cvt_pk_bf16_f32 v57, v64, v65
	ds_write2_b64 v244, v[50:51], v[52:53] offset0:8 offset1:10
	ds_write2_b64 v244, v[54:55], v[56:57] offset0:12 offset1:14
	v_add_u32_e32 v248, 64, v241
	v_min_i32_e32 v248, 0x8000, v248
	v_ashrrev_i32_e32 v248, 11, v248
	v_mul_u32_u24_e32 v245, 0x6000, v248
	v_add_u32_e32 v245, v245, v240
	global_load_dwordx4 v[34:37], v245, s[36:37]
	global_load_dwordx4 v[38:41], v245, s[36:37] offset:16
	v_add_u32_e32 v249, 88, v241
	v_min_i32_e32 v249, 0x8000, v249
	v_ashrrev_i32_e32 v249, 11, v249
	v_mul_u32_u24_e32 v245, 0x6000, v249
	v_add_u32_e32 v245, v245, v240
	global_load_dwordx4 v[42:45], v245, s[36:37]
	global_load_dwordx4 v[46:49], v245, s[36:37] offset:16
	v_add_u32_e32 v245, 0x20000, v239
	global_load_dwordx4 v[50:53], v245, s[46:47]
	v_add_u32_e32 v245, 0x24000, v239
	global_load_dwordx4 v[54:57], v245, s[46:47]
	v_add_u32_e32 v245, 0x28000, v239
	global_load_dwordx4 v[58:61], v245, s[46:47]
	v_add_u32_e32 v245, 0x2c000, v239
	global_load_dwordx4 v[62:65], v245, s[46:47]
	v_cvt_pk_bf16_f32 v2, v2, v3
	v_cvt_pk_bf16_f32 v3, v4, v5
	v_cvt_pk_bf16_f32 v4, v6, v7
	v_cvt_pk_bf16_f32 v5, v8, v9
	v_cvt_pk_bf16_f32 v6, v10, v11
	v_cvt_pk_bf16_f32 v7, v12, v13
	v_cvt_pk_bf16_f32 v8, v14, v15
	v_cvt_pk_bf16_f32 v9, v16, v17
	ds_write2_b64 v242, v[2:3], v[4:5] offset0:0 offset1:2
	ds_write2_b64 v242, v[6:7], v[8:9] offset0:4 offset1:6
	v_cvt_pk_bf16_f32 v18, v18, v19
	v_cvt_pk_bf16_f32 v19, v20, v21
	v_cvt_pk_bf16_f32 v20, v22, v23
	v_cvt_pk_bf16_f32 v21, v24, v25
	v_cvt_pk_bf16_f32 v22, v26, v27
	v_cvt_pk_bf16_f32 v23, v28, v29
	v_cvt_pk_bf16_f32 v24, v30, v31
	v_cvt_pk_bf16_f32 v25, v32, v33
	ds_write2_b64 v242, v[18:19], v[20:21] offset0:8 offset1:10
	ds_write2_b64 v242, v[22:23], v[24:25] offset0:12 offset1:14
	v_cmp_ne_u32_e32 vcc, v246, v247
	s_cbranch_vccnz .Lres1_slowA
;   DI void operator()(f32x16 (&acc)[2][MB], int wm, int wn, int r, int h) {
;     ...
;         for (int j = 0; j < 8; ++j) {
;           const int rowl = (lane >> 3) + 8 * j, ch = lane & 7;
;           if (rowl < ntok) {
;             const u32x4 yv = *(const u32x4*)(slab + rowl * 72 + ch * 8);
;             const int R = R0 + rowl;
;             const int mi = (R < NLAT) ? (R >> 11) : 16;
;             const int col = n0 + wn * 64 + ch * 8;
;             const float* g = gate + (size_t)mi * 6144 + col;
;             const f32x4n g0 = *(const f32x4n*)(g), g1 = *(const f32x4n*)(g + 4);
;             _Float16* xp = X + (size_t)R * 1024 + col;
;             const h8 xv = *(const h8*)xp;
;             const float y[8] = {__uint_as_float(yv.x << 16), __uint_as_float(yv.x & 0xffff0000u), __uint_as_float(yv.y << 16), __uint_as_float(yv.y & 0xffff0000u),
;                                 __uint_as_float(yv.z << 16), __uint_as_float(yv.z & 0xffff0000u), __uint_as_float(yv.w << 16), __uint_as_float(yv.w & 0xffff0000u)};
;             const float gg[8] = {g0.x, g0.y, g0.z, g0.w, g1.x, g1.y, g1.z, g1.w};
;             h8 o;
; #pragma unroll
;             for (int q = 0; q < 8; ++q) o[q] = (_Float16)(ALPHA * (float)xv[q] + gg[q] * y[q]);
;             *(h8*)xp = o;
	ds_read_b128 v[2:5], v238
	ds_read_b128 v[6:9], v238 offset:1152
	s_waitcnt vmcnt(15) lgkmcnt(1)
	v_lshlrev_b32_e32 v10, 16, v2
	v_and_b32_e32 v11, 0xffff0000, v2
	v_lshlrev_b32_e32 v12, 16, v3
	v_and_b32_e32 v13, 0xffff0000, v3
	v_lshlrev_b32_e32 v14, 16, v4
	v_and_b32_e32 v15, 0xffff0000, v4
	v_lshlrev_b32_e32 v16, 16, v5
	v_and_b32_e32 v17, 0xffff0000, v5
	ds_read_b128 v[2:5], v238 offset:2304
	v_cvt_f32_f16_e32 v18, v114
	v_cvt_f32_f16_sdwa v19, v114 dst_sel:DWORD dst_unused:UNUSED_PAD src0_sel:WORD_1
	v_cvt_f32_f16_e32 v20, v115
	v_cvt_f32_f16_sdwa v21, v115 dst_sel:DWORD dst_unused:UNUSED_PAD src0_sel:WORD_1
	v_cvt_f32_f16_e32 v22, v116
	v_cvt_f32_f16_sdwa v23, v116 dst_sel:DWORD dst_unused:UNUSED_PAD src0_sel:WORD_1
	v_cvt_f32_f16_e32 v24, v117
	v_cvt_f32_f16_sdwa v25, v117 dst_sel:DWORD dst_unused:UNUSED_PAD src0_sel:WORD_1
	v_pk_mul_f32 v[18:19], v[18:19], s[30:31] op_sel_hi:[1,0]
	v_pk_mul_f32 v[20:21], v[20:21], s[30:31] op_sel_hi:[1,0]
	v_pk_mul_f32 v[22:23], v[22:23], s[30:31] op_sel_hi:[1,0]
	v_pk_mul_f32 v[24:25], v[24:25], s[30:31] op_sel_hi:[1,0]
	v_pk_fma_f32 v[18:19], v[98:99], v[10:11], v[18:19]
	v_pk_fma_f32 v[20:21], v[100:101], v[12:13], v[20:21]
	v_pk_fma_f32 v[22:23], v[102:103], v[14:15], v[22:23]
	v_pk_fma_f32 v[24:25], v[104:105], v[16:17], v[24:25]
	v_cvt_pk_f16_f32 v114, v18, v19
	v_cvt_pk_f16_f32 v115, v20, v21
	v_cvt_pk_f16_f32 v116, v22, v23
	v_cvt_pk_f16_f32 v117, v24, v25
	global_store_dwordx4 v239, v[114:117], s[46:47]
	s_waitcnt vmcnt(15) lgkmcnt(1)
	v_lshlrev_b32_e32 v10, 16, v6
	v_and_b32_e32 v11, 0xffff0000, v6
	v_lshlrev_b32_e32 v12, 16, v7
	v_and_b32_e32 v13, 0xffff0000, v7
	v_lshlrev_b32_e32 v14, 16, v8
	v_and_b32_e32 v15, 0xffff0000, v8
	v_lshlrev_b32_e32 v16, 16, v9
	v_and_b32_e32 v17, 0xffff0000, v9
	ds_read_b128 v[6:9], v238 offset:3456
	v_add_u32_e32 v0, 0x4000, v239
	v_cvt_f32_f16_e32 v18, v118
	v_cvt_f32_f16_sdwa v19, v118 dst_sel:DWORD dst_unused:UNUSED_PAD src0_sel:WORD_1
	v_cvt_f32_f16_e32 v20, v119
	v_cvt_f32_f16_sdwa v21, v119 dst_sel:DWORD dst_unused:UNUSED_PAD src0_sel:WORD_1
	v_cvt_f32_f16_e32 v22, v120
	v_cvt_f32_f16_sdwa v23, v120 dst_sel:DWORD dst_unused:UNUSED_PAD src0_sel:WORD_1
	v_cvt_f32_f16_e32 v24, v121
	v_cvt_f32_f16_sdwa v25, v121 dst_sel:DWORD dst_unused:UNUSED_PAD src0_sel:WORD_1
	v_pk_mul_f32 v[18:19], v[18:19], s[30:31] op_sel_hi:[1,0]
	v_pk_mul_f32 v[20:21], v[20:21], s[30:31] op_sel_hi:[1,0]
	v_pk_mul_f32 v[22:23], v[22:23], s[30:31] op_sel_hi:[1,0]
	v_pk_mul_f32 v[24:25], v[24:25], s[30:31] op_sel_hi:[1,0]
	v_pk_fma_f32 v[18:19], v[98:99], v[10:11], v[18:19]
	v_pk_fma_f32 v[20:21], v[100:101], v[12:13], v[20:21]
	v_pk_fma_f32 v[22:23], v[102:103], v[14:15], v[22:23]
	v_pk_fma_f32 v[24:25], v[104:105], v[16:17], v[24:25]
	v_cvt_pk_f16_f32 v118, v18, v19
	v_cvt_pk_f16_f32 v119, v20, v21
	v_cvt_pk_f16_f32 v120, v22, v23
	v_cvt_pk_f16_f32 v121, v24, v25
	global_store_dwordx4 v0, v[118:121], s[46:47]
	s_waitcnt vmcnt(15) lgkmcnt(1)
	v_lshlrev_b32_e32 v10, 16, v2
	v_and_b32_e32 v11, 0xffff0000, v2
	v_lshlrev_b32_e32 v12, 16, v3
	v_and_b32_e32 v13, 0xffff0000, v3
	v_lshlrev_b32_e32 v14, 16, v4
	v_and_b32_e32 v15, 0xffff0000, v4
	v_lshlrev_b32_e32 v16, 16, v5
	v_and_b32_e32 v17, 0xffff0000, v5
	ds_read_b128 v[2:5], v238 offset:4608
	v_add_u32_e32 v0, 0x8000, v239
	v_cvt_f32_f16_e32 v18, v122
	v_cvt_f32_f16_sdwa v19, v122 dst_sel:DWORD dst_unused:UNUSED_PAD src0_sel:WORD_1
	v_cvt_f32_f16_e32 v20, v123
	v_cvt_f32_f16_sdwa v21, v123 dst_sel:DWORD dst_unused:UNUSED_PAD src0_sel:WORD_1
	v_cvt_f32_f16_e32 v22, v124
	v_cvt_f32_f16_sdwa v23, v124 dst_sel:DWORD dst_unused:UNUSED_PAD src0_sel:WORD_1
	v_cvt_f32_f16_e32 v24, v125
	v_cvt_f32_f16_sdwa v25, v125 dst_sel:DWORD dst_unused:UNUSED_PAD src0_sel:WORD_1
	v_pk_mul_f32 v[18:19], v[18:19], s[30:31] op_sel_hi:[1,0]
	v_pk_mul_f32 v[20:21], v[20:21], s[30:31] op_sel_hi:[1,0]
	v_pk_mul_f32 v[22:23], v[22:23], s[30:31] op_sel_hi:[1,0]
	v_pk_mul_f32 v[24:25], v[24:25], s[30:31] op_sel_hi:[1,0]
	v_pk_fma_f32 v[18:19], v[98:99], v[10:11], v[18:19]
	v_pk_fma_f32 v[20:21], v[100:101], v[12:13], v[20:21]
	v_pk_fma_f32 v[22:23], v[102:103], v[14:15], v[22:23]
	v_pk_fma_f32 v[24:25], v[104:105], v[16:17], v[24:25]
	v_cvt_pk_f16_f32 v122, v18, v19
	v_cvt_pk_f16_f32 v123, v20, v21
	v_cvt_pk_f16_f32 v124, v22, v23
	v_cvt_pk_f16_f32 v125, v24, v25
	global_store_dwordx4 v0, v[122:125], s[46:47]
	s_waitcnt vmcnt(15) lgkmcnt(1)
	v_lshlrev_b32_e32 v10, 16, v6
	v_and_b32_e32 v11, 0xffff0000, v6
	v_lshlrev_b32_e32 v12, 16, v7
	v_and_b32_e32 v13, 0xffff0000, v7
	v_lshlrev_b32_e32 v14, 16, v8
	v_and_b32_e32 v15, 0xffff0000, v8
	v_lshlrev_b32_e32 v16, 16, v9
	v_and_b32_e32 v17, 0xffff0000, v9
	ds_read_b128 v[6:9], v238 offset:5760
	v_add_u32_e32 v0, 0xc000, v239
	v_cvt_f32_f16_e32 v18, v126
	v_cvt_f32_f16_sdwa v19, v126 dst_sel:DWORD dst_unused:UNUSED_PAD src0_sel:WORD_1
	v_cvt_f32_f16_e32 v20, v127
	v_cvt_f32_f16_sdwa v21, v127 dst_sel:DWORD dst_unused:UNUSED_PAD src0_sel:WORD_1
	v_cvt_f32_f16_e32 v22, v128
	v_cvt_f32_f16_sdwa v23, v128 dst_sel:DWORD dst_unused:UNUSED_PAD src0_sel:WORD_1
	v_cvt_f32_f16_e32 v24, v129
	v_cvt_f32_f16_sdwa v25, v129 dst_sel:DWORD dst_unused:UNUSED_PAD src0_sel:WORD_1
	v_pk_mul_f32 v[18:19], v[18:19], s[30:31] op_sel_hi:[1,0]
	v_pk_mul_f32 v[20:21], v[20:21], s[30:31] op_sel_hi:[1,0]
	v_pk_mul_f32 v[22:23], v[22:23], s[30:31] op_sel_hi:[1,0]
	v_pk_mul_f32 v[24:25], v[24:25], s[30:31] op_sel_hi:[1,0]
	v_pk_fma_f32 v[18:19], v[98:99], v[10:11], v[18:19]
	v_pk_fma_f32 v[20:21], v[100:101], v[12:13], v[20:21]
	v_pk_fma_f32 v[22:23], v[102:103], v[14:15], v[22:23]
	v_pk_fma_f32 v[24:25], v[104:105], v[16:17], v[24:25]
	v_cvt_pk_f16_f32 v126, v18, v19
	v_cvt_pk_f16_f32 v127, v20, v21
	v_cvt_pk_f16_f32 v128, v22, v23
	v_cvt_pk_f16_f32 v129, v24, v25
	global_store_dwordx4 v0, v[126:129], s[46:47]
	s_waitcnt vmcnt(15) lgkmcnt(1)
;   DI void operator()(f32x16 (&acc)[2][MB], int wm, int wn, int r, int h) {
;     ...
;         for (int j = 0; j < 8; ++j) {
;           const int rowl = (lane >> 3) + 8 * j, ch = lane & 7;
;           if (rowl < ntok) {
;             const u32x4 yv = *(const u32x4*)(slab + rowl * 72 + ch * 8);
;             const int R = R0 + rowl;
;             const int mi = (R < NLAT) ? (R >> 11) : 16;
;             const int col = n0 + wn * 64 + ch * 8;
;             const float* g = gate + (size_t)mi * 6144 + col;
;             const f32x4n g0 = *(const f32x4n*)(g), g1 = *(const f32x4n*)(g + 4);
;             _Float16* xp = X + (size_t)R * 1024 + col;
;             const h8 xv = *(const h8*)xp;
;             const float y[8] = {__uint_as_float(yv.x << 16), __uint_as_float(yv.x & 0xffff0000u), __uint_as_float(yv.y << 16), __uint_as_float(yv.y & 0xffff0000u),
;                                 __uint_as_float(yv.z << 16), __uint_as_float(yv.z & 0xffff0000u), __uint_as_float(yv.w << 16), __uint_as_float(yv.w & 0xffff0000u)};
;             const float gg[8] = {g0.x, g0.y, g0.z, g0.w, g1.x, g1.y, g1.z, g1.w};
;             h8 o;
; #pragma unroll
;             for (int q = 0; q < 8; ++q) o[q] = (_Float16)(ALPHA * (float)xv[q] + gg[q] * y[q]);
;             *(h8*)xp = o;
	v_lshlrev_b32_e32 v10, 16, v2
	v_and_b32_e32 v11, 0xffff0000, v2
	v_lshlrev_b32_e32 v12, 16, v3
	v_and_b32_e32 v13, 0xffff0000, v3
	v_lshlrev_b32_e32 v14, 16, v4
	v_and_b32_e32 v15, 0xffff0000, v4
	v_lshlrev_b32_e32 v16, 16, v5
	v_and_b32_e32 v17, 0xffff0000, v5
	ds_read_b128 v[2:5], v238 offset:6912
	v_add_u32_e32 v0, 0x10000, v239
	v_cvt_f32_f16_e32 v18, v66
	v_cvt_f32_f16_sdwa v19, v66 dst_sel:DWORD dst_unused:UNUSED_PAD src0_sel:WORD_1
	v_cvt_f32_f16_e32 v20, v67
	v_cvt_f32_f16_sdwa v21, v67 dst_sel:DWORD dst_unused:UNUSED_PAD src0_sel:WORD_1
	v_cvt_f32_f16_e32 v22, v68
	v_cvt_f32_f16_sdwa v23, v68 dst_sel:DWORD dst_unused:UNUSED_PAD src0_sel:WORD_1
	v_cvt_f32_f16_e32 v24, v69
	v_cvt_f32_f16_sdwa v25, v69 dst_sel:DWORD dst_unused:UNUSED_PAD src0_sel:WORD_1
	v_pk_mul_f32 v[18:19], v[18:19], s[30:31] op_sel_hi:[1,0]
	v_pk_mul_f32 v[20:21], v[20:21], s[30:31] op_sel_hi:[1,0]
	v_pk_mul_f32 v[22:23], v[22:23], s[30:31] op_sel_hi:[1,0]
	v_pk_mul_f32 v[24:25], v[24:25], s[30:31] op_sel_hi:[1,0]
	v_pk_fma_f32 v[18:19], v[98:99], v[10:11], v[18:19]
	v_pk_fma_f32 v[20:21], v[100:101], v[12:13], v[20:21]
	v_pk_fma_f32 v[22:23], v[102:103], v[14:15], v[22:23]
	v_pk_fma_f32 v[24:25], v[104:105], v[16:17], v[24:25]
	v_cvt_pk_f16_f32 v66, v18, v19
	v_cvt_pk_f16_f32 v67, v20, v21
	v_cvt_pk_f16_f32 v68, v22, v23
	v_cvt_pk_f16_f32 v69, v24, v25
	global_store_dwordx4 v0, v[66:69], s[46:47]
	s_waitcnt vmcnt(15) lgkmcnt(1)
	v_lshlrev_b32_e32 v10, 16, v6
	v_and_b32_e32 v11, 0xffff0000, v6
	v_lshlrev_b32_e32 v12, 16, v7
	v_and_b32_e32 v13, 0xffff0000, v7
	v_lshlrev_b32_e32 v14, 16, v8
	v_and_b32_e32 v15, 0xffff0000, v8
	v_lshlrev_b32_e32 v16, 16, v9
	v_and_b32_e32 v17, 0xffff0000, v9
	ds_read_b128 v[6:9], v238 offset:8064
	v_add_u32_e32 v0, 0x14000, v239
	v_cvt_f32_f16_e32 v18, v70
	v_cvt_f32_f16_sdwa v19, v70 dst_sel:DWORD dst_unused:UNUSED_PAD src0_sel:WORD_1
	v_cvt_f32_f16_e32 v20, v71
	v_cvt_f32_f16_sdwa v21, v71 dst_sel:DWORD dst_unused:UNUSED_PAD src0_sel:WORD_1
	v_cvt_f32_f16_e32 v22, v72
	v_cvt_f32_f16_sdwa v23, v72 dst_sel:DWORD dst_unused:UNUSED_PAD src0_sel:WORD_1
	v_cvt_f32_f16_e32 v24, v73
	v_cvt_f32_f16_sdwa v25, v73 dst_sel:DWORD dst_unused:UNUSED_PAD src0_sel:WORD_1
	v_pk_mul_f32 v[18:19], v[18:19], s[30:31] op_sel_hi:[1,0]
	v_pk_mul_f32 v[20:21], v[20:21], s[30:31] op_sel_hi:[1,0]
	v_pk_mul_f32 v[22:23], v[22:23], s[30:31] op_sel_hi:[1,0]
	v_pk_mul_f32 v[24:25], v[24:25], s[30:31] op_sel_hi:[1,0]
	v_pk_fma_f32 v[18:19], v[98:99], v[10:11], v[18:19]
	v_pk_fma_f32 v[20:21], v[100:101], v[12:13], v[20:21]
	v_pk_fma_f32 v[22:23], v[102:103], v[14:15], v[22:23]
	v_pk_fma_f32 v[24:25], v[104:105], v[16:17], v[24:25]
	v_cvt_pk_f16_f32 v70, v18, v19
	v_cvt_pk_f16_f32 v71, v20, v21
	v_cvt_pk_f16_f32 v72, v22, v23
	v_cvt_pk_f16_f32 v73, v24, v25
	global_store_dwordx4 v0, v[70:73], s[46:47]
	s_waitcnt vmcnt(15) lgkmcnt(1)
	v_lshlrev_b32_e32 v10, 16, v2
	v_and_b32_e32 v11, 0xffff0000, v2
	v_lshlrev_b32_e32 v12, 16, v3
	v_and_b32_e32 v13, 0xffff0000, v3
	v_lshlrev_b32_e32 v14, 16, v4
	v_and_b32_e32 v15, 0xffff0000, v4
	v_lshlrev_b32_e32 v16, 16, v5
	v_and_b32_e32 v17, 0xffff0000, v5
	v_add_u32_e32 v0, 0x18000, v239
	v_cvt_f32_f16_e32 v18, v74
	v_cvt_f32_f16_sdwa v19, v74 dst_sel:DWORD dst_unused:UNUSED_PAD src0_sel:WORD_1
	v_cvt_f32_f16_e32 v20, v75
	v_cvt_f32_f16_sdwa v21, v75 dst_sel:DWORD dst_unused:UNUSED_PAD src0_sel:WORD_1
	v_cvt_f32_f16_e32 v22, v76
	v_cvt_f32_f16_sdwa v23, v76 dst_sel:DWORD dst_unused:UNUSED_PAD src0_sel:WORD_1
	v_cvt_f32_f16_e32 v24, v77
	v_cvt_f32_f16_sdwa v25, v77 dst_sel:DWORD dst_unused:UNUSED_PAD src0_sel:WORD_1
	v_pk_mul_f32 v[18:19], v[18:19], s[30:31] op_sel_hi:[1,0]
	v_pk_mul_f32 v[20:21], v[20:21], s[30:31] op_sel_hi:[1,0]
	v_pk_mul_f32 v[22:23], v[22:23], s[30:31] op_sel_hi:[1,0]
	v_pk_mul_f32 v[24:25], v[24:25], s[30:31] op_sel_hi:[1,0]
	v_pk_fma_f32 v[18:19], v[98:99], v[10:11], v[18:19]
	v_pk_fma_f32 v[20:21], v[100:101], v[12:13], v[20:21]
	v_pk_fma_f32 v[22:23], v[102:103], v[14:15], v[22:23]
	v_pk_fma_f32 v[24:25], v[104:105], v[16:17], v[24:25]
	v_cvt_pk_f16_f32 v74, v18, v19
	v_cvt_pk_f16_f32 v75, v20, v21
	v_cvt_pk_f16_f32 v76, v22, v23
	v_cvt_pk_f16_f32 v77, v24, v25
	global_store_dwordx4 v0, v[74:77], s[46:47]
	s_waitcnt vmcnt(15) lgkmcnt(0)
	v_lshlrev_b32_e32 v10, 16, v6
	v_and_b32_e32 v11, 0xffff0000, v6
	v_lshlrev_b32_e32 v12, 16, v7
	v_and_b32_e32 v13, 0xffff0000, v7
	v_lshlrev_b32_e32 v14, 16, v8
	v_and_b32_e32 v15, 0xffff0000, v8
	v_lshlrev_b32_e32 v16, 16, v9
	v_and_b32_e32 v17, 0xffff0000, v9
	v_add_u32_e32 v0, 0x1c000, v239
	v_cvt_f32_f16_e32 v18, v78
	v_cvt_f32_f16_sdwa v19, v78 dst_sel:DWORD dst_unused:UNUSED_PAD src0_sel:WORD_1
	v_cvt_f32_f16_e32 v20, v79
	v_cvt_f32_f16_sdwa v21, v79 dst_sel:DWORD dst_unused:UNUSED_PAD src0_sel:WORD_1
	v_cvt_f32_f16_e32 v22, v80
	v_cvt_f32_f16_sdwa v23, v80 dst_sel:DWORD dst_unused:UNUSED_PAD src0_sel:WORD_1
	v_cvt_f32_f16_e32 v24, v81
	v_cvt_f32_f16_sdwa v25, v81 dst_sel:DWORD dst_unused:UNUSED_PAD src0_sel:WORD_1
	v_pk_mul_f32 v[18:19], v[18:19], s[30:31] op_sel_hi:[1,0]
	v_pk_mul_f32 v[20:21], v[20:21], s[30:31] op_sel_hi:[1,0]
	v_pk_mul_f32 v[22:23], v[22:23], s[30:31] op_sel_hi:[1,0]
	v_pk_mul_f32 v[24:25], v[24:25], s[30:31] op_sel_hi:[1,0]
	v_pk_fma_f32 v[18:19], v[98:99], v[10:11], v[18:19]
	v_pk_fma_f32 v[20:21], v[100:101], v[12:13], v[20:21]
	v_pk_fma_f32 v[22:23], v[102:103], v[14:15], v[22:23]
	v_pk_fma_f32 v[24:25], v[104:105], v[16:17], v[24:25]
	v_cvt_pk_f16_f32 v78, v18, v19
	v_cvt_pk_f16_f32 v79, v20, v21
	v_cvt_pk_f16_f32 v80, v22, v23
	v_cvt_pk_f16_f32 v81, v24, v25
	global_store_dwordx4 v0, v[78:81], s[46:47]
	s_branch .Lres1_B

;   DI void operator()(f32x16 (&acc)[2][MB], int wm, int wn, int r, int h) {
;     ...
;     __syncthreads();
.Lres1_end:
	s_mov_b32 s40, s76
	s_waitcnt lgkmcnt(0)
	s_barrier
	s_branch .LBB0_853

; template <int MB, class Epi>
; DI void gemm_tile(const u16* __restrict__ A, int lda, int row0, int Mrows, const u16* __restrict__ Bt, int ldb, int K, char* smem, Epi& epi, int rot) {
;     ...
;   for (int kt = 0; kt < KT; ++kt) {
;     const bool more = (kt + 1 < KT);
;     const bool more2 = (kt + 2 < KT);
;     const int nstg = (kt + 1) & 1;
;     const char* as = As + (kt & 1) * 32768 + wm * (32 * MB) * 128;
;     const char* bs = Bs + (kt & 1) * 32768 + wn * 64 * 128;
;     int k1_ = kbase + kt + 1; if (k1_ >= KT) k1_ -= KT;
;     int k2_ = kbase + kt + 2; if (k2_ >= KT) k2_ -= KT; if (k2_ >= KT) k2_ -= KT;
; #pragma unroll
;     for (int ks = 0; ks < 3; ++ks) {
; #pragma unroll
;       for (int idx = 0; idx < 2 * MB; ++idx) {
;         const int nb = idx / MB, mb = idx % MB;
;         acc[nb][mb] = mfma32(bfr[ks & 1][nb], af[ks & 1][mb], acc[nb][mb]);
;         if (idx < MB) af[(ks + 1) & 1][idx] = *(const bf8*)(as + idx * 32 * 128 + foff[ks + 1]);
;         else if (idx < MB + 2) bfr[(ks + 1) & 1][idx - MB] = *(const bf8*)(bs + (idx - MB) * 32 * 128 + foff[ks + 1]);
;         if (more && ks < 2 && idx < 3) {
;           const int ko_ = k1_ * 64;
;           GEMM_PIECE(nstg, 3 + ks * 3 + idx)
;         }
;         __builtin_amdgcn_sched_barrier(0);
;       }
;     }
;     if (more) {
;       asm volatile("s_waitcnt vmcnt(0)" ::: "memory");
;       __syncthreads();
;       if (more2) {
;         const int ko_ = k2_ * 64;
; #pragma unroll
;         for (int pc = 0; pc < 3; ++pc) GEMM_PIECE(kt & 1, pc)
;       }
;       __builtin_amdgcn_sched_barrier(0);
;       const char* asn = As + nstg * 32768 + wm * (32 * MB) * 128;
;       const char* bsn = Bs + nstg * 32768 + wn * 64 * 128;
; #pragma unroll
;       for (int mb = 0; mb < MB; ++mb) af[0][mb] = *(const bf8*)(asn + mb * 32 * 128 + foff[0]);
; #pragma unroll
;       for (int nb = 0; nb < 2; ++nb) bfr[0][nb] = *(const bf8*)(bsn + nb * 32 * 128 + foff[0]);
;     }
; #pragma unroll
;     for (int nb = 0; nb < 2; ++nb)
; #pragma unroll
;       for (int mb = 0; mb < MB; ++mb) acc[nb][mb] = mfma32(bfr[1][nb], af[1][mb], acc[nb][mb]);
; #pragma unroll
;     for (int gk = 0; gk < 2 * MB; ++gk) {
;       __builtin_amdgcn_sched_group_barrier(0x008, 1, 0);
;       __builtin_amdgcn_sched_group_barrier(0x100, 1, 0);
;     }
;     __builtin_amdgcn_sched_barrier(0);
;   }
.LBB0_865:
	s_and_b32 s17, s12, 0x8000
	s_add_i32 s19, s18, 1
	s_add_i32 s25, s11, s17
	s_add_i32 s23, s10, s17
	s_add_i32 s22, s14, s18
	s_cmp_lt_i32 s22, 43
	s_cselect_b32 s18, 0, 0xffffffd4
	s_add_i32 s18, s22, s18
	s_waitcnt lgkmcnt(1)
	v_mfma_f32_32x32x16_bf16 v[114:129], v[150:153], v[146:149], v[114:129]
	s_lshl_b32 s18, s18, 6
	s_add_i32 s26, s18, 64
	s_ashr_i32 s27, s26, 31
	s_add_i32 s12, s12, 0x8000
	v_add_u32_e32 v188, s25, v171
	s_lshl_b64 s[26:27], s[26:27], 1
	s_and_b32 s18, s12, 0x8000
	ds_read_b128 v[172:175], v188
	s_add_i32 s29, s18, s16
	v_lshl_add_u64 v[176:177], v[160:161], 0, s[26:27]
	s_mov_b32 m0, s29
	s_nop 0
	global_load_lds_dwordx4 v[176:177], off
	v_lshl_add_u64 v[184:185], v[158:159], 0, s[26:27]
	s_add_i32 s28, s18, s13
	v_mfma_f32_32x32x16_bf16 v[66:81], v[150:153], v[142:145], v[66:81]
	ds_read_b128 v[176:179], v188 offset:4096
	s_mov_b32 m0, s28
	s_nop 0
	global_load_lds_dwordx4 v[184:185], off
	v_mfma_f32_32x32x16_bf16 v[18:33], v[150:153], v[134:137], v[18:33]
	ds_read_b128 v[180:183], v188 offset:8192
	s_add_i32 s26, s28, 0x2000
	v_lshl_add_u64 v[186:187], v[184:185], 0, s[36:37]
	s_mov_b32 m0, s26
	s_nop 0
	global_load_lds_dwordx4 v[186:187], off
	v_mfma_f32_32x32x16_bf16 v[2:17], v[150:153], v[130:133], v[2:17]
	ds_read_b128 v[150:153], v188 offset:12288
	s_waitcnt lgkmcnt(4)
	v_mfma_f32_32x32x16_bf16 v[98:113], v[138:141], v[146:149], v[98:113]
	v_add_u32_e32 v186, s23, v171
	ds_read_b128 v[146:149], v186
	v_mfma_f32_32x32x16_bf16 v[82:97], v[138:141], v[142:145], v[82:97]
	ds_read_b128 v[142:145], v186 offset:4096
	v_mfma_f32_32x32x16_bf16 v[50:65], v[138:141], v[134:137], v[50:65]
	v_mfma_f32_32x32x16_bf16 v[34:49], v[138:141], v[130:133], v[34:49]
	s_waitcnt lgkmcnt(1)
	v_mfma_f32_32x32x16_bf16 v[114:129], v[146:149], v[172:175], v[114:129]
	v_add_u32_e32 v186, s25, v170
	ds_read_b128 v[130:133], v186
	s_add_i32 s26, s28, 0x4000
	v_lshl_add_u64 v[134:135], v[184:185], 0, s[40:41]
	s_mov_b32 m0, s26
	s_nop 0
	global_load_lds_dwordx4 v[134:135], off
	v_mfma_f32_32x32x16_bf16 v[66:81], v[146:149], v[176:179], v[66:81]
	ds_read_b128 v[134:137], v186 offset:4096
	s_addk_i32 s28, 0x6000
	v_lshl_add_u64 v[138:139], v[184:185], 0, s[48:49]
	s_mov_b32 m0, s28
	s_nop 0
	global_load_lds_dwordx4 v[138:139], off
	v_mfma_f32_32x32x16_bf16 v[18:33], v[146:149], v[180:183], v[18:33]
	ds_read_b128 v[138:141], v186 offset:8192
	v_mfma_f32_32x32x16_bf16 v[2:17], v[146:149], v[150:153], v[2:17]
	ds_read_b128 v[146:149], v186 offset:12288
	s_waitcnt lgkmcnt(4)
	v_mfma_f32_32x32x16_bf16 v[98:113], v[142:145], v[172:175], v[98:113]
	v_add_u32_e32 v184, s23, v170
	ds_read_b128 v[172:175], v184
	v_mfma_f32_32x32x16_bf16 v[82:97], v[142:145], v[176:179], v[82:97]
	ds_read_b128 v[176:179], v184 offset:4096
	v_mfma_f32_32x32x16_bf16 v[50:65], v[142:145], v[180:183], v[50:65]
	v_mfma_f32_32x32x16_bf16 v[34:49], v[142:145], v[150:153], v[34:49]
	s_waitcnt lgkmcnt(1)
	v_mfma_f32_32x32x16_bf16 v[114:129], v[172:175], v[130:133], v[114:129]
	v_add_u32_e32 v142, s25, v169
	ds_read_b128 v[150:153], v142
	v_mfma_f32_32x32x16_bf16 v[66:81], v[172:175], v[134:137], v[66:81]
	ds_read_b128 v[180:183], v142 offset:4096
	v_mfma_f32_32x32x16_bf16 v[18:33], v[172:175], v[138:141], v[18:33]
	ds_read_b128 v[184:187], v142 offset:8192
	v_mfma_f32_32x32x16_bf16 v[2:17], v[172:175], v[146:149], v[2:17]
	ds_read_b128 v[172:175], v142 offset:12288
	s_waitcnt lgkmcnt(4)
	v_mfma_f32_32x32x16_bf16 v[98:113], v[176:179], v[130:133], v[98:113]
	v_add_u32_e32 v142, s23, v169
	ds_read_b128 v[130:133], v142
	v_mfma_f32_32x32x16_bf16 v[82:97], v[176:179], v[134:137], v[82:97]
	ds_read_b128 v[188:191], v142 offset:4096
	v_mfma_f32_32x32x16_bf16 v[50:65], v[176:179], v[138:141], v[50:65]
	v_mfma_f32_32x32x16_bf16 v[34:49], v[176:179], v[146:149], v[34:49]
	s_cmp_lt_i32 s22, 42
	s_cselect_b32 s23, 0, 0xffffffd4
	s_add_i32 s25, s22, s23
	s_add_i32 s25, s25, 2
	s_cmp_lt_i32 s25, 44
	s_cselect_b32 s25, 0, 0xffffffd4
	s_add_i32 s23, s23, s25
	s_add_i32 s22, s22, s23
	s_lshl_b32 s22, s22, 6
	s_addk_i32 s22, 0x80
	s_ashr_i32 s23, s22, 31
	s_lshl_b64 s[22:23], s[22:23], 1
	s_add_u32 s22, s20, s22
	s_addc_u32 s23, s21, s23
	s_waitcnt vmcnt(0)
	s_waitcnt lgkmcnt(0)
	s_barrier
	s_add_i32 s25, s17, s15
	v_lshl_add_u64 v[134:135], v[0:1], 1, s[22:23]
	s_mov_b32 m0, s25
	s_nop 0
	global_load_lds_dwordx4 v[134:135], off
	v_lshl_add_u64 v[134:135], v[154:155], 1, s[22:23]
	s_add_i32 s26, s25, 0x2000
	s_mov_b32 m0, s26
	s_nop 0
	global_load_lds_dwordx4 v[134:135], off
	v_lshl_add_u64 v[134:135], v[156:157], 1, s[22:23]
	s_addk_i32 s25, 0x4000
	s_mov_b32 m0, s25
	s_nop 0
	global_load_lds_dwordx4 v[134:135], off
	v_add_u32_e32 v138, s18, v168
	v_mfma_f32_32x32x16_bf16 v[114:129], v[130:133], v[150:153], v[114:129]
	ds_read_b128 v[146:149], v138
	v_mfma_f32_32x32x16_bf16 v[66:81], v[130:133], v[180:183], v[66:81]
	ds_read_b128 v[142:145], v138 offset:4096
	v_mfma_f32_32x32x16_bf16 v[18:33], v[130:133], v[184:187], v[18:33]
	ds_read_b128 v[134:137], v138 offset:8192
	v_mfma_f32_32x32x16_bf16 v[2:17], v[130:133], v[172:175], v[2:17]
	ds_read_b128 v[130:133], v138 offset:12288
	v_add_u32_e32 v138, s18, v167
	v_mfma_f32_32x32x16_bf16 v[98:113], v[188:191], v[150:153], v[98:113]
	ds_read_b128 v[150:153], v138
	v_mfma_f32_32x32x16_bf16 v[82:97], v[188:191], v[180:183], v[82:97]
	ds_read_b128 v[138:141], v138 offset:4096
	v_mfma_f32_32x32x16_bf16 v[50:65], v[188:191], v[184:187], v[50:65]
	v_mfma_f32_32x32x16_bf16 v[34:49], v[188:191], v[172:175], v[34:49]
	s_cmp_lg_u32 s19, 42
	s_mov_b32 s18, s19
	s_cbranch_scc1 .LBB0_865
; template <int MB, class Epi>
; DI void gemm_tile(const u16* __restrict__ A, int lda, int row0, int Mrows, const u16* __restrict__ Bt, int ldb, int K, char* smem, Epi& epi, int rot) {
;     ...
;   for (int kt = 0; kt < KT; ++kt) {
;     const bool more = (kt + 1 < KT);
;     const bool more2 = (kt + 2 < KT);
;     const int nstg = (kt + 1) & 1;
;     const char* as = As + (kt & 1) * 32768 + wm * (32 * MB) * 128;
;     const char* bs = Bs + (kt & 1) * 32768 + wn * 64 * 128;
;     int k1_ = kbase + kt + 1; if (k1_ >= KT) k1_ -= KT;
;     int k2_ = kbase + kt + 2; if (k2_ >= KT) k2_ -= KT; if (k2_ >= KT) k2_ -= KT;
; #pragma unroll
;     for (int ks = 0; ks < 3; ++ks) {
; #pragma unroll
;       for (int idx = 0; idx < 2 * MB; ++idx) {
;         const int nb = idx / MB, mb = idx % MB;
;         acc[nb][mb] = mfma32(bfr[ks & 1][nb], af[ks & 1][mb], acc[nb][mb]);
;         if (idx < MB) af[(ks + 1) & 1][idx] = *(const bf8*)(as + idx * 32 * 128 + foff[ks + 1]);
;         else if (idx < MB + 2) bfr[(ks + 1) & 1][idx - MB] = *(const bf8*)(bs + (idx - MB) * 32 * 128 + foff[ks + 1]);
;         if (more && ks < 2 && idx < 3) {
;           const int ko_ = k1_ * 64;
;           GEMM_PIECE(nstg, 3 + ks * 3 + idx)
;         }
;         __builtin_amdgcn_sched_barrier(0);
;       }
;     }
;     if (more) {
;       asm volatile("s_waitcnt vmcnt(0)" ::: "memory");
;       __syncthreads();
;       if (more2) {
;         const int ko_ = k2_ * 64;
; #pragma unroll
;         for (int pc = 0; pc < 3; ++pc) GEMM_PIECE(kt & 1, pc)
;       }
;       __builtin_amdgcn_sched_barrier(0);
;       const char* asn = As + nstg * 32768 + wm * (32 * MB) * 128;
;       const char* bsn = Bs + nstg * 32768 + wn * 64 * 128;
; #pragma unroll
;       for (int mb = 0; mb < MB; ++mb) af[0][mb] = *(const bf8*)(asn + mb * 32 * 128 + foff[0]);
; #pragma unroll
;       for (int nb = 0; nb < 2; ++nb) bfr[0][nb] = *(const bf8*)(bsn + nb * 32 * 128 + foff[0]);
;     }
; #pragma unroll
;     for (int nb = 0; nb < 2; ++nb)
; #pragma unroll
;       for (int mb = 0; mb < MB; ++mb) acc[nb][mb] = mfma32(bfr[1][nb], af[1][mb], acc[nb][mb]);
; #pragma unroll
;     for (int gk = 0; gk < 2 * MB; ++gk) {
;       __builtin_amdgcn_sched_group_barrier(0x008, 1, 0);
;       __builtin_amdgcn_sched_group_barrier(0x100, 1, 0);
;     }
;     __builtin_amdgcn_sched_barrier(0);
;   }
	s_add_i32 s12, s14, 42
	s_cmp_lt_i32 s12, 43
	s_cselect_b32 s14, 0, 0xffffffd4
	s_add_i32 s12, s12, s14
	s_lshl_b32 s12, s12, 6
	s_add_i32 s14, s12, 64
	s_ashr_i32 s15, s14, 31
	v_add_u32_e32 v0, s11, v171
	s_lshl_b64 s[14:15], s[14:15], 1
	ds_read_b128 v[154:157], v0
	v_lshl_add_u64 v[176:177], v[158:159], 0, s[14:15]
	s_add_i32 s12, s17, s13
	s_add_i32 s13, s17, s16
	v_lshl_add_u64 v[158:159], v[160:161], 0, s[14:15]
	s_mov_b32 m0, s13
	s_nop 0
	global_load_lds_dwordx4 v[158:159], off
	s_waitcnt lgkmcnt(2)
	v_mfma_f32_32x32x16_bf16 v[114:129], v[150:153], v[146:149], v[114:129]
	ds_read_b128 v[158:161], v0 offset:4096
	s_mov_b32 m0, s12
	s_nop 0
	global_load_lds_dwordx4 v[176:177], off
	v_mfma_f32_32x32x16_bf16 v[66:81], v[150:153], v[142:145], v[66:81]
	ds_read_b128 v[172:175], v0 offset:8192
	s_add_i32 s13, s12, 0x2000
	v_lshl_add_u64 v[178:179], v[176:177], 0, s[36:37]
	s_mov_b32 m0, s13
	s_nop 0
	global_load_lds_dwordx4 v[178:179], off
	v_mfma_f32_32x32x16_bf16 v[18:33], v[150:153], v[134:137], v[18:33]
	v_mfma_f32_32x32x16_bf16 v[2:17], v[150:153], v[130:133], v[2:17]
	ds_read_b128 v[150:153], v0 offset:12288
	v_add_u32_e32 v178, s10, v171
	s_waitcnt lgkmcnt(4)
	v_mfma_f32_32x32x16_bf16 v[98:113], v[138:141], v[146:149], v[98:113]
	ds_read_b128 v[146:149], v178
	v_mfma_f32_32x32x16_bf16 v[82:97], v[138:141], v[142:145], v[82:97]
	ds_read_b128 v[142:145], v178 offset:4096
	v_mfma_f32_32x32x16_bf16 v[50:65], v[138:141], v[134:137], v[50:65]
	v_mfma_f32_32x32x16_bf16 v[34:49], v[138:141], v[130:133], v[34:49]
	v_add_u32_e32 v179, s11, v170
	ds_read_b128 v[130:133], v179
	s_add_i32 s13, s12, 0x4000
	v_lshl_add_u64 v[134:135], v[176:177], 0, s[40:41]
	s_mov_b32 m0, s13
	s_nop 0
	global_load_lds_dwordx4 v[134:135], off
	s_waitcnt lgkmcnt(2)
	v_mfma_f32_32x32x16_bf16 v[114:129], v[146:149], v[154:157], v[114:129]
	ds_read_b128 v[134:137], v179 offset:4096
	s_addk_i32 s12, 0x6000
	v_lshl_add_u64 v[138:139], v[176:177], 0, s[48:49]
	s_mov_b32 m0, s12
	s_nop 0
	global_load_lds_dwordx4 v[138:139], off
	v_mfma_f32_32x32x16_bf16 v[66:81], v[146:149], v[158:161], v[66:81]
	ds_read_b128 v[138:141], v179 offset:8192
	v_mfma_f32_32x32x16_bf16 v[18:33], v[146:149], v[172:175], v[18:33]
	v_mfma_f32_32x32x16_bf16 v[2:17], v[146:149], v[150:153], v[2:17]
	ds_read_b128 v[146:149], v179 offset:12288
	v_add_u32_e32 v176, s10, v170
	s_waitcnt lgkmcnt(4)
	v_mfma_f32_32x32x16_bf16 v[98:113], v[142:145], v[154:157], v[98:113]
	ds_read_b128 v[154:157], v176
	v_mfma_f32_32x32x16_bf16 v[82:97], v[142:145], v[158:161], v[82:97]
	ds_read_b128 v[158:161], v176 offset:4096
	v_mfma_f32_32x32x16_bf16 v[50:65], v[142:145], v[172:175], v[50:65]
	v_mfma_f32_32x32x16_bf16 v[34:49], v[142:145], v[150:153], v[34:49]
	v_add_u32_e32 v174, s11, v169
	ds_read_b128 v[142:145], v174
	s_waitcnt lgkmcnt(2)
	v_mfma_f32_32x32x16_bf16 v[114:129], v[154:157], v[130:133], v[114:129]
	ds_read_b128 v[150:153], v174 offset:4096
	v_mfma_f32_32x32x16_bf16 v[66:81], v[154:157], v[134:137], v[66:81]
	ds_read_b128 v[170:173], v174 offset:8192
	v_mfma_f32_32x32x16_bf16 v[18:33], v[154:157], v[138:141], v[18:33]
	v_mfma_f32_32x32x16_bf16 v[2:17], v[154:157], v[146:149], v[2:17]
	ds_read_b128 v[154:157], v174 offset:12288
	v_add_u32_e32 v175, s10, v169
	s_waitcnt lgkmcnt(4)
	v_mfma_f32_32x32x16_bf16 v[98:113], v[158:161], v[130:133], v[98:113]
	ds_read_b128 v[130:133], v175
	v_mfma_f32_32x32x16_bf16 v[82:97], v[158:161], v[134:137], v[82:97]
	ds_read_b128 v[134:137], v175 offset:4096
	v_mfma_f32_32x32x16_bf16 v[50:65], v[158:161], v[138:141], v[50:65]
	v_mfma_f32_32x32x16_bf16 v[34:49], v[158:161], v[146:149], v[34:49]
	s_waitcnt vmcnt(0)
	s_waitcnt lgkmcnt(0)
	s_barrier
	s_lshr_b32 s100, s0, 5
	s_lshl_b32 s100, s100, 3
	s_and_b32 s101, s0, 7
	s_or_b32 s100, s100, s101
	s_mul_i32 s100, s100, 0x100
	s_lshr_b32 s101, s0, 3
	s_and_b32 s101, s101, 3
	s_lshl_b32 s101, s101, 9
	v_lshrrev_b32_e32 v237, 2, v163
	v_and_b32_e32 v238, 3, v163
	v_add_u32_e32 v237, s100, v237
	v_lshlrev_b32_e32 v237, 11, v237
	v_lshl_add_u32 v237, v238, 7, v237
	v_add_u32_e32 v237, s101, v237
	global_load_dword v255, v237, s[46:47]
	v_add_u32_e32 v237, 0x40000, v237
	global_load_dword v255, v237, s[46:47]
	v_add_u32_e32 v168, s17, v168
	v_add_u32_e32 v167, s17, v167
	v_mfma_f32_32x32x16_bf16 v[114:129], v[130:133], v[142:145], v[114:129]
	ds_read_b128 v[138:141], v168
	v_mfma_f32_32x32x16_bf16 v[66:81], v[130:133], v[150:153], v[66:81]
	ds_read_b128 v[146:149], v168 offset:4096
	v_mfma_f32_32x32x16_bf16 v[18:33], v[130:133], v[170:173], v[18:33]
	ds_read_b128 v[158:161], v168 offset:8192
	v_mfma_f32_32x32x16_bf16 v[2:17], v[130:133], v[154:157], v[2:17]
	ds_read_b128 v[130:133], v168 offset:12288
	v_mfma_f32_32x32x16_bf16 v[98:113], v[134:137], v[142:145], v[98:113]
	ds_read_b128 v[142:145], v167
	v_mfma_f32_32x32x16_bf16 v[82:97], v[134:137], v[150:153], v[82:97]
	ds_read_b128 v[150:153], v167 offset:4096
	v_mfma_f32_32x32x16_bf16 v[50:65], v[134:137], v[170:173], v[50:65]
	v_mfma_f32_32x32x16_bf16 v[34:49], v[134:137], v[154:157], v[34:49]
	ds_read_b128 v[134:137], v0 offset:32768
	s_waitcnt lgkmcnt(2)
	v_mfma_f32_32x32x16_bf16 v[114:129], v[142:145], v[138:141], v[114:129]
	ds_read_b128 v[154:157], v0 offset:36864
	v_mfma_f32_32x32x16_bf16 v[66:81], v[142:145], v[146:149], v[66:81]
	ds_read_b128 v[168:171], v0 offset:40960
	v_mfma_f32_32x32x16_bf16 v[18:33], v[142:145], v[158:161], v[18:33]
	v_mfma_f32_32x32x16_bf16 v[2:17], v[142:145], v[130:133], v[2:17]
	ds_read_b128 v[142:145], v0 offset:45056
	s_waitcnt lgkmcnt(4)
; DI unsigned pack2(float a, float b) { f2 v = {a, b}; bf2 r = __builtin_convertvector(v, bf2); return __builtin_bit_cast(unsigned, r); }
; DI f32x16 mfma32(bf8 a, bf8 b, f32x16 c) { return __builtin_amdgcn_mfma_f32_32x32x16_bf16(a, b, c, 0, 0, 0); }
; template <int MB, class Epi>
; DI void gemm_tile(const u16* __restrict__ A, int lda, int row0, int Mrows, const u16* __restrict__ Bt, int ldb, int K, char* smem, Epi& epi, int rot) {
;     ...
; #pragma unroll
;     for (int nb = 0; nb < 2; ++nb)
; #pragma unroll
;       for (int mb = 0; mb < MB; ++mb) acc[nb][mb] = mfma32(bfr[1][nb], af[1][mb], acc[nb][mb]);
; #pragma unroll
;     for (int gk = 0; gk < 2 * MB; ++gk) {
;       __builtin_amdgcn_sched_group_barrier(0x008, 1, 0);
;       __builtin_amdgcn_sched_group_barrier(0x100, 1, 0);
;     }
;     __builtin_amdgcn_sched_barrier(0);
;   }
;   DI void operator()(f32x16 (&acc)[2][MB], int wm, int wn, int r, int h) {
;     u16* slab = ostage + (wm * 4 + wn) * (64 * 72);
;     const int lane = h * 32 + r;
; #pragma unroll
;     for (int mb = 0; mb < MB; ++mb) {
;       const int tokl = (mb & 1) * 32 + r;
; #pragma unroll
;       for (int nb = 0; nb < 2; ++nb)
; #pragma unroll
;         for (int ig = 0; ig < 4; ++ig) {
;           u32x2 o;
;           o.x = pack2(acc[nb][mb][ig * 4 + 0], acc[nb][mb][ig * 4 + 1]);
;           o.y = pack2(acc[nb][mb][ig * 4 + 2], acc[nb][mb][ig * 4 + 3]);
;           *(u32x2*)(slab + tokl * 72 + nb * 32 + ig * 8 + h * 4) = o;
;         }
;       if ((mb & 1) || mb == MB - 1) {
;         asm volatile("s_waitcnt lgkmcnt(0)" ::: "memory");
;         const int ntok = (mb & 1) ? 64 : 32;
;         const int R0 = row0 + wm * (32 * MB) + (mb >> 1) * 64;
; #pragma unroll
;         for (int j = 0; j < 8; ++j) {
;           const int rowl = (lane >> 3) + 8 * j, ch = lane & 7;
;           if (rowl < ntok) {
;             const u32x4 yv = *(const u32x4*)(slab + rowl * 72 + ch * 8);
;             const int R = R0 + rowl;
;             const int mi = (R < NLAT) ? (R >> 11) : 16;
;             const int col = n0 + wn * 64 + ch * 8;
;             const float* g = gate + (size_t)mi * 6144 + col;
;             const f32x4n g0 = *(const f32x4n*)(g), g1 = *(const f32x4n*)(g + 4);
;             _Float16* xp = X + (size_t)R * 1024 + col;
;             const h8 xv = *(const h8*)xp;
	v_mfma_f32_32x32x16_bf16 v[98:113], v[150:153], v[138:141], v[98:113]
	ds_read_b128 v[138:141], v178 offset:32768
	v_mfma_f32_32x32x16_bf16 v[82:97], v[150:153], v[146:149], v[82:97]
	ds_read_b128 v[146:149], v178 offset:36864
	v_mfma_f32_32x32x16_bf16 v[50:65], v[150:153], v[158:161], v[50:65]
	v_mfma_f32_32x32x16_bf16 v[34:49], v[150:153], v[130:133], v[34:49]
	ds_read_b128 v[130:133], v179 offset:32768
	s_waitcnt lgkmcnt(2)
	v_mfma_f32_32x32x16_bf16 v[114:129], v[138:141], v[134:137], v[114:129]
	ds_read_b128 v[150:153], v179 offset:36864
	v_mfma_f32_32x32x16_bf16 v[66:81], v[138:141], v[154:157], v[66:81]
	ds_read_b128 v[158:161], v179 offset:40960
	v_mfma_f32_32x32x16_bf16 v[18:33], v[138:141], v[168:171], v[18:33]
	v_mfma_f32_32x32x16_bf16 v[2:17], v[138:141], v[142:145], v[2:17]
	ds_read_b128 v[138:141], v179 offset:45056
	s_waitcnt lgkmcnt(4)
	v_mfma_f32_32x32x16_bf16 v[98:113], v[146:149], v[134:137], v[98:113]
	ds_read_b128 v[134:137], v176 offset:32768
	v_mfma_f32_32x32x16_bf16 v[82:97], v[146:149], v[154:157], v[82:97]
	ds_read_b128 v[154:157], v176 offset:36864
	v_mfma_f32_32x32x16_bf16 v[50:65], v[146:149], v[168:171], v[50:65]
	v_mfma_f32_32x32x16_bf16 v[34:49], v[146:149], v[142:145], v[34:49]
	ds_read_b128 v[142:145], v174 offset:32768
	s_waitcnt lgkmcnt(2)
	v_mfma_f32_32x32x16_bf16 v[114:129], v[134:137], v[130:133], v[114:129]
	ds_read_b128 v[146:149], v174 offset:36864
	v_mfma_f32_32x32x16_bf16 v[66:81], v[134:137], v[150:153], v[66:81]
	ds_read_b128 v[168:171], v174 offset:40960
	v_mfma_f32_32x32x16_bf16 v[18:33], v[134:137], v[158:161], v[18:33]
	v_mfma_f32_32x32x16_bf16 v[2:17], v[134:137], v[138:141], v[2:17]
	ds_read_b128 v[134:137], v174 offset:45056
	s_waitcnt lgkmcnt(4)
	v_mfma_f32_32x32x16_bf16 v[98:113], v[154:157], v[130:133], v[98:113]
	ds_read_b128 v[130:133], v175 offset:32768
	v_mfma_f32_32x32x16_bf16 v[82:97], v[154:157], v[150:153], v[82:97]
	ds_read_b128 v[150:153], v175 offset:36864
	v_mfma_f32_32x32x16_bf16 v[50:65], v[154:157], v[158:161], v[50:65]
	v_mfma_f32_32x32x16_bf16 v[34:49], v[154:157], v[138:141], v[34:49]
	s_waitcnt lgkmcnt(1)
	v_mfma_f32_32x32x16_bf16 v[114:129], v[130:133], v[142:145], v[114:129]
	v_mfma_f32_32x32x16_bf16 v[66:81], v[130:133], v[146:149], v[66:81]
	v_mfma_f32_32x32x16_bf16 v[18:33], v[130:133], v[168:171], v[18:33]
	v_mfma_f32_32x32x16_bf16 v[2:17], v[130:133], v[134:137], v[2:17]
	s_waitcnt lgkmcnt(0)
	v_mfma_f32_32x32x16_bf16 v[98:113], v[150:153], v[142:145], v[98:113]
	v_mfma_f32_32x32x16_bf16 v[82:97], v[150:153], v[146:149], v[82:97]
	v_mfma_f32_32x32x16_bf16 v[50:65], v[150:153], v[168:171], v[50:65]
	v_mfma_f32_32x32x16_bf16 v[34:49], v[150:153], v[134:137], v[34:49]
	s_lshl_b32 s10, s9, 2
	s_or_b32 s10, s10, s8
	s_mulk_i32 s10, 0x2400
	v_lshl_or_b32 v0, v166, 3, s10
	v_lshlrev_b32_e32 v130, 3, v165
	v_and_b32_e32 v132, 56, v130
	v_mad_u32_u24 v130, v165, s78, v0
	v_cvt_pk_bf16_f32 v66, v66, v67
	v_cvt_pk_bf16_f32 v67, v68, v69
	v_cvt_pk_bf16_f32 v68, v70, v71
	v_cvt_pk_bf16_f32 v69, v72, v73
	v_add_u32_e32 v70, 0x1000, v130
	s_barrier
	ds_write2_b64 v70, v[66:67], v[68:69] offset0:64 offset1:66
	v_cvt_pk_bf16_f32 v66, v74, v75
	v_cvt_pk_bf16_f32 v67, v76, v77
	v_cvt_pk_bf16_f32 v68, v78, v79
	v_cvt_pk_bf16_f32 v69, v80, v81
	s_lshl_b32 s9, s9, 7
	ds_write2_b64 v70, v[66:67], v[68:69] offset0:68 offset1:70
	v_cvt_pk_bf16_f32 v66, v82, v83
	v_cvt_pk_bf16_f32 v67, v84, v85
	v_cvt_pk_bf16_f32 v68, v86, v87
	v_cvt_pk_bf16_f32 v69, v88, v89
	s_lshl_b32 s3, s3, 8
	v_bfe_u32 v131, v164, 3, 3
	s_lshl_b32 s8, s8, 6
	ds_write2_b64 v70, v[66:67], v[68:69] offset0:72 offset1:74
	v_cvt_pk_bf16_f32 v66, v90, v91
	v_cvt_pk_bf16_f32 v67, v92, v93
	v_cvt_pk_bf16_f32 v68, v94, v95
	v_cvt_pk_bf16_f32 v69, v96, v97
	s_add_i32 s2, s9, s2
	ds_write2_b64 v70, v[66:67], v[68:69] offset0:76 offset1:78
	v_or_b32_e32 v66, s2, v131
	s_or_b32 s3, s8, s3
	v_cvt_pk_bf16_f32 v114, v114, v115
	v_cvt_pk_bf16_f32 v115, v116, v117
	v_cvt_pk_bf16_f32 v116, v118, v119
	v_cvt_pk_bf16_f32 v117, v120, v121
	v_cvt_pk_bf16_f32 v98, v98, v99
	v_cvt_pk_bf16_f32 v99, v100, v101
	v_cvt_pk_bf16_f32 v100, v102, v103
	v_cvt_pk_bf16_f32 v101, v104, v105
	v_or_b32_e32 v68, s3, v132
	v_ashrrev_i32_e32 v67, 31, v66
	ds_write2_b64 v130, v[114:115], v[116:117] offset1:2
	v_cvt_pk_bf16_f32 v114, v122, v123
	v_cvt_pk_bf16_f32 v115, v124, v125
	v_cvt_pk_bf16_f32 v116, v126, v127
	v_cvt_pk_bf16_f32 v117, v128, v129
	ds_write2_b64 v130, v[98:99], v[100:101] offset0:8 offset1:10
	v_cvt_pk_bf16_f32 v98, v106, v107
	v_cvt_pk_bf16_f32 v99, v108, v109
	v_cvt_pk_bf16_f32 v100, v110, v111
	v_cvt_pk_bf16_f32 v101, v112, v113
	v_min_i32_e32 v0, 0x8000, v66
	v_ashrrev_i32_e32 v69, 31, v68
	v_lshlrev_b64 v[66:67], 11, v[66:67]
	ds_write2_b64 v130, v[114:115], v[116:117] offset0:4 offset1:6
	ds_write2_b64 v130, v[98:99], v[100:101] offset0:12 offset1:14
	v_lshl_add_u64 v[72:73], s[46:47], 0, v[66:67]
	v_lshlrev_b64 v[66:67], 1, v[68:69]
	s_waitcnt lgkmcnt(0)
	v_lshl_add_u64 v[96:97], v[72:73], 0, v[66:67]
	global_load_dwordx4 v[72:75], v[96:97], off
	v_ashrrev_i32_e32 v0, 11, v0
	v_readlane_b32 s8, v234, 10
	v_mul_hi_i32_i24_e32 v77, 0x6000, v0
	v_mul_i32_i24_e32 v76, 0x6000, v0
	v_readlane_b32 s9, v234, 11
	v_lshlrev_b64 v[68:69], 2, v[68:69]
	v_or_b32_e32 v71, 8, v131
	v_lshl_add_u64 v[76:77], s[8:9], 0, v[76:77]
	v_lshl_add_u64 v[80:81], v[76:77], 0, v[68:69]
	global_load_dwordx4 v[76:79], v[80:81], off
	v_or_b32_e32 v98, s2, v71
	global_load_dwordx4 v[80:83], v[80:81], off offset:16
	v_ashrrev_i32_e32 v99, 31, v98
	v_lshl_or_b32 v0, v132, 1, s10
	v_lshlrev_b64 v[84:85], 11, v[98:99]
	v_mad_u32_u24 v0, v131, s78, v0
	v_lshl_add_u64 v[84:85], s[46:47], 0, v[84:85]
	v_lshl_add_u64 v[100:101], v[84:85], 0, v[66:67]
	ds_read_b128 v[84:87], v0
	global_load_dwordx4 v[92:95], v[100:101], off
	ds_read_b128 v[88:91], v0 offset:1152
	v_cvt_pk_bf16_f32 v2, v2, v3
	v_cvt_pk_bf16_f32 v3, v4, v5
	s_waitcnt lgkmcnt(1)
;   DI void operator()(f32x16 (&acc)[2][MB], int wm, int wn, int r, int h) {
;     ...
;         for (int j = 0; j < 8; ++j) {
;           const int rowl = (lane >> 3) + 8 * j, ch = lane & 7;
;           if (rowl < ntok) {
;             const u32x4 yv = *(const u32x4*)(slab + rowl * 72 + ch * 8);
;             const int R = R0 + rowl;
;             const int mi = (R < NLAT) ? (R >> 11) : 16;
;             const int col = n0 + wn * 64 + ch * 8;
;             const float* g = gate + (size_t)mi * 6144 + col;
;             const f32x4n g0 = *(const f32x4n*)(g), g1 = *(const f32x4n*)(g + 4);
;             _Float16* xp = X + (size_t)R * 1024 + col;
;             const h8 xv = *(const h8*)xp;
;             const float y[8] = {__uint_as_float(yv.x << 16), __uint_as_float(yv.x & 0xffff0000u), __uint_as_float(yv.y << 16), __uint_as_float(yv.y & 0xffff0000u),
;                                 __uint_as_float(yv.z << 16), __uint_as_float(yv.z & 0xffff0000u), __uint_as_float(yv.w << 16), __uint_as_float(yv.w & 0xffff0000u)};
;             const float gg[8] = {g0.x, g0.y, g0.z, g0.w, g1.x, g1.y, g1.z, g1.w};
;             h8 o;
; #pragma unroll
;             for (int q = 0; q < 8; ++q) o[q] = (_Float16)(ALPHA * (float)xv[q] + gg[q] * y[q]);
;             *(h8*)xp = o;
	v_lshlrev_b32_e32 v104, 16, v84
	v_and_b32_e32 v105, 0xffff0000, v84
	v_cvt_pk_bf16_f32 v4, v6, v7
	v_cvt_pk_bf16_f32 v5, v8, v9
	v_cvt_pk_bf16_f32 v6, v10, v11
	v_cvt_pk_bf16_f32 v7, v12, v13
	v_cvt_pk_bf16_f32 v8, v14, v15
	v_cvt_pk_bf16_f32 v9, v16, v17
	v_cvt_pk_bf16_f32 v10, v34, v35
	v_cvt_pk_bf16_f32 v11, v36, v37
	v_cvt_pk_bf16_f32 v12, v38, v39
	v_cvt_pk_bf16_f32 v13, v40, v41
	v_cvt_pk_bf16_f32 v14, v42, v43
	v_cvt_pk_bf16_f32 v15, v44, v45
	v_cvt_pk_bf16_f32 v16, v46, v47
	v_cvt_pk_bf16_f32 v17, v48, v49
	v_cvt_pk_bf16_f32 v18, v18, v19
	v_cvt_pk_bf16_f32 v19, v20, v21
	v_cvt_pk_bf16_f32 v20, v22, v23
	v_cvt_pk_bf16_f32 v21, v24, v25
	v_cvt_pk_bf16_f32 v22, v26, v27
	v_cvt_pk_bf16_f32 v23, v28, v29
	v_cvt_pk_bf16_f32 v24, v30, v31
	v_cvt_pk_bf16_f32 v25, v32, v33
	v_cvt_pk_bf16_f32 v26, v50, v51
	v_cvt_pk_bf16_f32 v27, v52, v53
	v_cvt_pk_bf16_f32 v28, v54, v55
	v_cvt_pk_bf16_f32 v29, v56, v57
	v_cvt_pk_bf16_f32 v30, v58, v59
	v_cvt_pk_bf16_f32 v31, v60, v61
	v_cvt_pk_bf16_f32 v32, v62, v63
	v_cvt_pk_bf16_f32 v33, v64, v65
	s_mov_b32 s40, s76
	s_waitcnt vmcnt(3)
	v_cvt_f32_f16_e32 v102, v72
	v_cvt_f32_f16_sdwa v103, v72 dst_sel:DWORD dst_unused:UNUSED_PAD src0_sel:WORD_1
	v_cvt_f32_f16_e32 v106, v73
	v_cvt_f32_f16_sdwa v107, v73 dst_sel:DWORD dst_unused:UNUSED_PAD src0_sel:WORD_1
	v_pk_mul_f32 v[102:103], v[102:103], s[30:31] op_sel_hi:[1,0]
	s_waitcnt vmcnt(2)
	v_pk_fma_f32 v[76:77], v[76:77], v[104:105], v[102:103]
	s_nop 0
	v_cvt_pk_f16_f32 v72, v76, v77
	v_lshlrev_b32_e32 v76, 16, v85
	v_and_b32_e32 v77, 0xffff0000, v85
	v_pk_mul_f32 v[84:85], v[106:107], s[30:31] op_sel_hi:[1,0]
	s_waitcnt lgkmcnt(0)
	v_lshlrev_b32_e32 v102, 16, v90
	v_pk_fma_f32 v[76:77], v[78:79], v[76:77], v[84:85]
	v_cvt_f32_f16_e32 v78, v74
	v_cvt_f32_f16_sdwa v79, v74 dst_sel:DWORD dst_unused:UNUSED_PAD src0_sel:WORD_1
	v_cvt_pk_f16_f32 v73, v76, v77
	v_lshlrev_b32_e32 v76, 16, v86
	v_and_b32_e32 v77, 0xffff0000, v86
	v_pk_mul_f32 v[78:79], v[78:79], s[30:31] op_sel_hi:[1,0]
	s_waitcnt vmcnt(0)
	v_cvt_f32_f16_e32 v104, v92
	v_pk_fma_f32 v[76:77], v[80:81], v[76:77], v[78:79]
	v_cvt_f32_f16_e32 v78, v75
	v_cvt_f32_f16_sdwa v79, v75 dst_sel:DWORD dst_unused:UNUSED_PAD src0_sel:WORD_1
	v_cvt_pk_f16_f32 v74, v76, v77
	v_lshlrev_b32_e32 v76, 16, v87
	v_and_b32_e32 v77, 0xffff0000, v87
	v_pk_mul_f32 v[78:79], v[78:79], s[30:31] op_sel_hi:[1,0]
	v_cvt_f32_f16_sdwa v105, v92 dst_sel:DWORD dst_unused:UNUSED_PAD src0_sel:WORD_1
	v_pk_fma_f32 v[76:77], v[82:83], v[76:77], v[78:79]
	v_cvt_f32_f16_e32 v92, v93
	v_cvt_pk_f16_f32 v75, v76, v77
	global_store_dwordx4 v[96:97], v[72:75], off
	v_cvt_f32_f16_sdwa v93, v93 dst_sel:DWORD dst_unused:UNUSED_PAD src0_sel:WORD_1
	v_cvt_f32_f16_e32 v106, v94
	v_min_i32_e32 v72, 0x8000, v98
	v_ashrrev_i32_e32 v72, 11, v72
	v_mul_hi_i32_i24_e32 v73, 0x6000, v72
	v_mul_i32_i24_e32 v72, 0x6000, v72
	v_lshl_add_u64 v[72:73], s[8:9], 0, v[72:73]
	v_lshl_add_u64 v[72:73], v[72:73], 0, v[68:69]
	global_load_dwordx4 v[74:77], v[72:73], off
	global_load_dwordx4 v[78:81], v[72:73], off offset:16
	v_or_b32_e32 v72, 16, v131
	v_or_b32_e32 v82, s2, v72
	v_min_i32_e32 v73, 0x8000, v82
	v_ashrrev_i32_e32 v83, 31, v82
	v_ashrrev_i32_e32 v73, 11, v73
	v_lshlrev_b64 v[82:83], 11, v[82:83]
	v_cvt_f32_f16_sdwa v107, v94 dst_sel:DWORD dst_unused:UNUSED_PAD src0_sel:WORD_1
	v_cvt_f32_f16_e32 v94, v95
	v_cvt_f32_f16_sdwa v95, v95 dst_sel:DWORD dst_unused:UNUSED_PAD src0_sel:WORD_1
	v_mul_hi_i32_i24_e32 v85, 0x6000, v73
	v_mul_i32_i24_e32 v84, 0x6000, v73
	v_lshl_add_u64 v[82:83], s[46:47], 0, v[82:83]
	v_lshl_add_u64 v[84:85], s[8:9], 0, v[84:85]
	v_lshl_add_u64 v[98:99], v[82:83], 0, v[66:67]
	v_lshl_add_u64 v[86:87], v[84:85], 0, v[68:69]
	global_load_dwordx4 v[82:85], v[98:99], off
	v_lshlrev_b32_e32 v96, 16, v88
	v_and_b32_e32 v97, 0xffff0000, v88
	v_lshlrev_b32_e32 v88, 16, v89
	v_and_b32_e32 v89, 0xffff0000, v89
	v_and_b32_e32 v103, 0xffff0000, v90
	v_lshlrev_b32_e32 v90, 16, v91
	v_and_b32_e32 v91, 0xffff0000, v91
	v_pk_mul_f32 v[104:105], v[104:105], s[30:31] op_sel_hi:[1,0]
	v_pk_mul_f32 v[92:93], v[92:93], s[30:31] op_sel_hi:[1,0]
	v_pk_mul_f32 v[106:107], v[106:107], s[30:31] op_sel_hi:[1,0]
	v_pk_mul_f32 v[94:95], v[94:95], s[30:31] op_sel_hi:[1,0]
	v_or_b32_e32 v73, 24, v131
	s_waitcnt vmcnt(2)
	v_pk_fma_f32 v[74:75], v[74:75], v[96:97], v[104:105]
	v_pk_fma_f32 v[76:77], v[76:77], v[88:89], v[92:93]
	s_waitcnt vmcnt(1)
	v_pk_fma_f32 v[78:79], v[78:79], v[102:103], v[106:107]
	v_pk_fma_f32 v[80:81], v[80:81], v[90:91], v[94:95]
	v_cvt_pk_f16_f32 v74, v74, v75
	v_cvt_pk_f16_f32 v75, v76, v77
	v_cvt_pk_f16_f32 v76, v78, v79
	v_cvt_pk_f16_f32 v77, v80, v81
	global_store_dwordx4 v[100:101], v[74:77], off
	global_load_dwordx4 v[74:77], v[86:87], off
	s_waitcnt vmcnt(2)
	v_cvt_f32_f16_e32 v108, v82
	global_load_dwordx4 v[78:81], v[86:87], off offset:16
	v_or_b32_e32 v86, s2, v73
	v_min_i32_e32 v88, 0x8000, v86
	v_ashrrev_i32_e32 v87, 31, v86
	v_ashrrev_i32_e32 v88, 11, v88
	v_lshlrev_b64 v[86:87], 11, v[86:87]
	v_mul_hi_i32_i24_e32 v89, 0x6000, v88
	v_mul_i32_i24_e32 v88, 0x6000, v88
	v_lshl_add_u64 v[90:91], s[46:47], 0, v[86:87]
	v_lshl_add_u64 v[92:93], s[8:9], 0, v[88:89]
	ds_read_b128 v[86:89], v0 offset:2304
	v_cvt_f32_f16_sdwa v109, v82 dst_sel:DWORD dst_unused:UNUSED_PAD src0_sel:WORD_1
	v_cvt_f32_f16_e32 v82, v83
	v_cvt_f32_f16_sdwa v83, v83 dst_sel:DWORD dst_unused:UNUSED_PAD src0_sel:WORD_1
	v_cvt_f32_f16_e32 v110, v84
	v_cvt_f32_f16_sdwa v111, v84 dst_sel:DWORD dst_unused:UNUSED_PAD src0_sel:WORD_1
	v_cvt_f32_f16_e32 v84, v85
	v_cvt_f32_f16_sdwa v85, v85 dst_sel:DWORD dst_unused:UNUSED_PAD src0_sel:WORD_1
	v_lshl_add_u64 v[100:101], v[90:91], 0, v[66:67]
	global_load_dwordx4 v[94:97], v[100:101], off
	s_waitcnt lgkmcnt(0)
;   DI void operator()(f32x16 (&acc)[2][MB], int wm, int wn, int r, int h) {
;     ...
;         for (int j = 0; j < 8; ++j) {
;           const int rowl = (lane >> 3) + 8 * j, ch = lane & 7;
;           if (rowl < ntok) {
;             const u32x4 yv = *(const u32x4*)(slab + rowl * 72 + ch * 8);
;             const int R = R0 + rowl;
;             const int mi = (R < NLAT) ? (R >> 11) : 16;
;             const int col = n0 + wn * 64 + ch * 8;
;             const float* g = gate + (size_t)mi * 6144 + col;
;             const f32x4n g0 = *(const f32x4n*)(g), g1 = *(const f32x4n*)(g + 4);
;             _Float16* xp = X + (size_t)R * 1024 + col;
;             const h8 xv = *(const h8*)xp;
;             const float y[8] = {__uint_as_float(yv.x << 16), __uint_as_float(yv.x & 0xffff0000u), __uint_as_float(yv.y << 16), __uint_as_float(yv.y & 0xffff0000u),
;                                 __uint_as_float(yv.z << 16), __uint_as_float(yv.z & 0xffff0000u), __uint_as_float(yv.w << 16), __uint_as_float(yv.w & 0xffff0000u)};
;             const float gg[8] = {g0.x, g0.y, g0.z, g0.w, g1.x, g1.y, g1.z, g1.w};
;             h8 o;
; #pragma unroll
;             for (int q = 0; q < 8; ++q) o[q] = (_Float16)(ALPHA * (float)xv[q] + gg[q] * y[q]);
;             *(h8*)xp = o;
	v_lshlrev_b32_e32 v104, 16, v86
	v_and_b32_e32 v105, 0xffff0000, v86
	v_lshlrev_b32_e32 v86, 16, v87
	v_and_b32_e32 v87, 0xffff0000, v87
	v_lshlrev_b32_e32 v106, 16, v88
	v_and_b32_e32 v107, 0xffff0000, v88
	v_lshlrev_b32_e32 v88, 16, v89
	v_and_b32_e32 v89, 0xffff0000, v89
	v_pk_mul_f32 v[108:109], v[108:109], s[30:31] op_sel_hi:[1,0]
	v_pk_mul_f32 v[82:83], v[82:83], s[30:31] op_sel_hi:[1,0]
	v_pk_mul_f32 v[110:111], v[110:111], s[30:31] op_sel_hi:[1,0]
	v_pk_mul_f32 v[84:85], v[84:85], s[30:31] op_sel_hi:[1,0]
	v_lshl_add_u64 v[102:103], v[92:93], 0, v[68:69]
	ds_read_b128 v[90:93], v0 offset:3456
	s_waitcnt vmcnt(2)
	v_pk_fma_f32 v[74:75], v[74:75], v[104:105], v[108:109]
	v_pk_fma_f32 v[76:77], v[76:77], v[86:87], v[82:83]
	v_cvt_pk_f16_f32 v74, v74, v75
	v_cvt_pk_f16_f32 v75, v76, v77
	s_waitcnt lgkmcnt(0)
	v_lshlrev_b32_e32 v104, 16, v92
	v_and_b32_e32 v105, 0xffff0000, v92
	v_lshlrev_b32_e32 v92, 16, v93
	v_and_b32_e32 v93, 0xffff0000, v93
	s_waitcnt vmcnt(1)
	v_pk_fma_f32 v[78:79], v[78:79], v[106:107], v[110:111]
	v_pk_fma_f32 v[80:81], v[80:81], v[88:89], v[84:85]
	v_cvt_pk_f16_f32 v76, v78, v79
	v_cvt_pk_f16_f32 v77, v80, v81
	global_store_dwordx4 v[98:99], v[74:77], off
	global_load_dwordx4 v[76:79], v[102:103], off
	v_lshlrev_b32_e32 v98, 16, v90
	global_load_dwordx4 v[80:83], v[102:103], off offset:16
	v_or_b32_e32 v74, 32, v131
	v_or_b32_e32 v84, s2, v74
	v_min_i32_e32 v75, 0x8000, v84
	v_ashrrev_i32_e32 v85, 31, v84
	v_ashrrev_i32_e32 v75, 11, v75
	v_lshlrev_b64 v[84:85], 11, v[84:85]
	v_mul_hi_i32_i24_e32 v87, 0x6000, v75
	v_mul_i32_i24_e32 v86, 0x6000, v75
	v_lshl_add_u64 v[84:85], s[46:47], 0, v[84:85]
	v_lshl_add_u64 v[86:87], s[8:9], 0, v[86:87]
	v_lshl_add_u64 v[102:103], v[84:85], 0, v[66:67]
	s_waitcnt vmcnt(3)
	v_cvt_f32_f16_e32 v106, v94
	v_cvt_f32_f16_sdwa v107, v94 dst_sel:DWORD dst_unused:UNUSED_PAD src0_sel:WORD_1
	v_cvt_f32_f16_e32 v94, v95
	v_cvt_f32_f16_sdwa v95, v95 dst_sel:DWORD dst_unused:UNUSED_PAD src0_sel:WORD_1
	v_cvt_f32_f16_e32 v108, v96
	v_cvt_f32_f16_sdwa v109, v96 dst_sel:DWORD dst_unused:UNUSED_PAD src0_sel:WORD_1
	v_cvt_f32_f16_e32 v96, v97
	v_cvt_f32_f16_sdwa v97, v97 dst_sel:DWORD dst_unused:UNUSED_PAD src0_sel:WORD_1
	v_lshl_add_u64 v[88:89], v[86:87], 0, v[68:69]
	global_load_dwordx4 v[84:87], v[102:103], off
	v_and_b32_e32 v99, 0xffff0000, v90
	v_lshlrev_b32_e32 v90, 16, v91
	v_and_b32_e32 v91, 0xffff0000, v91
	v_pk_mul_f32 v[106:107], v[106:107], s[30:31] op_sel_hi:[1,0]
	v_pk_mul_f32 v[94:95], v[94:95], s[30:31] op_sel_hi:[1,0]
	v_pk_mul_f32 v[108:109], v[108:109], s[30:31] op_sel_hi:[1,0]
	v_pk_mul_f32 v[96:97], v[96:97], s[30:31] op_sel_hi:[1,0]
	v_or_b32_e32 v75, 40, v131
	s_waitcnt vmcnt(2)
	v_pk_fma_f32 v[76:77], v[76:77], v[98:99], v[106:107]
	v_pk_fma_f32 v[78:79], v[78:79], v[90:91], v[94:95]
	s_waitcnt vmcnt(1)
	v_pk_fma_f32 v[80:81], v[80:81], v[104:105], v[108:109]
	v_pk_fma_f32 v[82:83], v[82:83], v[92:93], v[96:97]
	v_cvt_pk_f16_f32 v76, v76, v77
	v_cvt_pk_f16_f32 v77, v78, v79
	v_cvt_pk_f16_f32 v78, v80, v81
	v_cvt_pk_f16_f32 v79, v82, v83
	global_store_dwordx4 v[100:101], v[76:79], off
	global_load_dwordx4 v[76:79], v[88:89], off
	s_waitcnt vmcnt(2)
	v_cvt_f32_f16_e32 v110, v84
	global_load_dwordx4 v[80:83], v[88:89], off offset:16
	v_or_b32_e32 v88, s2, v75
	v_min_i32_e32 v90, 0x8000, v88
	v_ashrrev_i32_e32 v89, 31, v88
	v_ashrrev_i32_e32 v90, 11, v90
	v_lshlrev_b64 v[88:89], 11, v[88:89]
	v_mul_hi_i32_i24_e32 v91, 0x6000, v90
	v_mul_i32_i24_e32 v90, 0x6000, v90
	v_lshl_add_u64 v[92:93], s[46:47], 0, v[88:89]
	v_lshl_add_u64 v[94:95], s[8:9], 0, v[90:91]
	ds_read_b128 v[88:91], v0 offset:4608
	v_cvt_f32_f16_sdwa v111, v84 dst_sel:DWORD dst_unused:UNUSED_PAD src0_sel:WORD_1
	v_cvt_f32_f16_e32 v84, v85
	v_cvt_f32_f16_sdwa v85, v85 dst_sel:DWORD dst_unused:UNUSED_PAD src0_sel:WORD_1
	v_cvt_f32_f16_e32 v112, v86
	v_cvt_f32_f16_sdwa v113, v86 dst_sel:DWORD dst_unused:UNUSED_PAD src0_sel:WORD_1
	v_cvt_f32_f16_e32 v86, v87
	v_cvt_f32_f16_sdwa v87, v87 dst_sel:DWORD dst_unused:UNUSED_PAD src0_sel:WORD_1
	v_lshl_add_u64 v[100:101], v[92:93], 0, v[66:67]
	global_load_dwordx4 v[96:99], v[100:101], off
	s_waitcnt lgkmcnt(0)
	v_lshlrev_b32_e32 v106, 16, v88
	v_and_b32_e32 v107, 0xffff0000, v88
	v_lshlrev_b32_e32 v88, 16, v89
	v_and_b32_e32 v89, 0xffff0000, v89
	v_lshlrev_b32_e32 v108, 16, v90
	v_and_b32_e32 v109, 0xffff0000, v90
	v_lshlrev_b32_e32 v90, 16, v91
	v_and_b32_e32 v91, 0xffff0000, v91
	v_pk_mul_f32 v[110:111], v[110:111], s[30:31] op_sel_hi:[1,0]
	v_pk_mul_f32 v[84:85], v[84:85], s[30:31] op_sel_hi:[1,0]
	v_pk_mul_f32 v[112:113], v[112:113], s[30:31] op_sel_hi:[1,0]
	v_pk_mul_f32 v[86:87], v[86:87], s[30:31] op_sel_hi:[1,0]
	v_lshl_add_u64 v[104:105], v[94:95], 0, v[68:69]
	ds_read_b128 v[92:95], v0 offset:5760
	s_waitcnt vmcnt(2)
	v_pk_fma_f32 v[76:77], v[76:77], v[106:107], v[110:111]
	v_pk_fma_f32 v[78:79], v[78:79], v[88:89], v[84:85]
	v_cvt_pk_f16_f32 v76, v76, v77
	v_cvt_pk_f16_f32 v77, v78, v79
	s_waitcnt lgkmcnt(0)
	v_lshlrev_b32_e32 v106, 16, v94
	v_and_b32_e32 v107, 0xffff0000, v94
	v_lshlrev_b32_e32 v94, 16, v95
	v_and_b32_e32 v95, 0xffff0000, v95
	s_waitcnt vmcnt(1)
	v_pk_fma_f32 v[80:81], v[80:81], v[108:109], v[112:113]
	v_pk_fma_f32 v[82:83], v[82:83], v[90:91], v[86:87]
	v_cvt_pk_f16_f32 v78, v80, v81
	v_cvt_pk_f16_f32 v79, v82, v83
	global_store_dwordx4 v[102:103], v[76:79], off
	global_load_dwordx4 v[78:81], v[104:105], off
	s_waitcnt vmcnt(2)
; DI unsigned pack2(float a, float b) { f2 v = {a, b}; bf2 r = __builtin_convertvector(v, bf2); return __builtin_bit_cast(unsigned, r); }
;   DI void operator()(f32x16 (&acc)[2][MB], int wm, int wn, int r, int h) {
;     ...
; #pragma unroll
;     for (int mb = 0; mb < MB; ++mb) {
;       const int tokl = (mb & 1) * 32 + r;
; #pragma unroll
;       for (int nb = 0; nb < 2; ++nb)
; #pragma unroll
;         for (int ig = 0; ig < 4; ++ig) {
;           u32x2 o;
;           o.x = pack2(acc[nb][mb][ig * 4 + 0], acc[nb][mb][ig * 4 + 1]);
;           o.y = pack2(acc[nb][mb][ig * 4 + 2], acc[nb][mb][ig * 4 + 3]);
;           *(u32x2*)(slab + tokl * 72 + nb * 32 + ig * 8 + h * 4) = o;
;         }
;       if ((mb & 1) || mb == MB - 1) {
;         asm volatile("s_waitcnt lgkmcnt(0)" ::: "memory");
;         const int ntok = (mb & 1) ? 64 : 32;
;         const int R0 = row0 + wm * (32 * MB) + (mb >> 1) * 64;
; #pragma unroll
;         for (int j = 0; j < 8; ++j) {
;           const int rowl = (lane >> 3) + 8 * j, ch = lane & 7;
;           if (rowl < ntok) {
;             const u32x4 yv = *(const u32x4*)(slab + rowl * 72 + ch * 8);
;             const int R = R0 + rowl;
;             const int mi = (R < NLAT) ? (R >> 11) : 16;
;             const int col = n0 + wn * 64 + ch * 8;
;             const float* g = gate + (size_t)mi * 6144 + col;
;             const f32x4n g0 = *(const f32x4n*)(g), g1 = *(const f32x4n*)(g + 4);
;             _Float16* xp = X + (size_t)R * 1024 + col;
;             const h8 xv = *(const h8*)xp;
;             const float y[8] = {__uint_as_float(yv.x << 16), __uint_as_float(yv.x & 0xffff0000u), __uint_as_float(yv.y << 16), __uint_as_float(yv.y & 0xffff0000u),
;                                 __uint_as_float(yv.z << 16), __uint_as_float(yv.z & 0xffff0000u), __uint_as_float(yv.w << 16), __uint_as_float(yv.w & 0xffff0000u)};
;             const float gg[8] = {g0.x, g0.y, g0.z, g0.w, g1.x, g1.y, g1.z, g1.w};
;             h8 o;
; #pragma unroll
;             for (int q = 0; q < 8; ++q) o[q] = (_Float16)(ALPHA * (float)xv[q] + gg[q] * y[q]);
;             *(h8*)xp = o;
	v_cvt_f32_f16_e32 v108, v96
	global_load_dwordx4 v[82:85], v[104:105], off offset:16
	v_or_b32_e32 v76, 48, v131
	v_or_b32_e32 v86, s2, v76
	v_min_i32_e32 v77, 0x8000, v86
	v_ashrrev_i32_e32 v87, 31, v86
	v_ashrrev_i32_e32 v77, 11, v77
	v_lshlrev_b64 v[86:87], 11, v[86:87]
	v_cvt_f32_f16_sdwa v109, v96 dst_sel:DWORD dst_unused:UNUSED_PAD src0_sel:WORD_1
	v_cvt_f32_f16_e32 v96, v97
	v_cvt_f32_f16_sdwa v97, v97 dst_sel:DWORD dst_unused:UNUSED_PAD src0_sel:WORD_1
	v_cvt_f32_f16_e32 v110, v98
	v_cvt_f32_f16_sdwa v111, v98 dst_sel:DWORD dst_unused:UNUSED_PAD src0_sel:WORD_1
	v_cvt_f32_f16_e32 v98, v99
	v_cvt_f32_f16_sdwa v99, v99 dst_sel:DWORD dst_unused:UNUSED_PAD src0_sel:WORD_1
	v_mul_hi_i32_i24_e32 v89, 0x6000, v77
	v_mul_i32_i24_e32 v88, 0x6000, v77
	v_lshl_add_u64 v[86:87], s[46:47], 0, v[86:87]
	v_lshl_add_u64 v[88:89], s[8:9], 0, v[88:89]
	v_lshl_add_u64 v[102:103], v[86:87], 0, v[66:67]
	v_lshl_add_u64 v[90:91], v[88:89], 0, v[68:69]
	global_load_dwordx4 v[86:89], v[102:103], off
	v_lshlrev_b32_e32 v104, 16, v92
	v_and_b32_e32 v105, 0xffff0000, v92
	v_lshlrev_b32_e32 v92, 16, v93
	v_and_b32_e32 v93, 0xffff0000, v93
	v_pk_mul_f32 v[108:109], v[108:109], s[30:31] op_sel_hi:[1,0]
	v_pk_mul_f32 v[96:97], v[96:97], s[30:31] op_sel_hi:[1,0]
	v_pk_mul_f32 v[110:111], v[110:111], s[30:31] op_sel_hi:[1,0]
	v_pk_mul_f32 v[98:99], v[98:99], s[30:31] op_sel_hi:[1,0]
	v_or_b32_e32 v77, 56, v131
	s_waitcnt vmcnt(2)
	v_pk_fma_f32 v[78:79], v[78:79], v[104:105], v[108:109]
	v_pk_fma_f32 v[80:81], v[80:81], v[92:93], v[96:97]
	v_cvt_pk_f16_f32 v78, v78, v79
	v_cvt_pk_f16_f32 v79, v80, v81
	s_waitcnt vmcnt(1)
	v_pk_fma_f32 v[82:83], v[82:83], v[106:107], v[110:111]
	v_pk_fma_f32 v[84:85], v[84:85], v[94:95], v[98:99]
	v_cvt_pk_f16_f32 v80, v82, v83
	v_cvt_pk_f16_f32 v81, v84, v85
	global_store_dwordx4 v[100:101], v[78:81], off
	global_load_dwordx4 v[78:81], v[90:91], off
	s_waitcnt vmcnt(2)
	v_cvt_f32_f16_e32 v112, v86
	global_load_dwordx4 v[82:85], v[90:91], off offset:16
	v_or_b32_e32 v90, s2, v77
	v_min_i32_e32 v92, 0x8000, v90
	v_ashrrev_i32_e32 v91, 31, v90
	v_ashrrev_i32_e32 v92, 11, v92
	v_lshlrev_b64 v[90:91], 11, v[90:91]
	v_mul_hi_i32_i24_e32 v93, 0x6000, v92
	v_mul_i32_i24_e32 v92, 0x6000, v92
	v_lshl_add_u64 v[94:95], s[46:47], 0, v[90:91]
	v_lshl_add_u64 v[96:97], s[8:9], 0, v[92:93]
	ds_read_b128 v[90:93], v0 offset:6912
	v_cvt_f32_f16_sdwa v113, v86 dst_sel:DWORD dst_unused:UNUSED_PAD src0_sel:WORD_1
	v_cvt_f32_f16_e32 v86, v87
	v_cvt_f32_f16_sdwa v87, v87 dst_sel:DWORD dst_unused:UNUSED_PAD src0_sel:WORD_1
	v_cvt_f32_f16_e32 v114, v88
	v_cvt_f32_f16_sdwa v115, v88 dst_sel:DWORD dst_unused:UNUSED_PAD src0_sel:WORD_1
	v_cvt_f32_f16_e32 v88, v89
	v_cvt_f32_f16_sdwa v89, v89 dst_sel:DWORD dst_unused:UNUSED_PAD src0_sel:WORD_1
	v_lshl_add_u64 v[104:105], v[94:95], 0, v[66:67]
	global_load_dwordx4 v[98:101], v[104:105], off
	s_waitcnt lgkmcnt(0)
	v_lshlrev_b32_e32 v108, 16, v90
	v_and_b32_e32 v109, 0xffff0000, v90
	v_lshlrev_b32_e32 v90, 16, v91
	v_and_b32_e32 v91, 0xffff0000, v91
	v_lshlrev_b32_e32 v110, 16, v92
	v_and_b32_e32 v111, 0xffff0000, v92
	v_lshlrev_b32_e32 v92, 16, v93
	v_and_b32_e32 v93, 0xffff0000, v93
	v_pk_mul_f32 v[112:113], v[112:113], s[30:31] op_sel_hi:[1,0]
	v_pk_mul_f32 v[86:87], v[86:87], s[30:31] op_sel_hi:[1,0]
	v_pk_mul_f32 v[114:115], v[114:115], s[30:31] op_sel_hi:[1,0]
	v_pk_mul_f32 v[88:89], v[88:89], s[30:31] op_sel_hi:[1,0]
	v_lshl_add_u64 v[106:107], v[96:97], 0, v[68:69]
	ds_read_b128 v[94:97], v0 offset:8064
	ds_write2_b64 v70, v[10:11], v[12:13] offset0:72 offset1:74
	ds_write2_b64 v70, v[14:15], v[16:17] offset0:76 offset1:78
	s_add_i32 s2, s2, 64
	v_or_b32_e32 v34, s2, v131
	ds_write2_b64 v70, v[2:3], v[4:5] offset0:64 offset1:66
	ds_write2_b64 v70, v[6:7], v[8:9] offset0:68 offset1:70
	s_waitcnt lgkmcnt(4)
	v_lshlrev_b32_e32 v2, 16, v94
	v_and_b32_e32 v3, 0xffff0000, v94
	v_lshlrev_b32_e32 v4, 16, v95
	v_and_b32_e32 v5, 0xffff0000, v95
	v_lshlrev_b32_e32 v6, 16, v96
	v_and_b32_e32 v7, 0xffff0000, v96
	v_lshlrev_b32_e32 v8, 16, v97
	v_and_b32_e32 v9, 0xffff0000, v97
	v_ashrrev_i32_e32 v35, 31, v34
	v_lshlrev_b64 v[36:37], 11, v[34:35]
	v_lshl_add_u64 v[36:37], s[46:47], 0, v[36:37]
	ds_write2_b64 v130, v[18:19], v[20:21] offset1:2
	ds_write2_b64 v130, v[22:23], v[24:25] offset0:4 offset1:6
	ds_write2_b64 v130, v[26:27], v[28:29] offset0:8 offset1:10
	ds_write2_b64 v130, v[30:31], v[32:33] offset0:12 offset1:14
	v_lshl_add_u64 v[36:37], v[36:37], 0, v[66:67]
	s_waitcnt vmcnt(2)
	v_pk_fma_f32 v[78:79], v[78:79], v[108:109], v[112:113]
	v_pk_fma_f32 v[80:81], v[80:81], v[90:91], v[86:87]
	v_cvt_pk_f16_f32 v78, v78, v79
	v_cvt_pk_f16_f32 v79, v80, v81
	s_waitcnt vmcnt(1)
	v_pk_fma_f32 v[82:83], v[82:83], v[110:111], v[114:115]
	v_pk_fma_f32 v[84:85], v[84:85], v[92:93], v[88:89]
	v_cvt_pk_f16_f32 v80, v82, v83
	v_cvt_pk_f16_f32 v81, v84, v85
	global_store_dwordx4 v[102:103], v[78:81], off
	global_load_dwordx4 v[78:81], v[106:107], off
	s_waitcnt vmcnt(2)
	v_cvt_f32_f16_e32 v10, v98
	global_load_dwordx4 v[82:85], v[106:107], off offset:16
	v_cvt_f32_f16_sdwa v11, v98 dst_sel:DWORD dst_unused:UNUSED_PAD src0_sel:WORD_1
	v_cvt_f32_f16_e32 v12, v99
	v_cvt_f32_f16_sdwa v13, v99 dst_sel:DWORD dst_unused:UNUSED_PAD src0_sel:WORD_1
	v_cvt_f32_f16_e32 v14, v100
	v_cvt_f32_f16_sdwa v15, v100 dst_sel:DWORD dst_unused:UNUSED_PAD src0_sel:WORD_1
	v_cvt_f32_f16_e32 v16, v101
	v_cvt_f32_f16_sdwa v17, v101 dst_sel:DWORD dst_unused:UNUSED_PAD src0_sel:WORD_1
	v_pk_mul_f32 v[10:11], v[10:11], s[30:31] op_sel_hi:[1,0]
	v_pk_mul_f32 v[12:13], v[12:13], s[30:31] op_sel_hi:[1,0]
	v_pk_mul_f32 v[14:15], v[14:15], s[30:31] op_sel_hi:[1,0]
	v_pk_mul_f32 v[16:17], v[16:17], s[30:31] op_sel_hi:[1,0]
	s_waitcnt vmcnt(1)
;   DI void operator()(f32x16 (&acc)[2][MB], int wm, int wn, int r, int h) {
;     ...
;         for (int j = 0; j < 8; ++j) {
;           const int rowl = (lane >> 3) + 8 * j, ch = lane & 7;
;           if (rowl < ntok) {
;             const u32x4 yv = *(const u32x4*)(slab + rowl * 72 + ch * 8);
;             const int R = R0 + rowl;
;             const int mi = (R < NLAT) ? (R >> 11) : 16;
;             const int col = n0 + wn * 64 + ch * 8;
;             const float* g = gate + (size_t)mi * 6144 + col;
;             const f32x4n g0 = *(const f32x4n*)(g), g1 = *(const f32x4n*)(g + 4);
;             _Float16* xp = X + (size_t)R * 1024 + col;
;             const h8 xv = *(const h8*)xp;
;             const float y[8] = {__uint_as_float(yv.x << 16), __uint_as_float(yv.x & 0xffff0000u), __uint_as_float(yv.y << 16), __uint_as_float(yv.y & 0xffff0000u),
;                                 __uint_as_float(yv.z << 16), __uint_as_float(yv.z & 0xffff0000u), __uint_as_float(yv.w << 16), __uint_as_float(yv.w & 0xffff0000u)};
;             const float gg[8] = {g0.x, g0.y, g0.z, g0.w, g1.x, g1.y, g1.z, g1.w};
;             h8 o;
; #pragma unroll
;             for (int q = 0; q < 8; ++q) o[q] = (_Float16)(ALPHA * (float)xv[q] + gg[q] * y[q]);
;             *(h8*)xp = o;
	v_pk_fma_f32 v[2:3], v[78:79], v[2:3], v[10:11]
	v_pk_fma_f32 v[4:5], v[80:81], v[4:5], v[12:13]
	v_cvt_pk_f16_f32 v2, v2, v3
	v_cvt_pk_f16_f32 v3, v4, v5
	s_waitcnt vmcnt(0)
	v_pk_fma_f32 v[6:7], v[82:83], v[6:7], v[14:15]
	v_pk_fma_f32 v[8:9], v[84:85], v[8:9], v[16:17]
	v_cvt_pk_f16_f32 v4, v6, v7
	v_cvt_pk_f16_f32 v5, v8, v9
	global_store_dwordx4 v[104:105], v[2:5], off
	s_waitcnt lgkmcnt(0)
	global_load_dwordx4 v[2:5], v[36:37], off
	v_min_i32_e32 v6, 0x8000, v34
	v_ashrrev_i32_e32 v6, 11, v6
	v_mul_hi_i32_i24_e32 v7, 0x6000, v6
	v_mul_i32_i24_e32 v6, 0x6000, v6
	v_lshl_add_u64 v[6:7], s[8:9], 0, v[6:7]
	v_lshl_add_u64 v[10:11], v[6:7], 0, v[68:69]
	global_load_dwordx4 v[6:9], v[10:11], off
	v_or_b32_e32 v14, s2, v71
	global_load_dwordx4 v[10:13], v[10:11], off offset:16
	v_min_i32_e32 v16, 0x8000, v14
	v_ashrrev_i32_e32 v15, 31, v14
	v_ashrrev_i32_e32 v16, 11, v16
	v_lshlrev_b64 v[14:15], 11, v[14:15]
	v_mul_hi_i32_i24_e32 v17, 0x6000, v16
	v_mul_i32_i24_e32 v16, 0x6000, v16
	v_lshl_add_u64 v[18:19], s[46:47], 0, v[14:15]
	v_lshl_add_u64 v[20:21], s[8:9], 0, v[16:17]
	ds_read_b128 v[14:17], v0
	v_lshl_add_u64 v[26:27], v[18:19], 0, v[66:67]
	global_load_dwordx4 v[22:25], v[26:27], off
	v_lshl_add_u64 v[28:29], v[20:21], 0, v[68:69]
	ds_read_b128 v[18:21], v0 offset:1152
	s_waitcnt lgkmcnt(1)
	v_lshlrev_b32_e32 v30, 16, v14
	v_and_b32_e32 v31, 0xffff0000, v14
	v_lshlrev_b32_e32 v14, 16, v15
	v_and_b32_e32 v15, 0xffff0000, v15
	v_lshlrev_b32_e32 v32, 16, v16
	v_and_b32_e32 v33, 0xffff0000, v16
	v_lshlrev_b32_e32 v16, 16, v17
	v_and_b32_e32 v17, 0xffff0000, v17
	s_waitcnt vmcnt(3)
	v_cvt_f32_f16_e32 v34, v2
	v_cvt_f32_f16_sdwa v35, v2 dst_sel:DWORD dst_unused:UNUSED_PAD src0_sel:WORD_1
	v_cvt_f32_f16_e32 v2, v3
	v_cvt_f32_f16_sdwa v3, v3 dst_sel:DWORD dst_unused:UNUSED_PAD src0_sel:WORD_1
	v_cvt_f32_f16_e32 v38, v4
	v_cvt_f32_f16_sdwa v39, v4 dst_sel:DWORD dst_unused:UNUSED_PAD src0_sel:WORD_1
	v_cvt_f32_f16_e32 v4, v5
	v_cvt_f32_f16_sdwa v5, v5 dst_sel:DWORD dst_unused:UNUSED_PAD src0_sel:WORD_1
	v_pk_mul_f32 v[34:35], v[34:35], s[30:31] op_sel_hi:[1,0]
	v_pk_mul_f32 v[2:3], v[2:3], s[30:31] op_sel_hi:[1,0]
	v_pk_mul_f32 v[38:39], v[38:39], s[30:31] op_sel_hi:[1,0]
	v_pk_mul_f32 v[4:5], v[4:5], s[30:31] op_sel_hi:[1,0]
	s_waitcnt vmcnt(2)
	v_pk_fma_f32 v[6:7], v[6:7], v[30:31], v[34:35]
	v_pk_fma_f32 v[8:9], v[8:9], v[14:15], v[2:3]
	s_waitcnt vmcnt(1)
	v_pk_fma_f32 v[10:11], v[10:11], v[32:33], v[38:39]
	v_pk_fma_f32 v[12:13], v[12:13], v[16:17], v[4:5]
	v_cvt_pk_f16_f32 v2, v6, v7
	v_cvt_pk_f16_f32 v3, v8, v9
	v_cvt_pk_f16_f32 v4, v10, v11
	v_cvt_pk_f16_f32 v5, v12, v13
	global_store_dwordx4 v[36:37], v[2:5], off
	global_load_dwordx4 v[2:5], v[28:29], off
	v_or_b32_e32 v10, s2, v72
	global_load_dwordx4 v[6:9], v[28:29], off offset:16
	v_min_i32_e32 v12, 0x8000, v10
	v_ashrrev_i32_e32 v11, 31, v10
	v_ashrrev_i32_e32 v12, 11, v12
	v_lshlrev_b64 v[10:11], 11, v[10:11]
	s_waitcnt vmcnt(3)
	v_cvt_f32_f16_e32 v32, v22
	v_cvt_f32_f16_sdwa v33, v22 dst_sel:DWORD dst_unused:UNUSED_PAD src0_sel:WORD_1
	v_cvt_f32_f16_e32 v22, v23
	v_cvt_f32_f16_sdwa v23, v23 dst_sel:DWORD dst_unused:UNUSED_PAD src0_sel:WORD_1
	v_cvt_f32_f16_e32 v34, v24
	v_cvt_f32_f16_sdwa v35, v24 dst_sel:DWORD dst_unused:UNUSED_PAD src0_sel:WORD_1
	v_cvt_f32_f16_e32 v24, v25
	v_cvt_f32_f16_sdwa v25, v25 dst_sel:DWORD dst_unused:UNUSED_PAD src0_sel:WORD_1
	v_mul_hi_i32_i24_e32 v13, 0x6000, v12
	v_mul_i32_i24_e32 v12, 0x6000, v12
	v_lshl_add_u64 v[10:11], s[46:47], 0, v[10:11]
	v_lshl_add_u64 v[12:13], s[8:9], 0, v[12:13]
	v_lshl_add_u64 v[28:29], v[10:11], 0, v[66:67]
	v_lshl_add_u64 v[14:15], v[12:13], 0, v[68:69]
	global_load_dwordx4 v[10:13], v[28:29], off
	s_waitcnt lgkmcnt(0)
	v_lshlrev_b32_e32 v16, 16, v18
	v_and_b32_e32 v17, 0xffff0000, v18
	v_lshlrev_b32_e32 v18, 16, v19
	v_and_b32_e32 v19, 0xffff0000, v19
	v_lshlrev_b32_e32 v30, 16, v20
	v_and_b32_e32 v31, 0xffff0000, v20
	v_lshlrev_b32_e32 v20, 16, v21
	v_and_b32_e32 v21, 0xffff0000, v21
	v_pk_mul_f32 v[32:33], v[32:33], s[30:31] op_sel_hi:[1,0]
	v_pk_mul_f32 v[22:23], v[22:23], s[30:31] op_sel_hi:[1,0]
	v_pk_mul_f32 v[34:35], v[34:35], s[30:31] op_sel_hi:[1,0]
	v_pk_mul_f32 v[24:25], v[24:25], s[30:31] op_sel_hi:[1,0]
	s_waitcnt vmcnt(2)
	v_pk_fma_f32 v[2:3], v[2:3], v[16:17], v[32:33]
	v_pk_fma_f32 v[4:5], v[4:5], v[18:19], v[22:23]
	s_waitcnt vmcnt(1)
	v_pk_fma_f32 v[6:7], v[6:7], v[30:31], v[34:35]
	v_pk_fma_f32 v[8:9], v[8:9], v[20:21], v[24:25]
	v_cvt_pk_f16_f32 v2, v2, v3
	v_cvt_pk_f16_f32 v3, v4, v5
	v_cvt_pk_f16_f32 v4, v6, v7
	v_cvt_pk_f16_f32 v5, v8, v9
	global_store_dwordx4 v[26:27], v[2:5], off
	global_load_dwordx4 v[2:5], v[14:15], off
	s_waitcnt vmcnt(2)
	v_cvt_f32_f16_e32 v36, v10
	global_load_dwordx4 v[6:9], v[14:15], off offset:16
	v_or_b32_e32 v14, s2, v73
	v_min_i32_e32 v16, 0x8000, v14
	v_ashrrev_i32_e32 v15, 31, v14
	v_ashrrev_i32_e32 v16, 11, v16
	v_lshlrev_b64 v[14:15], 11, v[14:15]
	v_mul_hi_i32_i24_e32 v17, 0x6000, v16
	v_mul_i32_i24_e32 v16, 0x6000, v16
	v_lshl_add_u64 v[18:19], s[46:47], 0, v[14:15]
	v_lshl_add_u64 v[20:21], s[8:9], 0, v[16:17]
	ds_read_b128 v[14:17], v0 offset:2304
	v_cvt_f32_f16_sdwa v37, v10 dst_sel:DWORD dst_unused:UNUSED_PAD src0_sel:WORD_1
	v_cvt_f32_f16_e32 v10, v11
	v_cvt_f32_f16_sdwa v11, v11 dst_sel:DWORD dst_unused:UNUSED_PAD src0_sel:WORD_1
	v_cvt_f32_f16_e32 v38, v12
	v_cvt_f32_f16_sdwa v39, v12 dst_sel:DWORD dst_unused:UNUSED_PAD src0_sel:WORD_1
	v_cvt_f32_f16_e32 v12, v13
	v_cvt_f32_f16_sdwa v13, v13 dst_sel:DWORD dst_unused:UNUSED_PAD src0_sel:WORD_1
	v_lshl_add_u64 v[26:27], v[18:19], 0, v[66:67]
	global_load_dwordx4 v[22:25], v[26:27], off
	s_waitcnt lgkmcnt(0)
;   DI void operator()(f32x16 (&acc)[2][MB], int wm, int wn, int r, int h) {
;     ...
;         for (int j = 0; j < 8; ++j) {
;           const int rowl = (lane >> 3) + 8 * j, ch = lane & 7;
;           if (rowl < ntok) {
;             const u32x4 yv = *(const u32x4*)(slab + rowl * 72 + ch * 8);
;             const int R = R0 + rowl;
;             const int mi = (R < NLAT) ? (R >> 11) : 16;
;             const int col = n0 + wn * 64 + ch * 8;
;             const float* g = gate + (size_t)mi * 6144 + col;
;             const f32x4n g0 = *(const f32x4n*)(g), g1 = *(const f32x4n*)(g + 4);
;             _Float16* xp = X + (size_t)R * 1024 + col;
;             const h8 xv = *(const h8*)xp;
;             const float y[8] = {__uint_as_float(yv.x << 16), __uint_as_float(yv.x & 0xffff0000u), __uint_as_float(yv.y << 16), __uint_as_float(yv.y & 0xffff0000u),
;                                 __uint_as_float(yv.z << 16), __uint_as_float(yv.z & 0xffff0000u), __uint_as_float(yv.w << 16), __uint_as_float(yv.w & 0xffff0000u)};
;             const float gg[8] = {g0.x, g0.y, g0.z, g0.w, g1.x, g1.y, g1.z, g1.w};
;             h8 o;
; #pragma unroll
;             for (int q = 0; q < 8; ++q) o[q] = (_Float16)(ALPHA * (float)xv[q] + gg[q] * y[q]);
;             *(h8*)xp = o;
	v_lshlrev_b32_e32 v32, 16, v14
	v_and_b32_e32 v33, 0xffff0000, v14
	v_lshlrev_b32_e32 v14, 16, v15
	v_and_b32_e32 v15, 0xffff0000, v15
	v_lshlrev_b32_e32 v34, 16, v16
	v_and_b32_e32 v35, 0xffff0000, v16
	v_lshlrev_b32_e32 v16, 16, v17
	v_and_b32_e32 v17, 0xffff0000, v17
	v_pk_mul_f32 v[36:37], v[36:37], s[30:31] op_sel_hi:[1,0]
	v_pk_mul_f32 v[10:11], v[10:11], s[30:31] op_sel_hi:[1,0]
	v_pk_mul_f32 v[38:39], v[38:39], s[30:31] op_sel_hi:[1,0]
	v_pk_mul_f32 v[12:13], v[12:13], s[30:31] op_sel_hi:[1,0]
	v_lshl_add_u64 v[30:31], v[20:21], 0, v[68:69]
	ds_read_b128 v[18:21], v0 offset:3456
	s_waitcnt vmcnt(2)
	v_pk_fma_f32 v[2:3], v[2:3], v[32:33], v[36:37]
	v_pk_fma_f32 v[4:5], v[4:5], v[14:15], v[10:11]
	v_cvt_pk_f16_f32 v2, v2, v3
	v_cvt_pk_f16_f32 v3, v4, v5
	v_or_b32_e32 v10, s2, v74
	v_ashrrev_i32_e32 v11, 31, v10
	s_waitcnt vmcnt(1)
	v_pk_fma_f32 v[6:7], v[6:7], v[34:35], v[38:39]
	v_pk_fma_f32 v[8:9], v[8:9], v[16:17], v[12:13]
	v_cvt_pk_f16_f32 v4, v6, v7
	v_cvt_pk_f16_f32 v5, v8, v9
	global_store_dwordx4 v[28:29], v[2:5], off
	global_load_dwordx4 v[2:5], v[30:31], off
	v_min_i32_e32 v12, 0x8000, v10
	global_load_dwordx4 v[6:9], v[30:31], off offset:16
	v_ashrrev_i32_e32 v12, 11, v12
	v_lshlrev_b64 v[10:11], 11, v[10:11]
	v_mul_hi_i32_i24_e32 v13, 0x6000, v12
	v_mul_i32_i24_e32 v12, 0x6000, v12
	v_lshl_add_u64 v[10:11], s[46:47], 0, v[10:11]
	v_lshl_add_u64 v[12:13], s[8:9], 0, v[12:13]
	v_lshl_add_u64 v[28:29], v[10:11], 0, v[66:67]
	v_lshl_add_u64 v[14:15], v[12:13], 0, v[68:69]
	global_load_dwordx4 v[10:13], v[28:29], off
	s_waitcnt lgkmcnt(0)
	v_lshlrev_b32_e32 v16, 16, v18
	v_and_b32_e32 v17, 0xffff0000, v18
	s_waitcnt vmcnt(4)
	v_cvt_f32_f16_e32 v32, v22
	v_cvt_f32_f16_sdwa v33, v22 dst_sel:DWORD dst_unused:UNUSED_PAD src0_sel:WORD_1
	v_cvt_f32_f16_e32 v22, v23
	v_cvt_f32_f16_sdwa v23, v23 dst_sel:DWORD dst_unused:UNUSED_PAD src0_sel:WORD_1
	v_cvt_f32_f16_e32 v34, v24
	v_cvt_f32_f16_sdwa v35, v24 dst_sel:DWORD dst_unused:UNUSED_PAD src0_sel:WORD_1
	v_cvt_f32_f16_e32 v24, v25
	v_cvt_f32_f16_sdwa v25, v25 dst_sel:DWORD dst_unused:UNUSED_PAD src0_sel:WORD_1
	v_lshlrev_b32_e32 v18, 16, v19
	v_and_b32_e32 v19, 0xffff0000, v19
	v_lshlrev_b32_e32 v30, 16, v20
	v_and_b32_e32 v31, 0xffff0000, v20
	v_lshlrev_b32_e32 v20, 16, v21
	v_and_b32_e32 v21, 0xffff0000, v21
	v_pk_mul_f32 v[32:33], v[32:33], s[30:31] op_sel_hi:[1,0]
	v_pk_mul_f32 v[22:23], v[22:23], s[30:31] op_sel_hi:[1,0]
	v_pk_mul_f32 v[34:35], v[34:35], s[30:31] op_sel_hi:[1,0]
	v_pk_mul_f32 v[24:25], v[24:25], s[30:31] op_sel_hi:[1,0]
	s_waitcnt vmcnt(2)
	v_pk_fma_f32 v[2:3], v[2:3], v[16:17], v[32:33]
	v_pk_fma_f32 v[4:5], v[4:5], v[18:19], v[22:23]
	s_waitcnt vmcnt(1)
	v_pk_fma_f32 v[6:7], v[6:7], v[30:31], v[34:35]
	v_pk_fma_f32 v[8:9], v[8:9], v[20:21], v[24:25]
	v_cvt_pk_f16_f32 v2, v2, v3
	v_cvt_pk_f16_f32 v3, v4, v5
	v_cvt_pk_f16_f32 v4, v6, v7
	v_cvt_pk_f16_f32 v5, v8, v9
	global_store_dwordx4 v[26:27], v[2:5], off
	global_load_dwordx4 v[2:5], v[14:15], off
	s_waitcnt vmcnt(2)
	v_cvt_f32_f16_e32 v36, v10
	global_load_dwordx4 v[6:9], v[14:15], off offset:16
	v_or_b32_e32 v14, s2, v75
	v_min_i32_e32 v16, 0x8000, v14
	v_ashrrev_i32_e32 v15, 31, v14
	v_ashrrev_i32_e32 v16, 11, v16
	v_lshlrev_b64 v[14:15], 11, v[14:15]
	v_mul_hi_i32_i24_e32 v17, 0x6000, v16
	v_mul_i32_i24_e32 v16, 0x6000, v16
	v_lshl_add_u64 v[18:19], s[46:47], 0, v[14:15]
	v_lshl_add_u64 v[20:21], s[8:9], 0, v[16:17]
	ds_read_b128 v[14:17], v0 offset:4608
	v_cvt_f32_f16_sdwa v37, v10 dst_sel:DWORD dst_unused:UNUSED_PAD src0_sel:WORD_1
	v_cvt_f32_f16_e32 v10, v11
	v_cvt_f32_f16_sdwa v11, v11 dst_sel:DWORD dst_unused:UNUSED_PAD src0_sel:WORD_1
	v_cvt_f32_f16_e32 v38, v12
	v_cvt_f32_f16_sdwa v39, v12 dst_sel:DWORD dst_unused:UNUSED_PAD src0_sel:WORD_1
	v_cvt_f32_f16_e32 v12, v13
	v_cvt_f32_f16_sdwa v13, v13 dst_sel:DWORD dst_unused:UNUSED_PAD src0_sel:WORD_1
	v_lshl_add_u64 v[26:27], v[18:19], 0, v[66:67]
	global_load_dwordx4 v[22:25], v[26:27], off
	s_waitcnt lgkmcnt(0)
	v_lshlrev_b32_e32 v32, 16, v14
	v_and_b32_e32 v33, 0xffff0000, v14
	v_lshlrev_b32_e32 v14, 16, v15
	v_and_b32_e32 v15, 0xffff0000, v15
	v_lshlrev_b32_e32 v34, 16, v16
	v_and_b32_e32 v35, 0xffff0000, v16
	v_lshlrev_b32_e32 v16, 16, v17
	v_and_b32_e32 v17, 0xffff0000, v17
	v_pk_mul_f32 v[36:37], v[36:37], s[30:31] op_sel_hi:[1,0]
	v_pk_mul_f32 v[10:11], v[10:11], s[30:31] op_sel_hi:[1,0]
	v_pk_mul_f32 v[38:39], v[38:39], s[30:31] op_sel_hi:[1,0]
	v_pk_mul_f32 v[12:13], v[12:13], s[30:31] op_sel_hi:[1,0]
	v_lshl_add_u64 v[30:31], v[20:21], 0, v[68:69]
	ds_read_b128 v[18:21], v0 offset:5760
	s_waitcnt vmcnt(2)
	v_pk_fma_f32 v[2:3], v[2:3], v[32:33], v[36:37]
	v_pk_fma_f32 v[4:5], v[4:5], v[14:15], v[10:11]
	v_cvt_pk_f16_f32 v2, v2, v3
	s_waitcnt vmcnt(1)
	v_pk_fma_f32 v[6:7], v[6:7], v[34:35], v[38:39]
	v_pk_fma_f32 v[8:9], v[8:9], v[16:17], v[12:13]
	v_cvt_pk_f16_f32 v3, v4, v5
	v_cvt_pk_f16_f32 v4, v6, v7
	v_cvt_pk_f16_f32 v5, v8, v9
	global_store_dwordx4 v[28:29], v[2:5], off
	global_load_dwordx4 v[2:5], v[30:31], off
	v_or_b32_e32 v10, s2, v76
	global_load_dwordx4 v[6:9], v[30:31], off offset:16
	v_min_i32_e32 v12, 0x8000, v10
	v_ashrrev_i32_e32 v11, 31, v10
	v_ashrrev_i32_e32 v12, 11, v12
	v_lshlrev_b64 v[10:11], 11, v[10:11]
	v_mul_hi_i32_i24_e32 v13, 0x6000, v12
	v_mul_i32_i24_e32 v12, 0x6000, v12
	v_lshl_add_u64 v[10:11], s[46:47], 0, v[10:11]
	v_lshl_add_u64 v[12:13], s[8:9], 0, v[12:13]
	v_lshl_add_u64 v[28:29], v[10:11], 0, v[66:67]
	v_lshl_add_u64 v[14:15], v[12:13], 0, v[68:69]
	s_waitcnt vmcnt(3)
;   DI void operator()(f32x16 (&acc)[2][MB], int wm, int wn, int r, int h) {
;     ...
;         for (int j = 0; j < 8; ++j) {
;           const int rowl = (lane >> 3) + 8 * j, ch = lane & 7;
;           if (rowl < ntok) {
;             const u32x4 yv = *(const u32x4*)(slab + rowl * 72 + ch * 8);
;             const int R = R0 + rowl;
;             const int mi = (R < NLAT) ? (R >> 11) : 16;
;             const int col = n0 + wn * 64 + ch * 8;
;             const float* g = gate + (size_t)mi * 6144 + col;
;             const f32x4n g0 = *(const f32x4n*)(g), g1 = *(const f32x4n*)(g + 4);
;             _Float16* xp = X + (size_t)R * 1024 + col;
;             const h8 xv = *(const h8*)xp;
;             const float y[8] = {__uint_as_float(yv.x << 16), __uint_as_float(yv.x & 0xffff0000u), __uint_as_float(yv.y << 16), __uint_as_float(yv.y & 0xffff0000u),
;                                 __uint_as_float(yv.z << 16), __uint_as_float(yv.z & 0xffff0000u), __uint_as_float(yv.w << 16), __uint_as_float(yv.w & 0xffff0000u)};
;             const float gg[8] = {g0.x, g0.y, g0.z, g0.w, g1.x, g1.y, g1.z, g1.w};
;             h8 o;
; #pragma unroll
;             for (int q = 0; q < 8; ++q) o[q] = (_Float16)(ALPHA * (float)xv[q] + gg[q] * y[q]);
;             *(h8*)xp = o;
;           }
;         }
;       }
;     }
;     __syncthreads();
	v_cvt_f32_f16_e32 v32, v22
	v_cvt_f32_f16_sdwa v33, v22 dst_sel:DWORD dst_unused:UNUSED_PAD src0_sel:WORD_1
	v_cvt_f32_f16_e32 v22, v23
	v_cvt_f32_f16_sdwa v23, v23 dst_sel:DWORD dst_unused:UNUSED_PAD src0_sel:WORD_1
	v_cvt_f32_f16_e32 v34, v24
	v_cvt_f32_f16_sdwa v35, v24 dst_sel:DWORD dst_unused:UNUSED_PAD src0_sel:WORD_1
	v_cvt_f32_f16_e32 v24, v25
	v_cvt_f32_f16_sdwa v25, v25 dst_sel:DWORD dst_unused:UNUSED_PAD src0_sel:WORD_1
	global_load_dwordx4 v[10:13], v[28:29], off
	s_waitcnt lgkmcnt(0)
	v_lshlrev_b32_e32 v16, 16, v18
	v_and_b32_e32 v17, 0xffff0000, v18
	v_lshlrev_b32_e32 v18, 16, v19
	v_and_b32_e32 v19, 0xffff0000, v19
	v_lshlrev_b32_e32 v30, 16, v20
	v_and_b32_e32 v31, 0xffff0000, v20
	v_lshlrev_b32_e32 v20, 16, v21
	v_and_b32_e32 v21, 0xffff0000, v21
	v_pk_mul_f32 v[32:33], v[32:33], s[30:31] op_sel_hi:[1,0]
	v_pk_mul_f32 v[22:23], v[22:23], s[30:31] op_sel_hi:[1,0]
	v_pk_mul_f32 v[34:35], v[34:35], s[30:31] op_sel_hi:[1,0]
	v_pk_mul_f32 v[24:25], v[24:25], s[30:31] op_sel_hi:[1,0]
	s_waitcnt vmcnt(2)
	v_pk_fma_f32 v[2:3], v[2:3], v[16:17], v[32:33]
	v_pk_fma_f32 v[4:5], v[4:5], v[18:19], v[22:23]
	s_waitcnt vmcnt(1)
	v_pk_fma_f32 v[6:7], v[6:7], v[30:31], v[34:35]
	v_pk_fma_f32 v[8:9], v[8:9], v[20:21], v[24:25]
	v_cvt_pk_f16_f32 v2, v2, v3
	v_cvt_pk_f16_f32 v3, v4, v5
	v_cvt_pk_f16_f32 v4, v6, v7
	v_cvt_pk_f16_f32 v5, v8, v9
	global_store_dwordx4 v[26:27], v[2:5], off
	global_load_dwordx4 v[2:5], v[14:15], off
	s_waitcnt vmcnt(2)
	v_cvt_f32_f16_e32 v36, v10
	global_load_dwordx4 v[6:9], v[14:15], off offset:16
	v_or_b32_e32 v14, s2, v77
	v_min_i32_e32 v16, 0x8000, v14
	v_ashrrev_i32_e32 v15, 31, v14
	v_ashrrev_i32_e32 v16, 11, v16
	v_lshlrev_b64 v[14:15], 11, v[14:15]
	v_mul_hi_i32_i24_e32 v17, 0x6000, v16
	v_mul_i32_i24_e32 v16, 0x6000, v16
	v_lshl_add_u64 v[18:19], s[46:47], 0, v[14:15]
	v_lshl_add_u64 v[20:21], s[8:9], 0, v[16:17]
	ds_read_b128 v[14:17], v0 offset:6912
	v_cvt_f32_f16_sdwa v37, v10 dst_sel:DWORD dst_unused:UNUSED_PAD src0_sel:WORD_1
	v_cvt_f32_f16_e32 v10, v11
	v_cvt_f32_f16_sdwa v11, v11 dst_sel:DWORD dst_unused:UNUSED_PAD src0_sel:WORD_1
	v_cvt_f32_f16_e32 v38, v12
	v_cvt_f32_f16_sdwa v39, v12 dst_sel:DWORD dst_unused:UNUSED_PAD src0_sel:WORD_1
	v_cvt_f32_f16_e32 v12, v13
	v_cvt_f32_f16_sdwa v13, v13 dst_sel:DWORD dst_unused:UNUSED_PAD src0_sel:WORD_1
	v_lshl_add_u64 v[26:27], v[18:19], 0, v[66:67]
	global_load_dwordx4 v[22:25], v[26:27], off
	s_waitcnt lgkmcnt(0)
	v_lshlrev_b32_e32 v32, 16, v14
	v_and_b32_e32 v33, 0xffff0000, v14
	v_lshlrev_b32_e32 v14, 16, v15
	v_and_b32_e32 v15, 0xffff0000, v15
	v_lshlrev_b32_e32 v34, 16, v16
	v_and_b32_e32 v35, 0xffff0000, v16
	v_lshlrev_b32_e32 v16, 16, v17
	v_and_b32_e32 v17, 0xffff0000, v17
	v_pk_mul_f32 v[36:37], v[36:37], s[30:31] op_sel_hi:[1,0]
	v_pk_mul_f32 v[10:11], v[10:11], s[30:31] op_sel_hi:[1,0]
	v_pk_mul_f32 v[38:39], v[38:39], s[30:31] op_sel_hi:[1,0]
	v_pk_mul_f32 v[12:13], v[12:13], s[30:31] op_sel_hi:[1,0]
	v_lshl_add_u64 v[30:31], v[20:21], 0, v[68:69]
	ds_read_b128 v[18:21], v0 offset:8064
	s_waitcnt vmcnt(2)
	v_pk_fma_f32 v[2:3], v[2:3], v[32:33], v[36:37]
	v_pk_fma_f32 v[4:5], v[4:5], v[14:15], v[10:11]
	v_cvt_pk_f16_f32 v2, v2, v3
	v_cvt_pk_f16_f32 v3, v4, v5
	s_waitcnt lgkmcnt(0)
	v_lshlrev_b32_e32 v10, 16, v18
	v_and_b32_e32 v11, 0xffff0000, v18
	v_lshlrev_b32_e32 v14, 16, v20
	v_and_b32_e32 v15, 0xffff0000, v20
	s_waitcnt vmcnt(1)
	v_pk_fma_f32 v[6:7], v[6:7], v[34:35], v[38:39]
	v_pk_fma_f32 v[8:9], v[8:9], v[16:17], v[12:13]
	v_cvt_pk_f16_f32 v4, v6, v7
	v_cvt_pk_f16_f32 v5, v8, v9
	global_store_dwordx4 v[28:29], v[2:5], off
	global_load_dwordx4 v[2:5], v[30:31], off
	v_lshlrev_b32_e32 v12, 16, v19
	global_load_dwordx4 v[6:9], v[30:31], off offset:16
	v_and_b32_e32 v13, 0xffff0000, v19
	v_lshlrev_b32_e32 v16, 16, v21
	v_and_b32_e32 v17, 0xffff0000, v21
	s_waitcnt vmcnt(3)
	v_cvt_f32_f16_e32 v18, v22
	v_cvt_f32_f16_sdwa v19, v22 dst_sel:DWORD dst_unused:UNUSED_PAD src0_sel:WORD_1
	v_cvt_f32_f16_e32 v20, v23
	v_cvt_f32_f16_sdwa v21, v23 dst_sel:DWORD dst_unused:UNUSED_PAD src0_sel:WORD_1
	v_cvt_f32_f16_e32 v22, v24
	v_cvt_f32_f16_sdwa v23, v24 dst_sel:DWORD dst_unused:UNUSED_PAD src0_sel:WORD_1
	v_cvt_f32_f16_e32 v24, v25
	v_cvt_f32_f16_sdwa v25, v25 dst_sel:DWORD dst_unused:UNUSED_PAD src0_sel:WORD_1
	v_pk_mul_f32 v[18:19], v[18:19], s[30:31] op_sel_hi:[1,0]
	v_pk_mul_f32 v[20:21], v[20:21], s[30:31] op_sel_hi:[1,0]
	v_pk_mul_f32 v[22:23], v[22:23], s[30:31] op_sel_hi:[1,0]
	v_pk_mul_f32 v[24:25], v[24:25], s[30:31] op_sel_hi:[1,0]
	s_waitcnt vmcnt(1)
	v_pk_fma_f32 v[2:3], v[2:3], v[10:11], v[18:19]
	v_pk_fma_f32 v[4:5], v[4:5], v[12:13], v[20:21]
	s_waitcnt vmcnt(0)
	v_pk_fma_f32 v[6:7], v[6:7], v[14:15], v[22:23]
	v_pk_fma_f32 v[8:9], v[8:9], v[16:17], v[24:25]
	v_cvt_pk_f16_f32 v2, v2, v3
	v_cvt_pk_f16_f32 v3, v4, v5
	v_cvt_pk_f16_f32 v4, v6, v7
	v_cvt_pk_f16_f32 v5, v8, v9
	global_store_dwordx4 v[26:27], v[2:5], off
	s_barrier
	s_branch .LBB0_861
